# 256x128-tile GEMMs: weight (B) tile by LDS-DMA into a 2x16KiB swizzled ring, A tile still via registers; weight-conversion tiles: 16 loads in flight
# speedup vs baseline: 1.0633x; 1.0134x over previous
; #define ZERO_ACC(acc, MI_, NI_)                 \
;   _Pragma("unroll") for (int mi = 0; mi < MI_; ++mi) \
;   _Pragma("unroll") for (int ni = 0; ni < NI_; ++ni) \
;   _Pragma("unroll") for (int e = 0; e < 16; ++e) acc[mi][ni][e] = 0.f;
; template <int MI, int NI>
; __device__ __forceinline__ void gemm_kloop(const bf16* __restrict__ A, size_t lda, const bf16* __restrict__ Bt, size_t ldb, int K,
;                                            f16v (&acc)[MI][NI], bf16* sA, bf16* sB) {
;     ...
;   u4v ra[2 * MI], rb[2 * NI];
;   const int KT = K >> 6;
; #pragma unroll
;   for (int i = 0; i < 2 * MI; ++i) ra[i] = *(const u4v*)(A + (size_t)(lrow + 32 * i) * lda + lseg * 8);
; #pragma unroll
;   for (int i = 0; i < 2 * NI; ++i) rb[i] = *(const u4v*)(Bt + (size_t)(lrow + 32 * i) * ldb + lseg * 8);
; __device__ __forceinline__ void resid_tile(const Params& p, const bf16* A, size_t lda, const bf16* Bt, int K, int mt, int nt, bool x_from_input, bf16* sA, bf16* sB, int dry) {
;   const int m0 = mt * 256, n0 = nt * 128;
;   f16v acc[4][2];
;   ZERO_ACC(acc, 4, 2)
;   gemm_kloop<4, 2>(A + (size_t)m0 * lda, lda, Bt + (size_t)n0 * K, K, K, acc, sA, sB);
.LBB0_16:
	s_lshr_b32 s2, s0, 3
	s_and_b32 s24, s2, 12
	s_lshl_b32 s2, s24, 3
	s_sub_i32 s2, s0, s2
	s_bfe_i32 s3, s2, 0x80000
	s_bfe_u32 s3, s3, 0x2000d
	s_add_i32 s3, s2, s3
	s_bfe_i32 s21, s3, 0x80000
	s_and_b32 s3, s3, 0xfc
	s_sub_i32 s2, s2, s3
	s_or_b32 s20, s24, s88
	s_sext_i32_i8 s25, s2
	s_add_i32 s20, s20, s25
	s_mul_i32 s2, s20, 0xb0000
	s_sext_i32_i16 s21, s21
	s_ashr_i32 s3, s2, 31
	s_ashr_i32 s21, s21, 2
	s_lshl_b64 s[2:3], s[2:3], 1
	v_readlane_b32 s28, v254, 12
	v_mov_b32_e32 v8, v195
	v_readlane_b32 s29, v254, 13
	s_add_u32 s2, s28, s2
	s_addc_u32 s3, s29, s3
	v_lshlrev_b32_e32 v0, 4, v8
	v_ashrrev_i32_e32 v9, 3, v8
	v_and_b32_e32 v0, 0x70, v0
	v_lshl_add_u64 v[2:3], s[2:3], 0, v[0:1]
	s_movk_i32 s26, 0x1600
	v_add_u32_e32 v10, 32, v9
	v_mad_i64_i32 v[4:5], s[2:3], v9, s26, v[2:3]
	v_mad_i64_i32 v[6:7], s[2:3], v10, s26, v[2:3]
	v_add_u32_e32 v11, 64, v9
	v_add_u32_e32 v12, 0x60, v9
	s_mul_i32 s22, s21, 0x58000
	global_load_dwordx4 v[134:137], v[4:5], off
	global_load_dwordx4 v[138:141], v[6:7], off
	v_mad_i64_i32 v[4:5], s[2:3], v11, s26, v[2:3]
	v_mad_i64_i32 v[6:7], s[2:3], v12, s26, v[2:3]
	s_ashr_i32 s23, s22, 31
	global_load_dwordx4 v[142:145], v[4:5], off
	global_load_dwordx4 v[146:149], v[6:7], off
	v_add_u32_e32 v4, 0x80, v9
	v_add_u32_e32 v6, 0xa0, v9
	s_lshl_b64 s[22:23], s[22:23], 1
	v_readlane_b32 s64, v252, 23
	v_mad_i64_i32 v[4:5], s[2:3], v4, s26, v[2:3]
	v_mad_i64_i32 v[6:7], s[2:3], v6, s26, v[2:3]
	v_readlane_b32 s65, v252, 24
	s_add_u32 s22, s64, s22
	global_load_dwordx4 v[154:157], v[4:5], off
	global_load_dwordx4 v[150:153], v[6:7], off
	v_add_u32_e32 v4, 0xc0, v9
	v_add_u32_e32 v6, 0xe0, v9
	s_addc_u32 s23, s65, s23
	v_mad_i64_i32 v[4:5], s[2:3], v4, s26, v[2:3]
	v_mad_i64_i32 v[2:3], s[2:3], v6, s26, v[2:3]
	global_load_dwordx4 v[162:165], v[4:5], off
	global_load_dwordx4 v[158:161], v[2:3], off
	v_lshl_add_u64 v[2:3], s[22:23], 0, v[0:1]
	v_mad_i64_i32 v[4:5], s[2:3], v9, s26, v[2:3]
	v_mad_i64_i32 v[6:7], s[2:3], v10, s26, v[2:3]
	v_mad_i64_i32 v[4:5], s[2:3], v11, s26, v[2:3]
	v_mad_i64_i32 v[2:3], s[2:3], v12, s26, v[2:3]
	v_and_b32_e32 v2, 0xfffff9f, v8
	v_lshrrev_b32_e32 v3, 1, v8
	v_and_b32_e32 v4, 16, v3
	v_and_b32_e32 v3, 0x5f, v8
	v_mul_lo_u32 v6, v2, s33
	v_or_b32_e32 v2, 0x60, v8
	v_mul_lo_u32 v7, v2, s33
	v_mul_u32_u24_e32 v8, 0x90, v3
	v_mad_i64_i32 v[2:3], s[2:3], v9, s26, 0
	s_add_i32 s2, s88, s24
	s_add_i32 s2, s2, s25
	s_mul_i32 s2, s2, 0xb0000
	s_ashr_i32 s3, s2, 31
	s_lshl_b64 s[2:3], s[2:3], 1
	s_add_u32 s2, s28, s2
	v_or_b32_e32 v2, v2, v0
	s_addc_u32 s3, s29, s3
	v_mul_lo_u32 v5, v9, s33
	s_waitcnt vmcnt(31)
	v_lshl_add_u64 v[178:179], s[2:3], 0, v[2:3]
	v_lshl_add_u64 v[180:181], s[22:23], 0, v[2:3]
	v_mov_b32_e32 v2, 0
	s_mov_b64 s[2:3], 0
	s_waitcnt vmcnt(30)
	v_add_u32_e32 v184, v0, v5
	v_add_u32_e32 v182, v4, v6
	v_add_u32_e32 v0, v4, v7
	v_add_u32_e32 v183, v4, v8
	v_mov_b32_e32 v3, v2
	v_mov_b32_e32 v4, v2
	v_mov_b32_e32 v5, v2
	v_mov_b32_e32 v6, v2
	v_mov_b32_e32 v7, v2
	v_mov_b32_e32 v8, v2
	v_mov_b32_e32 v9, v2
	v_mov_b32_e32 v10, v2
	v_mov_b32_e32 v11, v2
	v_mov_b32_e32 v12, v2
	v_mov_b32_e32 v13, v2
	v_mov_b32_e32 v14, v2
	v_mov_b32_e32 v15, v2
	v_mov_b32_e32 v16, v2
	v_mov_b32_e32 v17, v2
	v_mov_b32_e32 v18, v2
	v_mov_b32_e32 v19, v2
	v_mov_b32_e32 v20, v2
	v_mov_b32_e32 v21, v2
	v_mov_b32_e32 v22, v2
	v_mov_b32_e32 v23, v2
	v_mov_b32_e32 v24, v2
	v_mov_b32_e32 v25, v2
	v_mov_b32_e32 v26, v2
	v_mov_b32_e32 v27, v2
	v_mov_b32_e32 v28, v2
	v_mov_b32_e32 v29, v2
	v_mov_b32_e32 v30, v2
	v_mov_b32_e32 v31, v2
	v_mov_b32_e32 v32, v2
	v_mov_b32_e32 v33, v2
	v_mov_b32_e32 v34, v2
	v_mov_b32_e32 v35, v2
	v_mov_b32_e32 v36, v2
	v_mov_b32_e32 v37, v2
	v_mov_b32_e32 v38, v2
	v_mov_b32_e32 v39, v2
	v_mov_b32_e32 v40, v2
	v_mov_b32_e32 v41, v2
	v_mov_b32_e32 v42, v2
	v_mov_b32_e32 v43, v2
	v_mov_b32_e32 v44, v2
	v_mov_b32_e32 v45, v2
	v_mov_b32_e32 v46, v2
	v_mov_b32_e32 v47, v2
	v_mov_b32_e32 v48, v2
	v_mov_b32_e32 v49, v2
	v_mov_b32_e32 v50, v2
	v_mov_b32_e32 v51, v2
	v_mov_b32_e32 v52, v2
	v_mov_b32_e32 v53, v2
	v_mov_b32_e32 v54, v2
	v_mov_b32_e32 v55, v2
	v_mov_b32_e32 v56, v2
	v_mov_b32_e32 v57, v2
	v_mov_b32_e32 v58, v2
	v_mov_b32_e32 v59, v2
	v_mov_b32_e32 v60, v2
	v_mov_b32_e32 v61, v2
	v_mov_b32_e32 v62, v2
	v_mov_b32_e32 v63, v2
	v_mov_b32_e32 v64, v2
	v_mov_b32_e32 v65, v2
	v_mov_b32_e32 v66, v2
	v_mov_b32_e32 v67, v2
	v_mov_b32_e32 v68, v2
	v_mov_b32_e32 v69, v2
	v_mov_b32_e32 v70, v2
	v_mov_b32_e32 v71, v2
	v_mov_b32_e32 v72, v2
	v_mov_b32_e32 v73, v2
	v_mov_b32_e32 v74, v2
	v_mov_b32_e32 v75, v2
	v_mov_b32_e32 v76, v2
	v_mov_b32_e32 v77, v2
	v_mov_b32_e32 v78, v2
	v_mov_b32_e32 v79, v2
	v_mov_b32_e32 v80, v2
	v_mov_b32_e32 v81, v2
	v_mov_b32_e32 v82, v2
	v_mov_b32_e32 v83, v2
	v_mov_b32_e32 v84, v2
	v_mov_b32_e32 v85, v2
	v_mov_b32_e32 v86, v2
	v_mov_b32_e32 v87, v2
	v_mov_b32_e32 v88, v2
	v_mov_b32_e32 v89, v2
	v_mov_b32_e32 v90, v2
	v_mov_b32_e32 v91, v2
	v_mov_b32_e32 v92, v2
	v_mov_b32_e32 v93, v2
	v_mov_b32_e32 v94, v2
	v_mov_b32_e32 v95, v2
	v_mov_b32_e32 v96, v2
	v_mov_b32_e32 v97, v2
	v_mov_b32_e32 v98, v2
	v_mov_b32_e32 v99, v2
	v_mov_b32_e32 v100, v2
	v_mov_b32_e32 v101, v2
	v_mov_b32_e32 v102, v2
	v_mov_b32_e32 v103, v2
	v_mov_b32_e32 v104, v2
	v_mov_b32_e32 v105, v2
	v_mov_b32_e32 v106, v2
	v_mov_b32_e32 v107, v2
	v_mov_b32_e32 v108, v2
	v_mov_b32_e32 v109, v2
	v_mov_b32_e32 v110, v2
	v_mov_b32_e32 v111, v2
	v_mov_b32_e32 v112, v2
	v_mov_b32_e32 v113, v2
	v_mov_b32_e32 v114, v2
	v_mov_b32_e32 v115, v2
	v_mov_b32_e32 v116, v2
	v_mov_b32_e32 v117, v2
	v_mov_b32_e32 v118, v2
	v_mov_b32_e32 v119, v2
	v_mov_b32_e32 v120, v2
	v_mov_b32_e32 v121, v2
; template <int MI, int NI>
; __device__ __forceinline__ void gemm_kloop(const bf16* __restrict__ A, size_t lda, const bf16* __restrict__ Bt, size_t ldb, int K,
;                                            f16v (&acc)[MI][NI], bf16* sA, bf16* sB) {
;   const int tid = tid_opaque(), lane = tid & 63, w = tid >> 6;
;   const int r = lane & 31, hh = lane >> 5;
;   const int wm = w >> 1, wn = w & 1;
;   const int lrow = tid >> 3, lseg = tid & 7;
;   u4v ra[2 * MI], rb[2 * NI];
;   const int KT = K >> 6;
; #pragma unroll
;   for (int i = 0; i < 2 * MI; ++i) ra[i] = *(const u4v*)(A + (size_t)(lrow + 32 * i) * lda + lseg * 8);
; #pragma unroll
;   for (int i = 0; i < 2 * NI; ++i) rb[i] = *(const u4v*)(Bt + (size_t)(lrow + 32 * i) * ldb + lseg * 8);
;   unsigned pfs = 0;
;   {
;     if (tid < 64 * MI) pfs ^= *(const unsigned*)(A + (size_t)tid * lda + 64) ^ *(const unsigned*)(A + (size_t)tid * lda + 128);
;     if (tid < 64 * NI) pfs ^= *(const unsigned*)(Bt + (size_t)tid * ldb + 64) ^ *(const unsigned*)(Bt + (size_t)tid * ldb + 128);
;   }
;   for (int kt = 0; kt < KT; ++kt) {
;     __syncthreads();
; #pragma unroll
;     for (int i = 0; i < 2 * MI; ++i) *(u4v*)(sA + (lrow + 32 * i) * 72 + lseg * 8) = ra[i];
; #pragma unroll
;     for (int i = 0; i < 2 * NI; ++i) *(u4v*)(sB + (lrow + 32 * i) * 72 + lseg * 8) = rb[i];
;     __syncthreads();
;     if (kt + 3 < KT) {
;       const int k2 = (kt + 3) << 6;
;       if (tid < 64 * MI) pfs ^= *(const unsigned*)(A + (size_t)tid * lda + k2);
;       if (tid < 64 * NI) pfs ^= *(const unsigned*)(Bt + (size_t)tid * ldb + k2);
;     }
;     if (kt + 1 < KT) {
;       const int k0 = (kt + 1) << 6;
; #pragma unroll
;       for (int i = 0; i < 2 * MI; ++i) ra[i] = *(const u4v*)(A + (size_t)(lrow + 32 * i) * lda + k0 + lseg * 8);
; #pragma unroll
;       for (int i = 0; i < 2 * NI; ++i) rb[i] = *(const u4v*)(Bt + (size_t)(lrow + 32 * i) * ldb + k0 + lseg * 8);
;     }
; #pragma unroll
;     for (int ks = 0; ks < 4; ++ks) {
;       s8v a[MI], b[NI];
; #pragma unroll
;       for (int mi = 0; mi < MI; ++mi) a[mi] = *(const s8v*)(sA + (wm * 32 * MI + mi * 32 + r) * 72 + ks * 16 + hh * 8);
; #pragma unroll
;       for (int ni = 0; ni < NI; ++ni) b[ni] = *(const s8v*)(sB + (wn * 32 * NI + ni * 32 + r) * 72 + ks * 16 + hh * 8);
; #pragma unroll
;       for (int mi = 0; mi < MI; ++mi)
; #pragma unroll
	v_mov_b32_e32 v122, v2
	v_mov_b32_e32 v123, v2
	v_mov_b32_e32 v124, v2
	v_mov_b32_e32 v125, v2
	v_mov_b32_e32 v126, v2
	v_mov_b32_e32 v127, v2
	v_mov_b32_e32 v128, v2
	v_mov_b32_e32 v129, v2
	s_mov_b32 s23, 0x58000
	s_mov_b32 s24, 0x2c000
	s_mov_b32 s25, 0x84000
	v_readlane_b32 s30, v254, 14
	v_readlane_b32 s31, v254, 15
	v_readlane_b32 s66, v252, 25
	v_readlane_b32 s67, v252, 26
	v_readlane_b32 s68, v252, 27
	v_readlane_b32 s69, v252, 28
	v_readlane_b32 s70, v252, 29
	v_readlane_b32 s71, v252, 30
	v_readlane_b32 s72, v252, 31
	v_readlane_b32 s73, v252, 32
	v_readlane_b32 s74, v252, 33
	v_readlane_b32 s75, v252, 34
	v_readlane_b32 s76, v252, 35
	v_readlane_b32 s77, v252, 36
	v_readlane_b32 s78, v252, 37
	v_readlane_b32 s79, v252, 38
	v_readfirstlane_b32 s56, v178
	v_readfirstlane_b32 s57, v179
	v_readfirstlane_b32 s58, v180
	v_readfirstlane_b32 s59, v181
	v_readfirstlane_b32 s94, v195
	v_subrev_u32_e32 v178, s56, v178
	v_add_u32_e32 v179, 0x2c000, v178
	v_add_u32_e32 v180, 0x58000, v178
	v_add_u32_e32 v181, 0x84000, v178
	v_add_u32_e32 v185, 0xb0000, v178
	v_add_u32_e32 v222, 0xdc000, v178
	v_add_u32_e32 v223, 0x108000, v178
	v_add_u32_e32 v227, 0x134000, v178
	s_lshr_b32 s94, s94, 6
	s_mul_i32 s95, s94, 0xb000
	s_sub_u32 s58, s58, s95
	s_subb_u32 s59, s59, 0
	s_lshl_b32 s96, s94, 12
	s_add_u32 s96, s96, 36864
	v_and_b32_e32 v170, 63, v195
	v_lshrrev_b32_e32 v171, 3, v170
	v_lshrrev_b32_e32 v172, 4, v170
	v_and_b32_e32 v173, 7, v170
	v_xor_b32_e32 v172, v172, v173
	v_lshlrev_b32_e32 v172, 4, v172
	v_lshrrev_b32_e32 v173, 6, v195
	v_lshl_add_u32 v170, v173, 5, v171
	v_mul_u32_u24_e32 v170, 0x1600, v170
	v_add_u32_e32 v130, v170, v172
	v_xor_b32_e32 v172, 64, v172
	v_add_u32_e32 v170, v170, v172
	v_add_u32_e32 v131, 0xac00, v170
	v_add_u32_e32 v132, 0x15800, v130
	v_add_u32_e32 v133, 0x20400, v170
	v_and_b32_e32 v170, 31, v195
	v_bfe_u32 v171, v195, 5, 1
	v_bfe_u32 v172, v170, 1, 3
	v_xor_b32_e32 v171, v171, v172
	v_lshlrev_b32_e32 v171, 4, v171
	v_bfe_u32 v172, v195, 6, 1
	v_lshl_add_u32 v172, v172, 6, v170
	v_lshl_add_u32 v166, v172, 7, v171
	v_xor_b32_e32 v167, 32, v166
	v_xor_b32_e32 v168, 64, v166
	v_xor_b32_e32 v169, 96, v166
	s_barrier
	s_add_u32 m0, s96, 0
	s_nop 0
	global_load_lds_dwordx4 v130, s[58:59] offset:0
	global_load_lds_dwordx4 v131, s[58:59] offset:1024
	global_load_lds_dwordx4 v132, s[58:59] offset:2048
	global_load_lds_dwordx4 v133, s[58:59] offset:3072
	s_barrier
	s_waitcnt vmcnt(11)
	ds_write_b128 v184, v[134:137]
	s_waitcnt vmcnt(10)
	ds_write_b128 v184, v[138:141] offset:4608
	s_waitcnt vmcnt(9)
	ds_write_b128 v184, v[142:145] offset:9216
	s_waitcnt vmcnt(8)
	ds_write_b128 v184, v[146:149] offset:13824
	s_waitcnt vmcnt(7)
	ds_write_b128 v184, v[154:157] offset:18432
	s_waitcnt vmcnt(6)
	ds_write_b128 v184, v[150:153] offset:23040
	s_waitcnt vmcnt(5)
	ds_write_b128 v184, v[162:165] offset:27648
	s_waitcnt vmcnt(4)
	ds_write_b128 v184, v[158:161] offset:32256
	s_waitcnt vmcnt(0) lgkmcnt(0)
	s_barrier
	ds_read_b128 v[186:189], v182
	ds_read_b128 v[204:207], v166 offset:36864
	ds_read_b128 v[208:211], v166 offset:40960
	ds_read_b128 v[190:193], v182 offset:4608
	ds_read_b128 v[196:199], v182 offset:9216
	ds_read_b128 v[200:203], v0
	ds_read_b128 v[212:215], v182 offset:32
	ds_read_b128 v[244:247], v167 offset:36864
	ds_read_b128 v[248:251], v167 offset:40960
	ds_read_b128 v[216:219], v182 offset:4640
	ds_read_b128 v[232:235], v182 offset:9248
	ds_read_b128 v[236:239], v0 offset:32
	s_waitcnt lgkmcnt(10)
	v_mfma_f32_32x32x16_bf16 v[114:129], v[186:189], v[204:207], v[114:129]
	s_add_u32 m0, s96, 16256
	s_nop 0
	s_waitcnt lgkmcnt(9)
	v_mfma_f32_32x32x16_bf16 v[98:113], v[186:189], v[208:211], v[98:113]
	global_load_lds_dwordx4 v130, s[58:59] offset:128
	ds_read_b128 v[186:189], v182 offset:64
	s_waitcnt lgkmcnt(9)
	v_mfma_f32_32x32x16_bf16 v[82:97], v[190:193], v[204:207], v[82:97]
	global_load_lds_dwordx4 v131, s[58:59] offset:1152
	v_mfma_f32_32x32x16_bf16 v[66:81], v[190:193], v[208:211], v[66:81]
	global_load_lds_dwordx4 v132, s[58:59] offset:2176
	ds_read_b128 v[190:193], v182 offset:4672
	s_waitcnt lgkmcnt(9)
	v_mfma_f32_32x32x16_bf16 v[50:65], v[196:199], v[204:207], v[50:65]
	global_load_lds_dwordx4 v133, s[58:59] offset:3200
	v_mfma_f32_32x32x16_bf16 v[34:49], v[196:199], v[208:211], v[34:49]
	global_load_dwordx4 v[134:137], v178, s[56:57] offset:128
	ds_read_b128 v[196:199], v182 offset:9280
	s_waitcnt lgkmcnt(9)
	v_mfma_f32_32x32x16_bf16 v[18:33], v[200:203], v[204:207], v[18:33]
	global_load_dwordx4 v[138:141], v179, s[56:57] offset:128
	v_mfma_f32_32x32x16_bf16 v[2:17], v[200:203], v[208:211], v[2:17]
	global_load_dwordx4 v[142:145], v180, s[56:57] offset:128
	ds_read_b128 v[200:203], v0 offset:64
	ds_read_b128 v[204:207], v168 offset:36864
	ds_read_b128 v[208:211], v168 offset:40960
	s_waitcnt lgkmcnt(10)
	v_mfma_f32_32x32x16_bf16 v[114:129], v[212:215], v[244:247], v[114:129]
	global_load_dwordx4 v[146:149], v181, s[56:57] offset:128
	s_waitcnt lgkmcnt(9)
	v_mfma_f32_32x32x16_bf16 v[98:113], v[212:215], v[248:251], v[98:113]
	global_load_dwordx4 v[154:157], v185, s[56:57] offset:128
	ds_read_b128 v[212:215], v182 offset:96
	s_waitcnt lgkmcnt(9)
	v_mfma_f32_32x32x16_bf16 v[82:97], v[216:219], v[244:247], v[82:97]
	global_load_dwordx4 v[150:153], v222, s[56:57] offset:128
	v_mfma_f32_32x32x16_bf16 v[66:81], v[216:219], v[248:251], v[66:81]
	global_load_dwordx4 v[162:165], v223, s[56:57] offset:128
	ds_read_b128 v[216:219], v182 offset:4704
	s_waitcnt lgkmcnt(9)
	v_mfma_f32_32x32x16_bf16 v[50:65], v[232:235], v[244:247], v[50:65]
	global_load_dwordx4 v[158:161], v227, s[56:57] offset:128
	v_mfma_f32_32x32x16_bf16 v[34:49], v[232:235], v[248:251], v[34:49]
	ds_read_b128 v[232:235], v182 offset:9312
	s_waitcnt lgkmcnt(9)
; #define MFMA(a, b, c) __builtin_amdgcn_mfma_f32_32x32x16_bf16((a), (b), (c), 0, 0, 0)
; template <int MI, int NI>
; __device__ __forceinline__ void gemm_kloop(const bf16* __restrict__ A, size_t lda, const bf16* __restrict__ Bt, size_t ldb, int K,
;                                            f16v (&acc)[MI][NI], bf16* sA, bf16* sB) {
;     ...
;   for (int kt = 0; kt < KT; ++kt) {
;     __syncthreads();
; #pragma unroll
;     for (int i = 0; i < 2 * MI; ++i) *(u4v*)(sA + (lrow + 32 * i) * 72 + lseg * 8) = ra[i];
; #pragma unroll
;     for (int i = 0; i < 2 * NI; ++i) *(u4v*)(sB + (lrow + 32 * i) * 72 + lseg * 8) = rb[i];
;     __syncthreads();
;     if (kt + 3 < KT) {
;       const int k2 = (kt + 3) << 6;
;       if (tid < 64 * MI) pfs ^= *(const unsigned*)(A + (size_t)tid * lda + k2);
;       if (tid < 64 * NI) pfs ^= *(const unsigned*)(Bt + (size_t)tid * ldb + k2);
;     }
;     if (kt + 1 < KT) {
;       const int k0 = (kt + 1) << 6;
; #pragma unroll
;       for (int i = 0; i < 2 * MI; ++i) ra[i] = *(const u4v*)(A + (size_t)(lrow + 32 * i) * lda + k0 + lseg * 8);
; #pragma unroll
;       for (int i = 0; i < 2 * NI; ++i) rb[i] = *(const u4v*)(Bt + (size_t)(lrow + 32 * i) * ldb + k0 + lseg * 8);
;     }
; #pragma unroll
;     for (int ks = 0; ks < 4; ++ks) {
;       s8v a[MI], b[NI];
; #pragma unroll
;       for (int mi = 0; mi < MI; ++mi) a[mi] = *(const s8v*)(sA + (wm * 32 * MI + mi * 32 + r) * 72 + ks * 16 + hh * 8);
; #pragma unroll
;       for (int ni = 0; ni < NI; ++ni) b[ni] = *(const s8v*)(sB + (wn * 32 * NI + ni * 32 + r) * 72 + ks * 16 + hh * 8);
; #pragma unroll
;       for (int mi = 0; mi < MI; ++mi)
; #pragma unroll
;         for (int ni = 0; ni < NI; ++ni) acc[mi][ni] = MFMA(a[mi], b[ni], acc[mi][ni]);
;     }
;   }
	v_mfma_f32_32x32x16_bf16 v[18:33], v[236:239], v[244:247], v[18:33]
	v_mfma_f32_32x32x16_bf16 v[2:17], v[236:239], v[248:251], v[2:17]
	ds_read_b128 v[236:239], v0 offset:96
	ds_read_b128 v[244:247], v169 offset:36864
	ds_read_b128 v[248:251], v169 offset:40960
	s_waitcnt lgkmcnt(7)
	v_mfma_f32_32x32x16_bf16 v[114:129], v[186:189], v[204:207], v[114:129]
	s_waitcnt lgkmcnt(6)
	v_mfma_f32_32x32x16_bf16 v[98:113], v[186:189], v[208:211], v[98:113]
	v_mfma_f32_32x32x16_bf16 v[82:97], v[190:193], v[204:207], v[82:97]
	v_mfma_f32_32x32x16_bf16 v[66:81], v[190:193], v[208:211], v[66:81]
	v_mfma_f32_32x32x16_bf16 v[50:65], v[196:199], v[204:207], v[50:65]
	v_mfma_f32_32x32x16_bf16 v[34:49], v[196:199], v[208:211], v[34:49]
	v_mfma_f32_32x32x16_bf16 v[18:33], v[200:203], v[204:207], v[18:33]
	v_mfma_f32_32x32x16_bf16 v[2:17], v[200:203], v[208:211], v[2:17]
	s_waitcnt lgkmcnt(1)
	v_mfma_f32_32x32x16_bf16 v[114:129], v[212:215], v[244:247], v[114:129]
	s_waitcnt lgkmcnt(0)
	v_mfma_f32_32x32x16_bf16 v[98:113], v[212:215], v[248:251], v[98:113]
	v_mfma_f32_32x32x16_bf16 v[82:97], v[216:219], v[244:247], v[82:97]
	v_mfma_f32_32x32x16_bf16 v[66:81], v[216:219], v[248:251], v[66:81]
	v_mfma_f32_32x32x16_bf16 v[50:65], v[232:235], v[244:247], v[50:65]
	v_mfma_f32_32x32x16_bf16 v[34:49], v[232:235], v[248:251], v[34:49]
	v_mfma_f32_32x32x16_bf16 v[18:33], v[236:239], v[244:247], v[18:33]
	v_mfma_f32_32x32x16_bf16 v[2:17], v[236:239], v[248:251], v[2:17]
	s_add_u32 s56, s56, 0x80
	s_addc_u32 s57, s57, 0
	s_add_u32 s58, s58, 0x80
	s_addc_u32 s59, s59, 0
	s_barrier
	s_waitcnt vmcnt(7)
	ds_write_b128 v184, v[134:137]
	s_waitcnt vmcnt(6)
	ds_write_b128 v184, v[138:141] offset:4608
	s_waitcnt vmcnt(5)
	ds_write_b128 v184, v[142:145] offset:9216
	s_waitcnt vmcnt(4)
	ds_write_b128 v184, v[146:149] offset:13824
	s_waitcnt vmcnt(3)
	ds_write_b128 v184, v[154:157] offset:18432
	s_waitcnt vmcnt(2)
	ds_write_b128 v184, v[150:153] offset:23040
	s_waitcnt vmcnt(1)
	ds_write_b128 v184, v[162:165] offset:27648
	s_waitcnt vmcnt(0)
	ds_write_b128 v184, v[158:161] offset:32256
	s_waitcnt lgkmcnt(0)
	s_barrier
	ds_read_b128 v[186:189], v182
	ds_read_b128 v[204:207], v166 offset:53248
	ds_read_b128 v[208:211], v166 offset:57344
	ds_read_b128 v[190:193], v182 offset:4608
	ds_read_b128 v[196:199], v182 offset:9216
	ds_read_b128 v[200:203], v0
	ds_read_b128 v[212:215], v182 offset:32
	ds_read_b128 v[244:247], v167 offset:53248
	ds_read_b128 v[248:251], v167 offset:57344
	ds_read_b128 v[216:219], v182 offset:4640
	ds_read_b128 v[232:235], v182 offset:9248
	ds_read_b128 v[236:239], v0 offset:32
	s_waitcnt lgkmcnt(10)
	v_mfma_f32_32x32x16_bf16 v[114:129], v[186:189], v[204:207], v[114:129]
	s_add_u32 m0, s96, -128
	s_nop 0
	s_waitcnt lgkmcnt(9)
	v_mfma_f32_32x32x16_bf16 v[98:113], v[186:189], v[208:211], v[98:113]
	global_load_lds_dwordx4 v130, s[58:59] offset:128
	ds_read_b128 v[186:189], v182 offset:64
	s_waitcnt lgkmcnt(9)
	v_mfma_f32_32x32x16_bf16 v[82:97], v[190:193], v[204:207], v[82:97]
	global_load_lds_dwordx4 v131, s[58:59] offset:1152
	v_mfma_f32_32x32x16_bf16 v[66:81], v[190:193], v[208:211], v[66:81]
	global_load_lds_dwordx4 v132, s[58:59] offset:2176
	ds_read_b128 v[190:193], v182 offset:4672
	s_waitcnt lgkmcnt(9)
	v_mfma_f32_32x32x16_bf16 v[50:65], v[196:199], v[204:207], v[50:65]
	global_load_lds_dwordx4 v133, s[58:59] offset:3200
	v_mfma_f32_32x32x16_bf16 v[34:49], v[196:199], v[208:211], v[34:49]
	global_load_dwordx4 v[134:137], v178, s[56:57] offset:128
	ds_read_b128 v[196:199], v182 offset:9280
	s_waitcnt lgkmcnt(9)
	v_mfma_f32_32x32x16_bf16 v[18:33], v[200:203], v[204:207], v[18:33]
	global_load_dwordx4 v[138:141], v179, s[56:57] offset:128
	v_mfma_f32_32x32x16_bf16 v[2:17], v[200:203], v[208:211], v[2:17]
	global_load_dwordx4 v[142:145], v180, s[56:57] offset:128
	ds_read_b128 v[200:203], v0 offset:64
	ds_read_b128 v[204:207], v168 offset:53248
	ds_read_b128 v[208:211], v168 offset:57344
	s_waitcnt lgkmcnt(10)
	v_mfma_f32_32x32x16_bf16 v[114:129], v[212:215], v[244:247], v[114:129]
	global_load_dwordx4 v[146:149], v181, s[56:57] offset:128
	s_waitcnt lgkmcnt(9)
	v_mfma_f32_32x32x16_bf16 v[98:113], v[212:215], v[248:251], v[98:113]
	global_load_dwordx4 v[154:157], v185, s[56:57] offset:128
	ds_read_b128 v[212:215], v182 offset:96
	s_waitcnt lgkmcnt(9)
	v_mfma_f32_32x32x16_bf16 v[82:97], v[216:219], v[244:247], v[82:97]
	global_load_dwordx4 v[150:153], v222, s[56:57] offset:128
	v_mfma_f32_32x32x16_bf16 v[66:81], v[216:219], v[248:251], v[66:81]
	global_load_dwordx4 v[162:165], v223, s[56:57] offset:128
	ds_read_b128 v[216:219], v182 offset:4704
	s_waitcnt lgkmcnt(9)
	v_mfma_f32_32x32x16_bf16 v[50:65], v[232:235], v[244:247], v[50:65]
	global_load_dwordx4 v[158:161], v227, s[56:57] offset:128
	v_mfma_f32_32x32x16_bf16 v[34:49], v[232:235], v[248:251], v[34:49]
	ds_read_b128 v[232:235], v182 offset:9312
	s_waitcnt lgkmcnt(9)
	v_mfma_f32_32x32x16_bf16 v[18:33], v[236:239], v[244:247], v[18:33]
	v_mfma_f32_32x32x16_bf16 v[2:17], v[236:239], v[248:251], v[2:17]
	ds_read_b128 v[236:239], v0 offset:96
	ds_read_b128 v[244:247], v169 offset:53248
	ds_read_b128 v[248:251], v169 offset:57344
	s_waitcnt lgkmcnt(7)
	v_mfma_f32_32x32x16_bf16 v[114:129], v[186:189], v[204:207], v[114:129]
	s_waitcnt lgkmcnt(6)
	v_mfma_f32_32x32x16_bf16 v[98:113], v[186:189], v[208:211], v[98:113]
	v_mfma_f32_32x32x16_bf16 v[82:97], v[190:193], v[204:207], v[82:97]
	v_mfma_f32_32x32x16_bf16 v[66:81], v[190:193], v[208:211], v[66:81]
	v_mfma_f32_32x32x16_bf16 v[50:65], v[196:199], v[204:207], v[50:65]
	v_mfma_f32_32x32x16_bf16 v[34:49], v[196:199], v[208:211], v[34:49]
	v_mfma_f32_32x32x16_bf16 v[18:33], v[200:203], v[204:207], v[18:33]
	v_mfma_f32_32x32x16_bf16 v[2:17], v[200:203], v[208:211], v[2:17]
	s_waitcnt lgkmcnt(1)
	v_mfma_f32_32x32x16_bf16 v[114:129], v[212:215], v[244:247], v[114:129]
	s_waitcnt lgkmcnt(0)
	v_mfma_f32_32x32x16_bf16 v[98:113], v[212:215], v[248:251], v[98:113]
	v_mfma_f32_32x32x16_bf16 v[82:97], v[216:219], v[244:247], v[82:97]
	v_mfma_f32_32x32x16_bf16 v[66:81], v[216:219], v[248:251], v[66:81]
	v_mfma_f32_32x32x16_bf16 v[50:65], v[232:235], v[244:247], v[50:65]
	v_mfma_f32_32x32x16_bf16 v[34:49], v[232:235], v[248:251], v[34:49]
	v_mfma_f32_32x32x16_bf16 v[18:33], v[236:239], v[244:247], v[18:33]
	v_mfma_f32_32x32x16_bf16 v[2:17], v[236:239], v[248:251], v[2:17]
	s_add_u32 s56, s56, 0x80
	s_addc_u32 s57, s57, 0
	s_add_u32 s58, s58, 0x80
	s_addc_u32 s59, s59, 0
	s_movk_i32 s94, 20
; #define MFMA(a, b, c) __builtin_amdgcn_mfma_f32_32x32x16_bf16((a), (b), (c), 0, 0, 0)
; template <int MI, int NI>
; __device__ __forceinline__ void gemm_kloop(const bf16* __restrict__ A, size_t lda, const bf16* __restrict__ Bt, size_t ldb, int K,
;                                            f16v (&acc)[MI][NI], bf16* sA, bf16* sB) {
;     ...
;   for (int kt = 0; kt < KT; ++kt) {
;     __syncthreads();
; #pragma unroll
;     for (int i = 0; i < 2 * MI; ++i) *(u4v*)(sA + (lrow + 32 * i) * 72 + lseg * 8) = ra[i];
; #pragma unroll
;     for (int i = 0; i < 2 * NI; ++i) *(u4v*)(sB + (lrow + 32 * i) * 72 + lseg * 8) = rb[i];
;     __syncthreads();
;     if (kt + 3 < KT) {
;       const int k2 = (kt + 3) << 6;
;       if (tid < 64 * MI) pfs ^= *(const unsigned*)(A + (size_t)tid * lda + k2);
;       if (tid < 64 * NI) pfs ^= *(const unsigned*)(Bt + (size_t)tid * ldb + k2);
;     }
;     if (kt + 1 < KT) {
;       const int k0 = (kt + 1) << 6;
; #pragma unroll
;       for (int i = 0; i < 2 * MI; ++i) ra[i] = *(const u4v*)(A + (size_t)(lrow + 32 * i) * lda + k0 + lseg * 8);
; #pragma unroll
;       for (int i = 0; i < 2 * NI; ++i) rb[i] = *(const u4v*)(Bt + (size_t)(lrow + 32 * i) * ldb + k0 + lseg * 8);
;     }
; #pragma unroll
;     for (int ks = 0; ks < 4; ++ks) {
;       s8v a[MI], b[NI];
; #pragma unroll
;       for (int mi = 0; mi < MI; ++mi) a[mi] = *(const s8v*)(sA + (wm * 32 * MI + mi * 32 + r) * 72 + ks * 16 + hh * 8);
; #pragma unroll
;       for (int ni = 0; ni < NI; ++ni) b[ni] = *(const s8v*)(sB + (wn * 32 * NI + ni * 32 + r) * 72 + ks * 16 + hh * 8);
; #pragma unroll
;       for (int mi = 0; mi < MI; ++mi)
; #pragma unroll
;         for (int ni = 0; ni < NI; ++ni) acc[mi][ni] = MFMA(a[mi], b[ni], acc[mi][ni]);
;     }
;   }
.Lhyb_p9_loop:
	s_barrier
	s_waitcnt vmcnt(7)
	ds_write_b128 v184, v[134:137]
	s_waitcnt vmcnt(6)
	ds_write_b128 v184, v[138:141] offset:4608
	s_waitcnt vmcnt(5)
	ds_write_b128 v184, v[142:145] offset:9216
	s_waitcnt vmcnt(4)
	ds_write_b128 v184, v[146:149] offset:13824
	s_waitcnt vmcnt(3)
	ds_write_b128 v184, v[154:157] offset:18432
	s_waitcnt vmcnt(2)
	ds_write_b128 v184, v[150:153] offset:23040
	s_waitcnt vmcnt(1)
	ds_write_b128 v184, v[162:165] offset:27648
	s_waitcnt vmcnt(0)
	ds_write_b128 v184, v[158:161] offset:32256
	s_waitcnt lgkmcnt(0)
	s_barrier
	ds_read_b128 v[186:189], v182
	ds_read_b128 v[204:207], v166 offset:36864
	ds_read_b128 v[208:211], v166 offset:40960
	ds_read_b128 v[190:193], v182 offset:4608
	ds_read_b128 v[196:199], v182 offset:9216
	ds_read_b128 v[200:203], v0
	ds_read_b128 v[212:215], v182 offset:32
	ds_read_b128 v[244:247], v167 offset:36864
	ds_read_b128 v[248:251], v167 offset:40960
	ds_read_b128 v[216:219], v182 offset:4640
	ds_read_b128 v[232:235], v182 offset:9248
	ds_read_b128 v[236:239], v0 offset:32
	s_waitcnt lgkmcnt(10)
	v_mfma_f32_32x32x16_bf16 v[114:129], v[186:189], v[204:207], v[114:129]
	s_add_u32 m0, s96, 16256
	s_nop 0
	s_waitcnt lgkmcnt(9)
	v_mfma_f32_32x32x16_bf16 v[98:113], v[186:189], v[208:211], v[98:113]
	global_load_lds_dwordx4 v130, s[58:59] offset:128
	ds_read_b128 v[186:189], v182 offset:64
	s_waitcnt lgkmcnt(9)
	v_mfma_f32_32x32x16_bf16 v[82:97], v[190:193], v[204:207], v[82:97]
	global_load_lds_dwordx4 v131, s[58:59] offset:1152
	v_mfma_f32_32x32x16_bf16 v[66:81], v[190:193], v[208:211], v[66:81]
	global_load_lds_dwordx4 v132, s[58:59] offset:2176
	ds_read_b128 v[190:193], v182 offset:4672
	s_waitcnt lgkmcnt(9)
	v_mfma_f32_32x32x16_bf16 v[50:65], v[196:199], v[204:207], v[50:65]
	global_load_lds_dwordx4 v133, s[58:59] offset:3200
	v_mfma_f32_32x32x16_bf16 v[34:49], v[196:199], v[208:211], v[34:49]
	global_load_dwordx4 v[134:137], v178, s[56:57] offset:128
	ds_read_b128 v[196:199], v182 offset:9280
	s_waitcnt lgkmcnt(9)
	v_mfma_f32_32x32x16_bf16 v[18:33], v[200:203], v[204:207], v[18:33]
	global_load_dwordx4 v[138:141], v179, s[56:57] offset:128
	v_mfma_f32_32x32x16_bf16 v[2:17], v[200:203], v[208:211], v[2:17]
	global_load_dwordx4 v[142:145], v180, s[56:57] offset:128
	ds_read_b128 v[200:203], v0 offset:64
	ds_read_b128 v[204:207], v168 offset:36864
	ds_read_b128 v[208:211], v168 offset:40960
	s_waitcnt lgkmcnt(10)
	v_mfma_f32_32x32x16_bf16 v[114:129], v[212:215], v[244:247], v[114:129]
	global_load_dwordx4 v[146:149], v181, s[56:57] offset:128
	s_waitcnt lgkmcnt(9)
	v_mfma_f32_32x32x16_bf16 v[98:113], v[212:215], v[248:251], v[98:113]
	global_load_dwordx4 v[154:157], v185, s[56:57] offset:128
	ds_read_b128 v[212:215], v182 offset:96
	s_waitcnt lgkmcnt(9)
	v_mfma_f32_32x32x16_bf16 v[82:97], v[216:219], v[244:247], v[82:97]
	global_load_dwordx4 v[150:153], v222, s[56:57] offset:128
	v_mfma_f32_32x32x16_bf16 v[66:81], v[216:219], v[248:251], v[66:81]
	global_load_dwordx4 v[162:165], v223, s[56:57] offset:128
	ds_read_b128 v[216:219], v182 offset:4704
	s_waitcnt lgkmcnt(9)
	v_mfma_f32_32x32x16_bf16 v[50:65], v[232:235], v[244:247], v[50:65]
	global_load_dwordx4 v[158:161], v227, s[56:57] offset:128
	v_mfma_f32_32x32x16_bf16 v[34:49], v[232:235], v[248:251], v[34:49]
	ds_read_b128 v[232:235], v182 offset:9312
	s_waitcnt lgkmcnt(9)
	v_mfma_f32_32x32x16_bf16 v[18:33], v[236:239], v[244:247], v[18:33]
	v_mfma_f32_32x32x16_bf16 v[2:17], v[236:239], v[248:251], v[2:17]
	ds_read_b128 v[236:239], v0 offset:96
	ds_read_b128 v[244:247], v169 offset:36864
	ds_read_b128 v[248:251], v169 offset:40960
	s_waitcnt lgkmcnt(7)
	v_mfma_f32_32x32x16_bf16 v[114:129], v[186:189], v[204:207], v[114:129]
	s_waitcnt lgkmcnt(6)
	v_mfma_f32_32x32x16_bf16 v[98:113], v[186:189], v[208:211], v[98:113]
	v_mfma_f32_32x32x16_bf16 v[82:97], v[190:193], v[204:207], v[82:97]
	v_mfma_f32_32x32x16_bf16 v[66:81], v[190:193], v[208:211], v[66:81]
	v_mfma_f32_32x32x16_bf16 v[50:65], v[196:199], v[204:207], v[50:65]
	v_mfma_f32_32x32x16_bf16 v[34:49], v[196:199], v[208:211], v[34:49]
	v_mfma_f32_32x32x16_bf16 v[18:33], v[200:203], v[204:207], v[18:33]
	v_mfma_f32_32x32x16_bf16 v[2:17], v[200:203], v[208:211], v[2:17]
	s_waitcnt lgkmcnt(1)
	v_mfma_f32_32x32x16_bf16 v[114:129], v[212:215], v[244:247], v[114:129]
	s_waitcnt lgkmcnt(0)
	v_mfma_f32_32x32x16_bf16 v[98:113], v[212:215], v[248:251], v[98:113]
	v_mfma_f32_32x32x16_bf16 v[82:97], v[216:219], v[244:247], v[82:97]
	v_mfma_f32_32x32x16_bf16 v[66:81], v[216:219], v[248:251], v[66:81]
	v_mfma_f32_32x32x16_bf16 v[50:65], v[232:235], v[244:247], v[50:65]
	v_mfma_f32_32x32x16_bf16 v[34:49], v[232:235], v[248:251], v[34:49]
	v_mfma_f32_32x32x16_bf16 v[18:33], v[236:239], v[244:247], v[18:33]
	v_mfma_f32_32x32x16_bf16 v[2:17], v[236:239], v[248:251], v[2:17]
	s_add_u32 s56, s56, 0x80
	s_addc_u32 s57, s57, 0
	s_add_u32 s58, s58, 0x80
	s_addc_u32 s59, s59, 0
	s_barrier
	s_waitcnt vmcnt(7)
	ds_write_b128 v184, v[134:137]
	s_waitcnt vmcnt(6)
	ds_write_b128 v184, v[138:141] offset:4608
	s_waitcnt vmcnt(5)
	ds_write_b128 v184, v[142:145] offset:9216
	s_waitcnt vmcnt(4)
	ds_write_b128 v184, v[146:149] offset:13824
	s_waitcnt vmcnt(3)
	ds_write_b128 v184, v[154:157] offset:18432
	s_waitcnt vmcnt(2)
	ds_write_b128 v184, v[150:153] offset:23040
	s_waitcnt vmcnt(1)
	ds_write_b128 v184, v[162:165] offset:27648
	s_waitcnt vmcnt(0)
	ds_write_b128 v184, v[158:161] offset:32256
	s_waitcnt lgkmcnt(0)
	s_barrier
; #define MFMA(a, b, c) __builtin_amdgcn_mfma_f32_32x32x16_bf16((a), (b), (c), 0, 0, 0)
; template <int MI, int NI>
; __device__ __forceinline__ void gemm_kloop(const bf16* __restrict__ A, size_t lda, const bf16* __restrict__ Bt, size_t ldb, int K,
;                                            f16v (&acc)[MI][NI], bf16* sA, bf16* sB) {
;     ...
;   for (int kt = 0; kt < KT; ++kt) {
;     __syncthreads();
; #pragma unroll
;     for (int i = 0; i < 2 * MI; ++i) *(u4v*)(sA + (lrow + 32 * i) * 72 + lseg * 8) = ra[i];
; #pragma unroll
;     for (int i = 0; i < 2 * NI; ++i) *(u4v*)(sB + (lrow + 32 * i) * 72 + lseg * 8) = rb[i];
;     __syncthreads();
;     if (kt + 3 < KT) {
;       const int k2 = (kt + 3) << 6;
;       if (tid < 64 * MI) pfs ^= *(const unsigned*)(A + (size_t)tid * lda + k2);
;       if (tid < 64 * NI) pfs ^= *(const unsigned*)(Bt + (size_t)tid * ldb + k2);
;     }
;     if (kt + 1 < KT) {
;       const int k0 = (kt + 1) << 6;
; #pragma unroll
;       for (int i = 0; i < 2 * MI; ++i) ra[i] = *(const u4v*)(A + (size_t)(lrow + 32 * i) * lda + k0 + lseg * 8);
; #pragma unroll
;       for (int i = 0; i < 2 * NI; ++i) rb[i] = *(const u4v*)(Bt + (size_t)(lrow + 32 * i) * ldb + k0 + lseg * 8);
;     }
; #pragma unroll
;     for (int ks = 0; ks < 4; ++ks) {
;       s8v a[MI], b[NI];
; #pragma unroll
;       for (int mi = 0; mi < MI; ++mi) a[mi] = *(const s8v*)(sA + (wm * 32 * MI + mi * 32 + r) * 72 + ks * 16 + hh * 8);
; #pragma unroll
;       for (int ni = 0; ni < NI; ++ni) b[ni] = *(const s8v*)(sB + (wn * 32 * NI + ni * 32 + r) * 72 + ks * 16 + hh * 8);
; #pragma unroll
;       for (int mi = 0; mi < MI; ++mi)
; #pragma unroll
;         for (int ni = 0; ni < NI; ++ni) acc[mi][ni] = MFMA(a[mi], b[ni], acc[mi][ni]);
;     }
;   }
	ds_read_b128 v[186:189], v182
	ds_read_b128 v[204:207], v166 offset:53248
	ds_read_b128 v[208:211], v166 offset:57344
	ds_read_b128 v[190:193], v182 offset:4608
	ds_read_b128 v[196:199], v182 offset:9216
	ds_read_b128 v[200:203], v0
	ds_read_b128 v[212:215], v182 offset:32
	ds_read_b128 v[244:247], v167 offset:53248
	ds_read_b128 v[248:251], v167 offset:57344
	ds_read_b128 v[216:219], v182 offset:4640
	ds_read_b128 v[232:235], v182 offset:9248
	ds_read_b128 v[236:239], v0 offset:32
	s_waitcnt lgkmcnt(10)
	v_mfma_f32_32x32x16_bf16 v[114:129], v[186:189], v[204:207], v[114:129]
	s_add_u32 m0, s96, -128
	s_nop 0
	s_waitcnt lgkmcnt(9)
	v_mfma_f32_32x32x16_bf16 v[98:113], v[186:189], v[208:211], v[98:113]
	global_load_lds_dwordx4 v130, s[58:59] offset:128
	ds_read_b128 v[186:189], v182 offset:64
	s_waitcnt lgkmcnt(9)
	v_mfma_f32_32x32x16_bf16 v[82:97], v[190:193], v[204:207], v[82:97]
	global_load_lds_dwordx4 v131, s[58:59] offset:1152
	v_mfma_f32_32x32x16_bf16 v[66:81], v[190:193], v[208:211], v[66:81]
	global_load_lds_dwordx4 v132, s[58:59] offset:2176
	ds_read_b128 v[190:193], v182 offset:4672
	s_waitcnt lgkmcnt(9)
	v_mfma_f32_32x32x16_bf16 v[50:65], v[196:199], v[204:207], v[50:65]
	global_load_lds_dwordx4 v133, s[58:59] offset:3200
	v_mfma_f32_32x32x16_bf16 v[34:49], v[196:199], v[208:211], v[34:49]
	global_load_dwordx4 v[134:137], v178, s[56:57] offset:128
	ds_read_b128 v[196:199], v182 offset:9280
	s_waitcnt lgkmcnt(9)
	v_mfma_f32_32x32x16_bf16 v[18:33], v[200:203], v[204:207], v[18:33]
	global_load_dwordx4 v[138:141], v179, s[56:57] offset:128
	v_mfma_f32_32x32x16_bf16 v[2:17], v[200:203], v[208:211], v[2:17]
	global_load_dwordx4 v[142:145], v180, s[56:57] offset:128
	ds_read_b128 v[200:203], v0 offset:64
	ds_read_b128 v[204:207], v168 offset:53248
	ds_read_b128 v[208:211], v168 offset:57344
	s_waitcnt lgkmcnt(10)
	v_mfma_f32_32x32x16_bf16 v[114:129], v[212:215], v[244:247], v[114:129]
	global_load_dwordx4 v[146:149], v181, s[56:57] offset:128
	s_waitcnt lgkmcnt(9)
	v_mfma_f32_32x32x16_bf16 v[98:113], v[212:215], v[248:251], v[98:113]
	global_load_dwordx4 v[154:157], v185, s[56:57] offset:128
	ds_read_b128 v[212:215], v182 offset:96
	s_waitcnt lgkmcnt(9)
	v_mfma_f32_32x32x16_bf16 v[82:97], v[216:219], v[244:247], v[82:97]
	global_load_dwordx4 v[150:153], v222, s[56:57] offset:128
	v_mfma_f32_32x32x16_bf16 v[66:81], v[216:219], v[248:251], v[66:81]
	global_load_dwordx4 v[162:165], v223, s[56:57] offset:128
	ds_read_b128 v[216:219], v182 offset:4704
	s_waitcnt lgkmcnt(9)
	v_mfma_f32_32x32x16_bf16 v[50:65], v[232:235], v[244:247], v[50:65]
	global_load_dwordx4 v[158:161], v227, s[56:57] offset:128
	v_mfma_f32_32x32x16_bf16 v[34:49], v[232:235], v[248:251], v[34:49]
	ds_read_b128 v[232:235], v182 offset:9312
	s_waitcnt lgkmcnt(9)
	v_mfma_f32_32x32x16_bf16 v[18:33], v[236:239], v[244:247], v[18:33]
	v_mfma_f32_32x32x16_bf16 v[2:17], v[236:239], v[248:251], v[2:17]
	ds_read_b128 v[236:239], v0 offset:96
	ds_read_b128 v[244:247], v169 offset:53248
	ds_read_b128 v[248:251], v169 offset:57344
	s_waitcnt lgkmcnt(7)
	v_mfma_f32_32x32x16_bf16 v[114:129], v[186:189], v[204:207], v[114:129]
	s_waitcnt lgkmcnt(6)
	v_mfma_f32_32x32x16_bf16 v[98:113], v[186:189], v[208:211], v[98:113]
	v_mfma_f32_32x32x16_bf16 v[82:97], v[190:193], v[204:207], v[82:97]
	v_mfma_f32_32x32x16_bf16 v[66:81], v[190:193], v[208:211], v[66:81]
	v_mfma_f32_32x32x16_bf16 v[50:65], v[196:199], v[204:207], v[50:65]
	v_mfma_f32_32x32x16_bf16 v[34:49], v[196:199], v[208:211], v[34:49]
	v_mfma_f32_32x32x16_bf16 v[18:33], v[200:203], v[204:207], v[18:33]
	v_mfma_f32_32x32x16_bf16 v[2:17], v[200:203], v[208:211], v[2:17]
	s_waitcnt lgkmcnt(1)
	v_mfma_f32_32x32x16_bf16 v[114:129], v[212:215], v[244:247], v[114:129]
	s_waitcnt lgkmcnt(0)
	v_mfma_f32_32x32x16_bf16 v[98:113], v[212:215], v[248:251], v[98:113]
	v_mfma_f32_32x32x16_bf16 v[82:97], v[216:219], v[244:247], v[82:97]
	v_mfma_f32_32x32x16_bf16 v[66:81], v[216:219], v[248:251], v[66:81]
	v_mfma_f32_32x32x16_bf16 v[50:65], v[232:235], v[244:247], v[50:65]
	v_mfma_f32_32x32x16_bf16 v[34:49], v[232:235], v[248:251], v[34:49]
	v_mfma_f32_32x32x16_bf16 v[18:33], v[236:239], v[244:247], v[18:33]
	v_mfma_f32_32x32x16_bf16 v[2:17], v[236:239], v[248:251], v[2:17]
	s_add_u32 s56, s56, 0x80
	s_addc_u32 s57, s57, 0
	s_add_u32 s58, s58, 0x80
	s_addc_u32 s59, s59, 0
	s_sub_u32 s94, s94, 1
	s_cmp_lg_u32 s94, 0
	s_cbranch_scc1 .Lhyb_p9_loop
	s_barrier
	s_waitcnt vmcnt(7)
	ds_write_b128 v184, v[134:137]
	s_waitcnt vmcnt(6)
	ds_write_b128 v184, v[138:141] offset:4608
	s_waitcnt vmcnt(5)
	ds_write_b128 v184, v[142:145] offset:9216
	s_waitcnt vmcnt(4)
	ds_write_b128 v184, v[146:149] offset:13824
	s_waitcnt vmcnt(3)
	ds_write_b128 v184, v[154:157] offset:18432
	s_waitcnt vmcnt(2)
	ds_write_b128 v184, v[150:153] offset:23040
	s_waitcnt vmcnt(1)
	ds_write_b128 v184, v[162:165] offset:27648
	s_waitcnt vmcnt(0)
	ds_write_b128 v184, v[158:161] offset:32256
	s_waitcnt lgkmcnt(0)
	s_barrier
; #define MFMA(a, b, c) __builtin_amdgcn_mfma_f32_32x32x16_bf16((a), (b), (c), 0, 0, 0)
; template <int MI, int NI>
; __device__ __forceinline__ void gemm_kloop(const bf16* __restrict__ A, size_t lda, const bf16* __restrict__ Bt, size_t ldb, int K,
;                                            f16v (&acc)[MI][NI], bf16* sA, bf16* sB) {
;     ...
;   for (int kt = 0; kt < KT; ++kt) {
;     __syncthreads();
; #pragma unroll
;     for (int i = 0; i < 2 * MI; ++i) *(u4v*)(sA + (lrow + 32 * i) * 72 + lseg * 8) = ra[i];
; #pragma unroll
;     for (int i = 0; i < 2 * NI; ++i) *(u4v*)(sB + (lrow + 32 * i) * 72 + lseg * 8) = rb[i];
;     __syncthreads();
;     if (kt + 3 < KT) {
;       const int k2 = (kt + 3) << 6;
;       if (tid < 64 * MI) pfs ^= *(const unsigned*)(A + (size_t)tid * lda + k2);
;       if (tid < 64 * NI) pfs ^= *(const unsigned*)(Bt + (size_t)tid * ldb + k2);
;     }
;     if (kt + 1 < KT) {
;       const int k0 = (kt + 1) << 6;
; #pragma unroll
;       for (int i = 0; i < 2 * MI; ++i) ra[i] = *(const u4v*)(A + (size_t)(lrow + 32 * i) * lda + k0 + lseg * 8);
; #pragma unroll
;       for (int i = 0; i < 2 * NI; ++i) rb[i] = *(const u4v*)(Bt + (size_t)(lrow + 32 * i) * ldb + k0 + lseg * 8);
;     }
; #pragma unroll
;     for (int ks = 0; ks < 4; ++ks) {
;       s8v a[MI], b[NI];
; #pragma unroll
;       for (int mi = 0; mi < MI; ++mi) a[mi] = *(const s8v*)(sA + (wm * 32 * MI + mi * 32 + r) * 72 + ks * 16 + hh * 8);
; #pragma unroll
;       for (int ni = 0; ni < NI; ++ni) b[ni] = *(const s8v*)(sB + (wn * 32 * NI + ni * 32 + r) * 72 + ks * 16 + hh * 8);
; #pragma unroll
;       for (int mi = 0; mi < MI; ++mi)
; #pragma unroll
;         for (int ni = 0; ni < NI; ++ni) acc[mi][ni] = MFMA(a[mi], b[ni], acc[mi][ni]);
;     }
;   }
	ds_read_b128 v[186:189], v182
	ds_read_b128 v[204:207], v166 offset:36864
	ds_read_b128 v[208:211], v166 offset:40960
	ds_read_b128 v[190:193], v182 offset:4608
	ds_read_b128 v[196:199], v182 offset:9216
	ds_read_b128 v[200:203], v0
	ds_read_b128 v[212:215], v182 offset:32
	ds_read_b128 v[244:247], v167 offset:36864
	ds_read_b128 v[248:251], v167 offset:40960
	ds_read_b128 v[216:219], v182 offset:4640
	ds_read_b128 v[232:235], v182 offset:9248
	ds_read_b128 v[236:239], v0 offset:32
	s_waitcnt lgkmcnt(10)
	v_mfma_f32_32x32x16_bf16 v[114:129], v[186:189], v[204:207], v[114:129]
	s_add_u32 m0, s96, 16256
	s_nop 0
	s_waitcnt lgkmcnt(9)
	v_mfma_f32_32x32x16_bf16 v[98:113], v[186:189], v[208:211], v[98:113]
	global_load_lds_dwordx4 v130, s[58:59] offset:128
	ds_read_b128 v[186:189], v182 offset:64
	s_waitcnt lgkmcnt(9)
	v_mfma_f32_32x32x16_bf16 v[82:97], v[190:193], v[204:207], v[82:97]
	global_load_lds_dwordx4 v131, s[58:59] offset:1152
	v_mfma_f32_32x32x16_bf16 v[66:81], v[190:193], v[208:211], v[66:81]
	global_load_lds_dwordx4 v132, s[58:59] offset:2176
	ds_read_b128 v[190:193], v182 offset:4672
	s_waitcnt lgkmcnt(9)
	v_mfma_f32_32x32x16_bf16 v[50:65], v[196:199], v[204:207], v[50:65]
	global_load_lds_dwordx4 v133, s[58:59] offset:3200
	v_mfma_f32_32x32x16_bf16 v[34:49], v[196:199], v[208:211], v[34:49]
	global_load_dwordx4 v[134:137], v178, s[56:57] offset:128
	ds_read_b128 v[196:199], v182 offset:9280
	s_waitcnt lgkmcnt(9)
	v_mfma_f32_32x32x16_bf16 v[18:33], v[200:203], v[204:207], v[18:33]
	global_load_dwordx4 v[138:141], v179, s[56:57] offset:128
	v_mfma_f32_32x32x16_bf16 v[2:17], v[200:203], v[208:211], v[2:17]
	global_load_dwordx4 v[142:145], v180, s[56:57] offset:128
	ds_read_b128 v[200:203], v0 offset:64
	ds_read_b128 v[204:207], v168 offset:36864
	ds_read_b128 v[208:211], v168 offset:40960
	s_waitcnt lgkmcnt(10)
	v_mfma_f32_32x32x16_bf16 v[114:129], v[212:215], v[244:247], v[114:129]
	global_load_dwordx4 v[146:149], v181, s[56:57] offset:128
	s_waitcnt lgkmcnt(9)
	v_mfma_f32_32x32x16_bf16 v[98:113], v[212:215], v[248:251], v[98:113]
	global_load_dwordx4 v[154:157], v185, s[56:57] offset:128
	ds_read_b128 v[212:215], v182 offset:96
	s_waitcnt lgkmcnt(9)
	v_mfma_f32_32x32x16_bf16 v[82:97], v[216:219], v[244:247], v[82:97]
	global_load_dwordx4 v[150:153], v222, s[56:57] offset:128
	v_mfma_f32_32x32x16_bf16 v[66:81], v[216:219], v[248:251], v[66:81]
	global_load_dwordx4 v[162:165], v223, s[56:57] offset:128
	ds_read_b128 v[216:219], v182 offset:4704
	s_waitcnt lgkmcnt(9)
	v_mfma_f32_32x32x16_bf16 v[50:65], v[232:235], v[244:247], v[50:65]
	global_load_dwordx4 v[158:161], v227, s[56:57] offset:128
	v_mfma_f32_32x32x16_bf16 v[34:49], v[232:235], v[248:251], v[34:49]
	ds_read_b128 v[232:235], v182 offset:9312
	s_waitcnt lgkmcnt(9)
	v_mfma_f32_32x32x16_bf16 v[18:33], v[236:239], v[244:247], v[18:33]
	v_mfma_f32_32x32x16_bf16 v[2:17], v[236:239], v[248:251], v[2:17]
	ds_read_b128 v[236:239], v0 offset:96
	ds_read_b128 v[244:247], v169 offset:36864
	ds_read_b128 v[248:251], v169 offset:40960
	s_waitcnt lgkmcnt(7)
	v_mfma_f32_32x32x16_bf16 v[114:129], v[186:189], v[204:207], v[114:129]
	s_waitcnt lgkmcnt(6)
	v_mfma_f32_32x32x16_bf16 v[98:113], v[186:189], v[208:211], v[98:113]
	v_mfma_f32_32x32x16_bf16 v[82:97], v[190:193], v[204:207], v[82:97]
	v_mfma_f32_32x32x16_bf16 v[66:81], v[190:193], v[208:211], v[66:81]
	v_mfma_f32_32x32x16_bf16 v[50:65], v[196:199], v[204:207], v[50:65]
	v_mfma_f32_32x32x16_bf16 v[34:49], v[196:199], v[208:211], v[34:49]
	v_mfma_f32_32x32x16_bf16 v[18:33], v[200:203], v[204:207], v[18:33]
	v_mfma_f32_32x32x16_bf16 v[2:17], v[200:203], v[208:211], v[2:17]
	s_waitcnt lgkmcnt(1)
	v_mfma_f32_32x32x16_bf16 v[114:129], v[212:215], v[244:247], v[114:129]
	s_waitcnt lgkmcnt(0)
	v_mfma_f32_32x32x16_bf16 v[98:113], v[212:215], v[248:251], v[98:113]
	v_mfma_f32_32x32x16_bf16 v[82:97], v[216:219], v[244:247], v[82:97]
	v_mfma_f32_32x32x16_bf16 v[66:81], v[216:219], v[248:251], v[66:81]
	v_mfma_f32_32x32x16_bf16 v[50:65], v[232:235], v[244:247], v[50:65]
	v_mfma_f32_32x32x16_bf16 v[34:49], v[232:235], v[248:251], v[34:49]
	v_mfma_f32_32x32x16_bf16 v[18:33], v[236:239], v[244:247], v[18:33]
	v_mfma_f32_32x32x16_bf16 v[2:17], v[236:239], v[248:251], v[2:17]
	s_add_u32 s56, s56, 0x80
	s_addc_u32 s57, s57, 0
	s_add_u32 s58, s58, 0x80
	s_addc_u32 s59, s59, 0
	s_barrier
	s_waitcnt vmcnt(7)
	ds_write_b128 v184, v[134:137]
	s_waitcnt vmcnt(6)
	ds_write_b128 v184, v[138:141] offset:4608
	s_waitcnt vmcnt(5)
	ds_write_b128 v184, v[142:145] offset:9216
	s_waitcnt vmcnt(4)
	ds_write_b128 v184, v[146:149] offset:13824
	s_waitcnt vmcnt(3)
	ds_write_b128 v184, v[154:157] offset:18432
	s_waitcnt vmcnt(2)
	ds_write_b128 v184, v[150:153] offset:23040
	s_waitcnt vmcnt(1)
	ds_write_b128 v184, v[162:165] offset:27648
	s_waitcnt vmcnt(0)
	ds_write_b128 v184, v[158:161] offset:32256
	s_waitcnt lgkmcnt(0)
	s_barrier
; #define MFMA(a, b, c) __builtin_amdgcn_mfma_f32_32x32x16_bf16((a), (b), (c), 0, 0, 0)
; template <int MI, int NI>
; __device__ __forceinline__ void gemm_kloop(const bf16* __restrict__ A, size_t lda, const bf16* __restrict__ Bt, size_t ldb, int K,
;                                            f16v (&acc)[MI][NI], bf16* sA, bf16* sB) {
;     ...
;     for (int ks = 0; ks < 4; ++ks) {
;       s8v a[MI], b[NI];
; #pragma unroll
;       for (int mi = 0; mi < MI; ++mi) a[mi] = *(const s8v*)(sA + (wm * 32 * MI + mi * 32 + r) * 72 + ks * 16 + hh * 8);
; #pragma unroll
;       for (int ni = 0; ni < NI; ++ni) b[ni] = *(const s8v*)(sB + (wn * 32 * NI + ni * 32 + r) * 72 + ks * 16 + hh * 8);
; #pragma unroll
;       for (int mi = 0; mi < MI; ++mi)
; #pragma unroll
;         for (int ni = 0; ni < NI; ++ni) acc[mi][ni] = MFMA(a[mi], b[ni], acc[mi][ni]);
;     }
;   }
; __device__ __forceinline__ void resid_tile(const Params& p, const bf16* A, size_t lda, const bf16* Bt, int K, int mt, int nt, bool x_from_input, bf16* sA, bf16* sB, int dry) {
;     ...
; #pragma unroll
;   for (int mi = 0; mi < 4; ++mi)
; #pragma unroll
;     for (int ni = 0; ni < 2; ++ni) {
;       __builtin_amdgcn_sched_barrier(0);
; #pragma unroll
;       for (int e = 0; e < 16; ++e) {
;         const int t = m0 + wm * 128 + mi * 32 + ROW_OF(e, hh);
;         const int c = n0 + wn * 64 + ni * 32 + r;
;         const float xo = x_from_input ? (t < LP ? p.in[0][(size_t)t * DM + c] : p.in[1][(size_t)(t - LP) * DM + c]) : p.out[(size_t)t * DM + c];
;         if (!dry) p.out[(size_t)t * DM + c] = xo + acc[mi][ni][e];
;       }
;     }
	ds_read_b128 v[186:189], v182
	ds_read_b128 v[204:207], v166 offset:53248
	ds_read_b128 v[208:211], v166 offset:57344
	ds_read_b128 v[190:193], v182 offset:4608
	ds_read_b128 v[196:199], v182 offset:9216
	ds_read_b128 v[200:203], v0
	ds_read_b128 v[212:215], v182 offset:32
	ds_read_b128 v[244:247], v167 offset:53248
	ds_read_b128 v[248:251], v167 offset:57344
	ds_read_b128 v[216:219], v182 offset:4640
	ds_read_b128 v[232:235], v182 offset:9248
	ds_read_b128 v[236:239], v0 offset:32
	s_waitcnt lgkmcnt(10)
	v_mfma_f32_32x32x16_bf16 v[114:129], v[186:189], v[204:207], v[114:129]
	s_waitcnt lgkmcnt(9)
	v_mfma_f32_32x32x16_bf16 v[98:113], v[186:189], v[208:211], v[98:113]
	ds_read_b128 v[186:189], v182 offset:64
	s_waitcnt lgkmcnt(9)
	v_mfma_f32_32x32x16_bf16 v[82:97], v[190:193], v[204:207], v[82:97]
	v_mfma_f32_32x32x16_bf16 v[66:81], v[190:193], v[208:211], v[66:81]
	ds_read_b128 v[190:193], v182 offset:4672
	s_waitcnt lgkmcnt(9)
	v_mfma_f32_32x32x16_bf16 v[50:65], v[196:199], v[204:207], v[50:65]
	v_mfma_f32_32x32x16_bf16 v[34:49], v[196:199], v[208:211], v[34:49]
	ds_read_b128 v[196:199], v182 offset:9280
	s_waitcnt lgkmcnt(9)
	v_mfma_f32_32x32x16_bf16 v[18:33], v[200:203], v[204:207], v[18:33]
	v_mfma_f32_32x32x16_bf16 v[2:17], v[200:203], v[208:211], v[2:17]
	ds_read_b128 v[200:203], v0 offset:64
	ds_read_b128 v[204:207], v168 offset:53248
	ds_read_b128 v[208:211], v168 offset:57344
	s_waitcnt lgkmcnt(10)
	v_mfma_f32_32x32x16_bf16 v[114:129], v[212:215], v[244:247], v[114:129]
	s_waitcnt lgkmcnt(9)
	v_mfma_f32_32x32x16_bf16 v[98:113], v[212:215], v[248:251], v[98:113]
	ds_read_b128 v[212:215], v182 offset:96
	s_waitcnt lgkmcnt(9)
	v_mfma_f32_32x32x16_bf16 v[82:97], v[216:219], v[244:247], v[82:97]
	v_mfma_f32_32x32x16_bf16 v[66:81], v[216:219], v[248:251], v[66:81]
	ds_read_b128 v[216:219], v182 offset:4704
	s_waitcnt lgkmcnt(9)
	v_mfma_f32_32x32x16_bf16 v[50:65], v[232:235], v[244:247], v[50:65]
	v_mfma_f32_32x32x16_bf16 v[34:49], v[232:235], v[248:251], v[34:49]
	ds_read_b128 v[232:235], v182 offset:9312
	s_waitcnt lgkmcnt(9)
	v_mfma_f32_32x32x16_bf16 v[18:33], v[236:239], v[244:247], v[18:33]
	v_mfma_f32_32x32x16_bf16 v[2:17], v[236:239], v[248:251], v[2:17]
	ds_read_b128 v[236:239], v0 offset:96
	ds_read_b128 v[244:247], v169 offset:53248
	ds_read_b128 v[248:251], v169 offset:57344
	s_waitcnt lgkmcnt(7)
	v_mfma_f32_32x32x16_bf16 v[114:129], v[186:189], v[204:207], v[114:129]
	s_waitcnt lgkmcnt(6)
	v_mfma_f32_32x32x16_bf16 v[98:113], v[186:189], v[208:211], v[98:113]
	v_mfma_f32_32x32x16_bf16 v[82:97], v[190:193], v[204:207], v[82:97]
	v_mfma_f32_32x32x16_bf16 v[66:81], v[190:193], v[208:211], v[66:81]
	v_mfma_f32_32x32x16_bf16 v[50:65], v[196:199], v[204:207], v[50:65]
	v_mfma_f32_32x32x16_bf16 v[34:49], v[196:199], v[208:211], v[34:49]
	v_mfma_f32_32x32x16_bf16 v[18:33], v[200:203], v[204:207], v[18:33]
	v_mfma_f32_32x32x16_bf16 v[2:17], v[200:203], v[208:211], v[2:17]
	s_waitcnt lgkmcnt(1)
	v_mfma_f32_32x32x16_bf16 v[114:129], v[212:215], v[244:247], v[114:129]
	s_waitcnt lgkmcnt(0)
	v_mfma_f32_32x32x16_bf16 v[98:113], v[212:215], v[248:251], v[98:113]
	v_mfma_f32_32x32x16_bf16 v[82:97], v[216:219], v[244:247], v[82:97]
	v_mfma_f32_32x32x16_bf16 v[66:81], v[216:219], v[248:251], v[66:81]
	v_mfma_f32_32x32x16_bf16 v[50:65], v[232:235], v[244:247], v[50:65]
	v_mfma_f32_32x32x16_bf16 v[34:49], v[232:235], v[248:251], v[34:49]
	v_mfma_f32_32x32x16_bf16 v[18:33], v[236:239], v[244:247], v[18:33]
	v_mfma_f32_32x32x16_bf16 v[2:17], v[236:239], v[248:251], v[2:17]
	s_nop 15
	s_lshl_b32 s2, s21, 7
	v_mov_b32_e32 v0, v195
	v_mov_b32_e32 v130, v195
	s_nop 0
	v_and_b32_e32 v131, 31, v130
	v_and_b32_e32 v132, 64, v0
	v_and_b32_e32 v0, 0xffffff80, v0
	v_lshrrev_b32_e32 v130, 3, v130
	v_lshl_add_u32 v0, s20, 8, v0
	v_and_b32_e32 v150, 4, v130
	v_or3_b32 v130, v131, v132, s2
	v_or_b32_e32 v0, v0, v150
	v_lshlrev_b32_e32 v0, 12, v0
	v_lshl_add_u32 v0, v130, 2, v0
	s_add_u32 s2, s8, 0x1000
	s_addc_u32 s3, s9, 0
	s_add_u32 s22, s8, 0x1000
	s_addc_u32 s23, s9, 0
	global_load_dword v130, v0, s[2:3] offset:-4096
	global_load_dword v131, v0, s[2:3] offset:-3968
	global_load_dword v132, v0, s[2:3]
	global_load_dword v133, v0, s[2:3] offset:128
	s_add_u32 s2, s2, 0x2000
	s_addc_u32 s3, s3, 0
	global_load_dword v134, v0, s[2:3] offset:-4096
	global_load_dword v135, v0, s[2:3] offset:-3968
	global_load_dword v136, v0, s[2:3]
	global_load_dword v137, v0, s[2:3] offset:128
	s_add_u32 s2, s2, 0x6000
	s_addc_u32 s3, s3, 0
	global_load_dword v138, v0, s[2:3] offset:-4096
	global_load_dword v139, v0, s[2:3] offset:-3968
	global_load_dword v140, v0, s[2:3]
	global_load_dword v141, v0, s[2:3] offset:128
	s_add_u32 s2, s2, 0x2000
	s_addc_u32 s3, s3, 0
	global_load_dword v142, v0, s[2:3] offset:-4096
	global_load_dword v143, v0, s[2:3] offset:-3968
	global_load_dword v144, v0, s[2:3]
	global_load_dword v145, v0, s[2:3] offset:128
	s_add_u32 s2, s2, 0x6000
	s_addc_u32 s3, s3, 0
	global_load_dword v146, v0, s[2:3] offset:-4096
	global_load_dword v147, v0, s[2:3] offset:-3968
	global_load_dword v148, v0, s[2:3]
	global_load_dword v149, v0, s[2:3] offset:128
	s_add_u32 s2, s2, 0x2000
	s_addc_u32 s3, s3, 0
	global_load_dword v150, v0, s[2:3] offset:-4096
	global_load_dword v151, v0, s[2:3] offset:-3968
	global_load_dword v152, v0, s[2:3]
	global_load_dword v153, v0, s[2:3] offset:128
	s_add_u32 s2, s2, 0x6000
	s_addc_u32 s3, s3, 0
	global_load_dword v154, v0, s[2:3] offset:-4096
	global_load_dword v155, v0, s[2:3] offset:-3968
	global_load_dword v156, v0, s[2:3]
	global_load_dword v157, v0, s[2:3] offset:128
	s_add_u32 s2, s2, 0x2000
	s_addc_u32 s3, s3, 0
; __device__ __forceinline__ void resid_tile(const Params& p, const bf16* A, size_t lda, const bf16* Bt, int K, int mt, int nt, bool x_from_input, bf16* sA, bf16* sB, int dry) {
;     ...
; #pragma unroll
;   for (int mi = 0; mi < 4; ++mi)
; #pragma unroll
;     for (int ni = 0; ni < 2; ++ni) {
;       __builtin_amdgcn_sched_barrier(0);
; #pragma unroll
;       for (int e = 0; e < 16; ++e) {
;         const int t = m0 + wm * 128 + mi * 32 + ROW_OF(e, hh);
;         const int c = n0 + wn * 64 + ni * 32 + r;
;         const float xo = x_from_input ? (t < LP ? p.in[0][(size_t)t * DM + c] : p.in[1][(size_t)(t - LP) * DM + c]) : p.out[(size_t)t * DM + c];
;         if (!dry) p.out[(size_t)t * DM + c] = xo + acc[mi][ni][e];
;       }
;     }
	global_load_dword v158, v0, s[2:3] offset:-4096
	global_load_dword v159, v0, s[2:3] offset:-3968
	global_load_dword v160, v0, s[2:3]
	global_load_dword v161, v0, s[2:3] offset:128
	s_add_u32 s2, s2, 0x6000
	s_addc_u32 s3, s3, 0
	global_load_dword v162, v0, s[2:3] offset:-4096
	global_load_dword v163, v0, s[2:3] offset:-3968
	global_load_dword v164, v0, s[2:3]
	global_load_dword v165, v0, s[2:3] offset:128
	s_add_u32 s2, s2, 0x2000
	s_addc_u32 s3, s3, 0
	global_load_dword v166, v0, s[2:3] offset:-4096
	global_load_dword v167, v0, s[2:3] offset:-3968
	global_load_dword v168, v0, s[2:3]
	global_load_dword v169, v0, s[2:3] offset:128
	s_add_u32 s2, s2, 0x6000
	s_addc_u32 s3, s3, 0
	global_load_dword v170, v0, s[2:3] offset:-4096
	global_load_dword v171, v0, s[2:3] offset:-3968
	global_load_dword v172, v0, s[2:3]
	global_load_dword v173, v0, s[2:3] offset:128
	s_add_u32 s2, s2, 0x2000
	s_addc_u32 s3, s3, 0
	global_load_dword v174, v0, s[2:3] offset:-4096
	global_load_dword v175, v0, s[2:3] offset:-3968
	global_load_dword v176, v0, s[2:3]
	global_load_dword v177, v0, s[2:3] offset:128
	s_add_u32 s2, s2, 0x6000
	s_addc_u32 s3, s3, 0
	global_load_dword v178, v0, s[2:3] offset:-4096
	global_load_dword v179, v0, s[2:3] offset:-3968
	global_load_dword v180, v0, s[2:3]
	global_load_dword v181, v0, s[2:3] offset:128
	s_add_u32 s2, s2, 0x2000
	s_addc_u32 s3, s3, 0
	global_load_dword v182, v0, s[2:3] offset:-4096
	global_load_dword v183, v0, s[2:3] offset:-3968
	global_load_dword v184, v0, s[2:3]
	global_load_dword v185, v0, s[2:3] offset:128
	s_add_u32 s2, s2, 0x6000
	s_addc_u32 s3, s3, 0
	global_load_dword v186, v0, s[2:3] offset:-4096
	global_load_dword v187, v0, s[2:3] offset:-3968
	global_load_dword v188, v0, s[2:3]
	global_load_dword v189, v0, s[2:3] offset:128
	s_add_u32 s2, s2, 0x2000
	s_addc_u32 s3, s3, 0
	global_load_dword v190, v0, s[2:3] offset:-4096
	global_load_dword v191, v0, s[2:3] offset:-3968
	global_load_dword v192, v0, s[2:3]
	global_load_dword v193, v0, s[2:3] offset:128
	s_waitcnt vmcnt(60)
	v_add_f32_e32 v130, v114, v130
	v_add_f32_e32 v131, v98, v131
	v_add_f32_e32 v132, v115, v132
	v_add_f32_e32 v133, v99, v133
	global_store_dword v0, v130, s[22:23] offset:-4096
	global_store_dword v0, v131, s[22:23] offset:-3968
	global_store_dword v0, v132, s[22:23]
	global_store_dword v0, v133, s[22:23] offset:128
	s_waitcnt vmcnt(60)
	v_add_f32_e32 v134, v116, v134
	v_add_f32_e32 v135, v100, v135
	v_add_f32_e32 v136, v117, v136
	v_add_f32_e32 v137, v101, v137
	s_add_u32 s22, s22, 0x2000
	s_addc_u32 s23, s23, 0
	global_store_dword v0, v134, s[22:23] offset:-4096
	global_store_dword v0, v135, s[22:23] offset:-3968
	global_store_dword v0, v136, s[22:23]
	global_store_dword v0, v137, s[22:23] offset:128
	s_waitcnt vmcnt(60)
	v_add_f32_e32 v138, v118, v138
	v_add_f32_e32 v139, v102, v139
	v_add_f32_e32 v140, v119, v140
	v_add_f32_e32 v141, v103, v141
	s_add_u32 s22, s22, 0x6000
	s_addc_u32 s23, s23, 0
	global_store_dword v0, v138, s[22:23] offset:-4096
	global_store_dword v0, v139, s[22:23] offset:-3968
	global_store_dword v0, v140, s[22:23]
	global_store_dword v0, v141, s[22:23] offset:128
	s_waitcnt vmcnt(60)
	v_add_f32_e32 v142, v120, v142
	v_add_f32_e32 v143, v104, v143
	v_add_f32_e32 v144, v121, v144
	v_add_f32_e32 v145, v105, v145
	s_add_u32 s22, s22, 0x2000
	s_addc_u32 s23, s23, 0
	global_store_dword v0, v142, s[22:23] offset:-4096
	global_store_dword v0, v143, s[22:23] offset:-3968
	global_store_dword v0, v144, s[22:23]
	global_store_dword v0, v145, s[22:23] offset:128
	s_waitcnt vmcnt(60)
	v_add_f32_e32 v146, v122, v146
	v_add_f32_e32 v147, v106, v147
	v_add_f32_e32 v148, v123, v148
	v_add_f32_e32 v149, v107, v149
	s_add_u32 s22, s22, 0x6000
	s_addc_u32 s23, s23, 0
	global_store_dword v0, v146, s[22:23] offset:-4096
	global_store_dword v0, v147, s[22:23] offset:-3968
	global_store_dword v0, v148, s[22:23]
	global_store_dword v0, v149, s[22:23] offset:128
	s_waitcnt vmcnt(60)
	v_add_f32_e32 v150, v124, v150
	v_add_f32_e32 v151, v108, v151
	v_add_f32_e32 v152, v125, v152
	v_add_f32_e32 v153, v109, v153
	s_add_u32 s22, s22, 0x2000
	s_addc_u32 s23, s23, 0
	global_store_dword v0, v150, s[22:23] offset:-4096
	global_store_dword v0, v151, s[22:23] offset:-3968
	global_store_dword v0, v152, s[22:23]
	global_store_dword v0, v153, s[22:23] offset:128
	s_waitcnt vmcnt(60)
	v_add_f32_e32 v154, v126, v154
	v_add_f32_e32 v155, v110, v155
	v_add_f32_e32 v156, v127, v156
	v_add_f32_e32 v157, v111, v157
	s_add_u32 s22, s22, 0x6000
	s_addc_u32 s23, s23, 0
	global_store_dword v0, v154, s[22:23] offset:-4096
	global_store_dword v0, v155, s[22:23] offset:-3968
	global_store_dword v0, v156, s[22:23]
	global_store_dword v0, v157, s[22:23] offset:128
	s_waitcnt vmcnt(60)
	v_add_f32_e32 v158, v128, v158
	v_add_f32_e32 v159, v112, v159
	v_add_f32_e32 v160, v129, v160
	v_add_f32_e32 v161, v113, v161
	s_add_u32 s22, s22, 0x2000
	s_addc_u32 s23, s23, 0
	global_store_dword v0, v158, s[22:23] offset:-4096
	global_store_dword v0, v159, s[22:23] offset:-3968
	global_store_dword v0, v160, s[22:23]
	global_store_dword v0, v161, s[22:23] offset:128
	s_waitcnt vmcnt(60)
	v_add_f32_e32 v162, v82, v162
	v_add_f32_e32 v163, v66, v163
	v_add_f32_e32 v164, v83, v164
	v_add_f32_e32 v165, v67, v165
	s_add_u32 s22, s22, 0x6000
	s_addc_u32 s23, s23, 0
	global_store_dword v0, v162, s[22:23] offset:-4096
	global_store_dword v0, v163, s[22:23] offset:-3968
	global_store_dword v0, v164, s[22:23]
	global_store_dword v0, v165, s[22:23] offset:128
	s_waitcnt vmcnt(60)
; __device__ __forceinline__ void resid_tile(const Params& p, const bf16* A, size_t lda, const bf16* Bt, int K, int mt, int nt, bool x_from_input, bf16* sA, bf16* sB, int dry) {
;     ...
; #pragma unroll
;   for (int mi = 0; mi < 4; ++mi)
; #pragma unroll
;     for (int ni = 0; ni < 2; ++ni) {
;       __builtin_amdgcn_sched_barrier(0);
; #pragma unroll
;       for (int e = 0; e < 16; ++e) {
;         const int t = m0 + wm * 128 + mi * 32 + ROW_OF(e, hh);
;         const int c = n0 + wn * 64 + ni * 32 + r;
;         const float xo = x_from_input ? (t < LP ? p.in[0][(size_t)t * DM + c] : p.in[1][(size_t)(t - LP) * DM + c]) : p.out[(size_t)t * DM + c];
;         if (!dry) p.out[(size_t)t * DM + c] = xo + acc[mi][ni][e];
;       }
;     }
	v_add_f32_e32 v166, v84, v166
	v_add_f32_e32 v167, v68, v167
	v_add_f32_e32 v168, v85, v168
	v_add_f32_e32 v169, v69, v169
	s_add_u32 s22, s22, 0x2000
	s_addc_u32 s23, s23, 0
	global_store_dword v0, v166, s[22:23] offset:-4096
	global_store_dword v0, v167, s[22:23] offset:-3968
	global_store_dword v0, v168, s[22:23]
	global_store_dword v0, v169, s[22:23] offset:128
	s_waitcnt vmcnt(60)
	v_add_f32_e32 v170, v86, v170
	v_add_f32_e32 v171, v70, v171
	v_add_f32_e32 v172, v87, v172
	v_add_f32_e32 v173, v71, v173
	s_add_u32 s22, s22, 0x6000
	s_addc_u32 s23, s23, 0
	global_store_dword v0, v170, s[22:23] offset:-4096
	global_store_dword v0, v171, s[22:23] offset:-3968
	global_store_dword v0, v172, s[22:23]
	global_store_dword v0, v173, s[22:23] offset:128
	s_waitcnt vmcnt(60)
	v_add_f32_e32 v174, v88, v174
	v_add_f32_e32 v175, v72, v175
	v_add_f32_e32 v176, v89, v176
	v_add_f32_e32 v177, v73, v177
	s_add_u32 s22, s22, 0x2000
	s_addc_u32 s23, s23, 0
	global_store_dword v0, v174, s[22:23] offset:-4096
	global_store_dword v0, v175, s[22:23] offset:-3968
	global_store_dword v0, v176, s[22:23]
	global_store_dword v0, v177, s[22:23] offset:128
	s_waitcnt vmcnt(60)
	v_add_f32_e32 v178, v90, v178
	v_add_f32_e32 v179, v74, v179
	v_add_f32_e32 v180, v91, v180
	v_add_f32_e32 v181, v75, v181
	s_add_u32 s22, s22, 0x6000
	s_addc_u32 s23, s23, 0
	global_store_dword v0, v178, s[22:23] offset:-4096
	global_store_dword v0, v179, s[22:23] offset:-3968
	global_store_dword v0, v180, s[22:23]
	global_store_dword v0, v181, s[22:23] offset:128
	s_waitcnt vmcnt(60)
	v_add_f32_e32 v182, v92, v182
	v_add_f32_e32 v183, v76, v183
	v_add_f32_e32 v184, v93, v184
	v_add_f32_e32 v185, v77, v185
	s_add_u32 s22, s22, 0x2000
	s_addc_u32 s23, s23, 0
	global_store_dword v0, v182, s[22:23] offset:-4096
	global_store_dword v0, v183, s[22:23] offset:-3968
	global_store_dword v0, v184, s[22:23]
	global_store_dword v0, v185, s[22:23] offset:128
	s_waitcnt vmcnt(60)
	v_add_f32_e32 v186, v94, v186
	v_add_f32_e32 v187, v78, v187
	v_add_f32_e32 v188, v95, v188
	v_add_f32_e32 v189, v79, v189
	s_add_u32 s22, s22, 0x6000
	s_addc_u32 s23, s23, 0
	global_store_dword v0, v186, s[22:23] offset:-4096
	global_store_dword v0, v187, s[22:23] offset:-3968
	global_store_dword v0, v188, s[22:23]
	global_store_dword v0, v189, s[22:23] offset:128
	s_waitcnt vmcnt(60)
	v_add_f32_e32 v190, v96, v190
	v_add_f32_e32 v191, v80, v191
	v_add_f32_e32 v192, v97, v192
	v_add_f32_e32 v193, v81, v193
	s_add_u32 s22, s22, 0x2000
	s_addc_u32 s23, s23, 0
	global_store_dword v0, v190, s[22:23] offset:-4096
	global_store_dword v0, v191, s[22:23] offset:-3968
	global_store_dword v0, v192, s[22:23]
	global_store_dword v0, v193, s[22:23] offset:128
	s_add_u32 s2, s8, 0x41000
	s_addc_u32 s3, s9, 0
	s_add_u32 s22, s8, 0x41000
	s_addc_u32 s23, s9, 0
	global_load_dword v130, v0, s[2:3] offset:-4096
	global_load_dword v131, v0, s[2:3] offset:-3968
	global_load_dword v132, v0, s[2:3]
	global_load_dword v133, v0, s[2:3] offset:128
	s_add_u32 s2, s2, 0x2000
	s_addc_u32 s3, s3, 0
	global_load_dword v134, v0, s[2:3] offset:-4096
	global_load_dword v135, v0, s[2:3] offset:-3968
	global_load_dword v136, v0, s[2:3]
	global_load_dword v137, v0, s[2:3] offset:128
	s_add_u32 s2, s2, 0x6000
	s_addc_u32 s3, s3, 0
	global_load_dword v138, v0, s[2:3] offset:-4096
	global_load_dword v139, v0, s[2:3] offset:-3968
	global_load_dword v140, v0, s[2:3]
	global_load_dword v141, v0, s[2:3] offset:128
	s_add_u32 s2, s2, 0x2000
	s_addc_u32 s3, s3, 0
	global_load_dword v142, v0, s[2:3] offset:-4096
	global_load_dword v143, v0, s[2:3] offset:-3968
	global_load_dword v144, v0, s[2:3]
	global_load_dword v145, v0, s[2:3] offset:128
	s_add_u32 s2, s2, 0x6000
	s_addc_u32 s3, s3, 0
	global_load_dword v146, v0, s[2:3] offset:-4096
	global_load_dword v147, v0, s[2:3] offset:-3968
	global_load_dword v148, v0, s[2:3]
	global_load_dword v149, v0, s[2:3] offset:128
	s_add_u32 s2, s2, 0x2000
	s_addc_u32 s3, s3, 0
	global_load_dword v150, v0, s[2:3] offset:-4096
	global_load_dword v151, v0, s[2:3] offset:-3968
	global_load_dword v152, v0, s[2:3]
	global_load_dword v153, v0, s[2:3] offset:128
	s_add_u32 s2, s2, 0x6000
	s_addc_u32 s3, s3, 0
	global_load_dword v154, v0, s[2:3] offset:-4096
	global_load_dword v155, v0, s[2:3] offset:-3968
	global_load_dword v156, v0, s[2:3]
	global_load_dword v157, v0, s[2:3] offset:128
	s_add_u32 s2, s2, 0x2000
	s_addc_u32 s3, s3, 0
	global_load_dword v158, v0, s[2:3] offset:-4096
	global_load_dword v159, v0, s[2:3] offset:-3968
	global_load_dword v160, v0, s[2:3]
	global_load_dword v161, v0, s[2:3] offset:128
	s_add_u32 s2, s2, 0x6000
	s_addc_u32 s3, s3, 0
	global_load_dword v162, v0, s[2:3] offset:-4096
	global_load_dword v163, v0, s[2:3] offset:-3968
	global_load_dword v164, v0, s[2:3]
	global_load_dword v165, v0, s[2:3] offset:128
	s_add_u32 s2, s2, 0x2000
	s_addc_u32 s3, s3, 0
	global_load_dword v166, v0, s[2:3] offset:-4096
	global_load_dword v167, v0, s[2:3] offset:-3968
	global_load_dword v168, v0, s[2:3]
	global_load_dword v169, v0, s[2:3] offset:128
	s_add_u32 s2, s2, 0x6000
	s_addc_u32 s3, s3, 0
	global_load_dword v170, v0, s[2:3] offset:-4096
	global_load_dword v171, v0, s[2:3] offset:-3968
	global_load_dword v172, v0, s[2:3]
	global_load_dword v173, v0, s[2:3] offset:128
	s_add_u32 s2, s2, 0x2000
	s_addc_u32 s3, s3, 0
	global_load_dword v174, v0, s[2:3] offset:-4096
	global_load_dword v175, v0, s[2:3] offset:-3968
	global_load_dword v176, v0, s[2:3]
	global_load_dword v177, v0, s[2:3] offset:128
	s_add_u32 s2, s2, 0x6000
	s_addc_u32 s3, s3, 0
	global_load_dword v178, v0, s[2:3] offset:-4096
	global_load_dword v179, v0, s[2:3] offset:-3968
	global_load_dword v180, v0, s[2:3]
	global_load_dword v181, v0, s[2:3] offset:128
	s_add_u32 s2, s2, 0x2000
	s_addc_u32 s3, s3, 0
	global_load_dword v182, v0, s[2:3] offset:-4096
	global_load_dword v183, v0, s[2:3] offset:-3968
	global_load_dword v184, v0, s[2:3]
	global_load_dword v185, v0, s[2:3] offset:128
	s_add_u32 s2, s2, 0x6000
	s_addc_u32 s3, s3, 0
	global_load_dword v186, v0, s[2:3] offset:-4096
	global_load_dword v187, v0, s[2:3] offset:-3968
	global_load_dword v188, v0, s[2:3]
	global_load_dword v189, v0, s[2:3] offset:128
	s_add_u32 s2, s2, 0x2000
	s_addc_u32 s3, s3, 0
	global_load_dword v190, v0, s[2:3] offset:-4096
	global_load_dword v191, v0, s[2:3] offset:-3968
	global_load_dword v192, v0, s[2:3]
	global_load_dword v193, v0, s[2:3] offset:128
	s_waitcnt vmcnt(60)
; __device__ __forceinline__ void resid_tile(const Params& p, const bf16* A, size_t lda, const bf16* Bt, int K, int mt, int nt, bool x_from_input, bf16* sA, bf16* sB, int dry) {
;     ...
; #pragma unroll
;   for (int mi = 0; mi < 4; ++mi)
; #pragma unroll
;     for (int ni = 0; ni < 2; ++ni) {
;       __builtin_amdgcn_sched_barrier(0);
; #pragma unroll
;       for (int e = 0; e < 16; ++e) {
;         const int t = m0 + wm * 128 + mi * 32 + ROW_OF(e, hh);
;         const int c = n0 + wn * 64 + ni * 32 + r;
;         const float xo = x_from_input ? (t < LP ? p.in[0][(size_t)t * DM + c] : p.in[1][(size_t)(t - LP) * DM + c]) : p.out[(size_t)t * DM + c];
;         if (!dry) p.out[(size_t)t * DM + c] = xo + acc[mi][ni][e];
;       }
;     }
	v_add_f32_e32 v130, v50, v130
	v_add_f32_e32 v131, v34, v131
	v_add_f32_e32 v132, v51, v132
	v_add_f32_e32 v133, v35, v133
	global_store_dword v0, v130, s[22:23] offset:-4096
	global_store_dword v0, v131, s[22:23] offset:-3968
	global_store_dword v0, v132, s[22:23]
	global_store_dword v0, v133, s[22:23] offset:128
	s_waitcnt vmcnt(60)
	v_add_f32_e32 v134, v52, v134
	v_add_f32_e32 v135, v36, v135
	v_add_f32_e32 v136, v53, v136
	v_add_f32_e32 v137, v37, v137
	s_add_u32 s22, s22, 0x2000
	s_addc_u32 s23, s23, 0
	global_store_dword v0, v134, s[22:23] offset:-4096
	global_store_dword v0, v135, s[22:23] offset:-3968
	global_store_dword v0, v136, s[22:23]
	global_store_dword v0, v137, s[22:23] offset:128
	s_waitcnt vmcnt(60)
	v_add_f32_e32 v138, v54, v138
	v_add_f32_e32 v139, v38, v139
	v_add_f32_e32 v140, v55, v140
	v_add_f32_e32 v141, v39, v141
	s_add_u32 s22, s22, 0x6000
	s_addc_u32 s23, s23, 0
	global_store_dword v0, v138, s[22:23] offset:-4096
	global_store_dword v0, v139, s[22:23] offset:-3968
	global_store_dword v0, v140, s[22:23]
	global_store_dword v0, v141, s[22:23] offset:128
	s_waitcnt vmcnt(60)
	v_add_f32_e32 v142, v56, v142
	v_add_f32_e32 v143, v40, v143
	v_add_f32_e32 v144, v57, v144
	v_add_f32_e32 v145, v41, v145
	s_add_u32 s22, s22, 0x2000
	s_addc_u32 s23, s23, 0
	global_store_dword v0, v142, s[22:23] offset:-4096
	global_store_dword v0, v143, s[22:23] offset:-3968
	global_store_dword v0, v144, s[22:23]
	global_store_dword v0, v145, s[22:23] offset:128
	s_waitcnt vmcnt(60)
	v_add_f32_e32 v146, v58, v146
	v_add_f32_e32 v147, v42, v147
	v_add_f32_e32 v148, v59, v148
	v_add_f32_e32 v149, v43, v149
	s_add_u32 s22, s22, 0x6000
	s_addc_u32 s23, s23, 0
	global_store_dword v0, v146, s[22:23] offset:-4096
	global_store_dword v0, v147, s[22:23] offset:-3968
	global_store_dword v0, v148, s[22:23]
	global_store_dword v0, v149, s[22:23] offset:128
	s_waitcnt vmcnt(60)
	v_add_f32_e32 v150, v60, v150
	v_add_f32_e32 v151, v44, v151
	v_add_f32_e32 v152, v61, v152
	v_add_f32_e32 v153, v45, v153
	s_add_u32 s22, s22, 0x2000
	s_addc_u32 s23, s23, 0
	global_store_dword v0, v150, s[22:23] offset:-4096
	global_store_dword v0, v151, s[22:23] offset:-3968
	global_store_dword v0, v152, s[22:23]
	global_store_dword v0, v153, s[22:23] offset:128
	s_waitcnt vmcnt(60)
	v_add_f32_e32 v154, v62, v154
	v_add_f32_e32 v155, v46, v155
	v_add_f32_e32 v156, v63, v156
	v_add_f32_e32 v157, v47, v157
	s_add_u32 s22, s22, 0x6000
	s_addc_u32 s23, s23, 0
	global_store_dword v0, v154, s[22:23] offset:-4096
	global_store_dword v0, v155, s[22:23] offset:-3968
	global_store_dword v0, v156, s[22:23]
	global_store_dword v0, v157, s[22:23] offset:128
	s_waitcnt vmcnt(60)
	v_add_f32_e32 v158, v64, v158
	v_add_f32_e32 v159, v48, v159
	v_add_f32_e32 v160, v65, v160
	v_add_f32_e32 v161, v49, v161
	s_add_u32 s22, s22, 0x2000
	s_addc_u32 s23, s23, 0
	global_store_dword v0, v158, s[22:23] offset:-4096
	global_store_dword v0, v159, s[22:23] offset:-3968
	global_store_dword v0, v160, s[22:23]
	global_store_dword v0, v161, s[22:23] offset:128
	s_waitcnt vmcnt(60)
	v_add_f32_e32 v162, v18, v162
	v_add_f32_e32 v163, v2, v163
	v_add_f32_e32 v164, v19, v164
	v_add_f32_e32 v165, v3, v165
	s_add_u32 s22, s22, 0x6000
	s_addc_u32 s23, s23, 0
	global_store_dword v0, v162, s[22:23] offset:-4096
	global_store_dword v0, v163, s[22:23] offset:-3968
	global_store_dword v0, v164, s[22:23]
	global_store_dword v0, v165, s[22:23] offset:128
	s_waitcnt vmcnt(60)
	v_add_f32_e32 v166, v20, v166
	v_add_f32_e32 v167, v4, v167
	v_add_f32_e32 v168, v21, v168
	v_add_f32_e32 v169, v5, v169
	s_add_u32 s22, s22, 0x2000
	s_addc_u32 s23, s23, 0
	global_store_dword v0, v166, s[22:23] offset:-4096
	global_store_dword v0, v167, s[22:23] offset:-3968
	global_store_dword v0, v168, s[22:23]
	global_store_dword v0, v169, s[22:23] offset:128
	s_waitcnt vmcnt(60)
	v_add_f32_e32 v170, v22, v170
	v_add_f32_e32 v171, v6, v171
	v_add_f32_e32 v172, v23, v172
	v_add_f32_e32 v173, v7, v173
	s_add_u32 s22, s22, 0x6000
	s_addc_u32 s23, s23, 0
	global_store_dword v0, v170, s[22:23] offset:-4096
	global_store_dword v0, v171, s[22:23] offset:-3968
	global_store_dword v0, v172, s[22:23]
	global_store_dword v0, v173, s[22:23] offset:128
	s_waitcnt vmcnt(60)
	v_add_f32_e32 v174, v24, v174
	v_add_f32_e32 v175, v8, v175
	v_add_f32_e32 v176, v25, v176
	v_add_f32_e32 v177, v9, v177
	s_add_u32 s22, s22, 0x2000
	s_addc_u32 s23, s23, 0
	global_store_dword v0, v174, s[22:23] offset:-4096
	global_store_dword v0, v175, s[22:23] offset:-3968
	global_store_dword v0, v176, s[22:23]
	global_store_dword v0, v177, s[22:23] offset:128
	s_waitcnt vmcnt(60)
	v_add_f32_e32 v178, v26, v178
	v_add_f32_e32 v179, v10, v179
	v_add_f32_e32 v180, v27, v180
	v_add_f32_e32 v181, v11, v181
	s_add_u32 s22, s22, 0x6000
	s_addc_u32 s23, s23, 0
	global_store_dword v0, v178, s[22:23] offset:-4096
	global_store_dword v0, v179, s[22:23] offset:-3968
	global_store_dword v0, v180, s[22:23]
	global_store_dword v0, v181, s[22:23] offset:128
	s_waitcnt vmcnt(60)
	v_add_f32_e32 v182, v28, v182
	v_add_f32_e32 v183, v12, v183
	v_add_f32_e32 v184, v29, v184
	v_add_f32_e32 v185, v13, v185
	s_add_u32 s22, s22, 0x2000
	s_addc_u32 s23, s23, 0
	global_store_dword v0, v182, s[22:23] offset:-4096
	global_store_dword v0, v183, s[22:23] offset:-3968
	global_store_dword v0, v184, s[22:23]
	global_store_dword v0, v185, s[22:23] offset:128
	s_waitcnt vmcnt(60)
	v_add_f32_e32 v186, v30, v186
	v_add_f32_e32 v187, v14, v187
	v_add_f32_e32 v188, v31, v188
	v_add_f32_e32 v189, v15, v189
	s_add_u32 s22, s22, 0x6000
	s_addc_u32 s23, s23, 0
	global_store_dword v0, v186, s[22:23] offset:-4096
	global_store_dword v0, v187, s[22:23] offset:-3968
	global_store_dword v0, v188, s[22:23]
	global_store_dword v0, v189, s[22:23] offset:128
	s_waitcnt vmcnt(60)
	v_add_f32_e32 v190, v32, v190
	v_add_f32_e32 v191, v16, v191
	v_add_f32_e32 v192, v33, v192
	v_add_f32_e32 v193, v17, v193
	s_add_u32 s22, s22, 0x2000
	s_addc_u32 s23, s23, 0
	global_store_dword v0, v190, s[22:23] offset:-4096
	global_store_dword v0, v191, s[22:23] offset:-3968
	global_store_dword v0, v192, s[22:23]
	global_store_dword v0, v193, s[22:23] offset:128
	v_readlane_b32 s2, v254, 60
	s_add_i32 s0, s0, s2
	s_cmpk_lt_u32 s0, 0x80
	s_cbranch_scc1 .LBB0_16

; #define ZERO_ACC(acc, MI_, NI_)                 \
;   _Pragma("unroll") for (int mi = 0; mi < MI_; ++mi) \
;   _Pragma("unroll") for (int ni = 0; ni < NI_; ++ni) \
;   _Pragma("unroll") for (int e = 0; e < 16; ++e) acc[mi][ni][e] = 0.f;
; __device__ __forceinline__ void ffn1_tile(const Params& p, int mt, int nt, bf16* sA, bf16* sB) {
;   const int m0 = mt * 256;
;   f16v acc[4][2];
;   ZERO_ACC(acc, 4, 2)
;   gemm_kloop<4, 2>(p.h + (size_t)m0 * DM, DM, p.WfguT + (size_t)nt * 128 * DM, DM, DM, acc, sA, sB);
.LBB0_22:
	s_lshr_b32 s2, s0, 4
	s_and_b32 s20, s2, 48
	s_sub_i32 s2, 44, s20
	s_min_u32 s21, s2, 16
	s_lshl_b32 s2, s21, 2
	v_cvt_f32_ubyte0_e32 v0, s2
	v_rcp_iflag_f32_e32 v2, v0
	v_cvt_f32_ubyte0_e32 v3, s0
	s_and_b32 s22, s0, 0xff
	v_readlane_b32 s64, v252, 23
	v_mul_f32_e32 v2, v3, v2
	v_trunc_f32_e32 v2, v2
	v_cvt_u32_f32_e32 v4, v2
	v_fma_f32 v2, -v2, v0, v3
	v_cmp_ge_f32_e64 s[2:3], |v2|, v0
	s_cmp_lg_u64 s[2:3], 0
	v_readfirstlane_b32 s2, v4
	s_addc_u32 s2, s2, 0
	s_and_b32 s2, s2, 0xff
	s_lshl_b32 s2, s2, 2
	s_mul_i32 s21, s21, s2
	s_sub_i32 s3, s22, s21
	s_sext_i32_i16 s21, s3
	s_bfe_u32 s21, s21, 0x2001d
	s_add_i32 s21, s3, s21
	s_sext_i32_i16 s22, s21
	s_and_b32 s21, s21, 0xfffc
	s_sub_i32 s3, s3, s21
	s_add_i32 s2, s2, s88
	s_sext_i32_i16 s3, s3
	s_add_i32 s3, s2, s3
	s_ashr_i32 s2, s22, 2
	s_add_i32 s2, s20, s2
	s_lshl_b32 s20, s3, 8
	s_ashr_i32 s21, s20, 31
	s_lshl_b64 s[22:23], s[20:21], 11
	v_readlane_b32 s66, v252, 25
	v_mov_b32_e32 v18, v195
	v_readlane_b32 s67, v252, 26
	s_add_u32 s24, s66, s22
	s_addc_u32 s25, s67, s23
	v_ashrrev_i32_e32 v2, 3, v18
	v_lshlrev_b32_e32 v0, 4, v18
	v_and_b32_e32 v0, 0x70, v0
	v_ashrrev_i32_e32 v3, 31, v2
	v_lshl_add_u64 v[4:5], s[24:25], 0, v[0:1]
	v_lshlrev_b64 v[6:7], 11, v[2:3]
	s_mov_b64 s[24:25], 0x10000
	v_lshl_add_u64 v[10:11], v[6:7], 0, s[24:25]
	v_lshl_add_u64 v[8:9], v[4:5], 0, v[6:7]
	v_lshl_add_u64 v[12:13], v[4:5], 0, v[10:11]
	s_mov_b64 s[24:25], 0x20000
	global_load_dwordx4 v[130:133], v[8:9], off
	global_load_dwordx4 v[138:141], v[12:13], off
	v_lshl_add_u64 v[12:13], v[6:7], 0, s[24:25]
	s_mov_b64 s[24:25], 0x30000
	v_lshl_add_u64 v[16:17], v[6:7], 0, s[24:25]
	v_lshl_add_u64 v[14:15], v[4:5], 0, v[12:13]
	v_lshl_add_u64 v[4:5], v[4:5], 0, v[16:17]
	s_ashr_i32 s3, s2, 31
	global_load_dwordx4 v[142:145], v[14:15], off
	global_load_dwordx4 v[146:149], v[4:5], off
	v_add_co_u32_e32 v4, vcc, s62, v8
	s_lshl_b64 s[26:27], s[2:3], 18
	s_nop 0
	v_addc_co_u32_e32 v5, vcc, 0, v9, vcc
	s_mov_b32 s3, 0x50000
	v_add_co_u32_e32 v14, vcc, s3, v8
	s_add_u32 s28, s18, s26
	s_nop 0
	v_addc_co_u32_e32 v15, vcc, 0, v9, vcc
	global_load_dwordx4 v[150:153], v[4:5], off
	global_load_dwordx4 v[154:157], v[14:15], off
	v_add_co_u32_e32 v4, vcc, s92, v8
	s_addc_u32 s29, s19, s27
	s_nop 0
	v_addc_co_u32_e32 v5, vcc, 0, v9, vcc
	v_add_co_u32_e32 v8, vcc, s93, v8
	v_and_b32_e32 v3, 0xfffff9f, v18
	s_nop 0
	v_addc_co_u32_e32 v9, vcc, 0, v9, vcc
	global_load_dwordx4 v[158:161], v[4:5], off
	global_load_dwordx4 v[162:165], v[8:9], off
	v_lshl_add_u64 v[4:5], s[28:29], 0, v[0:1]
	v_lshl_add_u64 v[8:9], v[4:5], 0, v[6:7]
	v_lshl_add_u64 v[10:11], v[4:5], 0, v[10:11]
	v_lshl_add_u64 v[8:9], v[4:5], 0, v[12:13]
	v_lshl_add_u64 v[4:5], v[4:5], 0, v[16:17]
	v_mul_lo_u32 v8, v2, s33
	v_or_b32_e32 v2, 0x60, v18
	v_mul_lo_u32 v9, v3, s33
	v_mul_lo_u32 v10, v2, s33
	v_lshl_add_u64 v[2:3], v[6:7], 0, s[22:23]
	v_or_b32_e32 v2, v2, v0
	s_waitcnt vmcnt(31)
	v_lshl_add_u64 v[178:179], s[66:67], 0, v[2:3]
	v_lshl_add_u64 v[2:3], s[26:27], 0, v[6:7]
	v_lshrrev_b32_e32 v4, 1, v18
	v_and_b32_e32 v5, 0x5f, v18
	v_or_b32_e32 v2, v2, v0
	v_and_b32_e32 v4, 16, v4
	v_mul_u32_u24_e32 v5, 0x90, v5
	v_lshl_add_u64 v[180:181], s[18:19], 0, v[2:3]
	v_mov_b32_e32 v2, 0
	s_mov_b64 s[22:23], 0
	s_waitcnt vmcnt(30)
	v_add_u32_e32 v184, v0, v8
	v_add_u32_e32 v183, v4, v9
	v_add_u32_e32 v182, v4, v10
	v_add_u32_e32 v0, v4, v5
	v_mov_b32_e32 v3, v2
	v_mov_b32_e32 v4, v2
	v_mov_b32_e32 v5, v2
	v_mov_b32_e32 v6, v2
	v_mov_b32_e32 v7, v2
	v_mov_b32_e32 v8, v2
	v_mov_b32_e32 v9, v2
	v_mov_b32_e32 v10, v2
	v_mov_b32_e32 v11, v2
	v_mov_b32_e32 v12, v2
	v_mov_b32_e32 v13, v2
	v_mov_b32_e32 v14, v2
	v_mov_b32_e32 v15, v2
	v_mov_b32_e32 v16, v2
	v_mov_b32_e32 v17, v2
	v_mov_b32_e32 v18, v2
	v_mov_b32_e32 v19, v2
	v_mov_b32_e32 v20, v2
	v_mov_b32_e32 v21, v2
	v_mov_b32_e32 v22, v2
	v_mov_b32_e32 v23, v2
	v_mov_b32_e32 v24, v2
	v_mov_b32_e32 v25, v2
	v_mov_b32_e32 v26, v2
	v_mov_b32_e32 v27, v2
	v_mov_b32_e32 v28, v2
	v_mov_b32_e32 v29, v2
	v_mov_b32_e32 v30, v2
	v_mov_b32_e32 v31, v2
	v_mov_b32_e32 v32, v2
	v_mov_b32_e32 v33, v2
	v_mov_b32_e32 v34, v2
	v_mov_b32_e32 v35, v2
	v_mov_b32_e32 v36, v2
	v_mov_b32_e32 v37, v2
	v_mov_b32_e32 v38, v2
	v_mov_b32_e32 v39, v2
	v_mov_b32_e32 v40, v2
	v_mov_b32_e32 v41, v2
	v_mov_b32_e32 v42, v2
	v_mov_b32_e32 v43, v2
	v_mov_b32_e32 v44, v2
	v_mov_b32_e32 v45, v2
	v_mov_b32_e32 v46, v2
	v_mov_b32_e32 v47, v2
	v_mov_b32_e32 v48, v2
	v_mov_b32_e32 v49, v2
	v_mov_b32_e32 v50, v2
	v_mov_b32_e32 v51, v2
	v_mov_b32_e32 v52, v2
	v_mov_b32_e32 v53, v2
	v_mov_b32_e32 v54, v2
	v_mov_b32_e32 v55, v2
	v_mov_b32_e32 v56, v2
	v_mov_b32_e32 v57, v2
	v_mov_b32_e32 v58, v2
	v_mov_b32_e32 v59, v2
	v_mov_b32_e32 v60, v2
	v_mov_b32_e32 v61, v2
	v_mov_b32_e32 v62, v2
	v_mov_b32_e32 v63, v2
	v_mov_b32_e32 v64, v2
	v_mov_b32_e32 v65, v2
	v_mov_b32_e32 v66, v2
	v_mov_b32_e32 v67, v2
	v_mov_b32_e32 v68, v2
	v_mov_b32_e32 v69, v2
	v_mov_b32_e32 v70, v2
	v_mov_b32_e32 v71, v2
	v_mov_b32_e32 v72, v2
	v_mov_b32_e32 v73, v2
	v_mov_b32_e32 v74, v2
	v_mov_b32_e32 v75, v2
	v_mov_b32_e32 v76, v2
	v_mov_b32_e32 v77, v2
	v_mov_b32_e32 v78, v2
	v_mov_b32_e32 v79, v2
	v_mov_b32_e32 v80, v2
	v_mov_b32_e32 v81, v2
	v_mov_b32_e32 v82, v2
	v_mov_b32_e32 v83, v2
	v_mov_b32_e32 v84, v2
	v_mov_b32_e32 v85, v2
	v_mov_b32_e32 v86, v2
	v_mov_b32_e32 v87, v2
	v_mov_b32_e32 v88, v2
	v_mov_b32_e32 v89, v2
	v_mov_b32_e32 v90, v2
	v_mov_b32_e32 v91, v2
	v_mov_b32_e32 v92, v2
	v_mov_b32_e32 v93, v2
	v_mov_b32_e32 v94, v2
	v_mov_b32_e32 v95, v2
	v_mov_b32_e32 v96, v2
	v_mov_b32_e32 v97, v2
	v_mov_b32_e32 v98, v2
	v_mov_b32_e32 v99, v2
	v_mov_b32_e32 v100, v2
; template <int MI, int NI>
; __device__ __forceinline__ void gemm_kloop(const bf16* __restrict__ A, size_t lda, const bf16* __restrict__ Bt, size_t ldb, int K,
;                                            f16v (&acc)[MI][NI], bf16* sA, bf16* sB) {
;   const int tid = tid_opaque(), lane = tid & 63, w = tid >> 6;
;   const int r = lane & 31, hh = lane >> 5;
;   const int wm = w >> 1, wn = w & 1;
;   const int lrow = tid >> 3, lseg = tid & 7;
;   u4v ra[2 * MI], rb[2 * NI];
;   const int KT = K >> 6;
; #pragma unroll
;   for (int i = 0; i < 2 * MI; ++i) ra[i] = *(const u4v*)(A + (size_t)(lrow + 32 * i) * lda + lseg * 8);
; #pragma unroll
;   for (int i = 0; i < 2 * NI; ++i) rb[i] = *(const u4v*)(Bt + (size_t)(lrow + 32 * i) * ldb + lseg * 8);
;   unsigned pfs = 0;
;   {
;     if (tid < 64 * MI) pfs ^= *(const unsigned*)(A + (size_t)tid * lda + 64) ^ *(const unsigned*)(A + (size_t)tid * lda + 128);
;     if (tid < 64 * NI) pfs ^= *(const unsigned*)(Bt + (size_t)tid * ldb + 64) ^ *(const unsigned*)(Bt + (size_t)tid * ldb + 128);
;   }
;   for (int kt = 0; kt < KT; ++kt) {
;     __syncthreads();
; #pragma unroll
;     for (int i = 0; i < 2 * MI; ++i) *(u4v*)(sA + (lrow + 32 * i) * 72 + lseg * 8) = ra[i];
; #pragma unroll
;     for (int i = 0; i < 2 * NI; ++i) *(u4v*)(sB + (lrow + 32 * i) * 72 + lseg * 8) = rb[i];
;     __syncthreads();
;     if (kt + 3 < KT) {
;       const int k2 = (kt + 3) << 6;
;       if (tid < 64 * MI) pfs ^= *(const unsigned*)(A + (size_t)tid * lda + k2);
;       if (tid < 64 * NI) pfs ^= *(const unsigned*)(Bt + (size_t)tid * ldb + k2);
;     }
;     if (kt + 1 < KT) {
;       const int k0 = (kt + 1) << 6;
; #pragma unroll
;       for (int i = 0; i < 2 * MI; ++i) ra[i] = *(const u4v*)(A + (size_t)(lrow + 32 * i) * lda + k0 + lseg * 8);
; #pragma unroll
;       for (int i = 0; i < 2 * NI; ++i) rb[i] = *(const u4v*)(Bt + (size_t)(lrow + 32 * i) * ldb + k0 + lseg * 8);
;     }
; #pragma unroll
;     for (int ks = 0; ks < 4; ++ks) {
;       s8v a[MI], b[NI];
; #pragma unroll
;       for (int mi = 0; mi < MI; ++mi) a[mi] = *(const s8v*)(sA + (wm * 32 * MI + mi * 32 + r) * 72 + ks * 16 + hh * 8);
; #pragma unroll
;       for (int ni = 0; ni < NI; ++ni) b[ni] = *(const s8v*)(sB + (wn * 32 * NI + ni * 32 + r) * 72 + ks * 16 + hh * 8);
; #pragma unroll
;       for (int mi = 0; mi < MI; ++mi)
; #pragma unroll
	v_mov_b32_e32 v101, v2
	v_mov_b32_e32 v102, v2
	v_mov_b32_e32 v103, v2
	v_mov_b32_e32 v104, v2
	v_mov_b32_e32 v105, v2
	v_mov_b32_e32 v106, v2
	v_mov_b32_e32 v107, v2
	v_mov_b32_e32 v108, v2
	v_mov_b32_e32 v109, v2
	v_mov_b32_e32 v110, v2
	v_mov_b32_e32 v111, v2
	v_mov_b32_e32 v112, v2
	v_mov_b32_e32 v113, v2
	v_mov_b32_e32 v114, v2
	v_mov_b32_e32 v115, v2
	v_mov_b32_e32 v116, v2
	v_mov_b32_e32 v117, v2
	v_mov_b32_e32 v118, v2
	v_mov_b32_e32 v119, v2
	v_mov_b32_e32 v120, v2
	v_mov_b32_e32 v121, v2
	v_mov_b32_e32 v122, v2
	v_mov_b32_e32 v123, v2
	v_mov_b32_e32 v124, v2
	v_mov_b32_e32 v125, v2
	v_mov_b32_e32 v126, v2
	v_mov_b32_e32 v127, v2
	v_mov_b32_e32 v128, v2
	v_mov_b32_e32 v129, v2
	v_readlane_b32 s65, v252, 24
	v_readlane_b32 s68, v252, 27
	v_readlane_b32 s69, v252, 28
	v_readlane_b32 s70, v252, 29
	v_readlane_b32 s71, v252, 30
	v_readlane_b32 s72, v252, 31
	v_readlane_b32 s73, v252, 32
	v_readlane_b32 s74, v252, 33
	v_readlane_b32 s75, v252, 34
	v_readlane_b32 s76, v252, 35
	v_readlane_b32 s77, v252, 36
	v_readlane_b32 s78, v252, 37
	v_readlane_b32 s79, v252, 38
	v_readfirstlane_b32 s56, v178
	v_readfirstlane_b32 s57, v179
	v_readfirstlane_b32 s58, v180
	v_readfirstlane_b32 s59, v181
	v_readfirstlane_b32 s94, v195
	v_subrev_u32_e32 v178, s56, v178
	v_add_u32_e32 v179, 0x10000, v178
	v_add_u32_e32 v180, 0x20000, v178
	v_add_u32_e32 v181, 0x30000, v178
	v_add_u32_e32 v185, 0x40000, v178
	v_add_u32_e32 v222, 0x50000, v178
	v_add_u32_e32 v223, 0x60000, v178
	v_add_u32_e32 v227, 0x70000, v178
	s_lshr_b32 s94, s94, 6
	s_mul_i32 s95, s94, 0x4000
	s_sub_u32 s58, s58, s95
	s_subb_u32 s59, s59, 0
	s_lshl_b32 s96, s94, 12
	s_add_u32 s96, s96, 36864
	v_and_b32_e32 v170, 63, v195
	v_lshrrev_b32_e32 v171, 3, v170
	v_lshrrev_b32_e32 v172, 4, v170
	v_and_b32_e32 v173, 7, v170
	v_xor_b32_e32 v172, v172, v173
	v_lshlrev_b32_e32 v172, 4, v172
	v_lshrrev_b32_e32 v173, 6, v195
	v_lshl_add_u32 v170, v173, 5, v171
	v_mul_u32_u24_e32 v170, 0x800, v170
	v_add_u32_e32 v134, v170, v172
	v_xor_b32_e32 v172, 64, v172
	v_add_u32_e32 v170, v170, v172
	v_add_u32_e32 v135, 0x3c00, v170
	v_add_u32_e32 v136, 0x7800, v134
	v_add_u32_e32 v137, 0xb400, v170
	v_and_b32_e32 v170, 31, v195
	v_bfe_u32 v171, v195, 5, 1
	v_bfe_u32 v172, v170, 1, 3
	v_xor_b32_e32 v171, v171, v172
	v_lshlrev_b32_e32 v171, 4, v171
	v_bfe_u32 v172, v195, 6, 1
	v_lshl_add_u32 v172, v172, 6, v170
	v_lshl_add_u32 v166, v172, 7, v171
	v_xor_b32_e32 v167, 32, v166
	v_xor_b32_e32 v168, 64, v166
	v_xor_b32_e32 v169, 96, v166
	s_barrier
	s_add_u32 m0, s96, 0
	s_nop 0
	global_load_lds_dwordx4 v134, s[58:59] offset:0
	global_load_lds_dwordx4 v135, s[58:59] offset:1024
	global_load_lds_dwordx4 v136, s[58:59] offset:2048
	global_load_lds_dwordx4 v137, s[58:59] offset:3072
	s_barrier
	s_waitcnt vmcnt(11)
	ds_write_b128 v184, v[130:133]
	s_waitcnt vmcnt(10)
	ds_write_b128 v184, v[138:141] offset:4608
	s_waitcnt vmcnt(9)
	ds_write_b128 v184, v[142:145] offset:9216
	s_waitcnt vmcnt(8)
	ds_write_b128 v184, v[146:149] offset:13824
	s_waitcnt vmcnt(7)
	ds_write_b128 v184, v[150:153] offset:18432
	s_waitcnt vmcnt(6)
	ds_write_b128 v184, v[154:157] offset:23040
	s_waitcnt vmcnt(5)
	ds_write_b128 v184, v[158:161] offset:27648
	s_waitcnt vmcnt(4)
	ds_write_b128 v184, v[162:165] offset:32256
	s_waitcnt vmcnt(0) lgkmcnt(0)
	s_barrier
	ds_read_b128 v[186:189], v183
	ds_read_b128 v[204:207], v166 offset:36864
	ds_read_b128 v[208:211], v166 offset:40960
	ds_read_b128 v[190:193], v183 offset:4608
	ds_read_b128 v[196:199], v183 offset:9216
	ds_read_b128 v[200:203], v182
	ds_read_b128 v[212:215], v183 offset:32
	ds_read_b128 v[244:247], v167 offset:36864
	ds_read_b128 v[248:251], v167 offset:40960
	ds_read_b128 v[216:219], v183 offset:4640
	ds_read_b128 v[232:235], v183 offset:9248
	ds_read_b128 v[236:239], v182 offset:32
	s_waitcnt lgkmcnt(10)
	v_mfma_f32_32x32x16_bf16 v[114:129], v[186:189], v[204:207], v[114:129]
	s_add_u32 m0, s96, 16256
	s_nop 0
	s_waitcnt lgkmcnt(9)
	v_mfma_f32_32x32x16_bf16 v[98:113], v[186:189], v[208:211], v[98:113]
	global_load_lds_dwordx4 v134, s[58:59] offset:128
	ds_read_b128 v[186:189], v183 offset:64
	s_waitcnt lgkmcnt(9)
	v_mfma_f32_32x32x16_bf16 v[82:97], v[190:193], v[204:207], v[82:97]
	global_load_lds_dwordx4 v135, s[58:59] offset:1152
	v_mfma_f32_32x32x16_bf16 v[66:81], v[190:193], v[208:211], v[66:81]
	global_load_lds_dwordx4 v136, s[58:59] offset:2176
	ds_read_b128 v[190:193], v183 offset:4672
	s_waitcnt lgkmcnt(9)
	v_mfma_f32_32x32x16_bf16 v[50:65], v[196:199], v[204:207], v[50:65]
	global_load_lds_dwordx4 v137, s[58:59] offset:3200
	v_mfma_f32_32x32x16_bf16 v[34:49], v[196:199], v[208:211], v[34:49]
	global_load_dwordx4 v[130:133], v178, s[56:57] offset:128
	ds_read_b128 v[196:199], v183 offset:9280
	s_waitcnt lgkmcnt(9)
	v_mfma_f32_32x32x16_bf16 v[18:33], v[200:203], v[204:207], v[18:33]
	global_load_dwordx4 v[138:141], v179, s[56:57] offset:128
	v_mfma_f32_32x32x16_bf16 v[2:17], v[200:203], v[208:211], v[2:17]
	global_load_dwordx4 v[142:145], v180, s[56:57] offset:128
	ds_read_b128 v[200:203], v182 offset:64
	ds_read_b128 v[204:207], v168 offset:36864
	ds_read_b128 v[208:211], v168 offset:40960
	s_waitcnt lgkmcnt(10)
	v_mfma_f32_32x32x16_bf16 v[114:129], v[212:215], v[244:247], v[114:129]
	global_load_dwordx4 v[146:149], v181, s[56:57] offset:128
	s_waitcnt lgkmcnt(9)
	v_mfma_f32_32x32x16_bf16 v[98:113], v[212:215], v[248:251], v[98:113]
	global_load_dwordx4 v[150:153], v185, s[56:57] offset:128
	ds_read_b128 v[212:215], v183 offset:96
	s_waitcnt lgkmcnt(9)
; #define MFMA(a, b, c) __builtin_amdgcn_mfma_f32_32x32x16_bf16((a), (b), (c), 0, 0, 0)
; template <int MI, int NI>
; __device__ __forceinline__ void gemm_kloop(const bf16* __restrict__ A, size_t lda, const bf16* __restrict__ Bt, size_t ldb, int K,
;                                            f16v (&acc)[MI][NI], bf16* sA, bf16* sB) {
;     ...
;   for (int kt = 0; kt < KT; ++kt) {
;     __syncthreads();
; #pragma unroll
;     for (int i = 0; i < 2 * MI; ++i) *(u4v*)(sA + (lrow + 32 * i) * 72 + lseg * 8) = ra[i];
; #pragma unroll
;     for (int i = 0; i < 2 * NI; ++i) *(u4v*)(sB + (lrow + 32 * i) * 72 + lseg * 8) = rb[i];
;     __syncthreads();
;     if (kt + 3 < KT) {
;       const int k2 = (kt + 3) << 6;
;       if (tid < 64 * MI) pfs ^= *(const unsigned*)(A + (size_t)tid * lda + k2);
;       if (tid < 64 * NI) pfs ^= *(const unsigned*)(Bt + (size_t)tid * ldb + k2);
;     }
;     if (kt + 1 < KT) {
;       const int k0 = (kt + 1) << 6;
; #pragma unroll
;       for (int i = 0; i < 2 * MI; ++i) ra[i] = *(const u4v*)(A + (size_t)(lrow + 32 * i) * lda + k0 + lseg * 8);
; #pragma unroll
;       for (int i = 0; i < 2 * NI; ++i) rb[i] = *(const u4v*)(Bt + (size_t)(lrow + 32 * i) * ldb + k0 + lseg * 8);
;     }
; #pragma unroll
;     for (int ks = 0; ks < 4; ++ks) {
;       s8v a[MI], b[NI];
; #pragma unroll
;       for (int mi = 0; mi < MI; ++mi) a[mi] = *(const s8v*)(sA + (wm * 32 * MI + mi * 32 + r) * 72 + ks * 16 + hh * 8);
; #pragma unroll
;       for (int ni = 0; ni < NI; ++ni) b[ni] = *(const s8v*)(sB + (wn * 32 * NI + ni * 32 + r) * 72 + ks * 16 + hh * 8);
; #pragma unroll
;       for (int mi = 0; mi < MI; ++mi)
; #pragma unroll
;         for (int ni = 0; ni < NI; ++ni) acc[mi][ni] = MFMA(a[mi], b[ni], acc[mi][ni]);
;     }
;   }
	v_mfma_f32_32x32x16_bf16 v[82:97], v[216:219], v[244:247], v[82:97]
	global_load_dwordx4 v[154:157], v222, s[56:57] offset:128
	v_mfma_f32_32x32x16_bf16 v[66:81], v[216:219], v[248:251], v[66:81]
	global_load_dwordx4 v[158:161], v223, s[56:57] offset:128
	ds_read_b128 v[216:219], v183 offset:4704
	s_waitcnt lgkmcnt(9)
	v_mfma_f32_32x32x16_bf16 v[50:65], v[232:235], v[244:247], v[50:65]
	global_load_dwordx4 v[162:165], v227, s[56:57] offset:128
	v_mfma_f32_32x32x16_bf16 v[34:49], v[232:235], v[248:251], v[34:49]
	ds_read_b128 v[232:235], v183 offset:9312
	s_waitcnt lgkmcnt(9)
	v_mfma_f32_32x32x16_bf16 v[18:33], v[236:239], v[244:247], v[18:33]
	v_mfma_f32_32x32x16_bf16 v[2:17], v[236:239], v[248:251], v[2:17]
	ds_read_b128 v[236:239], v182 offset:96
	ds_read_b128 v[244:247], v169 offset:36864
	ds_read_b128 v[248:251], v169 offset:40960
	s_waitcnt lgkmcnt(7)
	v_mfma_f32_32x32x16_bf16 v[114:129], v[186:189], v[204:207], v[114:129]
	s_waitcnt lgkmcnt(6)
	v_mfma_f32_32x32x16_bf16 v[98:113], v[186:189], v[208:211], v[98:113]
	v_mfma_f32_32x32x16_bf16 v[82:97], v[190:193], v[204:207], v[82:97]
	v_mfma_f32_32x32x16_bf16 v[66:81], v[190:193], v[208:211], v[66:81]
	v_mfma_f32_32x32x16_bf16 v[50:65], v[196:199], v[204:207], v[50:65]
	v_mfma_f32_32x32x16_bf16 v[34:49], v[196:199], v[208:211], v[34:49]
	v_mfma_f32_32x32x16_bf16 v[2:17], v[200:203], v[208:211], v[2:17]
	v_mfma_f32_32x32x16_bf16 v[18:33], v[200:203], v[204:207], v[18:33]
	s_waitcnt lgkmcnt(1)
	v_mfma_f32_32x32x16_bf16 v[114:129], v[212:215], v[244:247], v[114:129]
	s_waitcnt lgkmcnt(0)
	v_mfma_f32_32x32x16_bf16 v[98:113], v[212:215], v[248:251], v[98:113]
	v_mfma_f32_32x32x16_bf16 v[82:97], v[216:219], v[244:247], v[82:97]
	v_mfma_f32_32x32x16_bf16 v[66:81], v[216:219], v[248:251], v[66:81]
	v_mfma_f32_32x32x16_bf16 v[50:65], v[232:235], v[244:247], v[50:65]
	v_mfma_f32_32x32x16_bf16 v[34:49], v[232:235], v[248:251], v[34:49]
	v_mfma_f32_32x32x16_bf16 v[18:33], v[236:239], v[244:247], v[18:33]
	v_mfma_f32_32x32x16_bf16 v[2:17], v[236:239], v[248:251], v[2:17]
	s_add_u32 s56, s56, 0x80
	s_addc_u32 s57, s57, 0
	s_add_u32 s58, s58, 0x80
	s_addc_u32 s59, s59, 0
	s_barrier
	s_waitcnt vmcnt(7)
	ds_write_b128 v184, v[130:133]
	s_waitcnt vmcnt(6)
	ds_write_b128 v184, v[138:141] offset:4608
	s_waitcnt vmcnt(5)
	ds_write_b128 v184, v[142:145] offset:9216
	s_waitcnt vmcnt(4)
	ds_write_b128 v184, v[146:149] offset:13824
	s_waitcnt vmcnt(3)
	ds_write_b128 v184, v[150:153] offset:18432
	s_waitcnt vmcnt(2)
	ds_write_b128 v184, v[154:157] offset:23040
	s_waitcnt vmcnt(1)
	ds_write_b128 v184, v[158:161] offset:27648
	s_waitcnt vmcnt(0)
	ds_write_b128 v184, v[162:165] offset:32256
	s_waitcnt lgkmcnt(0)
	s_barrier
	ds_read_b128 v[186:189], v183
	ds_read_b128 v[204:207], v166 offset:53248
	ds_read_b128 v[208:211], v166 offset:57344
	ds_read_b128 v[190:193], v183 offset:4608
	ds_read_b128 v[196:199], v183 offset:9216
	ds_read_b128 v[200:203], v182
	ds_read_b128 v[212:215], v183 offset:32
	ds_read_b128 v[244:247], v167 offset:53248
	ds_read_b128 v[248:251], v167 offset:57344
	ds_read_b128 v[216:219], v183 offset:4640
	ds_read_b128 v[232:235], v183 offset:9248
	ds_read_b128 v[236:239], v182 offset:32
	s_waitcnt lgkmcnt(10)
	v_mfma_f32_32x32x16_bf16 v[114:129], v[186:189], v[204:207], v[114:129]
	s_add_u32 m0, s96, -128
	s_nop 0
	s_waitcnt lgkmcnt(9)
	v_mfma_f32_32x32x16_bf16 v[98:113], v[186:189], v[208:211], v[98:113]
	global_load_lds_dwordx4 v134, s[58:59] offset:128
	ds_read_b128 v[186:189], v183 offset:64
	s_waitcnt lgkmcnt(9)
	v_mfma_f32_32x32x16_bf16 v[82:97], v[190:193], v[204:207], v[82:97]
	global_load_lds_dwordx4 v135, s[58:59] offset:1152
	v_mfma_f32_32x32x16_bf16 v[66:81], v[190:193], v[208:211], v[66:81]
	global_load_lds_dwordx4 v136, s[58:59] offset:2176
	ds_read_b128 v[190:193], v183 offset:4672
	s_waitcnt lgkmcnt(9)
	v_mfma_f32_32x32x16_bf16 v[50:65], v[196:199], v[204:207], v[50:65]
	global_load_lds_dwordx4 v137, s[58:59] offset:3200
	v_mfma_f32_32x32x16_bf16 v[34:49], v[196:199], v[208:211], v[34:49]
	global_load_dwordx4 v[130:133], v178, s[56:57] offset:128
	ds_read_b128 v[196:199], v183 offset:9280
	s_waitcnt lgkmcnt(9)
	v_mfma_f32_32x32x16_bf16 v[18:33], v[200:203], v[204:207], v[18:33]
	global_load_dwordx4 v[138:141], v179, s[56:57] offset:128
	v_mfma_f32_32x32x16_bf16 v[2:17], v[200:203], v[208:211], v[2:17]
	global_load_dwordx4 v[142:145], v180, s[56:57] offset:128
	ds_read_b128 v[200:203], v182 offset:64
	ds_read_b128 v[204:207], v168 offset:53248
	ds_read_b128 v[208:211], v168 offset:57344
	s_waitcnt lgkmcnt(10)
	v_mfma_f32_32x32x16_bf16 v[114:129], v[212:215], v[244:247], v[114:129]
	global_load_dwordx4 v[146:149], v181, s[56:57] offset:128
	s_waitcnt lgkmcnt(9)
	v_mfma_f32_32x32x16_bf16 v[98:113], v[212:215], v[248:251], v[98:113]
	global_load_dwordx4 v[150:153], v185, s[56:57] offset:128
	ds_read_b128 v[212:215], v183 offset:96
	s_waitcnt lgkmcnt(9)
	v_mfma_f32_32x32x16_bf16 v[82:97], v[216:219], v[244:247], v[82:97]
	global_load_dwordx4 v[154:157], v222, s[56:57] offset:128
	v_mfma_f32_32x32x16_bf16 v[66:81], v[216:219], v[248:251], v[66:81]
	global_load_dwordx4 v[158:161], v223, s[56:57] offset:128
	ds_read_b128 v[216:219], v183 offset:4704
	s_waitcnt lgkmcnt(9)
	v_mfma_f32_32x32x16_bf16 v[50:65], v[232:235], v[244:247], v[50:65]
	global_load_dwordx4 v[162:165], v227, s[56:57] offset:128
	v_mfma_f32_32x32x16_bf16 v[34:49], v[232:235], v[248:251], v[34:49]
	ds_read_b128 v[232:235], v183 offset:9312
	s_waitcnt lgkmcnt(9)
	v_mfma_f32_32x32x16_bf16 v[18:33], v[236:239], v[244:247], v[18:33]
	v_mfma_f32_32x32x16_bf16 v[2:17], v[236:239], v[248:251], v[2:17]
	ds_read_b128 v[236:239], v182 offset:96
	ds_read_b128 v[244:247], v169 offset:53248
	ds_read_b128 v[248:251], v169 offset:57344
	s_waitcnt lgkmcnt(7)
; #define MFMA(a, b, c) __builtin_amdgcn_mfma_f32_32x32x16_bf16((a), (b), (c), 0, 0, 0)
; template <int MI, int NI>
; __device__ __forceinline__ void gemm_kloop(const bf16* __restrict__ A, size_t lda, const bf16* __restrict__ Bt, size_t ldb, int K,
;                                            f16v (&acc)[MI][NI], bf16* sA, bf16* sB) {
;     ...
;   for (int kt = 0; kt < KT; ++kt) {
;     __syncthreads();
; #pragma unroll
;     for (int i = 0; i < 2 * MI; ++i) *(u4v*)(sA + (lrow + 32 * i) * 72 + lseg * 8) = ra[i];
; #pragma unroll
;     for (int i = 0; i < 2 * NI; ++i) *(u4v*)(sB + (lrow + 32 * i) * 72 + lseg * 8) = rb[i];
;     __syncthreads();
;     if (kt + 3 < KT) {
;       const int k2 = (kt + 3) << 6;
;       if (tid < 64 * MI) pfs ^= *(const unsigned*)(A + (size_t)tid * lda + k2);
;       if (tid < 64 * NI) pfs ^= *(const unsigned*)(Bt + (size_t)tid * ldb + k2);
;     }
;     if (kt + 1 < KT) {
;       const int k0 = (kt + 1) << 6;
; #pragma unroll
;       for (int i = 0; i < 2 * MI; ++i) ra[i] = *(const u4v*)(A + (size_t)(lrow + 32 * i) * lda + k0 + lseg * 8);
; #pragma unroll
;       for (int i = 0; i < 2 * NI; ++i) rb[i] = *(const u4v*)(Bt + (size_t)(lrow + 32 * i) * ldb + k0 + lseg * 8);
;     }
; #pragma unroll
;     for (int ks = 0; ks < 4; ++ks) {
;       s8v a[MI], b[NI];
; #pragma unroll
;       for (int mi = 0; mi < MI; ++mi) a[mi] = *(const s8v*)(sA + (wm * 32 * MI + mi * 32 + r) * 72 + ks * 16 + hh * 8);
; #pragma unroll
;       for (int ni = 0; ni < NI; ++ni) b[ni] = *(const s8v*)(sB + (wn * 32 * NI + ni * 32 + r) * 72 + ks * 16 + hh * 8);
; #pragma unroll
;       for (int mi = 0; mi < MI; ++mi)
; #pragma unroll
;         for (int ni = 0; ni < NI; ++ni) acc[mi][ni] = MFMA(a[mi], b[ni], acc[mi][ni]);
;     }
;   }
	v_mfma_f32_32x32x16_bf16 v[114:129], v[186:189], v[204:207], v[114:129]
	s_waitcnt lgkmcnt(6)
	v_mfma_f32_32x32x16_bf16 v[98:113], v[186:189], v[208:211], v[98:113]
	v_mfma_f32_32x32x16_bf16 v[82:97], v[190:193], v[204:207], v[82:97]
	v_mfma_f32_32x32x16_bf16 v[66:81], v[190:193], v[208:211], v[66:81]
	v_mfma_f32_32x32x16_bf16 v[50:65], v[196:199], v[204:207], v[50:65]
	v_mfma_f32_32x32x16_bf16 v[34:49], v[196:199], v[208:211], v[34:49]
	v_mfma_f32_32x32x16_bf16 v[2:17], v[200:203], v[208:211], v[2:17]
	v_mfma_f32_32x32x16_bf16 v[18:33], v[200:203], v[204:207], v[18:33]
	s_waitcnt lgkmcnt(1)
	v_mfma_f32_32x32x16_bf16 v[114:129], v[212:215], v[244:247], v[114:129]
	s_waitcnt lgkmcnt(0)
	v_mfma_f32_32x32x16_bf16 v[98:113], v[212:215], v[248:251], v[98:113]
	v_mfma_f32_32x32x16_bf16 v[82:97], v[216:219], v[244:247], v[82:97]
	v_mfma_f32_32x32x16_bf16 v[66:81], v[216:219], v[248:251], v[66:81]
	v_mfma_f32_32x32x16_bf16 v[50:65], v[232:235], v[244:247], v[50:65]
	v_mfma_f32_32x32x16_bf16 v[34:49], v[232:235], v[248:251], v[34:49]
	v_mfma_f32_32x32x16_bf16 v[18:33], v[236:239], v[244:247], v[18:33]
	v_mfma_f32_32x32x16_bf16 v[2:17], v[236:239], v[248:251], v[2:17]
	s_add_u32 s56, s56, 0x80
	s_addc_u32 s57, s57, 0
	s_add_u32 s58, s58, 0x80
	s_addc_u32 s59, s59, 0
	s_movk_i32 s94, 6
.Lhyb_p8_loop:
	s_barrier
	s_waitcnt vmcnt(7)
	ds_write_b128 v184, v[130:133]
	s_waitcnt vmcnt(6)
	ds_write_b128 v184, v[138:141] offset:4608
	s_waitcnt vmcnt(5)
	ds_write_b128 v184, v[142:145] offset:9216
	s_waitcnt vmcnt(4)
	ds_write_b128 v184, v[146:149] offset:13824
	s_waitcnt vmcnt(3)
	ds_write_b128 v184, v[150:153] offset:18432
	s_waitcnt vmcnt(2)
	ds_write_b128 v184, v[154:157] offset:23040
	s_waitcnt vmcnt(1)
	ds_write_b128 v184, v[158:161] offset:27648
	s_waitcnt vmcnt(0)
	ds_write_b128 v184, v[162:165] offset:32256
	s_waitcnt lgkmcnt(0)
	s_barrier
	ds_read_b128 v[186:189], v183
	ds_read_b128 v[204:207], v166 offset:36864
	ds_read_b128 v[208:211], v166 offset:40960
	ds_read_b128 v[190:193], v183 offset:4608
	ds_read_b128 v[196:199], v183 offset:9216
	ds_read_b128 v[200:203], v182
	ds_read_b128 v[212:215], v183 offset:32
	ds_read_b128 v[244:247], v167 offset:36864
	ds_read_b128 v[248:251], v167 offset:40960
	ds_read_b128 v[216:219], v183 offset:4640
	ds_read_b128 v[232:235], v183 offset:9248
	ds_read_b128 v[236:239], v182 offset:32
	s_waitcnt lgkmcnt(10)
	v_mfma_f32_32x32x16_bf16 v[114:129], v[186:189], v[204:207], v[114:129]
	s_add_u32 m0, s96, 16256
	s_nop 0
	s_waitcnt lgkmcnt(9)
	v_mfma_f32_32x32x16_bf16 v[98:113], v[186:189], v[208:211], v[98:113]
	global_load_lds_dwordx4 v134, s[58:59] offset:128
	ds_read_b128 v[186:189], v183 offset:64
	s_waitcnt lgkmcnt(9)
	v_mfma_f32_32x32x16_bf16 v[82:97], v[190:193], v[204:207], v[82:97]
	global_load_lds_dwordx4 v135, s[58:59] offset:1152
	v_mfma_f32_32x32x16_bf16 v[66:81], v[190:193], v[208:211], v[66:81]
	global_load_lds_dwordx4 v136, s[58:59] offset:2176
	ds_read_b128 v[190:193], v183 offset:4672
	s_waitcnt lgkmcnt(9)
	v_mfma_f32_32x32x16_bf16 v[50:65], v[196:199], v[204:207], v[50:65]
	global_load_lds_dwordx4 v137, s[58:59] offset:3200
	v_mfma_f32_32x32x16_bf16 v[34:49], v[196:199], v[208:211], v[34:49]
	global_load_dwordx4 v[130:133], v178, s[56:57] offset:128
	ds_read_b128 v[196:199], v183 offset:9280
	s_waitcnt lgkmcnt(9)
	v_mfma_f32_32x32x16_bf16 v[18:33], v[200:203], v[204:207], v[18:33]
	global_load_dwordx4 v[138:141], v179, s[56:57] offset:128
	v_mfma_f32_32x32x16_bf16 v[2:17], v[200:203], v[208:211], v[2:17]
	global_load_dwordx4 v[142:145], v180, s[56:57] offset:128
	ds_read_b128 v[200:203], v182 offset:64
	ds_read_b128 v[204:207], v168 offset:36864
	ds_read_b128 v[208:211], v168 offset:40960
	s_waitcnt lgkmcnt(10)
	v_mfma_f32_32x32x16_bf16 v[114:129], v[212:215], v[244:247], v[114:129]
	global_load_dwordx4 v[146:149], v181, s[56:57] offset:128
	s_waitcnt lgkmcnt(9)
	v_mfma_f32_32x32x16_bf16 v[98:113], v[212:215], v[248:251], v[98:113]
	global_load_dwordx4 v[150:153], v185, s[56:57] offset:128
	ds_read_b128 v[212:215], v183 offset:96
	s_waitcnt lgkmcnt(9)
	v_mfma_f32_32x32x16_bf16 v[82:97], v[216:219], v[244:247], v[82:97]
	global_load_dwordx4 v[154:157], v222, s[56:57] offset:128
	v_mfma_f32_32x32x16_bf16 v[66:81], v[216:219], v[248:251], v[66:81]
	global_load_dwordx4 v[158:161], v223, s[56:57] offset:128
	ds_read_b128 v[216:219], v183 offset:4704
	s_waitcnt lgkmcnt(9)
	v_mfma_f32_32x32x16_bf16 v[50:65], v[232:235], v[244:247], v[50:65]
	global_load_dwordx4 v[162:165], v227, s[56:57] offset:128
	v_mfma_f32_32x32x16_bf16 v[34:49], v[232:235], v[248:251], v[34:49]
	ds_read_b128 v[232:235], v183 offset:9312
	s_waitcnt lgkmcnt(9)
	v_mfma_f32_32x32x16_bf16 v[18:33], v[236:239], v[244:247], v[18:33]
	v_mfma_f32_32x32x16_bf16 v[2:17], v[236:239], v[248:251], v[2:17]
	ds_read_b128 v[236:239], v182 offset:96
	ds_read_b128 v[244:247], v169 offset:36864
	ds_read_b128 v[248:251], v169 offset:40960
	s_waitcnt lgkmcnt(7)
	v_mfma_f32_32x32x16_bf16 v[114:129], v[186:189], v[204:207], v[114:129]
	s_waitcnt lgkmcnt(6)
	v_mfma_f32_32x32x16_bf16 v[98:113], v[186:189], v[208:211], v[98:113]
	v_mfma_f32_32x32x16_bf16 v[82:97], v[190:193], v[204:207], v[82:97]
	v_mfma_f32_32x32x16_bf16 v[66:81], v[190:193], v[208:211], v[66:81]
	v_mfma_f32_32x32x16_bf16 v[50:65], v[196:199], v[204:207], v[50:65]
	v_mfma_f32_32x32x16_bf16 v[34:49], v[196:199], v[208:211], v[34:49]
	v_mfma_f32_32x32x16_bf16 v[2:17], v[200:203], v[208:211], v[2:17]
	v_mfma_f32_32x32x16_bf16 v[18:33], v[200:203], v[204:207], v[18:33]
	s_waitcnt lgkmcnt(1)
	v_mfma_f32_32x32x16_bf16 v[114:129], v[212:215], v[244:247], v[114:129]
	s_waitcnt lgkmcnt(0)
	v_mfma_f32_32x32x16_bf16 v[98:113], v[212:215], v[248:251], v[98:113]
	v_mfma_f32_32x32x16_bf16 v[82:97], v[216:219], v[244:247], v[82:97]
	v_mfma_f32_32x32x16_bf16 v[66:81], v[216:219], v[248:251], v[66:81]
	v_mfma_f32_32x32x16_bf16 v[50:65], v[232:235], v[244:247], v[50:65]
	v_mfma_f32_32x32x16_bf16 v[34:49], v[232:235], v[248:251], v[34:49]
	v_mfma_f32_32x32x16_bf16 v[18:33], v[236:239], v[244:247], v[18:33]
	v_mfma_f32_32x32x16_bf16 v[2:17], v[236:239], v[248:251], v[2:17]
	s_add_u32 s56, s56, 0x80
	s_addc_u32 s57, s57, 0
	s_add_u32 s58, s58, 0x80
	s_addc_u32 s59, s59, 0
	s_barrier
; #define MFMA(a, b, c) __builtin_amdgcn_mfma_f32_32x32x16_bf16((a), (b), (c), 0, 0, 0)
; template <int MI, int NI>
; __device__ __forceinline__ void gemm_kloop(const bf16* __restrict__ A, size_t lda, const bf16* __restrict__ Bt, size_t ldb, int K,
;                                            f16v (&acc)[MI][NI], bf16* sA, bf16* sB) {
;     ...
;   for (int kt = 0; kt < KT; ++kt) {
;     __syncthreads();
; #pragma unroll
;     for (int i = 0; i < 2 * MI; ++i) *(u4v*)(sA + (lrow + 32 * i) * 72 + lseg * 8) = ra[i];
; #pragma unroll
;     for (int i = 0; i < 2 * NI; ++i) *(u4v*)(sB + (lrow + 32 * i) * 72 + lseg * 8) = rb[i];
;     __syncthreads();
;     if (kt + 3 < KT) {
;       const int k2 = (kt + 3) << 6;
;       if (tid < 64 * MI) pfs ^= *(const unsigned*)(A + (size_t)tid * lda + k2);
;       if (tid < 64 * NI) pfs ^= *(const unsigned*)(Bt + (size_t)tid * ldb + k2);
;     }
;     if (kt + 1 < KT) {
;       const int k0 = (kt + 1) << 6;
; #pragma unroll
;       for (int i = 0; i < 2 * MI; ++i) ra[i] = *(const u4v*)(A + (size_t)(lrow + 32 * i) * lda + k0 + lseg * 8);
; #pragma unroll
;       for (int i = 0; i < 2 * NI; ++i) rb[i] = *(const u4v*)(Bt + (size_t)(lrow + 32 * i) * ldb + k0 + lseg * 8);
;     }
; #pragma unroll
;     for (int ks = 0; ks < 4; ++ks) {
;       s8v a[MI], b[NI];
; #pragma unroll
;       for (int mi = 0; mi < MI; ++mi) a[mi] = *(const s8v*)(sA + (wm * 32 * MI + mi * 32 + r) * 72 + ks * 16 + hh * 8);
; #pragma unroll
;       for (int ni = 0; ni < NI; ++ni) b[ni] = *(const s8v*)(sB + (wn * 32 * NI + ni * 32 + r) * 72 + ks * 16 + hh * 8);
; #pragma unroll
;       for (int mi = 0; mi < MI; ++mi)
; #pragma unroll
;         for (int ni = 0; ni < NI; ++ni) acc[mi][ni] = MFMA(a[mi], b[ni], acc[mi][ni]);
;     }
;   }
	s_waitcnt vmcnt(7)
	ds_write_b128 v184, v[130:133]
	s_waitcnt vmcnt(6)
	ds_write_b128 v184, v[138:141] offset:4608
	s_waitcnt vmcnt(5)
	ds_write_b128 v184, v[142:145] offset:9216
	s_waitcnt vmcnt(4)
	ds_write_b128 v184, v[146:149] offset:13824
	s_waitcnt vmcnt(3)
	ds_write_b128 v184, v[150:153] offset:18432
	s_waitcnt vmcnt(2)
	ds_write_b128 v184, v[154:157] offset:23040
	s_waitcnt vmcnt(1)
	ds_write_b128 v184, v[158:161] offset:27648
	s_waitcnt vmcnt(0)
	ds_write_b128 v184, v[162:165] offset:32256
	s_waitcnt lgkmcnt(0)
	s_barrier
	ds_read_b128 v[186:189], v183
	ds_read_b128 v[204:207], v166 offset:53248
	ds_read_b128 v[208:211], v166 offset:57344
	ds_read_b128 v[190:193], v183 offset:4608
	ds_read_b128 v[196:199], v183 offset:9216
	ds_read_b128 v[200:203], v182
	ds_read_b128 v[212:215], v183 offset:32
	ds_read_b128 v[244:247], v167 offset:53248
	ds_read_b128 v[248:251], v167 offset:57344
	ds_read_b128 v[216:219], v183 offset:4640
	ds_read_b128 v[232:235], v183 offset:9248
	ds_read_b128 v[236:239], v182 offset:32
	s_waitcnt lgkmcnt(10)
	v_mfma_f32_32x32x16_bf16 v[114:129], v[186:189], v[204:207], v[114:129]
	s_add_u32 m0, s96, -128
	s_nop 0
	s_waitcnt lgkmcnt(9)
	v_mfma_f32_32x32x16_bf16 v[98:113], v[186:189], v[208:211], v[98:113]
	global_load_lds_dwordx4 v134, s[58:59] offset:128
	ds_read_b128 v[186:189], v183 offset:64
	s_waitcnt lgkmcnt(9)
	v_mfma_f32_32x32x16_bf16 v[82:97], v[190:193], v[204:207], v[82:97]
	global_load_lds_dwordx4 v135, s[58:59] offset:1152
	v_mfma_f32_32x32x16_bf16 v[66:81], v[190:193], v[208:211], v[66:81]
	global_load_lds_dwordx4 v136, s[58:59] offset:2176
	ds_read_b128 v[190:193], v183 offset:4672
	s_waitcnt lgkmcnt(9)
	v_mfma_f32_32x32x16_bf16 v[50:65], v[196:199], v[204:207], v[50:65]
	global_load_lds_dwordx4 v137, s[58:59] offset:3200
	v_mfma_f32_32x32x16_bf16 v[34:49], v[196:199], v[208:211], v[34:49]
	global_load_dwordx4 v[130:133], v178, s[56:57] offset:128
	ds_read_b128 v[196:199], v183 offset:9280
	s_waitcnt lgkmcnt(9)
	v_mfma_f32_32x32x16_bf16 v[18:33], v[200:203], v[204:207], v[18:33]
	global_load_dwordx4 v[138:141], v179, s[56:57] offset:128
	v_mfma_f32_32x32x16_bf16 v[2:17], v[200:203], v[208:211], v[2:17]
	global_load_dwordx4 v[142:145], v180, s[56:57] offset:128
	ds_read_b128 v[200:203], v182 offset:64
	ds_read_b128 v[204:207], v168 offset:53248
	ds_read_b128 v[208:211], v168 offset:57344
	s_waitcnt lgkmcnt(10)
	v_mfma_f32_32x32x16_bf16 v[114:129], v[212:215], v[244:247], v[114:129]
	global_load_dwordx4 v[146:149], v181, s[56:57] offset:128
	s_waitcnt lgkmcnt(9)
	v_mfma_f32_32x32x16_bf16 v[98:113], v[212:215], v[248:251], v[98:113]
	global_load_dwordx4 v[150:153], v185, s[56:57] offset:128
	ds_read_b128 v[212:215], v183 offset:96
	s_waitcnt lgkmcnt(9)
	v_mfma_f32_32x32x16_bf16 v[82:97], v[216:219], v[244:247], v[82:97]
	global_load_dwordx4 v[154:157], v222, s[56:57] offset:128
	v_mfma_f32_32x32x16_bf16 v[66:81], v[216:219], v[248:251], v[66:81]
	global_load_dwordx4 v[158:161], v223, s[56:57] offset:128
	ds_read_b128 v[216:219], v183 offset:4704
	s_waitcnt lgkmcnt(9)
	v_mfma_f32_32x32x16_bf16 v[50:65], v[232:235], v[244:247], v[50:65]
	global_load_dwordx4 v[162:165], v227, s[56:57] offset:128
	v_mfma_f32_32x32x16_bf16 v[34:49], v[232:235], v[248:251], v[34:49]
	ds_read_b128 v[232:235], v183 offset:9312
	s_waitcnt lgkmcnt(9)
	v_mfma_f32_32x32x16_bf16 v[18:33], v[236:239], v[244:247], v[18:33]
	v_mfma_f32_32x32x16_bf16 v[2:17], v[236:239], v[248:251], v[2:17]
	ds_read_b128 v[236:239], v182 offset:96
	ds_read_b128 v[244:247], v169 offset:53248
	ds_read_b128 v[248:251], v169 offset:57344
	s_waitcnt lgkmcnt(7)
	v_mfma_f32_32x32x16_bf16 v[114:129], v[186:189], v[204:207], v[114:129]
	s_waitcnt lgkmcnt(6)
	v_mfma_f32_32x32x16_bf16 v[98:113], v[186:189], v[208:211], v[98:113]
	v_mfma_f32_32x32x16_bf16 v[82:97], v[190:193], v[204:207], v[82:97]
	v_mfma_f32_32x32x16_bf16 v[66:81], v[190:193], v[208:211], v[66:81]
	v_mfma_f32_32x32x16_bf16 v[50:65], v[196:199], v[204:207], v[50:65]
	v_mfma_f32_32x32x16_bf16 v[34:49], v[196:199], v[208:211], v[34:49]
	v_mfma_f32_32x32x16_bf16 v[2:17], v[200:203], v[208:211], v[2:17]
	v_mfma_f32_32x32x16_bf16 v[18:33], v[200:203], v[204:207], v[18:33]
	s_waitcnt lgkmcnt(1)
	v_mfma_f32_32x32x16_bf16 v[114:129], v[212:215], v[244:247], v[114:129]
	s_waitcnt lgkmcnt(0)
	v_mfma_f32_32x32x16_bf16 v[98:113], v[212:215], v[248:251], v[98:113]
	v_mfma_f32_32x32x16_bf16 v[82:97], v[216:219], v[244:247], v[82:97]
	v_mfma_f32_32x32x16_bf16 v[66:81], v[216:219], v[248:251], v[66:81]
	v_mfma_f32_32x32x16_bf16 v[50:65], v[232:235], v[244:247], v[50:65]
	v_mfma_f32_32x32x16_bf16 v[34:49], v[232:235], v[248:251], v[34:49]
	v_mfma_f32_32x32x16_bf16 v[18:33], v[236:239], v[244:247], v[18:33]
	v_mfma_f32_32x32x16_bf16 v[2:17], v[236:239], v[248:251], v[2:17]
	s_add_u32 s56, s56, 0x80
	s_addc_u32 s57, s57, 0
	s_add_u32 s58, s58, 0x80
	s_addc_u32 s59, s59, 0
	s_sub_u32 s94, s94, 1
	s_cmp_lg_u32 s94, 0
	s_cbranch_scc1 .Lhyb_p8_loop
	s_barrier
	s_waitcnt vmcnt(7)
	ds_write_b128 v184, v[130:133]
	s_waitcnt vmcnt(6)
	ds_write_b128 v184, v[138:141] offset:4608
	s_waitcnt vmcnt(5)
	ds_write_b128 v184, v[142:145] offset:9216
	s_waitcnt vmcnt(4)
	ds_write_b128 v184, v[146:149] offset:13824
	s_waitcnt vmcnt(3)
	ds_write_b128 v184, v[150:153] offset:18432
	s_waitcnt vmcnt(2)
	ds_write_b128 v184, v[154:157] offset:23040
	s_waitcnt vmcnt(1)
	ds_write_b128 v184, v[158:161] offset:27648
	s_waitcnt vmcnt(0)
	ds_write_b128 v184, v[162:165] offset:32256
	s_waitcnt lgkmcnt(0)
	s_barrier
; #define MFMA(a, b, c) __builtin_amdgcn_mfma_f32_32x32x16_bf16((a), (b), (c), 0, 0, 0)
; template <int MI, int NI>
; __device__ __forceinline__ void gemm_kloop(const bf16* __restrict__ A, size_t lda, const bf16* __restrict__ Bt, size_t ldb, int K,
;                                            f16v (&acc)[MI][NI], bf16* sA, bf16* sB) {
;     ...
;   for (int kt = 0; kt < KT; ++kt) {
;     __syncthreads();
; #pragma unroll
;     for (int i = 0; i < 2 * MI; ++i) *(u4v*)(sA + (lrow + 32 * i) * 72 + lseg * 8) = ra[i];
; #pragma unroll
;     for (int i = 0; i < 2 * NI; ++i) *(u4v*)(sB + (lrow + 32 * i) * 72 + lseg * 8) = rb[i];
;     __syncthreads();
;     if (kt + 3 < KT) {
;       const int k2 = (kt + 3) << 6;
;       if (tid < 64 * MI) pfs ^= *(const unsigned*)(A + (size_t)tid * lda + k2);
;       if (tid < 64 * NI) pfs ^= *(const unsigned*)(Bt + (size_t)tid * ldb + k2);
;     }
;     if (kt + 1 < KT) {
;       const int k0 = (kt + 1) << 6;
; #pragma unroll
;       for (int i = 0; i < 2 * MI; ++i) ra[i] = *(const u4v*)(A + (size_t)(lrow + 32 * i) * lda + k0 + lseg * 8);
; #pragma unroll
;       for (int i = 0; i < 2 * NI; ++i) rb[i] = *(const u4v*)(Bt + (size_t)(lrow + 32 * i) * ldb + k0 + lseg * 8);
;     }
; #pragma unroll
;     for (int ks = 0; ks < 4; ++ks) {
;       s8v a[MI], b[NI];
; #pragma unroll
;       for (int mi = 0; mi < MI; ++mi) a[mi] = *(const s8v*)(sA + (wm * 32 * MI + mi * 32 + r) * 72 + ks * 16 + hh * 8);
; #pragma unroll
;       for (int ni = 0; ni < NI; ++ni) b[ni] = *(const s8v*)(sB + (wn * 32 * NI + ni * 32 + r) * 72 + ks * 16 + hh * 8);
; #pragma unroll
;       for (int mi = 0; mi < MI; ++mi)
; #pragma unroll
;         for (int ni = 0; ni < NI; ++ni) acc[mi][ni] = MFMA(a[mi], b[ni], acc[mi][ni]);
;     }
;   }
	ds_read_b128 v[186:189], v183
	ds_read_b128 v[204:207], v166 offset:36864
	ds_read_b128 v[208:211], v166 offset:40960
	ds_read_b128 v[190:193], v183 offset:4608
	ds_read_b128 v[196:199], v183 offset:9216
	ds_read_b128 v[200:203], v182
	ds_read_b128 v[212:215], v183 offset:32
	ds_read_b128 v[244:247], v167 offset:36864
	ds_read_b128 v[248:251], v167 offset:40960
	ds_read_b128 v[216:219], v183 offset:4640
	ds_read_b128 v[232:235], v183 offset:9248
	ds_read_b128 v[236:239], v182 offset:32
	s_waitcnt lgkmcnt(10)
	v_mfma_f32_32x32x16_bf16 v[114:129], v[186:189], v[204:207], v[114:129]
	s_add_u32 m0, s96, 16256
	s_nop 0
	s_waitcnt lgkmcnt(9)
	v_mfma_f32_32x32x16_bf16 v[98:113], v[186:189], v[208:211], v[98:113]
	global_load_lds_dwordx4 v134, s[58:59] offset:128
	ds_read_b128 v[186:189], v183 offset:64
	s_waitcnt lgkmcnt(9)
	v_mfma_f32_32x32x16_bf16 v[82:97], v[190:193], v[204:207], v[82:97]
	global_load_lds_dwordx4 v135, s[58:59] offset:1152
	v_mfma_f32_32x32x16_bf16 v[66:81], v[190:193], v[208:211], v[66:81]
	global_load_lds_dwordx4 v136, s[58:59] offset:2176
	ds_read_b128 v[190:193], v183 offset:4672
	s_waitcnt lgkmcnt(9)
	v_mfma_f32_32x32x16_bf16 v[50:65], v[196:199], v[204:207], v[50:65]
	global_load_lds_dwordx4 v137, s[58:59] offset:3200
	v_mfma_f32_32x32x16_bf16 v[34:49], v[196:199], v[208:211], v[34:49]
	global_load_dwordx4 v[130:133], v178, s[56:57] offset:128
	ds_read_b128 v[196:199], v183 offset:9280
	s_waitcnt lgkmcnt(9)
	v_mfma_f32_32x32x16_bf16 v[18:33], v[200:203], v[204:207], v[18:33]
	global_load_dwordx4 v[138:141], v179, s[56:57] offset:128
	v_mfma_f32_32x32x16_bf16 v[2:17], v[200:203], v[208:211], v[2:17]
	global_load_dwordx4 v[142:145], v180, s[56:57] offset:128
	ds_read_b128 v[200:203], v182 offset:64
	ds_read_b128 v[204:207], v168 offset:36864
	ds_read_b128 v[208:211], v168 offset:40960
	s_waitcnt lgkmcnt(10)
	v_mfma_f32_32x32x16_bf16 v[114:129], v[212:215], v[244:247], v[114:129]
	global_load_dwordx4 v[146:149], v181, s[56:57] offset:128
	s_waitcnt lgkmcnt(9)
	v_mfma_f32_32x32x16_bf16 v[98:113], v[212:215], v[248:251], v[98:113]
	global_load_dwordx4 v[150:153], v185, s[56:57] offset:128
	ds_read_b128 v[212:215], v183 offset:96
	s_waitcnt lgkmcnt(9)
	v_mfma_f32_32x32x16_bf16 v[82:97], v[216:219], v[244:247], v[82:97]
	global_load_dwordx4 v[154:157], v222, s[56:57] offset:128
	v_mfma_f32_32x32x16_bf16 v[66:81], v[216:219], v[248:251], v[66:81]
	global_load_dwordx4 v[158:161], v223, s[56:57] offset:128
	ds_read_b128 v[216:219], v183 offset:4704
	s_waitcnt lgkmcnt(9)
	v_mfma_f32_32x32x16_bf16 v[50:65], v[232:235], v[244:247], v[50:65]
	global_load_dwordx4 v[162:165], v227, s[56:57] offset:128
	v_mfma_f32_32x32x16_bf16 v[34:49], v[232:235], v[248:251], v[34:49]
	ds_read_b128 v[232:235], v183 offset:9312
	s_waitcnt lgkmcnt(9)
	v_mfma_f32_32x32x16_bf16 v[18:33], v[236:239], v[244:247], v[18:33]
	v_mfma_f32_32x32x16_bf16 v[2:17], v[236:239], v[248:251], v[2:17]
	ds_read_b128 v[236:239], v182 offset:96
	ds_read_b128 v[244:247], v169 offset:36864
	ds_read_b128 v[248:251], v169 offset:40960
	s_waitcnt lgkmcnt(7)
	v_mfma_f32_32x32x16_bf16 v[114:129], v[186:189], v[204:207], v[114:129]
	s_waitcnt lgkmcnt(6)
	v_mfma_f32_32x32x16_bf16 v[98:113], v[186:189], v[208:211], v[98:113]
	v_mfma_f32_32x32x16_bf16 v[82:97], v[190:193], v[204:207], v[82:97]
	v_mfma_f32_32x32x16_bf16 v[66:81], v[190:193], v[208:211], v[66:81]
	v_mfma_f32_32x32x16_bf16 v[50:65], v[196:199], v[204:207], v[50:65]
	v_mfma_f32_32x32x16_bf16 v[34:49], v[196:199], v[208:211], v[34:49]
	v_mfma_f32_32x32x16_bf16 v[2:17], v[200:203], v[208:211], v[2:17]
	v_mfma_f32_32x32x16_bf16 v[18:33], v[200:203], v[204:207], v[18:33]
	s_waitcnt lgkmcnt(1)
	v_mfma_f32_32x32x16_bf16 v[114:129], v[212:215], v[244:247], v[114:129]
	s_waitcnt lgkmcnt(0)
	v_mfma_f32_32x32x16_bf16 v[98:113], v[212:215], v[248:251], v[98:113]
	v_mfma_f32_32x32x16_bf16 v[82:97], v[216:219], v[244:247], v[82:97]
	v_mfma_f32_32x32x16_bf16 v[66:81], v[216:219], v[248:251], v[66:81]
	v_mfma_f32_32x32x16_bf16 v[50:65], v[232:235], v[244:247], v[50:65]
	v_mfma_f32_32x32x16_bf16 v[34:49], v[232:235], v[248:251], v[34:49]
	v_mfma_f32_32x32x16_bf16 v[18:33], v[236:239], v[244:247], v[18:33]
	v_mfma_f32_32x32x16_bf16 v[2:17], v[236:239], v[248:251], v[2:17]
	s_add_u32 s56, s56, 0x80
	s_addc_u32 s57, s57, 0
	s_add_u32 s58, s58, 0x80
	s_addc_u32 s59, s59, 0
	s_barrier
	s_waitcnt vmcnt(7)
	ds_write_b128 v184, v[130:133]
	s_waitcnt vmcnt(6)
	ds_write_b128 v184, v[138:141] offset:4608
	s_waitcnt vmcnt(5)
	ds_write_b128 v184, v[142:145] offset:9216
	s_waitcnt vmcnt(4)
	ds_write_b128 v184, v[146:149] offset:13824
	s_waitcnt vmcnt(3)
	ds_write_b128 v184, v[150:153] offset:18432
	s_waitcnt vmcnt(2)
	ds_write_b128 v184, v[154:157] offset:23040
	s_waitcnt vmcnt(1)
	ds_write_b128 v184, v[158:161] offset:27648
	s_waitcnt vmcnt(0)
	ds_write_b128 v184, v[162:165] offset:32256
	s_waitcnt lgkmcnt(0)
	s_barrier
; #define MFMA(a, b, c) __builtin_amdgcn_mfma_f32_32x32x16_bf16((a), (b), (c), 0, 0, 0)
; __device__ __forceinline__ int tid_opaque() { int t = threadIdx.x; asm volatile("" : "+v"(t)); return t; }
; __device__ __forceinline__ float siluf_(float x) { return x * __builtin_amdgcn_rcpf(1.f + fexp(-x)); }
; template <int MI, int NI>
; __device__ __forceinline__ void gemm_kloop(const bf16* __restrict__ A, size_t lda, const bf16* __restrict__ Bt, size_t ldb, int K,
;                                            f16v (&acc)[MI][NI], bf16* sA, bf16* sB) {
;     ...
;     for (int ks = 0; ks < 4; ++ks) {
;       s8v a[MI], b[NI];
; #pragma unroll
;       for (int mi = 0; mi < MI; ++mi) a[mi] = *(const s8v*)(sA + (wm * 32 * MI + mi * 32 + r) * 72 + ks * 16 + hh * 8);
; #pragma unroll
;       for (int ni = 0; ni < NI; ++ni) b[ni] = *(const s8v*)(sB + (wn * 32 * NI + ni * 32 + r) * 72 + ks * 16 + hh * 8);
; #pragma unroll
;       for (int mi = 0; mi < MI; ++mi)
; #pragma unroll
;         for (int ni = 0; ni < NI; ++ni) acc[mi][ni] = MFMA(a[mi], b[ni], acc[mi][ni]);
; __device__ __forceinline__ void ffn1_tile(const Params& p, int mt, int nt, bf16* sA, bf16* sB) {
;     ...
;   const int lane = tid_opaque() & 63, w = tid_opaque() >> 6, r = lane & 31, hh = lane >> 5, wm = w >> 1, wn = w & 1;
; #pragma unroll
;   for (int mi = 0; mi < 4; ++mi)
; #pragma unroll
;     for (int e = 0; e < 16; ++e) {
;       const int t = m0 + wm * 128 + mi * 32 + ROW_OF(e, hh);
;       const float v = siluf_(acc[mi][0][e]) * acc[mi][1][e];
;       p.act[(size_t)t * 2816 + nt * 64 + wn * 32 + r] = f2bf(v);
;     }
	ds_read_b128 v[186:189], v183
	ds_read_b128 v[204:207], v166 offset:53248
	ds_read_b128 v[208:211], v166 offset:57344
	ds_read_b128 v[190:193], v183 offset:4608
	ds_read_b128 v[196:199], v183 offset:9216
	ds_read_b128 v[200:203], v182
	ds_read_b128 v[212:215], v183 offset:32
	ds_read_b128 v[244:247], v167 offset:53248
	ds_read_b128 v[248:251], v167 offset:57344
	ds_read_b128 v[216:219], v183 offset:4640
	ds_read_b128 v[232:235], v183 offset:9248
	ds_read_b128 v[236:239], v182 offset:32
	s_waitcnt lgkmcnt(10)
	v_mfma_f32_32x32x16_bf16 v[114:129], v[186:189], v[204:207], v[114:129]
	s_waitcnt lgkmcnt(9)
	v_mfma_f32_32x32x16_bf16 v[98:113], v[186:189], v[208:211], v[98:113]
	ds_read_b128 v[186:189], v183 offset:64
	s_waitcnt lgkmcnt(9)
	v_mfma_f32_32x32x16_bf16 v[82:97], v[190:193], v[204:207], v[82:97]
	v_mfma_f32_32x32x16_bf16 v[66:81], v[190:193], v[208:211], v[66:81]
	ds_read_b128 v[190:193], v183 offset:4672
	s_waitcnt lgkmcnt(9)
	v_mfma_f32_32x32x16_bf16 v[50:65], v[196:199], v[204:207], v[50:65]
	v_mfma_f32_32x32x16_bf16 v[34:49], v[196:199], v[208:211], v[34:49]
	ds_read_b128 v[196:199], v183 offset:9280
	s_waitcnt lgkmcnt(9)
	v_mfma_f32_32x32x16_bf16 v[18:33], v[200:203], v[204:207], v[18:33]
	v_mfma_f32_32x32x16_bf16 v[2:17], v[200:203], v[208:211], v[2:17]
	ds_read_b128 v[200:203], v182 offset:64
	ds_read_b128 v[204:207], v168 offset:53248
	ds_read_b128 v[208:211], v168 offset:57344
	s_waitcnt lgkmcnt(10)
	v_mfma_f32_32x32x16_bf16 v[114:129], v[212:215], v[244:247], v[114:129]
	s_waitcnt lgkmcnt(9)
	v_mfma_f32_32x32x16_bf16 v[98:113], v[212:215], v[248:251], v[98:113]
	ds_read_b128 v[212:215], v183 offset:96
	s_waitcnt lgkmcnt(9)
	v_mfma_f32_32x32x16_bf16 v[82:97], v[216:219], v[244:247], v[82:97]
	v_mfma_f32_32x32x16_bf16 v[66:81], v[216:219], v[248:251], v[66:81]
	ds_read_b128 v[216:219], v183 offset:4704
	s_waitcnt lgkmcnt(9)
	v_mfma_f32_32x32x16_bf16 v[50:65], v[232:235], v[244:247], v[50:65]
	v_mfma_f32_32x32x16_bf16 v[34:49], v[232:235], v[248:251], v[34:49]
	ds_read_b128 v[232:235], v183 offset:9312
	s_waitcnt lgkmcnt(9)
	v_mfma_f32_32x32x16_bf16 v[18:33], v[236:239], v[244:247], v[18:33]
	v_mfma_f32_32x32x16_bf16 v[2:17], v[236:239], v[248:251], v[2:17]
	ds_read_b128 v[236:239], v182 offset:96
	ds_read_b128 v[244:247], v169 offset:53248
	ds_read_b128 v[248:251], v169 offset:57344
	s_waitcnt lgkmcnt(7)
	v_mfma_f32_32x32x16_bf16 v[114:129], v[186:189], v[204:207], v[114:129]
	s_waitcnt lgkmcnt(6)
	v_mfma_f32_32x32x16_bf16 v[98:113], v[186:189], v[208:211], v[98:113]
	v_mfma_f32_32x32x16_bf16 v[82:97], v[190:193], v[204:207], v[82:97]
	v_mfma_f32_32x32x16_bf16 v[66:81], v[190:193], v[208:211], v[66:81]
	v_mfma_f32_32x32x16_bf16 v[50:65], v[196:199], v[204:207], v[50:65]
	v_mfma_f32_32x32x16_bf16 v[34:49], v[196:199], v[208:211], v[34:49]
	v_mfma_f32_32x32x16_bf16 v[2:17], v[200:203], v[208:211], v[2:17]
	v_mfma_f32_32x32x16_bf16 v[18:33], v[200:203], v[204:207], v[18:33]
	s_waitcnt lgkmcnt(1)
	v_mfma_f32_32x32x16_bf16 v[114:129], v[212:215], v[244:247], v[114:129]
	s_waitcnt lgkmcnt(0)
	v_mfma_f32_32x32x16_bf16 v[98:113], v[212:215], v[248:251], v[98:113]
	v_mfma_f32_32x32x16_bf16 v[82:97], v[216:219], v[244:247], v[82:97]
	v_mfma_f32_32x32x16_bf16 v[66:81], v[216:219], v[248:251], v[66:81]
	v_mfma_f32_32x32x16_bf16 v[50:65], v[232:235], v[244:247], v[50:65]
	v_mfma_f32_32x32x16_bf16 v[34:49], v[232:235], v[248:251], v[34:49]
	v_mfma_f32_32x32x16_bf16 v[18:33], v[236:239], v[244:247], v[18:33]
	v_mfma_f32_32x32x16_bf16 v[2:17], v[236:239], v[248:251], v[2:17]
	s_nop 15
	s_lshl_b32 s2, s2, 6
	s_ashr_i32 s3, s2, 31
	s_lshl_b64 s[2:3], s[2:3], 1
	v_mov_b32_e32 v0, v195
	v_mov_b32_e32 v130, v195
	v_and_b32_e32 v133, 31, v0
	v_and_b32_e32 v131, 0xffffff80, v130
	v_add_u32_e32 v131, s20, v131
	v_readlane_b32 s20, v254, 12
	v_lshrrev_b32_e32 v0, 3, v0
	v_readlane_b32 s21, v254, 13
	s_add_u32 s2, s20, s2
	v_and_or_b32 v132, v0, 4, v131
	s_addc_u32 s3, s21, s3
	v_and_b32_e32 v0, 64, v130
	v_lshl_add_u64 v[130:131], s[2:3], 0, v[0:1]
	v_lshlrev_b32_e32 v0, 1, v133
	v_lshl_add_u64 v[130:131], v[130:131], 0, v[0:1]
	v_mul_f32_e32 v0, 0xbfb8aa3b, v114
	v_exp_f32_e32 v0, v0
	s_movk_i32 s20, 0x1600
	v_readlane_b32 s22, v254, 14
	v_add_f32_e32 v0, 1.0, v0
	v_rcp_f32_e32 v0, v0
	v_readlane_b32 s23, v254, 15
	v_mul_f32_e32 v0, v114, v0
	v_mul_f32_e32 v0, v98, v0
	v_mul_f32_e32 v98, 0xbfb8aa3b, v115
	v_exp_f32_e32 v98, v98
	v_cvt_pk_bf16_f32 v0, v0, s0
	v_mad_i64_i32 v[134:135], s[2:3], v132, s20, v[130:131]
	v_add_f32_e32 v98, 1.0, v98
	v_rcp_f32_e32 v98, v98
	global_store_short v[134:135], v0, off
	v_or_b32_e32 v0, 1, v132
	v_mul_f32_e32 v98, v115, v98
	v_mul_f32_e32 v98, v99, v98
	v_cvt_pk_bf16_f32 v114, v98, s0
	v_mad_i64_i32 v[98:99], s[2:3], v0, s20, v[130:131]
	global_store_short v[98:99], v114, off
	v_mul_f32_e32 v98, 0xbfb8aa3b, v116
	v_exp_f32_e32 v98, v98
	v_or_b32_e32 v0, 2, v132
	v_add_f32_e32 v98, 1.0, v98
	v_rcp_f32_e32 v98, v98
	s_nop 0
	v_mul_f32_e32 v98, v116, v98
	v_mul_f32_e32 v98, v100, v98
	v_cvt_pk_bf16_f32 v100, v98, s0
	v_mad_i64_i32 v[98:99], s[2:3], v0, s20, v[130:131]
	global_store_short v[98:99], v100, off
	v_mul_f32_e32 v98, 0xbfb8aa3b, v117
	v_exp_f32_e32 v98, v98
	v_or_b32_e32 v0, 3, v132
	v_add_f32_e32 v98, 1.0, v98
	v_rcp_f32_e32 v98, v98
	s_nop 0
	v_mul_f32_e32 v98, v117, v98
	v_mul_f32_e32 v98, v101, v98
	v_cvt_pk_bf16_f32 v100, v98, s0
	v_mad_i64_i32 v[98:99], s[2:3], v0, s20, v[130:131]
	global_store_short v[98:99], v100, off
	v_mul_f32_e32 v98, 0xbfb8aa3b, v118
	v_exp_f32_e32 v98, v98
	v_or_b32_e32 v0, 8, v132
	v_add_f32_e32 v98, 1.0, v98
	v_rcp_f32_e32 v98, v98
	s_nop 0
	v_mul_f32_e32 v98, v118, v98
; __device__ __forceinline__ float siluf_(float x) { return x * __builtin_amdgcn_rcpf(1.f + fexp(-x)); }
; __device__ __forceinline__ void ffn1_tile(const Params& p, int mt, int nt, bf16* sA, bf16* sB) {
;     ...
; #pragma unroll
;   for (int mi = 0; mi < 4; ++mi)
; #pragma unroll
;     for (int e = 0; e < 16; ++e) {
;       const int t = m0 + wm * 128 + mi * 32 + ROW_OF(e, hh);
;       const float v = siluf_(acc[mi][0][e]) * acc[mi][1][e];
;       p.act[(size_t)t * 2816 + nt * 64 + wn * 32 + r] = f2bf(v);
;     }
	v_mul_f32_e32 v98, v102, v98
	v_cvt_pk_bf16_f32 v100, v98, s0
	v_mad_i64_i32 v[98:99], s[2:3], v0, s20, v[130:131]
	global_store_short v[98:99], v100, off
	v_mul_f32_e32 v98, 0xbfb8aa3b, v119
	v_exp_f32_e32 v98, v98
	v_or_b32_e32 v0, 9, v132
	v_add_f32_e32 v98, 1.0, v98
	v_rcp_f32_e32 v98, v98
	s_nop 0
	v_mul_f32_e32 v98, v119, v98
	v_mul_f32_e32 v98, v103, v98
	v_cvt_pk_bf16_f32 v100, v98, s0
	v_mad_i64_i32 v[98:99], s[2:3], v0, s20, v[130:131]
	global_store_short v[98:99], v100, off
	v_mul_f32_e32 v98, 0xbfb8aa3b, v120
	v_exp_f32_e32 v98, v98
	v_or_b32_e32 v0, 10, v132
	v_add_f32_e32 v98, 1.0, v98
	v_rcp_f32_e32 v98, v98
	s_nop 0
	v_mul_f32_e32 v98, v120, v98
	v_mul_f32_e32 v98, v104, v98
	v_cvt_pk_bf16_f32 v100, v98, s0
	v_mad_i64_i32 v[98:99], s[2:3], v0, s20, v[130:131]
	global_store_short v[98:99], v100, off
	v_mul_f32_e32 v98, 0xbfb8aa3b, v121
	v_exp_f32_e32 v98, v98
	v_or_b32_e32 v0, 11, v132
	v_add_f32_e32 v98, 1.0, v98
	v_rcp_f32_e32 v98, v98
	s_nop 0
	v_mul_f32_e32 v98, v121, v98
	v_mul_f32_e32 v98, v105, v98
	v_cvt_pk_bf16_f32 v100, v98, s0
	v_mad_i64_i32 v[98:99], s[2:3], v0, s20, v[130:131]
	global_store_short v[98:99], v100, off
	v_mul_f32_e32 v98, 0xbfb8aa3b, v122
	v_exp_f32_e32 v98, v98
	v_or_b32_e32 v0, 16, v132
	v_add_f32_e32 v98, 1.0, v98
	v_rcp_f32_e32 v98, v98
	s_nop 0
	v_mul_f32_e32 v98, v122, v98
	v_mul_f32_e32 v98, v106, v98
	v_cvt_pk_bf16_f32 v100, v98, s0
	v_mad_i64_i32 v[98:99], s[2:3], v0, s20, v[130:131]
	global_store_short v[98:99], v100, off
	v_mul_f32_e32 v98, 0xbfb8aa3b, v123
	v_exp_f32_e32 v98, v98
	v_or_b32_e32 v0, 17, v132
	v_add_f32_e32 v98, 1.0, v98
	v_rcp_f32_e32 v98, v98
	s_nop 0
	v_mul_f32_e32 v98, v123, v98
	v_mul_f32_e32 v98, v107, v98
	v_cvt_pk_bf16_f32 v100, v98, s0
	v_mad_i64_i32 v[98:99], s[2:3], v0, s20, v[130:131]
	global_store_short v[98:99], v100, off
	v_mul_f32_e32 v98, 0xbfb8aa3b, v124
	v_exp_f32_e32 v98, v98
	v_or_b32_e32 v0, 18, v132
	v_add_f32_e32 v98, 1.0, v98
	v_rcp_f32_e32 v98, v98
	s_nop 0
	v_mul_f32_e32 v98, v124, v98
	v_mul_f32_e32 v98, v108, v98
	v_cvt_pk_bf16_f32 v100, v98, s0
	v_mad_i64_i32 v[98:99], s[2:3], v0, s20, v[130:131]
	global_store_short v[98:99], v100, off
	v_mul_f32_e32 v98, 0xbfb8aa3b, v125
	v_exp_f32_e32 v98, v98
	v_or_b32_e32 v0, 19, v132
	v_add_f32_e32 v98, 1.0, v98
	v_rcp_f32_e32 v98, v98
	s_nop 0
	v_mul_f32_e32 v98, v125, v98
	v_mul_f32_e32 v98, v109, v98
	v_cvt_pk_bf16_f32 v100, v98, s0
	v_mad_i64_i32 v[98:99], s[2:3], v0, s20, v[130:131]
	global_store_short v[98:99], v100, off
	v_mul_f32_e32 v98, 0xbfb8aa3b, v126
	v_exp_f32_e32 v98, v98
	v_or_b32_e32 v0, 24, v132
	v_add_f32_e32 v98, 1.0, v98
	v_rcp_f32_e32 v98, v98
	s_nop 0
	v_mul_f32_e32 v98, v126, v98
	v_mul_f32_e32 v98, v110, v98
	v_cvt_pk_bf16_f32 v100, v98, s0
	v_mad_i64_i32 v[98:99], s[2:3], v0, s20, v[130:131]
	global_store_short v[98:99], v100, off
	v_mul_f32_e32 v98, 0xbfb8aa3b, v127
	v_exp_f32_e32 v98, v98
	v_or_b32_e32 v0, 25, v132
	v_add_f32_e32 v98, 1.0, v98
	v_rcp_f32_e32 v98, v98
	s_nop 0
	v_mul_f32_e32 v98, v127, v98
	v_mul_f32_e32 v98, v111, v98
	v_cvt_pk_bf16_f32 v100, v98, s0
	v_mad_i64_i32 v[98:99], s[2:3], v0, s20, v[130:131]
	global_store_short v[98:99], v100, off
	v_mul_f32_e32 v98, 0xbfb8aa3b, v128
	v_exp_f32_e32 v98, v98
	v_or_b32_e32 v0, 26, v132
	v_add_f32_e32 v98, 1.0, v98
	v_rcp_f32_e32 v98, v98
	s_nop 0
	v_mul_f32_e32 v98, v128, v98
	v_mul_f32_e32 v98, v112, v98
	v_cvt_pk_bf16_f32 v100, v98, s0
	v_mad_i64_i32 v[98:99], s[2:3], v0, s20, v[130:131]
	global_store_short v[98:99], v100, off
	v_mul_f32_e32 v98, 0xbfb8aa3b, v129
	v_exp_f32_e32 v98, v98
	v_or_b32_e32 v0, 27, v132
	v_add_f32_e32 v98, 1.0, v98
	v_rcp_f32_e32 v98, v98
	s_nop 0
	v_mul_f32_e32 v98, v129, v98
	v_mul_f32_e32 v98, v113, v98
	v_cvt_pk_bf16_f32 v100, v98, s0
	v_mad_i64_i32 v[98:99], s[2:3], v0, s20, v[130:131]
	global_store_short v[98:99], v100, off
	v_mul_f32_e32 v98, 0xbfb8aa3b, v82
	v_exp_f32_e32 v98, v98
	v_or_b32_e32 v0, 32, v132
	v_add_f32_e32 v98, 1.0, v98
	v_rcp_f32_e32 v98, v98
	s_nop 0
	v_mul_f32_e32 v82, v82, v98
	v_mul_f32_e32 v66, v66, v82
	v_cvt_pk_bf16_f32 v66, v66, s0
	v_mad_i64_i32 v[98:99], s[2:3], v0, s20, v[130:131]
	global_store_short v[98:99], v66, off
	v_mul_f32_e32 v66, 0xbfb8aa3b, v83
	v_exp_f32_e32 v66, v66
	v_or_b32_e32 v0, 33, v132
	v_add_f32_e32 v66, 1.0, v66
	v_rcp_f32_e32 v66, v66
	s_nop 0
	v_mul_f32_e32 v66, v83, v66
	v_mul_f32_e32 v66, v67, v66
	v_cvt_pk_bf16_f32 v82, v66, s0
	v_mad_i64_i32 v[66:67], s[2:3], v0, s20, v[130:131]
	global_store_short v[66:67], v82, off
	v_mul_f32_e32 v66, 0xbfb8aa3b, v84
	v_exp_f32_e32 v66, v66
	v_or_b32_e32 v0, 34, v132
	v_add_f32_e32 v66, 1.0, v66
	v_rcp_f32_e32 v66, v66
	s_nop 0
	v_mul_f32_e32 v66, v84, v66
	v_mul_f32_e32 v66, v68, v66
	v_cvt_pk_bf16_f32 v68, v66, s0
	v_mad_i64_i32 v[66:67], s[2:3], v0, s20, v[130:131]
	global_store_short v[66:67], v68, off
	v_mul_f32_e32 v66, 0xbfb8aa3b, v85
	v_exp_f32_e32 v66, v66
	v_or_b32_e32 v0, 35, v132
	v_add_f32_e32 v66, 1.0, v66
	v_rcp_f32_e32 v66, v66
	s_nop 0
	v_mul_f32_e32 v66, v85, v66
	v_mul_f32_e32 v66, v69, v66
	v_cvt_pk_bf16_f32 v68, v66, s0
	v_mad_i64_i32 v[66:67], s[2:3], v0, s20, v[130:131]
	global_store_short v[66:67], v68, off
	v_mul_f32_e32 v66, 0xbfb8aa3b, v86
	v_exp_f32_e32 v66, v66
	v_or_b32_e32 v0, 40, v132
	v_add_f32_e32 v66, 1.0, v66
	v_rcp_f32_e32 v66, v66
	s_nop 0
	v_mul_f32_e32 v66, v86, v66
	v_mul_f32_e32 v66, v70, v66
	v_cvt_pk_bf16_f32 v68, v66, s0
	v_mad_i64_i32 v[66:67], s[2:3], v0, s20, v[130:131]
	global_store_short v[66:67], v68, off
	v_mul_f32_e32 v66, 0xbfb8aa3b, v87
	v_exp_f32_e32 v66, v66
	v_or_b32_e32 v0, 41, v132
	v_add_f32_e32 v66, 1.0, v66
	v_rcp_f32_e32 v66, v66
; __device__ __forceinline__ float siluf_(float x) { return x * __builtin_amdgcn_rcpf(1.f + fexp(-x)); }
; __device__ __forceinline__ void ffn1_tile(const Params& p, int mt, int nt, bf16* sA, bf16* sB) {
;     ...
; #pragma unroll
;   for (int mi = 0; mi < 4; ++mi)
; #pragma unroll
;     for (int e = 0; e < 16; ++e) {
;       const int t = m0 + wm * 128 + mi * 32 + ROW_OF(e, hh);
;       const float v = siluf_(acc[mi][0][e]) * acc[mi][1][e];
;       p.act[(size_t)t * 2816 + nt * 64 + wn * 32 + r] = f2bf(v);
;     }
	s_nop 0
	v_mul_f32_e32 v66, v87, v66
	v_mul_f32_e32 v66, v71, v66
	v_cvt_pk_bf16_f32 v68, v66, s0
	v_mad_i64_i32 v[66:67], s[2:3], v0, s20, v[130:131]
	global_store_short v[66:67], v68, off
	v_mul_f32_e32 v66, 0xbfb8aa3b, v88
	v_exp_f32_e32 v66, v66
	v_or_b32_e32 v0, 42, v132
	v_add_f32_e32 v66, 1.0, v66
	v_rcp_f32_e32 v66, v66
	s_nop 0
	v_mul_f32_e32 v66, v88, v66
	v_mul_f32_e32 v66, v72, v66
	v_cvt_pk_bf16_f32 v68, v66, s0
	v_mad_i64_i32 v[66:67], s[2:3], v0, s20, v[130:131]
	global_store_short v[66:67], v68, off
	v_mul_f32_e32 v66, 0xbfb8aa3b, v89
	v_exp_f32_e32 v66, v66
	v_or_b32_e32 v0, 43, v132
	v_add_f32_e32 v66, 1.0, v66
	v_rcp_f32_e32 v66, v66
	s_nop 0
	v_mul_f32_e32 v66, v89, v66
	v_mul_f32_e32 v66, v73, v66
	v_cvt_pk_bf16_f32 v68, v66, s0
	v_mad_i64_i32 v[66:67], s[2:3], v0, s20, v[130:131]
	global_store_short v[66:67], v68, off
	v_mul_f32_e32 v66, 0xbfb8aa3b, v90
	v_exp_f32_e32 v66, v66
	v_or_b32_e32 v0, 48, v132
	v_add_f32_e32 v66, 1.0, v66
	v_rcp_f32_e32 v66, v66
	s_nop 0
	v_mul_f32_e32 v66, v90, v66
	v_mul_f32_e32 v66, v74, v66
	v_cvt_pk_bf16_f32 v68, v66, s0
	v_mad_i64_i32 v[66:67], s[2:3], v0, s20, v[130:131]
	global_store_short v[66:67], v68, off
	v_mul_f32_e32 v66, 0xbfb8aa3b, v91
	v_exp_f32_e32 v66, v66
	v_or_b32_e32 v0, 49, v132
	v_add_f32_e32 v66, 1.0, v66
	v_rcp_f32_e32 v66, v66
	s_nop 0
	v_mul_f32_e32 v66, v91, v66
	v_mul_f32_e32 v66, v75, v66
	v_cvt_pk_bf16_f32 v68, v66, s0
	v_mad_i64_i32 v[66:67], s[2:3], v0, s20, v[130:131]
	global_store_short v[66:67], v68, off
	v_mul_f32_e32 v66, 0xbfb8aa3b, v92
	v_exp_f32_e32 v66, v66
	v_or_b32_e32 v0, 50, v132
	v_add_f32_e32 v66, 1.0, v66
	v_rcp_f32_e32 v66, v66
	s_nop 0
	v_mul_f32_e32 v66, v92, v66
	v_mul_f32_e32 v66, v76, v66
	v_cvt_pk_bf16_f32 v68, v66, s0
	v_mad_i64_i32 v[66:67], s[2:3], v0, s20, v[130:131]
	global_store_short v[66:67], v68, off
	v_mul_f32_e32 v66, 0xbfb8aa3b, v93
	v_exp_f32_e32 v66, v66
	v_or_b32_e32 v0, 51, v132
	v_add_f32_e32 v66, 1.0, v66
	v_rcp_f32_e32 v66, v66
	s_nop 0
	v_mul_f32_e32 v66, v93, v66
	v_mul_f32_e32 v66, v77, v66
	v_cvt_pk_bf16_f32 v68, v66, s0
	v_mad_i64_i32 v[66:67], s[2:3], v0, s20, v[130:131]
	global_store_short v[66:67], v68, off
	v_mul_f32_e32 v66, 0xbfb8aa3b, v94
	v_exp_f32_e32 v66, v66
	v_or_b32_e32 v0, 56, v132
	v_add_f32_e32 v66, 1.0, v66
	v_rcp_f32_e32 v66, v66
	s_nop 0
	v_mul_f32_e32 v66, v94, v66
	v_mul_f32_e32 v66, v78, v66
	v_cvt_pk_bf16_f32 v68, v66, s0
	v_mad_i64_i32 v[66:67], s[2:3], v0, s20, v[130:131]
	global_store_short v[66:67], v68, off
	v_mul_f32_e32 v66, 0xbfb8aa3b, v95
	v_exp_f32_e32 v66, v66
	v_or_b32_e32 v0, 57, v132
	v_add_f32_e32 v66, 1.0, v66
	v_rcp_f32_e32 v66, v66
	s_nop 0
	v_mul_f32_e32 v66, v95, v66
	v_mul_f32_e32 v66, v79, v66
	v_cvt_pk_bf16_f32 v68, v66, s0
	v_mad_i64_i32 v[66:67], s[2:3], v0, s20, v[130:131]
	global_store_short v[66:67], v68, off
	v_mul_f32_e32 v66, 0xbfb8aa3b, v96
	v_exp_f32_e32 v66, v66
	v_or_b32_e32 v0, 58, v132
	v_add_f32_e32 v66, 1.0, v66
	v_rcp_f32_e32 v66, v66
	s_nop 0
	v_mul_f32_e32 v66, v96, v66
	v_mul_f32_e32 v66, v80, v66
	v_cvt_pk_bf16_f32 v68, v66, s0
	v_mad_i64_i32 v[66:67], s[2:3], v0, s20, v[130:131]
	global_store_short v[66:67], v68, off
	v_mul_f32_e32 v66, 0xbfb8aa3b, v97
	v_exp_f32_e32 v66, v66
	v_or_b32_e32 v0, 59, v132
	v_add_f32_e32 v66, 1.0, v66
	v_rcp_f32_e32 v66, v66
	s_nop 0
	v_mul_f32_e32 v66, v97, v66
	v_mul_f32_e32 v66, v81, v66
	v_cvt_pk_bf16_f32 v68, v66, s0
	v_mad_i64_i32 v[66:67], s[2:3], v0, s20, v[130:131]
	global_store_short v[66:67], v68, off
	v_mul_f32_e32 v66, 0xbfb8aa3b, v50
	v_exp_f32_e32 v66, v66
	v_or_b32_e32 v0, 64, v132
	v_add_f32_e32 v66, 1.0, v66
	v_rcp_f32_e32 v66, v66
	s_nop 0
	v_mul_f32_e32 v50, v50, v66
	v_mul_f32_e32 v34, v34, v50
	v_cvt_pk_bf16_f32 v34, v34, s0
	v_mad_i64_i32 v[66:67], s[2:3], v0, s20, v[130:131]
	global_store_short v[66:67], v34, off
	v_mul_f32_e32 v34, 0xbfb8aa3b, v51
	v_exp_f32_e32 v34, v34
	v_or_b32_e32 v0, 0x41, v132
	v_add_f32_e32 v34, 1.0, v34
	v_rcp_f32_e32 v34, v34
	s_nop 0
	v_mul_f32_e32 v34, v51, v34
	v_mul_f32_e32 v34, v35, v34
	v_cvt_pk_bf16_f32 v50, v34, s0
	v_mad_i64_i32 v[34:35], s[2:3], v0, s20, v[130:131]
	global_store_short v[34:35], v50, off
	v_mul_f32_e32 v34, 0xbfb8aa3b, v52
	v_exp_f32_e32 v34, v34
	v_or_b32_e32 v0, 0x42, v132
	v_add_f32_e32 v34, 1.0, v34
	v_rcp_f32_e32 v34, v34
	s_nop 0
	v_mul_f32_e32 v34, v52, v34
	v_mul_f32_e32 v34, v36, v34
	v_cvt_pk_bf16_f32 v36, v34, s0
	v_mad_i64_i32 v[34:35], s[2:3], v0, s20, v[130:131]
	global_store_short v[34:35], v36, off
	v_mul_f32_e32 v34, 0xbfb8aa3b, v53
	v_exp_f32_e32 v34, v34
	v_or_b32_e32 v0, 0x43, v132
	v_add_f32_e32 v34, 1.0, v34
	v_rcp_f32_e32 v34, v34
	s_nop 0
	v_mul_f32_e32 v34, v53, v34
	v_mul_f32_e32 v34, v37, v34
	v_cvt_pk_bf16_f32 v36, v34, s0
	v_mad_i64_i32 v[34:35], s[2:3], v0, s20, v[130:131]
	global_store_short v[34:35], v36, off
	v_mul_f32_e32 v34, 0xbfb8aa3b, v54
	v_exp_f32_e32 v34, v34
	v_or_b32_e32 v0, 0x48, v132
	v_add_f32_e32 v34, 1.0, v34
	v_rcp_f32_e32 v34, v34
	s_nop 0
	v_mul_f32_e32 v34, v54, v34
	v_mul_f32_e32 v34, v38, v34
	v_cvt_pk_bf16_f32 v36, v34, s0
	v_mad_i64_i32 v[34:35], s[2:3], v0, s20, v[130:131]
	global_store_short v[34:35], v36, off
	v_mul_f32_e32 v34, 0xbfb8aa3b, v55
	v_exp_f32_e32 v34, v34
	v_or_b32_e32 v0, 0x49, v132
	v_add_f32_e32 v34, 1.0, v34
	v_rcp_f32_e32 v34, v34
	s_nop 0
	v_mul_f32_e32 v34, v55, v34
	v_mul_f32_e32 v34, v39, v34
	v_cvt_pk_bf16_f32 v36, v34, s0
	v_mad_i64_i32 v[34:35], s[2:3], v0, s20, v[130:131]
	global_store_short v[34:35], v36, off
	v_mul_f32_e32 v34, 0xbfb8aa3b, v56
	v_exp_f32_e32 v34, v34
	v_or_b32_e32 v0, 0x4a, v132
	v_add_f32_e32 v34, 1.0, v34
	v_rcp_f32_e32 v34, v34
; __device__ __forceinline__ float siluf_(float x) { return x * __builtin_amdgcn_rcpf(1.f + fexp(-x)); }
; __device__ __forceinline__ void ffn1_tile(const Params& p, int mt, int nt, bf16* sA, bf16* sB) {
;     ...
; #pragma unroll
;   for (int mi = 0; mi < 4; ++mi)
; #pragma unroll
;     for (int e = 0; e < 16; ++e) {
;       const int t = m0 + wm * 128 + mi * 32 + ROW_OF(e, hh);
;       const float v = siluf_(acc[mi][0][e]) * acc[mi][1][e];
;       p.act[(size_t)t * 2816 + nt * 64 + wn * 32 + r] = f2bf(v);
;     }
	s_nop 0
	v_mul_f32_e32 v34, v56, v34
	v_mul_f32_e32 v34, v40, v34
	v_cvt_pk_bf16_f32 v36, v34, s0
	v_mad_i64_i32 v[34:35], s[2:3], v0, s20, v[130:131]
	global_store_short v[34:35], v36, off
	v_mul_f32_e32 v34, 0xbfb8aa3b, v57
	v_exp_f32_e32 v34, v34
	v_or_b32_e32 v0, 0x4b, v132
	v_add_f32_e32 v34, 1.0, v34
	v_rcp_f32_e32 v34, v34
	s_nop 0
	v_mul_f32_e32 v34, v57, v34
	v_mul_f32_e32 v34, v41, v34
	v_cvt_pk_bf16_f32 v36, v34, s0
	v_mad_i64_i32 v[34:35], s[2:3], v0, s20, v[130:131]
	global_store_short v[34:35], v36, off
	v_mul_f32_e32 v34, 0xbfb8aa3b, v58
	v_exp_f32_e32 v34, v34
	v_or_b32_e32 v0, 0x50, v132
	v_add_f32_e32 v34, 1.0, v34
	v_rcp_f32_e32 v34, v34
	s_nop 0
	v_mul_f32_e32 v34, v58, v34
	v_mul_f32_e32 v34, v42, v34
	v_cvt_pk_bf16_f32 v36, v34, s0
	v_mad_i64_i32 v[34:35], s[2:3], v0, s20, v[130:131]
	global_store_short v[34:35], v36, off
	v_mul_f32_e32 v34, 0xbfb8aa3b, v59
	v_exp_f32_e32 v34, v34
	v_or_b32_e32 v0, 0x51, v132
	v_add_f32_e32 v34, 1.0, v34
	v_rcp_f32_e32 v34, v34
	s_nop 0
	v_mul_f32_e32 v34, v59, v34
	v_mul_f32_e32 v34, v43, v34
	v_cvt_pk_bf16_f32 v36, v34, s0
	v_mad_i64_i32 v[34:35], s[2:3], v0, s20, v[130:131]
	global_store_short v[34:35], v36, off
	v_mul_f32_e32 v34, 0xbfb8aa3b, v60
	v_exp_f32_e32 v34, v34
	v_or_b32_e32 v0, 0x52, v132
	v_add_f32_e32 v34, 1.0, v34
	v_rcp_f32_e32 v34, v34
	s_nop 0
	v_mul_f32_e32 v34, v60, v34
	v_mul_f32_e32 v34, v44, v34
	v_cvt_pk_bf16_f32 v36, v34, s0
	v_mad_i64_i32 v[34:35], s[2:3], v0, s20, v[130:131]
	global_store_short v[34:35], v36, off
	v_mul_f32_e32 v34, 0xbfb8aa3b, v61
	v_exp_f32_e32 v34, v34
	v_or_b32_e32 v0, 0x53, v132
	v_add_f32_e32 v34, 1.0, v34
	v_rcp_f32_e32 v34, v34
	s_nop 0
	v_mul_f32_e32 v34, v61, v34
	v_mul_f32_e32 v34, v45, v34
	v_cvt_pk_bf16_f32 v36, v34, s0
	v_mad_i64_i32 v[34:35], s[2:3], v0, s20, v[130:131]
	global_store_short v[34:35], v36, off
	v_mul_f32_e32 v34, 0xbfb8aa3b, v62
	v_exp_f32_e32 v34, v34
	v_or_b32_e32 v0, 0x58, v132
	v_add_f32_e32 v34, 1.0, v34
	v_rcp_f32_e32 v34, v34
	s_nop 0
	v_mul_f32_e32 v34, v62, v34
	v_mul_f32_e32 v34, v46, v34
	v_cvt_pk_bf16_f32 v36, v34, s0
	v_mad_i64_i32 v[34:35], s[2:3], v0, s20, v[130:131]
	global_store_short v[34:35], v36, off
	v_mul_f32_e32 v34, 0xbfb8aa3b, v63
	v_exp_f32_e32 v34, v34
	v_or_b32_e32 v0, 0x59, v132
	v_add_f32_e32 v34, 1.0, v34
	v_rcp_f32_e32 v34, v34
	s_nop 0
	v_mul_f32_e32 v34, v63, v34
	v_mul_f32_e32 v34, v47, v34
	v_cvt_pk_bf16_f32 v36, v34, s0
	v_mad_i64_i32 v[34:35], s[2:3], v0, s20, v[130:131]
	global_store_short v[34:35], v36, off
	v_mul_f32_e32 v34, 0xbfb8aa3b, v64
	v_exp_f32_e32 v34, v34
	v_or_b32_e32 v0, 0x5a, v132
	v_add_f32_e32 v34, 1.0, v34
	v_rcp_f32_e32 v34, v34
	s_nop 0
	v_mul_f32_e32 v34, v64, v34
	v_mul_f32_e32 v34, v48, v34
	v_cvt_pk_bf16_f32 v36, v34, s0
	v_mad_i64_i32 v[34:35], s[2:3], v0, s20, v[130:131]
	global_store_short v[34:35], v36, off
	v_mul_f32_e32 v34, 0xbfb8aa3b, v65
	v_exp_f32_e32 v34, v34
	v_or_b32_e32 v0, 0x5b, v132
	v_add_f32_e32 v34, 1.0, v34
	v_rcp_f32_e32 v34, v34
	s_nop 0
	v_mul_f32_e32 v34, v65, v34
	v_mul_f32_e32 v34, v49, v34
	v_cvt_pk_bf16_f32 v36, v34, s0
	v_mad_i64_i32 v[34:35], s[2:3], v0, s20, v[130:131]
	global_store_short v[34:35], v36, off
	v_mul_f32_e32 v34, 0xbfb8aa3b, v18
	v_exp_f32_e32 v34, v34
	v_or_b32_e32 v0, 0x60, v132
	v_add_f32_e32 v34, 1.0, v34
	v_rcp_f32_e32 v34, v34
	s_nop 0
	v_mul_f32_e32 v18, v18, v34
	v_mul_f32_e32 v2, v2, v18
	v_cvt_pk_bf16_f32 v2, v2, s0
	v_mad_i64_i32 v[34:35], s[2:3], v0, s20, v[130:131]
	global_store_short v[34:35], v2, off
	v_mul_f32_e32 v2, 0xbfb8aa3b, v19
	v_exp_f32_e32 v2, v2
	v_or_b32_e32 v0, 0x61, v132
	v_add_f32_e32 v2, 1.0, v2
	v_rcp_f32_e32 v2, v2
	s_nop 0
	v_mul_f32_e32 v2, v19, v2
	v_mul_f32_e32 v2, v3, v2
	v_cvt_pk_bf16_f32 v18, v2, s0
	v_mad_i64_i32 v[2:3], s[2:3], v0, s20, v[130:131]
	global_store_short v[2:3], v18, off
	v_mul_f32_e32 v2, 0xbfb8aa3b, v20
	v_exp_f32_e32 v2, v2
	v_or_b32_e32 v0, 0x62, v132
	v_add_f32_e32 v2, 1.0, v2
	v_rcp_f32_e32 v2, v2
	s_nop 0
	v_mul_f32_e32 v2, v20, v2
	v_mul_f32_e32 v2, v4, v2
	v_cvt_pk_bf16_f32 v4, v2, s0
	v_mad_i64_i32 v[2:3], s[2:3], v0, s20, v[130:131]
	global_store_short v[2:3], v4, off
	v_mul_f32_e32 v2, 0xbfb8aa3b, v21
; __device__ __forceinline__ float siluf_(float x) { return x * __builtin_amdgcn_rcpf(1.f + fexp(-x)); }
; __device__ __forceinline__ void ffn1_tile(const Params& p, int mt, int nt, bf16* sA, bf16* sB) {
;     ...
; #pragma unroll
;   for (int mi = 0; mi < 4; ++mi)
; #pragma unroll
;     for (int e = 0; e < 16; ++e) {
;       const int t = m0 + wm * 128 + mi * 32 + ROW_OF(e, hh);
;       const float v = siluf_(acc[mi][0][e]) * acc[mi][1][e];
;       p.act[(size_t)t * 2816 + nt * 64 + wn * 32 + r] = f2bf(v);
;     }
; __device__ __forceinline__ void run_phase(const Params& p, int ph, char* smem, int* s_item, int dup, int dryflag) {
;     ...
;       for (int sq = bloc; sq < 16 * 44; sq += nloc) { int mt, nt; decode_tile(sq, 44, 16, 4, xcd, mt, nt); ffn1_tile(p, mt, nt, sA, sB); }
	v_exp_f32_e32 v2, v2
	v_or_b32_e32 v0, 0x63, v132
	v_add_f32_e32 v2, 1.0, v2
	v_rcp_f32_e32 v2, v2
	s_nop 0
	v_mul_f32_e32 v2, v21, v2
	v_mul_f32_e32 v2, v5, v2
	v_cvt_pk_bf16_f32 v4, v2, s0
	v_mad_i64_i32 v[2:3], s[2:3], v0, s20, v[130:131]
	global_store_short v[2:3], v4, off
	v_mul_f32_e32 v2, 0xbfb8aa3b, v22
	v_exp_f32_e32 v2, v2
	v_or_b32_e32 v0, 0x68, v132
	v_add_f32_e32 v2, 1.0, v2
	v_rcp_f32_e32 v2, v2
	s_nop 0
	v_mul_f32_e32 v2, v22, v2
	v_mul_f32_e32 v2, v6, v2
	v_cvt_pk_bf16_f32 v4, v2, s0
	v_mad_i64_i32 v[2:3], s[2:3], v0, s20, v[130:131]
	global_store_short v[2:3], v4, off
	v_mul_f32_e32 v2, 0xbfb8aa3b, v23
	v_exp_f32_e32 v2, v2
	v_or_b32_e32 v0, 0x69, v132
	v_add_f32_e32 v2, 1.0, v2
	v_rcp_f32_e32 v2, v2
	s_nop 0
	v_mul_f32_e32 v2, v23, v2
	v_mul_f32_e32 v2, v7, v2
	v_cvt_pk_bf16_f32 v4, v2, s0
	v_mad_i64_i32 v[2:3], s[2:3], v0, s20, v[130:131]
	global_store_short v[2:3], v4, off
	v_mul_f32_e32 v2, 0xbfb8aa3b, v24
	v_exp_f32_e32 v2, v2
	v_or_b32_e32 v0, 0x6a, v132
	v_add_f32_e32 v2, 1.0, v2
	v_rcp_f32_e32 v2, v2
	s_nop 0
	v_mul_f32_e32 v2, v24, v2
	v_mul_f32_e32 v2, v8, v2
	v_cvt_pk_bf16_f32 v4, v2, s0
	v_mad_i64_i32 v[2:3], s[2:3], v0, s20, v[130:131]
	global_store_short v[2:3], v4, off
	v_mul_f32_e32 v2, 0xbfb8aa3b, v25
	v_exp_f32_e32 v2, v2
	v_or_b32_e32 v0, 0x6b, v132
	v_add_f32_e32 v2, 1.0, v2
	v_rcp_f32_e32 v2, v2
	s_nop 0
	v_mul_f32_e32 v2, v25, v2
	v_mul_f32_e32 v2, v9, v2
	v_cvt_pk_bf16_f32 v4, v2, s0
	v_mad_i64_i32 v[2:3], s[2:3], v0, s20, v[130:131]
	global_store_short v[2:3], v4, off
	v_mul_f32_e32 v2, 0xbfb8aa3b, v26
	v_exp_f32_e32 v2, v2
	v_or_b32_e32 v0, 0x70, v132
	v_add_f32_e32 v2, 1.0, v2
	v_rcp_f32_e32 v2, v2
	s_nop 0
	v_mul_f32_e32 v2, v26, v2
	v_mul_f32_e32 v2, v10, v2
	v_cvt_pk_bf16_f32 v4, v2, s0
	v_mad_i64_i32 v[2:3], s[2:3], v0, s20, v[130:131]
	global_store_short v[2:3], v4, off
	v_mul_f32_e32 v2, 0xbfb8aa3b, v27
	v_exp_f32_e32 v2, v2
	v_or_b32_e32 v0, 0x71, v132
	v_add_f32_e32 v2, 1.0, v2
	v_rcp_f32_e32 v2, v2
	s_nop 0
	v_mul_f32_e32 v2, v27, v2
	v_mul_f32_e32 v2, v11, v2
	v_cvt_pk_bf16_f32 v4, v2, s0
	v_mad_i64_i32 v[2:3], s[2:3], v0, s20, v[130:131]
	global_store_short v[2:3], v4, off
	v_mul_f32_e32 v2, 0xbfb8aa3b, v28
	v_exp_f32_e32 v2, v2
	v_or_b32_e32 v0, 0x72, v132
	v_add_f32_e32 v2, 1.0, v2
	v_rcp_f32_e32 v2, v2
	s_nop 0
	v_mul_f32_e32 v2, v28, v2
	v_mul_f32_e32 v2, v12, v2
	v_cvt_pk_bf16_f32 v4, v2, s0
	v_mad_i64_i32 v[2:3], s[2:3], v0, s20, v[130:131]
	global_store_short v[2:3], v4, off
	v_mul_f32_e32 v2, 0xbfb8aa3b, v29
	v_exp_f32_e32 v2, v2
	v_or_b32_e32 v0, 0x73, v132
	v_add_f32_e32 v2, 1.0, v2
	v_rcp_f32_e32 v2, v2
	s_nop 0
	v_mul_f32_e32 v2, v29, v2
	v_mul_f32_e32 v2, v13, v2
	v_cvt_pk_bf16_f32 v4, v2, s0
	v_mad_i64_i32 v[2:3], s[2:3], v0, s20, v[130:131]
	global_store_short v[2:3], v4, off
	v_mul_f32_e32 v2, 0xbfb8aa3b, v30
	v_exp_f32_e32 v2, v2
	v_or_b32_e32 v0, 0x78, v132
	v_add_f32_e32 v2, 1.0, v2
	v_rcp_f32_e32 v2, v2
	s_nop 0
	v_mul_f32_e32 v2, v30, v2
	v_mul_f32_e32 v2, v14, v2
	v_cvt_pk_bf16_f32 v4, v2, s0
	v_mad_i64_i32 v[2:3], s[2:3], v0, s20, v[130:131]
	global_store_short v[2:3], v4, off
	v_mul_f32_e32 v2, 0xbfb8aa3b, v31
	v_exp_f32_e32 v2, v2
	v_or_b32_e32 v0, 0x79, v132
	v_add_f32_e32 v2, 1.0, v2
	v_rcp_f32_e32 v2, v2
	s_nop 0
	v_mul_f32_e32 v2, v31, v2
	v_mul_f32_e32 v2, v15, v2
	v_cvt_pk_bf16_f32 v4, v2, s0
	v_mad_i64_i32 v[2:3], s[2:3], v0, s20, v[130:131]
	global_store_short v[2:3], v4, off
	v_mul_f32_e32 v2, 0xbfb8aa3b, v32
	v_exp_f32_e32 v2, v2
	v_or_b32_e32 v0, 0x7a, v132
	v_add_f32_e32 v2, 1.0, v2
	v_rcp_f32_e32 v2, v2
	s_nop 0
	v_mul_f32_e32 v2, v32, v2
	v_mul_f32_e32 v2, v16, v2
	v_cvt_pk_bf16_f32 v4, v2, s0
	v_mad_i64_i32 v[2:3], s[2:3], v0, s20, v[130:131]
	global_store_short v[2:3], v4, off
	v_mul_f32_e32 v2, 0xbfb8aa3b, v33
	v_exp_f32_e32 v2, v2
	v_or_b32_e32 v0, 0x7b, v132
	v_add_f32_e32 v2, 1.0, v2
	v_rcp_f32_e32 v2, v2
	s_nop 0
	v_mul_f32_e32 v2, v33, v2
	v_mul_f32_e32 v2, v17, v2
	v_cvt_pk_bf16_f32 v4, v2, s0
	v_mad_i64_i32 v[2:3], s[2:3], v0, s20, v[130:131]
	v_readlane_b32 s2, v254, 60
	s_add_i32 s0, s0, s2
	s_cmpk_gt_u32 s0, 0x2bf
	global_store_short v[2:3], v4, off
	s_cbranch_scc0 .LBB0_22

; __device__ __forceinline__ int tid_opaque() { int t = threadIdx.x; asm volatile("" : "+v"(t)); return t; }
; #define ZERO_ACC(acc, MI_, NI_)                 \
;   _Pragma("unroll") for (int mi = 0; mi < MI_; ++mi) \
;   _Pragma("unroll") for (int ni = 0; ni < NI_; ++ni) \
;   _Pragma("unroll") for (int e = 0; e < 16; ++e) acc[mi][ni][e] = 0.f;
; template <int MI, int NI>
; __device__ __forceinline__ void gemm_kloop(const bf16* __restrict__ A, size_t lda, const bf16* __restrict__ Bt, size_t ldb, int K,
;                                            f16v (&acc)[MI][NI], bf16* sA, bf16* sB) {
;   const int tid = tid_opaque(), lane = tid & 63, w = tid >> 6;
;   const int r = lane & 31, hh = lane >> 5;
;   const int wm = w >> 1, wn = w & 1;
;   const int lrow = tid >> 3, lseg = tid & 7;
;   u4v ra[2 * MI], rb[2 * NI];
;   const int KT = K >> 6;
; #pragma unroll
;   for (int i = 0; i < 2 * MI; ++i) ra[i] = *(const u4v*)(A + (size_t)(lrow + 32 * i) * lda + lseg * 8);
; #pragma unroll
;   for (int i = 0; i < 2 * NI; ++i) rb[i] = *(const u4v*)(Bt + (size_t)(lrow + 32 * i) * ldb + lseg * 8);
; __device__ __forceinline__ void resid_tile(const Params& p, const bf16* A, size_t lda, const bf16* Bt, int K, int mt, int nt, bool x_from_input, bf16* sA, bf16* sB, int dry) {
;   const int m0 = mt * 256, n0 = nt * 128;
;   f16v acc[4][2];
;   ZERO_ACC(acc, 4, 2)
;   gemm_kloop<4, 2>(A + (size_t)m0 * lda, lda, Bt + (size_t)n0 * K, K, K, acc, sA, sB);
.LBB0_38:
	s_lshr_b32 s20, s0, 3
	s_and_b32 s30, s20, 12
	s_lshl_b32 s20, s30, 3
	s_sub_i32 s20, s0, s20
	s_bfe_i32 s22, s20, 0x80000
	s_bfe_u32 s22, s22, 0x2000d
	s_add_i32 s22, s20, s22
	s_bfe_i32 s23, s22, 0x80000
	s_and_b32 s22, s22, 0xfc
	s_sub_i32 s20, s20, s22
	s_or_b32 s21, s30, s88
	s_sext_i32_i8 s31, s20
	s_add_i32 s21, s21, s31
	s_sext_i32_i16 s23, s23
	s_lshl_b32 s22, s21, 8
	s_lshl_b32 s20, s23, 5
	s_ashr_i32 s23, s22, 31
	v_readlane_b32 s36, v252, 15
	s_and_b32 s20, s20, 0xffffff80
	s_lshl_b64 s[24:25], s[22:23], 11
	v_readlane_b32 s42, v252, 21
	v_mov_b32_e32 v18, v195
	v_readlane_b32 s43, v252, 22
	s_add_u32 s24, s42, s24
	s_addc_u32 s25, s43, s25
	v_ashrrev_i32_e32 v2, 3, v18
	v_lshlrev_b32_e32 v0, 4, v18
	v_and_b32_e32 v0, 0x70, v0
	v_ashrrev_i32_e32 v3, 31, v2
	v_lshl_add_u64 v[4:5], s[24:25], 0, v[0:1]
	v_lshlrev_b64 v[6:7], 11, v[2:3]
	s_mov_b64 s[24:25], 0x10000
	v_lshl_add_u64 v[10:11], v[6:7], 0, s[24:25]
	v_lshl_add_u64 v[8:9], v[4:5], 0, v[6:7]
	v_lshl_add_u64 v[12:13], v[4:5], 0, v[10:11]
	s_mov_b64 s[24:25], 0x20000
	global_load_dwordx4 v[130:133], v[8:9], off
	global_load_dwordx4 v[138:141], v[12:13], off
	v_lshl_add_u64 v[12:13], v[6:7], 0, s[24:25]
	s_mov_b64 s[24:25], 0x30000
	v_lshl_add_u64 v[16:17], v[6:7], 0, s[24:25]
	v_lshl_add_u64 v[14:15], v[4:5], 0, v[12:13]
	v_lshl_add_u64 v[4:5], v[4:5], 0, v[16:17]
	global_load_dwordx4 v[142:145], v[14:15], off
	global_load_dwordx4 v[146:149], v[4:5], off
	v_add_co_u32_e32 v4, vcc, s62, v8
	s_mov_b32 s23, 0x50000
	s_nop 0
	v_addc_co_u32_e32 v5, vcc, 0, v9, vcc
	v_add_co_u32_e32 v14, vcc, s23, v8
	s_ashr_i32 s21, s20, 31
	s_nop 0
	v_addc_co_u32_e32 v15, vcc, 0, v9, vcc
	s_lshl_b64 s[26:27], s[20:21], 11
	global_load_dwordx4 v[150:153], v[4:5], off
	global_load_dwordx4 v[154:157], v[14:15], off
	v_add_co_u32_e32 v4, vcc, s92, v8
	s_add_u32 s28, s16, s26
	s_nop 0
	v_addc_co_u32_e32 v5, vcc, 0, v9, vcc
	s_addc_u32 s29, s17, s27
	v_add_co_u32_e32 v8, vcc, s93, v8
	s_add_i32 s21, s88, s30
	s_nop 0
	v_addc_co_u32_e32 v9, vcc, 0, v9, vcc
	global_load_dwordx4 v[158:161], v[4:5], off
	global_load_dwordx4 v[162:165], v[8:9], off
	v_lshl_add_u64 v[4:5], s[28:29], 0, v[0:1]
	v_lshl_add_u64 v[8:9], v[4:5], 0, v[6:7]
	v_lshl_add_u64 v[10:11], v[4:5], 0, v[10:11]
	v_lshl_add_u64 v[8:9], v[4:5], 0, v[12:13]
	v_lshl_add_u64 v[4:5], v[4:5], 0, v[16:17]
	s_add_i32 s21, s21, s31
	s_lshl_b32 s24, s21, 8
	s_ashr_i32 s25, s24, 31
	v_and_b32_e32 v3, 0xfffff9f, v18
	v_mul_lo_u32 v8, v2, s33
	v_or_b32_e32 v2, 0x60, v18
	s_lshl_b64 s[24:25], s[24:25], 11
	v_mul_lo_u32 v9, v3, s33
	v_mul_lo_u32 v10, v2, s33
	v_lshl_add_u64 v[2:3], v[6:7], 0, s[24:25]
	v_or_b32_e32 v2, v2, v0
	s_waitcnt vmcnt(31)
	v_lshl_add_u64 v[178:179], s[42:43], 0, v[2:3]
	v_lshl_add_u64 v[2:3], v[6:7], 0, s[26:27]
	v_lshrrev_b32_e32 v4, 1, v18
	v_and_b32_e32 v5, 0x5f, v18
	v_or_b32_e32 v2, v2, v0
	v_and_b32_e32 v4, 16, v4
	v_mul_u32_u24_e32 v5, 0x90, v5
	v_lshl_add_u64 v[180:181], s[16:17], 0, v[2:3]
	v_mov_b32_e32 v2, 0
	s_mov_b64 s[24:25], 0
	s_waitcnt vmcnt(30)
	v_add_u32_e32 v184, v0, v8
	v_add_u32_e32 v182, v4, v9
	v_add_u32_e32 v0, v4, v10
	v_add_u32_e32 v183, v4, v5
	v_mov_b32_e32 v3, v2
	v_mov_b32_e32 v4, v2
	v_mov_b32_e32 v5, v2
	v_mov_b32_e32 v6, v2
	v_mov_b32_e32 v7, v2
	v_mov_b32_e32 v8, v2
	v_mov_b32_e32 v9, v2
	v_mov_b32_e32 v10, v2
	v_mov_b32_e32 v11, v2
	v_mov_b32_e32 v12, v2
	v_mov_b32_e32 v13, v2
	v_mov_b32_e32 v14, v2
	v_mov_b32_e32 v15, v2
	v_mov_b32_e32 v16, v2
	v_mov_b32_e32 v17, v2
	v_mov_b32_e32 v18, v2
	v_mov_b32_e32 v19, v2
	v_mov_b32_e32 v20, v2
	v_mov_b32_e32 v21, v2
	v_mov_b32_e32 v22, v2
	v_mov_b32_e32 v23, v2
	v_mov_b32_e32 v24, v2
	v_mov_b32_e32 v25, v2
	v_mov_b32_e32 v26, v2
	v_mov_b32_e32 v27, v2
	v_mov_b32_e32 v28, v2
	v_mov_b32_e32 v29, v2
	v_mov_b32_e32 v30, v2
	v_mov_b32_e32 v31, v2
	v_mov_b32_e32 v32, v2
	v_mov_b32_e32 v33, v2
	v_mov_b32_e32 v34, v2
	v_mov_b32_e32 v35, v2
	v_mov_b32_e32 v36, v2
	v_mov_b32_e32 v37, v2
	v_mov_b32_e32 v38, v2
	v_mov_b32_e32 v39, v2
	v_mov_b32_e32 v40, v2
	v_mov_b32_e32 v41, v2
	v_mov_b32_e32 v42, v2
	v_mov_b32_e32 v43, v2
	v_mov_b32_e32 v44, v2
	v_mov_b32_e32 v45, v2
	v_mov_b32_e32 v46, v2
	v_mov_b32_e32 v47, v2
	v_mov_b32_e32 v48, v2
	v_mov_b32_e32 v49, v2
	v_mov_b32_e32 v50, v2
	v_mov_b32_e32 v51, v2
	v_mov_b32_e32 v52, v2
	v_mov_b32_e32 v53, v2
	v_mov_b32_e32 v54, v2
	v_mov_b32_e32 v55, v2
	v_mov_b32_e32 v56, v2
	v_mov_b32_e32 v57, v2
	v_mov_b32_e32 v58, v2
	v_mov_b32_e32 v59, v2
	v_mov_b32_e32 v60, v2
	v_mov_b32_e32 v61, v2
	v_mov_b32_e32 v62, v2
	v_mov_b32_e32 v63, v2
	v_mov_b32_e32 v64, v2
	v_mov_b32_e32 v65, v2
	v_mov_b32_e32 v66, v2
	v_mov_b32_e32 v67, v2
	v_mov_b32_e32 v68, v2
	v_mov_b32_e32 v69, v2
	v_mov_b32_e32 v70, v2
	v_mov_b32_e32 v71, v2
	v_mov_b32_e32 v72, v2
	v_mov_b32_e32 v73, v2
	v_mov_b32_e32 v74, v2
	v_mov_b32_e32 v75, v2
	v_mov_b32_e32 v76, v2
	v_mov_b32_e32 v77, v2
	v_mov_b32_e32 v78, v2
	v_mov_b32_e32 v79, v2
	v_mov_b32_e32 v80, v2
	v_mov_b32_e32 v81, v2
	v_mov_b32_e32 v82, v2
	v_mov_b32_e32 v83, v2
	v_mov_b32_e32 v84, v2
	v_mov_b32_e32 v85, v2
	v_mov_b32_e32 v86, v2
	v_mov_b32_e32 v87, v2
	v_mov_b32_e32 v88, v2
	v_mov_b32_e32 v89, v2
	v_mov_b32_e32 v90, v2
	v_mov_b32_e32 v91, v2
	v_mov_b32_e32 v92, v2
	v_mov_b32_e32 v93, v2
	v_mov_b32_e32 v94, v2
	v_mov_b32_e32 v95, v2
	v_mov_b32_e32 v96, v2
	v_mov_b32_e32 v97, v2
	v_mov_b32_e32 v98, v2
	v_mov_b32_e32 v99, v2
	v_mov_b32_e32 v100, v2
	v_mov_b32_e32 v101, v2
	v_mov_b32_e32 v102, v2
	v_mov_b32_e32 v103, v2
	v_mov_b32_e32 v104, v2
	v_mov_b32_e32 v105, v2
	v_mov_b32_e32 v106, v2
	v_mov_b32_e32 v107, v2
	v_mov_b32_e32 v108, v2
	v_mov_b32_e32 v109, v2
	v_mov_b32_e32 v110, v2
; #define MFMA(a, b, c) __builtin_amdgcn_mfma_f32_32x32x16_bf16((a), (b), (c), 0, 0, 0)
; __device__ __forceinline__ int tid_opaque() { int t = threadIdx.x; asm volatile("" : "+v"(t)); return t; }
; template <int MI, int NI>
; __device__ __forceinline__ void gemm_kloop(const bf16* __restrict__ A, size_t lda, const bf16* __restrict__ Bt, size_t ldb, int K,
;                                            f16v (&acc)[MI][NI], bf16* sA, bf16* sB) {
;   const int tid = tid_opaque(), lane = tid & 63, w = tid >> 6;
;   const int r = lane & 31, hh = lane >> 5;
;   const int wm = w >> 1, wn = w & 1;
;   const int lrow = tid >> 3, lseg = tid & 7;
;   u4v ra[2 * MI], rb[2 * NI];
;   const int KT = K >> 6;
; #pragma unroll
;   for (int i = 0; i < 2 * MI; ++i) ra[i] = *(const u4v*)(A + (size_t)(lrow + 32 * i) * lda + lseg * 8);
; #pragma unroll
;   for (int i = 0; i < 2 * NI; ++i) rb[i] = *(const u4v*)(Bt + (size_t)(lrow + 32 * i) * ldb + lseg * 8);
;   unsigned pfs = 0;
;   {
;     if (tid < 64 * MI) pfs ^= *(const unsigned*)(A + (size_t)tid * lda + 64) ^ *(const unsigned*)(A + (size_t)tid * lda + 128);
;     if (tid < 64 * NI) pfs ^= *(const unsigned*)(Bt + (size_t)tid * ldb + 64) ^ *(const unsigned*)(Bt + (size_t)tid * ldb + 128);
;   }
;   for (int kt = 0; kt < KT; ++kt) {
;     __syncthreads();
; #pragma unroll
;     for (int i = 0; i < 2 * MI; ++i) *(u4v*)(sA + (lrow + 32 * i) * 72 + lseg * 8) = ra[i];
; #pragma unroll
;     for (int i = 0; i < 2 * NI; ++i) *(u4v*)(sB + (lrow + 32 * i) * 72 + lseg * 8) = rb[i];
;     __syncthreads();
;     ...
;     for (int ks = 0; ks < 4; ++ks) {
;       s8v a[MI], b[NI];
; #pragma unroll
;       for (int mi = 0; mi < MI; ++mi) a[mi] = *(const s8v*)(sA + (wm * 32 * MI + mi * 32 + r) * 72 + ks * 16 + hh * 8);
; #pragma unroll
;       for (int ni = 0; ni < NI; ++ni) b[ni] = *(const s8v*)(sB + (wn * 32 * NI + ni * 32 + r) * 72 + ks * 16 + hh * 8);
; #pragma unroll
;       for (int mi = 0; mi < MI; ++mi)
; #pragma unroll
;         for (int ni = 0; ni < NI; ++ni) acc[mi][ni] = MFMA(a[mi], b[ni], acc[mi][ni]);
	v_mov_b32_e32 v111, v2
	v_mov_b32_e32 v112, v2
	v_mov_b32_e32 v113, v2
	v_mov_b32_e32 v114, v2
	v_mov_b32_e32 v115, v2
	v_mov_b32_e32 v116, v2
	v_mov_b32_e32 v117, v2
	v_mov_b32_e32 v118, v2
	v_mov_b32_e32 v119, v2
	v_mov_b32_e32 v120, v2
	v_mov_b32_e32 v121, v2
	v_mov_b32_e32 v122, v2
	v_mov_b32_e32 v123, v2
	v_mov_b32_e32 v124, v2
	v_mov_b32_e32 v125, v2
	v_mov_b32_e32 v126, v2
	v_mov_b32_e32 v127, v2
	v_mov_b32_e32 v128, v2
	v_mov_b32_e32 v129, v2
	v_readlane_b32 s37, v252, 16
	v_readlane_b32 s38, v252, 17
	v_readlane_b32 s39, v252, 18
	v_readlane_b32 s40, v252, 19
	v_readlane_b32 s41, v252, 20
	v_readfirstlane_b32 s56, v178
	v_readfirstlane_b32 s57, v179
	v_readfirstlane_b32 s58, v180
	v_readfirstlane_b32 s59, v181
	v_readfirstlane_b32 s94, v195
	v_subrev_u32_e32 v178, s56, v178
	v_add_u32_e32 v179, 0x10000, v178
	v_add_u32_e32 v180, 0x20000, v178
	v_add_u32_e32 v181, 0x30000, v178
	v_add_u32_e32 v185, 0x40000, v178
	v_add_u32_e32 v222, 0x50000, v178
	v_add_u32_e32 v223, 0x60000, v178
	v_add_u32_e32 v227, 0x70000, v178
	s_lshr_b32 s94, s94, 6
	s_mul_i32 s95, s94, 0x4000
	s_sub_u32 s58, s58, s95
	s_subb_u32 s59, s59, 0
	s_lshl_b32 s96, s94, 12
	s_add_u32 s96, s96, 36864
	v_and_b32_e32 v170, 63, v195
	v_lshrrev_b32_e32 v171, 3, v170
	v_lshrrev_b32_e32 v172, 4, v170
	v_and_b32_e32 v173, 7, v170
	v_xor_b32_e32 v172, v172, v173
	v_lshlrev_b32_e32 v172, 4, v172
	v_lshrrev_b32_e32 v173, 6, v195
	v_lshl_add_u32 v170, v173, 5, v171
	v_mul_u32_u24_e32 v170, 0x800, v170
	v_add_u32_e32 v134, v170, v172
	v_xor_b32_e32 v172, 64, v172
	v_add_u32_e32 v170, v170, v172
	v_add_u32_e32 v135, 0x3c00, v170
	v_add_u32_e32 v136, 0x7800, v134
	v_add_u32_e32 v137, 0xb400, v170
	v_and_b32_e32 v170, 31, v195
	v_bfe_u32 v171, v195, 5, 1
	v_bfe_u32 v172, v170, 1, 3
	v_xor_b32_e32 v171, v171, v172
	v_lshlrev_b32_e32 v171, 4, v171
	v_bfe_u32 v172, v195, 6, 1
	v_lshl_add_u32 v172, v172, 6, v170
	v_lshl_add_u32 v166, v172, 7, v171
	v_xor_b32_e32 v167, 32, v166
	v_xor_b32_e32 v168, 64, v166
	v_xor_b32_e32 v169, 96, v166
	s_barrier
	s_add_u32 m0, s96, 0
	s_nop 0
	global_load_lds_dwordx4 v134, s[58:59] offset:0
	global_load_lds_dwordx4 v135, s[58:59] offset:1024
	global_load_lds_dwordx4 v136, s[58:59] offset:2048
	global_load_lds_dwordx4 v137, s[58:59] offset:3072
	s_barrier
	s_waitcnt vmcnt(11)
	ds_write_b128 v184, v[130:133]
	s_waitcnt vmcnt(10)
	ds_write_b128 v184, v[138:141] offset:4608
	s_waitcnt vmcnt(9)
	ds_write_b128 v184, v[142:145] offset:9216
	s_waitcnt vmcnt(8)
	ds_write_b128 v184, v[146:149] offset:13824
	s_waitcnt vmcnt(7)
	ds_write_b128 v184, v[150:153] offset:18432
	s_waitcnt vmcnt(6)
	ds_write_b128 v184, v[154:157] offset:23040
	s_waitcnt vmcnt(5)
	ds_write_b128 v184, v[158:161] offset:27648
	s_waitcnt vmcnt(4)
	ds_write_b128 v184, v[162:165] offset:32256
	s_waitcnt vmcnt(0) lgkmcnt(0)
	s_barrier
	ds_read_b128 v[186:189], v182
	ds_read_b128 v[204:207], v166 offset:36864
	ds_read_b128 v[208:211], v166 offset:40960
	ds_read_b128 v[190:193], v182 offset:4608
	ds_read_b128 v[196:199], v182 offset:9216
	ds_read_b128 v[200:203], v0
	ds_read_b128 v[212:215], v182 offset:32
	ds_read_b128 v[244:247], v167 offset:36864
	ds_read_b128 v[248:251], v167 offset:40960
	ds_read_b128 v[216:219], v182 offset:4640
	ds_read_b128 v[232:235], v182 offset:9248
	ds_read_b128 v[236:239], v0 offset:32
	s_waitcnt lgkmcnt(10)
	v_mfma_f32_32x32x16_bf16 v[114:129], v[186:189], v[204:207], v[114:129]
	s_add_u32 m0, s96, 16256
	s_nop 0
	s_waitcnt lgkmcnt(9)
	v_mfma_f32_32x32x16_bf16 v[98:113], v[186:189], v[208:211], v[98:113]
	global_load_lds_dwordx4 v134, s[58:59] offset:128
	ds_read_b128 v[186:189], v182 offset:64
	s_waitcnt lgkmcnt(9)
	v_mfma_f32_32x32x16_bf16 v[82:97], v[190:193], v[204:207], v[82:97]
	global_load_lds_dwordx4 v135, s[58:59] offset:1152
	v_mfma_f32_32x32x16_bf16 v[66:81], v[190:193], v[208:211], v[66:81]
	global_load_lds_dwordx4 v136, s[58:59] offset:2176
	ds_read_b128 v[190:193], v182 offset:4672
	s_waitcnt lgkmcnt(9)
	v_mfma_f32_32x32x16_bf16 v[50:65], v[196:199], v[204:207], v[50:65]
	global_load_lds_dwordx4 v137, s[58:59] offset:3200
	v_mfma_f32_32x32x16_bf16 v[34:49], v[196:199], v[208:211], v[34:49]
	global_load_dwordx4 v[130:133], v178, s[56:57] offset:128
	ds_read_b128 v[196:199], v182 offset:9280
	s_waitcnt lgkmcnt(9)
	v_mfma_f32_32x32x16_bf16 v[18:33], v[200:203], v[204:207], v[18:33]
	global_load_dwordx4 v[138:141], v179, s[56:57] offset:128
	v_mfma_f32_32x32x16_bf16 v[2:17], v[200:203], v[208:211], v[2:17]
	global_load_dwordx4 v[142:145], v180, s[56:57] offset:128
	ds_read_b128 v[200:203], v0 offset:64
	ds_read_b128 v[204:207], v168 offset:36864
	ds_read_b128 v[208:211], v168 offset:40960
	s_waitcnt lgkmcnt(10)
	v_mfma_f32_32x32x16_bf16 v[114:129], v[212:215], v[244:247], v[114:129]
	global_load_dwordx4 v[146:149], v181, s[56:57] offset:128
	s_waitcnt lgkmcnt(9)
	v_mfma_f32_32x32x16_bf16 v[98:113], v[212:215], v[248:251], v[98:113]
	global_load_dwordx4 v[150:153], v185, s[56:57] offset:128
	ds_read_b128 v[212:215], v182 offset:96
	s_waitcnt lgkmcnt(9)
	v_mfma_f32_32x32x16_bf16 v[82:97], v[216:219], v[244:247], v[82:97]
	global_load_dwordx4 v[154:157], v222, s[56:57] offset:128
	v_mfma_f32_32x32x16_bf16 v[66:81], v[216:219], v[248:251], v[66:81]
	global_load_dwordx4 v[158:161], v223, s[56:57] offset:128
	ds_read_b128 v[216:219], v182 offset:4704
	s_waitcnt lgkmcnt(9)
	v_mfma_f32_32x32x16_bf16 v[50:65], v[232:235], v[244:247], v[50:65]
	global_load_dwordx4 v[162:165], v227, s[56:57] offset:128
	v_mfma_f32_32x32x16_bf16 v[34:49], v[232:235], v[248:251], v[34:49]
	ds_read_b128 v[232:235], v182 offset:9312
	s_waitcnt lgkmcnt(9)
; #define MFMA(a, b, c) __builtin_amdgcn_mfma_f32_32x32x16_bf16((a), (b), (c), 0, 0, 0)
; template <int MI, int NI>
; __device__ __forceinline__ void gemm_kloop(const bf16* __restrict__ A, size_t lda, const bf16* __restrict__ Bt, size_t ldb, int K,
;                                            f16v (&acc)[MI][NI], bf16* sA, bf16* sB) {
;     ...
;   for (int kt = 0; kt < KT; ++kt) {
;     __syncthreads();
; #pragma unroll
;     for (int i = 0; i < 2 * MI; ++i) *(u4v*)(sA + (lrow + 32 * i) * 72 + lseg * 8) = ra[i];
; #pragma unroll
;     for (int i = 0; i < 2 * NI; ++i) *(u4v*)(sB + (lrow + 32 * i) * 72 + lseg * 8) = rb[i];
;     __syncthreads();
;     if (kt + 3 < KT) {
;       const int k2 = (kt + 3) << 6;
;       if (tid < 64 * MI) pfs ^= *(const unsigned*)(A + (size_t)tid * lda + k2);
;       if (tid < 64 * NI) pfs ^= *(const unsigned*)(Bt + (size_t)tid * ldb + k2);
;     }
;     if (kt + 1 < KT) {
;       const int k0 = (kt + 1) << 6;
; #pragma unroll
;       for (int i = 0; i < 2 * MI; ++i) ra[i] = *(const u4v*)(A + (size_t)(lrow + 32 * i) * lda + k0 + lseg * 8);
; #pragma unroll
;       for (int i = 0; i < 2 * NI; ++i) rb[i] = *(const u4v*)(Bt + (size_t)(lrow + 32 * i) * ldb + k0 + lseg * 8);
;     }
; #pragma unroll
;     for (int ks = 0; ks < 4; ++ks) {
;       s8v a[MI], b[NI];
; #pragma unroll
;       for (int mi = 0; mi < MI; ++mi) a[mi] = *(const s8v*)(sA + (wm * 32 * MI + mi * 32 + r) * 72 + ks * 16 + hh * 8);
; #pragma unroll
;       for (int ni = 0; ni < NI; ++ni) b[ni] = *(const s8v*)(sB + (wn * 32 * NI + ni * 32 + r) * 72 + ks * 16 + hh * 8);
; #pragma unroll
;       for (int mi = 0; mi < MI; ++mi)
; #pragma unroll
;         for (int ni = 0; ni < NI; ++ni) acc[mi][ni] = MFMA(a[mi], b[ni], acc[mi][ni]);
	v_mfma_f32_32x32x16_bf16 v[18:33], v[236:239], v[244:247], v[18:33]
	v_mfma_f32_32x32x16_bf16 v[2:17], v[236:239], v[248:251], v[2:17]
	ds_read_b128 v[236:239], v0 offset:96
	ds_read_b128 v[244:247], v169 offset:36864
	ds_read_b128 v[248:251], v169 offset:40960
	s_waitcnt lgkmcnt(7)
	v_mfma_f32_32x32x16_bf16 v[114:129], v[186:189], v[204:207], v[114:129]
	s_waitcnt lgkmcnt(6)
	v_mfma_f32_32x32x16_bf16 v[98:113], v[186:189], v[208:211], v[98:113]
	v_mfma_f32_32x32x16_bf16 v[82:97], v[190:193], v[204:207], v[82:97]
	v_mfma_f32_32x32x16_bf16 v[66:81], v[190:193], v[208:211], v[66:81]
	v_mfma_f32_32x32x16_bf16 v[50:65], v[196:199], v[204:207], v[50:65]
	v_mfma_f32_32x32x16_bf16 v[34:49], v[196:199], v[208:211], v[34:49]
	v_mfma_f32_32x32x16_bf16 v[2:17], v[200:203], v[208:211], v[2:17]
	v_mfma_f32_32x32x16_bf16 v[18:33], v[200:203], v[204:207], v[18:33]
	s_waitcnt lgkmcnt(1)
	v_mfma_f32_32x32x16_bf16 v[114:129], v[212:215], v[244:247], v[114:129]
	s_waitcnt lgkmcnt(0)
	v_mfma_f32_32x32x16_bf16 v[98:113], v[212:215], v[248:251], v[98:113]
	v_mfma_f32_32x32x16_bf16 v[82:97], v[216:219], v[244:247], v[82:97]
	v_mfma_f32_32x32x16_bf16 v[66:81], v[216:219], v[248:251], v[66:81]
	v_mfma_f32_32x32x16_bf16 v[50:65], v[232:235], v[244:247], v[50:65]
	v_mfma_f32_32x32x16_bf16 v[34:49], v[232:235], v[248:251], v[34:49]
	v_mfma_f32_32x32x16_bf16 v[18:33], v[236:239], v[244:247], v[18:33]
	v_mfma_f32_32x32x16_bf16 v[2:17], v[236:239], v[248:251], v[2:17]
	s_add_u32 s56, s56, 0x80
	s_addc_u32 s57, s57, 0
	s_add_u32 s58, s58, 0x80
	s_addc_u32 s59, s59, 0
	s_barrier
	s_waitcnt vmcnt(7)
	ds_write_b128 v184, v[130:133]
	s_waitcnt vmcnt(6)
	ds_write_b128 v184, v[138:141] offset:4608
	s_waitcnt vmcnt(5)
	ds_write_b128 v184, v[142:145] offset:9216
	s_waitcnt vmcnt(4)
	ds_write_b128 v184, v[146:149] offset:13824
	s_waitcnt vmcnt(3)
	ds_write_b128 v184, v[150:153] offset:18432
	s_waitcnt vmcnt(2)
	ds_write_b128 v184, v[154:157] offset:23040
	s_waitcnt vmcnt(1)
	ds_write_b128 v184, v[158:161] offset:27648
	s_waitcnt vmcnt(0)
	ds_write_b128 v184, v[162:165] offset:32256
	s_waitcnt lgkmcnt(0)
	s_barrier
	ds_read_b128 v[186:189], v182
	ds_read_b128 v[204:207], v166 offset:53248
	ds_read_b128 v[208:211], v166 offset:57344
	ds_read_b128 v[190:193], v182 offset:4608
	ds_read_b128 v[196:199], v182 offset:9216
	ds_read_b128 v[200:203], v0
	ds_read_b128 v[212:215], v182 offset:32
	ds_read_b128 v[244:247], v167 offset:53248
	ds_read_b128 v[248:251], v167 offset:57344
	ds_read_b128 v[216:219], v182 offset:4640
	ds_read_b128 v[232:235], v182 offset:9248
	ds_read_b128 v[236:239], v0 offset:32
	s_waitcnt lgkmcnt(10)
	v_mfma_f32_32x32x16_bf16 v[114:129], v[186:189], v[204:207], v[114:129]
	s_add_u32 m0, s96, -128
	s_nop 0
	s_waitcnt lgkmcnt(9)
	v_mfma_f32_32x32x16_bf16 v[98:113], v[186:189], v[208:211], v[98:113]
	global_load_lds_dwordx4 v134, s[58:59] offset:128
	ds_read_b128 v[186:189], v182 offset:64
	s_waitcnt lgkmcnt(9)
	v_mfma_f32_32x32x16_bf16 v[82:97], v[190:193], v[204:207], v[82:97]
	global_load_lds_dwordx4 v135, s[58:59] offset:1152
	v_mfma_f32_32x32x16_bf16 v[66:81], v[190:193], v[208:211], v[66:81]
	global_load_lds_dwordx4 v136, s[58:59] offset:2176
	ds_read_b128 v[190:193], v182 offset:4672
	s_waitcnt lgkmcnt(9)
	v_mfma_f32_32x32x16_bf16 v[50:65], v[196:199], v[204:207], v[50:65]
	global_load_lds_dwordx4 v137, s[58:59] offset:3200
	v_mfma_f32_32x32x16_bf16 v[34:49], v[196:199], v[208:211], v[34:49]
	global_load_dwordx4 v[130:133], v178, s[56:57] offset:128
	ds_read_b128 v[196:199], v182 offset:9280
	s_waitcnt lgkmcnt(9)
	v_mfma_f32_32x32x16_bf16 v[18:33], v[200:203], v[204:207], v[18:33]
	global_load_dwordx4 v[138:141], v179, s[56:57] offset:128
	v_mfma_f32_32x32x16_bf16 v[2:17], v[200:203], v[208:211], v[2:17]
	global_load_dwordx4 v[142:145], v180, s[56:57] offset:128
	ds_read_b128 v[200:203], v0 offset:64
	ds_read_b128 v[204:207], v168 offset:53248
	ds_read_b128 v[208:211], v168 offset:57344
	s_waitcnt lgkmcnt(10)
	v_mfma_f32_32x32x16_bf16 v[114:129], v[212:215], v[244:247], v[114:129]
	global_load_dwordx4 v[146:149], v181, s[56:57] offset:128
	s_waitcnt lgkmcnt(9)
	v_mfma_f32_32x32x16_bf16 v[98:113], v[212:215], v[248:251], v[98:113]
	global_load_dwordx4 v[150:153], v185, s[56:57] offset:128
	ds_read_b128 v[212:215], v182 offset:96
	s_waitcnt lgkmcnt(9)
	v_mfma_f32_32x32x16_bf16 v[82:97], v[216:219], v[244:247], v[82:97]
	global_load_dwordx4 v[154:157], v222, s[56:57] offset:128
	v_mfma_f32_32x32x16_bf16 v[66:81], v[216:219], v[248:251], v[66:81]
	global_load_dwordx4 v[158:161], v223, s[56:57] offset:128
	ds_read_b128 v[216:219], v182 offset:4704
	s_waitcnt lgkmcnt(9)
	v_mfma_f32_32x32x16_bf16 v[50:65], v[232:235], v[244:247], v[50:65]
	global_load_dwordx4 v[162:165], v227, s[56:57] offset:128
	v_mfma_f32_32x32x16_bf16 v[34:49], v[232:235], v[248:251], v[34:49]
	ds_read_b128 v[232:235], v182 offset:9312
	s_waitcnt lgkmcnt(9)
	v_mfma_f32_32x32x16_bf16 v[18:33], v[236:239], v[244:247], v[18:33]
	v_mfma_f32_32x32x16_bf16 v[2:17], v[236:239], v[248:251], v[2:17]
	ds_read_b128 v[236:239], v0 offset:96
	ds_read_b128 v[244:247], v169 offset:53248
	ds_read_b128 v[248:251], v169 offset:57344
	s_waitcnt lgkmcnt(7)
	v_mfma_f32_32x32x16_bf16 v[114:129], v[186:189], v[204:207], v[114:129]
	s_waitcnt lgkmcnt(6)
	v_mfma_f32_32x32x16_bf16 v[98:113], v[186:189], v[208:211], v[98:113]
	v_mfma_f32_32x32x16_bf16 v[82:97], v[190:193], v[204:207], v[82:97]
	v_mfma_f32_32x32x16_bf16 v[66:81], v[190:193], v[208:211], v[66:81]
	v_mfma_f32_32x32x16_bf16 v[50:65], v[196:199], v[204:207], v[50:65]
	v_mfma_f32_32x32x16_bf16 v[34:49], v[196:199], v[208:211], v[34:49]
	v_mfma_f32_32x32x16_bf16 v[2:17], v[200:203], v[208:211], v[2:17]
	v_mfma_f32_32x32x16_bf16 v[18:33], v[200:203], v[204:207], v[18:33]
	s_waitcnt lgkmcnt(1)
	v_mfma_f32_32x32x16_bf16 v[114:129], v[212:215], v[244:247], v[114:129]
	s_waitcnt lgkmcnt(0)
	v_mfma_f32_32x32x16_bf16 v[98:113], v[212:215], v[248:251], v[98:113]
	v_mfma_f32_32x32x16_bf16 v[82:97], v[216:219], v[244:247], v[82:97]
	v_mfma_f32_32x32x16_bf16 v[66:81], v[216:219], v[248:251], v[66:81]
	v_mfma_f32_32x32x16_bf16 v[50:65], v[232:235], v[244:247], v[50:65]
	v_mfma_f32_32x32x16_bf16 v[34:49], v[232:235], v[248:251], v[34:49]
	v_mfma_f32_32x32x16_bf16 v[18:33], v[236:239], v[244:247], v[18:33]
	v_mfma_f32_32x32x16_bf16 v[2:17], v[236:239], v[248:251], v[2:17]
	s_add_u32 s56, s56, 0x80
	s_addc_u32 s57, s57, 0
	s_add_u32 s58, s58, 0x80
	s_addc_u32 s59, s59, 0
	s_movk_i32 s94, 6
; #define MFMA(a, b, c) __builtin_amdgcn_mfma_f32_32x32x16_bf16((a), (b), (c), 0, 0, 0)
; template <int MI, int NI>
; __device__ __forceinline__ void gemm_kloop(const bf16* __restrict__ A, size_t lda, const bf16* __restrict__ Bt, size_t ldb, int K,
;                                            f16v (&acc)[MI][NI], bf16* sA, bf16* sB) {
;     ...
;   for (int kt = 0; kt < KT; ++kt) {
;     __syncthreads();
; #pragma unroll
;     for (int i = 0; i < 2 * MI; ++i) *(u4v*)(sA + (lrow + 32 * i) * 72 + lseg * 8) = ra[i];
; #pragma unroll
;     for (int i = 0; i < 2 * NI; ++i) *(u4v*)(sB + (lrow + 32 * i) * 72 + lseg * 8) = rb[i];
;     __syncthreads();
;     if (kt + 3 < KT) {
;       const int k2 = (kt + 3) << 6;
;       if (tid < 64 * MI) pfs ^= *(const unsigned*)(A + (size_t)tid * lda + k2);
;       if (tid < 64 * NI) pfs ^= *(const unsigned*)(Bt + (size_t)tid * ldb + k2);
;     }
;     if (kt + 1 < KT) {
;       const int k0 = (kt + 1) << 6;
; #pragma unroll
;       for (int i = 0; i < 2 * MI; ++i) ra[i] = *(const u4v*)(A + (size_t)(lrow + 32 * i) * lda + k0 + lseg * 8);
; #pragma unroll
;       for (int i = 0; i < 2 * NI; ++i) rb[i] = *(const u4v*)(Bt + (size_t)(lrow + 32 * i) * ldb + k0 + lseg * 8);
;     }
; #pragma unroll
;     for (int ks = 0; ks < 4; ++ks) {
;       s8v a[MI], b[NI];
; #pragma unroll
;       for (int mi = 0; mi < MI; ++mi) a[mi] = *(const s8v*)(sA + (wm * 32 * MI + mi * 32 + r) * 72 + ks * 16 + hh * 8);
; #pragma unroll
;       for (int ni = 0; ni < NI; ++ni) b[ni] = *(const s8v*)(sB + (wn * 32 * NI + ni * 32 + r) * 72 + ks * 16 + hh * 8);
; #pragma unroll
;       for (int mi = 0; mi < MI; ++mi)
; #pragma unroll
;         for (int ni = 0; ni < NI; ++ni) acc[mi][ni] = MFMA(a[mi], b[ni], acc[mi][ni]);
.Lhyb_p6_loop:
	s_barrier
	s_waitcnt vmcnt(7)
	ds_write_b128 v184, v[130:133]
	s_waitcnt vmcnt(6)
	ds_write_b128 v184, v[138:141] offset:4608
	s_waitcnt vmcnt(5)
	ds_write_b128 v184, v[142:145] offset:9216
	s_waitcnt vmcnt(4)
	ds_write_b128 v184, v[146:149] offset:13824
	s_waitcnt vmcnt(3)
	ds_write_b128 v184, v[150:153] offset:18432
	s_waitcnt vmcnt(2)
	ds_write_b128 v184, v[154:157] offset:23040
	s_waitcnt vmcnt(1)
	ds_write_b128 v184, v[158:161] offset:27648
	s_waitcnt vmcnt(0)
	ds_write_b128 v184, v[162:165] offset:32256
	s_waitcnt lgkmcnt(0)
	s_barrier
	ds_read_b128 v[186:189], v182
	ds_read_b128 v[204:207], v166 offset:36864
	ds_read_b128 v[208:211], v166 offset:40960
	ds_read_b128 v[190:193], v182 offset:4608
	ds_read_b128 v[196:199], v182 offset:9216
	ds_read_b128 v[200:203], v0
	ds_read_b128 v[212:215], v182 offset:32
	ds_read_b128 v[244:247], v167 offset:36864
	ds_read_b128 v[248:251], v167 offset:40960
	ds_read_b128 v[216:219], v182 offset:4640
	ds_read_b128 v[232:235], v182 offset:9248
	ds_read_b128 v[236:239], v0 offset:32
	s_waitcnt lgkmcnt(10)
	v_mfma_f32_32x32x16_bf16 v[114:129], v[186:189], v[204:207], v[114:129]
	s_add_u32 m0, s96, 16256
	s_nop 0
	s_waitcnt lgkmcnt(9)
	v_mfma_f32_32x32x16_bf16 v[98:113], v[186:189], v[208:211], v[98:113]
	global_load_lds_dwordx4 v134, s[58:59] offset:128
	ds_read_b128 v[186:189], v182 offset:64
	s_waitcnt lgkmcnt(9)
	v_mfma_f32_32x32x16_bf16 v[82:97], v[190:193], v[204:207], v[82:97]
	global_load_lds_dwordx4 v135, s[58:59] offset:1152
	v_mfma_f32_32x32x16_bf16 v[66:81], v[190:193], v[208:211], v[66:81]
	global_load_lds_dwordx4 v136, s[58:59] offset:2176
	ds_read_b128 v[190:193], v182 offset:4672
	s_waitcnt lgkmcnt(9)
	v_mfma_f32_32x32x16_bf16 v[50:65], v[196:199], v[204:207], v[50:65]
	global_load_lds_dwordx4 v137, s[58:59] offset:3200
	v_mfma_f32_32x32x16_bf16 v[34:49], v[196:199], v[208:211], v[34:49]
	global_load_dwordx4 v[130:133], v178, s[56:57] offset:128
	ds_read_b128 v[196:199], v182 offset:9280
	s_waitcnt lgkmcnt(9)
	v_mfma_f32_32x32x16_bf16 v[18:33], v[200:203], v[204:207], v[18:33]
	global_load_dwordx4 v[138:141], v179, s[56:57] offset:128
	v_mfma_f32_32x32x16_bf16 v[2:17], v[200:203], v[208:211], v[2:17]
	global_load_dwordx4 v[142:145], v180, s[56:57] offset:128
	ds_read_b128 v[200:203], v0 offset:64
	ds_read_b128 v[204:207], v168 offset:36864
	ds_read_b128 v[208:211], v168 offset:40960
	s_waitcnt lgkmcnt(10)
	v_mfma_f32_32x32x16_bf16 v[114:129], v[212:215], v[244:247], v[114:129]
	global_load_dwordx4 v[146:149], v181, s[56:57] offset:128
	s_waitcnt lgkmcnt(9)
	v_mfma_f32_32x32x16_bf16 v[98:113], v[212:215], v[248:251], v[98:113]
	global_load_dwordx4 v[150:153], v185, s[56:57] offset:128
	ds_read_b128 v[212:215], v182 offset:96
	s_waitcnt lgkmcnt(9)
	v_mfma_f32_32x32x16_bf16 v[82:97], v[216:219], v[244:247], v[82:97]
	global_load_dwordx4 v[154:157], v222, s[56:57] offset:128
	v_mfma_f32_32x32x16_bf16 v[66:81], v[216:219], v[248:251], v[66:81]
	global_load_dwordx4 v[158:161], v223, s[56:57] offset:128
	ds_read_b128 v[216:219], v182 offset:4704
	s_waitcnt lgkmcnt(9)
	v_mfma_f32_32x32x16_bf16 v[50:65], v[232:235], v[244:247], v[50:65]
	global_load_dwordx4 v[162:165], v227, s[56:57] offset:128
	v_mfma_f32_32x32x16_bf16 v[34:49], v[232:235], v[248:251], v[34:49]
	ds_read_b128 v[232:235], v182 offset:9312
	s_waitcnt lgkmcnt(9)
	v_mfma_f32_32x32x16_bf16 v[18:33], v[236:239], v[244:247], v[18:33]
	v_mfma_f32_32x32x16_bf16 v[2:17], v[236:239], v[248:251], v[2:17]
	ds_read_b128 v[236:239], v0 offset:96
	ds_read_b128 v[244:247], v169 offset:36864
	ds_read_b128 v[248:251], v169 offset:40960
	s_waitcnt lgkmcnt(7)
	v_mfma_f32_32x32x16_bf16 v[114:129], v[186:189], v[204:207], v[114:129]
	s_waitcnt lgkmcnt(6)
	v_mfma_f32_32x32x16_bf16 v[98:113], v[186:189], v[208:211], v[98:113]
	v_mfma_f32_32x32x16_bf16 v[82:97], v[190:193], v[204:207], v[82:97]
	v_mfma_f32_32x32x16_bf16 v[66:81], v[190:193], v[208:211], v[66:81]
	v_mfma_f32_32x32x16_bf16 v[50:65], v[196:199], v[204:207], v[50:65]
	v_mfma_f32_32x32x16_bf16 v[34:49], v[196:199], v[208:211], v[34:49]
	v_mfma_f32_32x32x16_bf16 v[2:17], v[200:203], v[208:211], v[2:17]
	v_mfma_f32_32x32x16_bf16 v[18:33], v[200:203], v[204:207], v[18:33]
	s_waitcnt lgkmcnt(1)
	v_mfma_f32_32x32x16_bf16 v[114:129], v[212:215], v[244:247], v[114:129]
	s_waitcnt lgkmcnt(0)
	v_mfma_f32_32x32x16_bf16 v[98:113], v[212:215], v[248:251], v[98:113]
	v_mfma_f32_32x32x16_bf16 v[82:97], v[216:219], v[244:247], v[82:97]
	v_mfma_f32_32x32x16_bf16 v[66:81], v[216:219], v[248:251], v[66:81]
	v_mfma_f32_32x32x16_bf16 v[50:65], v[232:235], v[244:247], v[50:65]
	v_mfma_f32_32x32x16_bf16 v[34:49], v[232:235], v[248:251], v[34:49]
	v_mfma_f32_32x32x16_bf16 v[18:33], v[236:239], v[244:247], v[18:33]
	v_mfma_f32_32x32x16_bf16 v[2:17], v[236:239], v[248:251], v[2:17]
	s_add_u32 s56, s56, 0x80
	s_addc_u32 s57, s57, 0
	s_add_u32 s58, s58, 0x80
	s_addc_u32 s59, s59, 0
	s_barrier
	s_waitcnt vmcnt(7)
	ds_write_b128 v184, v[130:133]
	s_waitcnt vmcnt(6)
	ds_write_b128 v184, v[138:141] offset:4608
	s_waitcnt vmcnt(5)
	ds_write_b128 v184, v[142:145] offset:9216
	s_waitcnt vmcnt(4)
	ds_write_b128 v184, v[146:149] offset:13824
	s_waitcnt vmcnt(3)
	ds_write_b128 v184, v[150:153] offset:18432
	s_waitcnt vmcnt(2)
	ds_write_b128 v184, v[154:157] offset:23040
	s_waitcnt vmcnt(1)
	ds_write_b128 v184, v[158:161] offset:27648
	s_waitcnt vmcnt(0)
	ds_write_b128 v184, v[162:165] offset:32256
	s_waitcnt lgkmcnt(0)
	s_barrier
; #define MFMA(a, b, c) __builtin_amdgcn_mfma_f32_32x32x16_bf16((a), (b), (c), 0, 0, 0)
; template <int MI, int NI>
; __device__ __forceinline__ void gemm_kloop(const bf16* __restrict__ A, size_t lda, const bf16* __restrict__ Bt, size_t ldb, int K,
;                                            f16v (&acc)[MI][NI], bf16* sA, bf16* sB) {
;     ...
;   for (int kt = 0; kt < KT; ++kt) {
;     __syncthreads();
; #pragma unroll
;     for (int i = 0; i < 2 * MI; ++i) *(u4v*)(sA + (lrow + 32 * i) * 72 + lseg * 8) = ra[i];
; #pragma unroll
;     for (int i = 0; i < 2 * NI; ++i) *(u4v*)(sB + (lrow + 32 * i) * 72 + lseg * 8) = rb[i];
;     __syncthreads();
;     if (kt + 3 < KT) {
;       const int k2 = (kt + 3) << 6;
;       if (tid < 64 * MI) pfs ^= *(const unsigned*)(A + (size_t)tid * lda + k2);
;       if (tid < 64 * NI) pfs ^= *(const unsigned*)(Bt + (size_t)tid * ldb + k2);
;     }
;     if (kt + 1 < KT) {
;       const int k0 = (kt + 1) << 6;
; #pragma unroll
;       for (int i = 0; i < 2 * MI; ++i) ra[i] = *(const u4v*)(A + (size_t)(lrow + 32 * i) * lda + k0 + lseg * 8);
; #pragma unroll
;       for (int i = 0; i < 2 * NI; ++i) rb[i] = *(const u4v*)(Bt + (size_t)(lrow + 32 * i) * ldb + k0 + lseg * 8);
;     }
; #pragma unroll
;     for (int ks = 0; ks < 4; ++ks) {
;       s8v a[MI], b[NI];
; #pragma unroll
;       for (int mi = 0; mi < MI; ++mi) a[mi] = *(const s8v*)(sA + (wm * 32 * MI + mi * 32 + r) * 72 + ks * 16 + hh * 8);
; #pragma unroll
;       for (int ni = 0; ni < NI; ++ni) b[ni] = *(const s8v*)(sB + (wn * 32 * NI + ni * 32 + r) * 72 + ks * 16 + hh * 8);
; #pragma unroll
;       for (int mi = 0; mi < MI; ++mi)
; #pragma unroll
;         for (int ni = 0; ni < NI; ++ni) acc[mi][ni] = MFMA(a[mi], b[ni], acc[mi][ni]);
	ds_read_b128 v[186:189], v182
	ds_read_b128 v[204:207], v166 offset:53248
	ds_read_b128 v[208:211], v166 offset:57344
	ds_read_b128 v[190:193], v182 offset:4608
	ds_read_b128 v[196:199], v182 offset:9216
	ds_read_b128 v[200:203], v0
	ds_read_b128 v[212:215], v182 offset:32
	ds_read_b128 v[244:247], v167 offset:53248
	ds_read_b128 v[248:251], v167 offset:57344
	ds_read_b128 v[216:219], v182 offset:4640
	ds_read_b128 v[232:235], v182 offset:9248
	ds_read_b128 v[236:239], v0 offset:32
	s_waitcnt lgkmcnt(10)
	v_mfma_f32_32x32x16_bf16 v[114:129], v[186:189], v[204:207], v[114:129]
	s_add_u32 m0, s96, -128
	s_nop 0
	s_waitcnt lgkmcnt(9)
	v_mfma_f32_32x32x16_bf16 v[98:113], v[186:189], v[208:211], v[98:113]
	global_load_lds_dwordx4 v134, s[58:59] offset:128
	ds_read_b128 v[186:189], v182 offset:64
	s_waitcnt lgkmcnt(9)
	v_mfma_f32_32x32x16_bf16 v[82:97], v[190:193], v[204:207], v[82:97]
	global_load_lds_dwordx4 v135, s[58:59] offset:1152
	v_mfma_f32_32x32x16_bf16 v[66:81], v[190:193], v[208:211], v[66:81]
	global_load_lds_dwordx4 v136, s[58:59] offset:2176
	ds_read_b128 v[190:193], v182 offset:4672
	s_waitcnt lgkmcnt(9)
	v_mfma_f32_32x32x16_bf16 v[50:65], v[196:199], v[204:207], v[50:65]
	global_load_lds_dwordx4 v137, s[58:59] offset:3200
	v_mfma_f32_32x32x16_bf16 v[34:49], v[196:199], v[208:211], v[34:49]
	global_load_dwordx4 v[130:133], v178, s[56:57] offset:128
	ds_read_b128 v[196:199], v182 offset:9280
	s_waitcnt lgkmcnt(9)
	v_mfma_f32_32x32x16_bf16 v[18:33], v[200:203], v[204:207], v[18:33]
	global_load_dwordx4 v[138:141], v179, s[56:57] offset:128
	v_mfma_f32_32x32x16_bf16 v[2:17], v[200:203], v[208:211], v[2:17]
	global_load_dwordx4 v[142:145], v180, s[56:57] offset:128
	ds_read_b128 v[200:203], v0 offset:64
	ds_read_b128 v[204:207], v168 offset:53248
	ds_read_b128 v[208:211], v168 offset:57344
	s_waitcnt lgkmcnt(10)
	v_mfma_f32_32x32x16_bf16 v[114:129], v[212:215], v[244:247], v[114:129]
	global_load_dwordx4 v[146:149], v181, s[56:57] offset:128
	s_waitcnt lgkmcnt(9)
	v_mfma_f32_32x32x16_bf16 v[98:113], v[212:215], v[248:251], v[98:113]
	global_load_dwordx4 v[150:153], v185, s[56:57] offset:128
	ds_read_b128 v[212:215], v182 offset:96
	s_waitcnt lgkmcnt(9)
	v_mfma_f32_32x32x16_bf16 v[82:97], v[216:219], v[244:247], v[82:97]
	global_load_dwordx4 v[154:157], v222, s[56:57] offset:128
	v_mfma_f32_32x32x16_bf16 v[66:81], v[216:219], v[248:251], v[66:81]
	global_load_dwordx4 v[158:161], v223, s[56:57] offset:128
	ds_read_b128 v[216:219], v182 offset:4704
	s_waitcnt lgkmcnt(9)
	v_mfma_f32_32x32x16_bf16 v[50:65], v[232:235], v[244:247], v[50:65]
	global_load_dwordx4 v[162:165], v227, s[56:57] offset:128
	v_mfma_f32_32x32x16_bf16 v[34:49], v[232:235], v[248:251], v[34:49]
	ds_read_b128 v[232:235], v182 offset:9312
	s_waitcnt lgkmcnt(9)
	v_mfma_f32_32x32x16_bf16 v[18:33], v[236:239], v[244:247], v[18:33]
	v_mfma_f32_32x32x16_bf16 v[2:17], v[236:239], v[248:251], v[2:17]
	ds_read_b128 v[236:239], v0 offset:96
	ds_read_b128 v[244:247], v169 offset:53248
	ds_read_b128 v[248:251], v169 offset:57344
	s_waitcnt lgkmcnt(7)
	v_mfma_f32_32x32x16_bf16 v[114:129], v[186:189], v[204:207], v[114:129]
	s_waitcnt lgkmcnt(6)
	v_mfma_f32_32x32x16_bf16 v[98:113], v[186:189], v[208:211], v[98:113]
	v_mfma_f32_32x32x16_bf16 v[82:97], v[190:193], v[204:207], v[82:97]
	v_mfma_f32_32x32x16_bf16 v[66:81], v[190:193], v[208:211], v[66:81]
	v_mfma_f32_32x32x16_bf16 v[50:65], v[196:199], v[204:207], v[50:65]
	v_mfma_f32_32x32x16_bf16 v[34:49], v[196:199], v[208:211], v[34:49]
	v_mfma_f32_32x32x16_bf16 v[2:17], v[200:203], v[208:211], v[2:17]
	v_mfma_f32_32x32x16_bf16 v[18:33], v[200:203], v[204:207], v[18:33]
	s_waitcnt lgkmcnt(1)
	v_mfma_f32_32x32x16_bf16 v[114:129], v[212:215], v[244:247], v[114:129]
	s_waitcnt lgkmcnt(0)
	v_mfma_f32_32x32x16_bf16 v[98:113], v[212:215], v[248:251], v[98:113]
	v_mfma_f32_32x32x16_bf16 v[82:97], v[216:219], v[244:247], v[82:97]
	v_mfma_f32_32x32x16_bf16 v[66:81], v[216:219], v[248:251], v[66:81]
	v_mfma_f32_32x32x16_bf16 v[50:65], v[232:235], v[244:247], v[50:65]
	v_mfma_f32_32x32x16_bf16 v[34:49], v[232:235], v[248:251], v[34:49]
	v_mfma_f32_32x32x16_bf16 v[18:33], v[236:239], v[244:247], v[18:33]
	v_mfma_f32_32x32x16_bf16 v[2:17], v[236:239], v[248:251], v[2:17]
	s_add_u32 s56, s56, 0x80
	s_addc_u32 s57, s57, 0
	s_add_u32 s58, s58, 0x80
	s_addc_u32 s59, s59, 0
	s_sub_u32 s94, s94, 1
	s_cmp_lg_u32 s94, 0
	s_cbranch_scc1 .Lhyb_p6_loop
	s_barrier
	s_waitcnt vmcnt(7)
	ds_write_b128 v184, v[130:133]
	s_waitcnt vmcnt(6)
	ds_write_b128 v184, v[138:141] offset:4608
	s_waitcnt vmcnt(5)
	ds_write_b128 v184, v[142:145] offset:9216
	s_waitcnt vmcnt(4)
	ds_write_b128 v184, v[146:149] offset:13824
	s_waitcnt vmcnt(3)
	ds_write_b128 v184, v[150:153] offset:18432
	s_waitcnt vmcnt(2)
	ds_write_b128 v184, v[154:157] offset:23040
	s_waitcnt vmcnt(1)
	ds_write_b128 v184, v[158:161] offset:27648
	s_waitcnt vmcnt(0)
	ds_write_b128 v184, v[162:165] offset:32256
	s_waitcnt lgkmcnt(0)
	s_barrier
; #define MFMA(a, b, c) __builtin_amdgcn_mfma_f32_32x32x16_bf16((a), (b), (c), 0, 0, 0)
; template <int MI, int NI>
; __device__ __forceinline__ void gemm_kloop(const bf16* __restrict__ A, size_t lda, const bf16* __restrict__ Bt, size_t ldb, int K,
;                                            f16v (&acc)[MI][NI], bf16* sA, bf16* sB) {
;     ...
;   for (int kt = 0; kt < KT; ++kt) {
;     __syncthreads();
; #pragma unroll
;     for (int i = 0; i < 2 * MI; ++i) *(u4v*)(sA + (lrow + 32 * i) * 72 + lseg * 8) = ra[i];
; #pragma unroll
;     for (int i = 0; i < 2 * NI; ++i) *(u4v*)(sB + (lrow + 32 * i) * 72 + lseg * 8) = rb[i];
;     __syncthreads();
;     if (kt + 3 < KT) {
;       const int k2 = (kt + 3) << 6;
;       if (tid < 64 * MI) pfs ^= *(const unsigned*)(A + (size_t)tid * lda + k2);
;       if (tid < 64 * NI) pfs ^= *(const unsigned*)(Bt + (size_t)tid * ldb + k2);
;     }
;     if (kt + 1 < KT) {
;       const int k0 = (kt + 1) << 6;
; #pragma unroll
;       for (int i = 0; i < 2 * MI; ++i) ra[i] = *(const u4v*)(A + (size_t)(lrow + 32 * i) * lda + k0 + lseg * 8);
; #pragma unroll
;       for (int i = 0; i < 2 * NI; ++i) rb[i] = *(const u4v*)(Bt + (size_t)(lrow + 32 * i) * ldb + k0 + lseg * 8);
;     }
; #pragma unroll
;     for (int ks = 0; ks < 4; ++ks) {
;       s8v a[MI], b[NI];
; #pragma unroll
;       for (int mi = 0; mi < MI; ++mi) a[mi] = *(const s8v*)(sA + (wm * 32 * MI + mi * 32 + r) * 72 + ks * 16 + hh * 8);
; #pragma unroll
;       for (int ni = 0; ni < NI; ++ni) b[ni] = *(const s8v*)(sB + (wn * 32 * NI + ni * 32 + r) * 72 + ks * 16 + hh * 8);
; #pragma unroll
;       for (int mi = 0; mi < MI; ++mi)
; #pragma unroll
;         for (int ni = 0; ni < NI; ++ni) acc[mi][ni] = MFMA(a[mi], b[ni], acc[mi][ni]);
	ds_read_b128 v[186:189], v182
	ds_read_b128 v[204:207], v166 offset:36864
	ds_read_b128 v[208:211], v166 offset:40960
	ds_read_b128 v[190:193], v182 offset:4608
	ds_read_b128 v[196:199], v182 offset:9216
	ds_read_b128 v[200:203], v0
	ds_read_b128 v[212:215], v182 offset:32
	ds_read_b128 v[244:247], v167 offset:36864
	ds_read_b128 v[248:251], v167 offset:40960
	ds_read_b128 v[216:219], v182 offset:4640
	ds_read_b128 v[232:235], v182 offset:9248
	ds_read_b128 v[236:239], v0 offset:32
	s_waitcnt lgkmcnt(10)
	v_mfma_f32_32x32x16_bf16 v[114:129], v[186:189], v[204:207], v[114:129]
	s_add_u32 m0, s96, 16256
	s_nop 0
	s_waitcnt lgkmcnt(9)
	v_mfma_f32_32x32x16_bf16 v[98:113], v[186:189], v[208:211], v[98:113]
	global_load_lds_dwordx4 v134, s[58:59] offset:128
	ds_read_b128 v[186:189], v182 offset:64
	s_waitcnt lgkmcnt(9)
	v_mfma_f32_32x32x16_bf16 v[82:97], v[190:193], v[204:207], v[82:97]
	global_load_lds_dwordx4 v135, s[58:59] offset:1152
	v_mfma_f32_32x32x16_bf16 v[66:81], v[190:193], v[208:211], v[66:81]
	global_load_lds_dwordx4 v136, s[58:59] offset:2176
	ds_read_b128 v[190:193], v182 offset:4672
	s_waitcnt lgkmcnt(9)
	v_mfma_f32_32x32x16_bf16 v[50:65], v[196:199], v[204:207], v[50:65]
	global_load_lds_dwordx4 v137, s[58:59] offset:3200
	v_mfma_f32_32x32x16_bf16 v[34:49], v[196:199], v[208:211], v[34:49]
	global_load_dwordx4 v[130:133], v178, s[56:57] offset:128
	ds_read_b128 v[196:199], v182 offset:9280
	s_waitcnt lgkmcnt(9)
	v_mfma_f32_32x32x16_bf16 v[18:33], v[200:203], v[204:207], v[18:33]
	global_load_dwordx4 v[138:141], v179, s[56:57] offset:128
	v_mfma_f32_32x32x16_bf16 v[2:17], v[200:203], v[208:211], v[2:17]
	global_load_dwordx4 v[142:145], v180, s[56:57] offset:128
	ds_read_b128 v[200:203], v0 offset:64
	ds_read_b128 v[204:207], v168 offset:36864
	ds_read_b128 v[208:211], v168 offset:40960
	s_waitcnt lgkmcnt(10)
	v_mfma_f32_32x32x16_bf16 v[114:129], v[212:215], v[244:247], v[114:129]
	global_load_dwordx4 v[146:149], v181, s[56:57] offset:128
	s_waitcnt lgkmcnt(9)
	v_mfma_f32_32x32x16_bf16 v[98:113], v[212:215], v[248:251], v[98:113]
	global_load_dwordx4 v[150:153], v185, s[56:57] offset:128
	ds_read_b128 v[212:215], v182 offset:96
	s_waitcnt lgkmcnt(9)
	v_mfma_f32_32x32x16_bf16 v[82:97], v[216:219], v[244:247], v[82:97]
	global_load_dwordx4 v[154:157], v222, s[56:57] offset:128
	v_mfma_f32_32x32x16_bf16 v[66:81], v[216:219], v[248:251], v[66:81]
	global_load_dwordx4 v[158:161], v223, s[56:57] offset:128
	ds_read_b128 v[216:219], v182 offset:4704
	s_waitcnt lgkmcnt(9)
	v_mfma_f32_32x32x16_bf16 v[50:65], v[232:235], v[244:247], v[50:65]
	global_load_dwordx4 v[162:165], v227, s[56:57] offset:128
	v_mfma_f32_32x32x16_bf16 v[34:49], v[232:235], v[248:251], v[34:49]
	ds_read_b128 v[232:235], v182 offset:9312
	s_waitcnt lgkmcnt(9)
	v_mfma_f32_32x32x16_bf16 v[18:33], v[236:239], v[244:247], v[18:33]
	v_mfma_f32_32x32x16_bf16 v[2:17], v[236:239], v[248:251], v[2:17]
	ds_read_b128 v[236:239], v0 offset:96
	ds_read_b128 v[244:247], v169 offset:36864
	ds_read_b128 v[248:251], v169 offset:40960
	s_waitcnt lgkmcnt(7)
	v_mfma_f32_32x32x16_bf16 v[114:129], v[186:189], v[204:207], v[114:129]
	s_waitcnt lgkmcnt(6)
	v_mfma_f32_32x32x16_bf16 v[98:113], v[186:189], v[208:211], v[98:113]
	v_mfma_f32_32x32x16_bf16 v[82:97], v[190:193], v[204:207], v[82:97]
	v_mfma_f32_32x32x16_bf16 v[66:81], v[190:193], v[208:211], v[66:81]
	v_mfma_f32_32x32x16_bf16 v[50:65], v[196:199], v[204:207], v[50:65]
	v_mfma_f32_32x32x16_bf16 v[34:49], v[196:199], v[208:211], v[34:49]
	v_mfma_f32_32x32x16_bf16 v[2:17], v[200:203], v[208:211], v[2:17]
	v_mfma_f32_32x32x16_bf16 v[18:33], v[200:203], v[204:207], v[18:33]
	s_waitcnt lgkmcnt(1)
	v_mfma_f32_32x32x16_bf16 v[114:129], v[212:215], v[244:247], v[114:129]
	s_waitcnt lgkmcnt(0)
	v_mfma_f32_32x32x16_bf16 v[98:113], v[212:215], v[248:251], v[98:113]
	v_mfma_f32_32x32x16_bf16 v[82:97], v[216:219], v[244:247], v[82:97]
	v_mfma_f32_32x32x16_bf16 v[66:81], v[216:219], v[248:251], v[66:81]
	v_mfma_f32_32x32x16_bf16 v[50:65], v[232:235], v[244:247], v[50:65]
	v_mfma_f32_32x32x16_bf16 v[34:49], v[232:235], v[248:251], v[34:49]
	v_mfma_f32_32x32x16_bf16 v[18:33], v[236:239], v[244:247], v[18:33]
	v_mfma_f32_32x32x16_bf16 v[2:17], v[236:239], v[248:251], v[2:17]
	s_add_u32 s56, s56, 0x80
	s_addc_u32 s57, s57, 0
	s_add_u32 s58, s58, 0x80
	s_addc_u32 s59, s59, 0
	s_barrier
; #define MFMA(a, b, c) __builtin_amdgcn_mfma_f32_32x32x16_bf16((a), (b), (c), 0, 0, 0)
; template <int MI, int NI>
; __device__ __forceinline__ void gemm_kloop(const bf16* __restrict__ A, size_t lda, const bf16* __restrict__ Bt, size_t ldb, int K,
;                                            f16v (&acc)[MI][NI], bf16* sA, bf16* sB) {
;     ...
;   for (int kt = 0; kt < KT; ++kt) {
;     __syncthreads();
; #pragma unroll
;     for (int i = 0; i < 2 * MI; ++i) *(u4v*)(sA + (lrow + 32 * i) * 72 + lseg * 8) = ra[i];
; #pragma unroll
;     for (int i = 0; i < 2 * NI; ++i) *(u4v*)(sB + (lrow + 32 * i) * 72 + lseg * 8) = rb[i];
;     __syncthreads();
;     if (kt + 3 < KT) {
;       const int k2 = (kt + 3) << 6;
;       if (tid < 64 * MI) pfs ^= *(const unsigned*)(A + (size_t)tid * lda + k2);
;       if (tid < 64 * NI) pfs ^= *(const unsigned*)(Bt + (size_t)tid * ldb + k2);
;     }
;     if (kt + 1 < KT) {
;       const int k0 = (kt + 1) << 6;
; #pragma unroll
;       for (int i = 0; i < 2 * MI; ++i) ra[i] = *(const u4v*)(A + (size_t)(lrow + 32 * i) * lda + k0 + lseg * 8);
; #pragma unroll
;       for (int i = 0; i < 2 * NI; ++i) rb[i] = *(const u4v*)(Bt + (size_t)(lrow + 32 * i) * ldb + k0 + lseg * 8);
;     }
; #pragma unroll
;     for (int ks = 0; ks < 4; ++ks) {
;       s8v a[MI], b[NI];
; #pragma unroll
;       for (int mi = 0; mi < MI; ++mi) a[mi] = *(const s8v*)(sA + (wm * 32 * MI + mi * 32 + r) * 72 + ks * 16 + hh * 8);
; #pragma unroll
;       for (int ni = 0; ni < NI; ++ni) b[ni] = *(const s8v*)(sB + (wn * 32 * NI + ni * 32 + r) * 72 + ks * 16 + hh * 8);
; #pragma unroll
;       for (int mi = 0; mi < MI; ++mi)
; #pragma unroll
;         for (int ni = 0; ni < NI; ++ni) acc[mi][ni] = MFMA(a[mi], b[ni], acc[mi][ni]);
; __device__ __forceinline__ void resid_tile(const Params& p, const bf16* A, size_t lda, const bf16* Bt, int K, int mt, int nt, bool x_from_input, bf16* sA, bf16* sB, int dry) {
;     ...
;   const int lane = tid_opaque() & 63, w = tid_opaque() >> 6, r = lane & 31, hh = lane >> 5, wm = w >> 1, wn = w & 1;
; #pragma unroll
;   for (int mi = 0; mi < 4; ++mi)
; #pragma unroll
;     for (int ni = 0; ni < 2; ++ni) {
;       __builtin_amdgcn_sched_barrier(0);
; #pragma unroll
;       for (int e = 0; e < 16; ++e) {
;         const int t = m0 + wm * 128 + mi * 32 + ROW_OF(e, hh);
;         const int c = n0 + wn * 64 + ni * 32 + r;
	s_waitcnt vmcnt(7)
	ds_write_b128 v184, v[130:133]
	s_waitcnt vmcnt(6)
	ds_write_b128 v184, v[138:141] offset:4608
	s_waitcnt vmcnt(5)
	ds_write_b128 v184, v[142:145] offset:9216
	s_waitcnt vmcnt(4)
	ds_write_b128 v184, v[146:149] offset:13824
	s_waitcnt vmcnt(3)
	ds_write_b128 v184, v[150:153] offset:18432
	s_waitcnt vmcnt(2)
	ds_write_b128 v184, v[154:157] offset:23040
	s_waitcnt vmcnt(1)
	ds_write_b128 v184, v[158:161] offset:27648
	s_waitcnt vmcnt(0)
	ds_write_b128 v184, v[162:165] offset:32256
	s_waitcnt lgkmcnt(0)
	s_barrier
	ds_read_b128 v[186:189], v182
	ds_read_b128 v[204:207], v166 offset:53248
	ds_read_b128 v[208:211], v166 offset:57344
	ds_read_b128 v[190:193], v182 offset:4608
	ds_read_b128 v[196:199], v182 offset:9216
	ds_read_b128 v[200:203], v0
	ds_read_b128 v[212:215], v182 offset:32
	ds_read_b128 v[244:247], v167 offset:53248
	ds_read_b128 v[248:251], v167 offset:57344
	ds_read_b128 v[216:219], v182 offset:4640
	ds_read_b128 v[232:235], v182 offset:9248
	ds_read_b128 v[236:239], v0 offset:32
	s_waitcnt lgkmcnt(10)
	v_mfma_f32_32x32x16_bf16 v[114:129], v[186:189], v[204:207], v[114:129]
	s_waitcnt lgkmcnt(9)
	v_mfma_f32_32x32x16_bf16 v[98:113], v[186:189], v[208:211], v[98:113]
	ds_read_b128 v[186:189], v182 offset:64
	s_waitcnt lgkmcnt(9)
	v_mfma_f32_32x32x16_bf16 v[82:97], v[190:193], v[204:207], v[82:97]
	v_mfma_f32_32x32x16_bf16 v[66:81], v[190:193], v[208:211], v[66:81]
	ds_read_b128 v[190:193], v182 offset:4672
	s_waitcnt lgkmcnt(9)
	v_mfma_f32_32x32x16_bf16 v[50:65], v[196:199], v[204:207], v[50:65]
	v_mfma_f32_32x32x16_bf16 v[34:49], v[196:199], v[208:211], v[34:49]
	ds_read_b128 v[196:199], v182 offset:9280
	s_waitcnt lgkmcnt(9)
	v_mfma_f32_32x32x16_bf16 v[18:33], v[200:203], v[204:207], v[18:33]
	v_mfma_f32_32x32x16_bf16 v[2:17], v[200:203], v[208:211], v[2:17]
	ds_read_b128 v[200:203], v0 offset:64
	ds_read_b128 v[204:207], v168 offset:53248
	ds_read_b128 v[208:211], v168 offset:57344
	s_waitcnt lgkmcnt(10)
	v_mfma_f32_32x32x16_bf16 v[114:129], v[212:215], v[244:247], v[114:129]
	s_waitcnt lgkmcnt(9)
	v_mfma_f32_32x32x16_bf16 v[98:113], v[212:215], v[248:251], v[98:113]
	ds_read_b128 v[212:215], v182 offset:96
	s_waitcnt lgkmcnt(9)
	v_mfma_f32_32x32x16_bf16 v[82:97], v[216:219], v[244:247], v[82:97]
	v_mfma_f32_32x32x16_bf16 v[66:81], v[216:219], v[248:251], v[66:81]
	ds_read_b128 v[216:219], v182 offset:4704
	s_waitcnt lgkmcnt(9)
	v_mfma_f32_32x32x16_bf16 v[50:65], v[232:235], v[244:247], v[50:65]
	v_mfma_f32_32x32x16_bf16 v[34:49], v[232:235], v[248:251], v[34:49]
	ds_read_b128 v[232:235], v182 offset:9312
	s_waitcnt lgkmcnt(9)
	v_mfma_f32_32x32x16_bf16 v[18:33], v[236:239], v[244:247], v[18:33]
	v_mfma_f32_32x32x16_bf16 v[2:17], v[236:239], v[248:251], v[2:17]
	ds_read_b128 v[236:239], v0 offset:96
	ds_read_b128 v[244:247], v169 offset:53248
	ds_read_b128 v[248:251], v169 offset:57344
	s_waitcnt lgkmcnt(7)
	v_mfma_f32_32x32x16_bf16 v[114:129], v[186:189], v[204:207], v[114:129]
	s_waitcnt lgkmcnt(6)
	v_mfma_f32_32x32x16_bf16 v[98:113], v[186:189], v[208:211], v[98:113]
	v_mfma_f32_32x32x16_bf16 v[82:97], v[190:193], v[204:207], v[82:97]
	v_mfma_f32_32x32x16_bf16 v[66:81], v[190:193], v[208:211], v[66:81]
	v_mfma_f32_32x32x16_bf16 v[50:65], v[196:199], v[204:207], v[50:65]
	v_mfma_f32_32x32x16_bf16 v[34:49], v[196:199], v[208:211], v[34:49]
	v_mfma_f32_32x32x16_bf16 v[2:17], v[200:203], v[208:211], v[2:17]
	v_mfma_f32_32x32x16_bf16 v[18:33], v[200:203], v[204:207], v[18:33]
	s_waitcnt lgkmcnt(1)
	v_mfma_f32_32x32x16_bf16 v[114:129], v[212:215], v[244:247], v[114:129]
	s_waitcnt lgkmcnt(0)
	v_mfma_f32_32x32x16_bf16 v[98:113], v[212:215], v[248:251], v[98:113]
	v_mfma_f32_32x32x16_bf16 v[82:97], v[216:219], v[244:247], v[82:97]
	v_mfma_f32_32x32x16_bf16 v[66:81], v[216:219], v[248:251], v[66:81]
	v_mfma_f32_32x32x16_bf16 v[50:65], v[232:235], v[244:247], v[50:65]
	v_mfma_f32_32x32x16_bf16 v[34:49], v[232:235], v[248:251], v[34:49]
	v_mfma_f32_32x32x16_bf16 v[18:33], v[236:239], v[244:247], v[18:33]
	v_mfma_f32_32x32x16_bf16 v[2:17], v[236:239], v[248:251], v[2:17]
	s_nop 15
	v_mov_b32_e32 v0, v195
	v_mov_b32_e32 v130, v195
	v_and_b32_e32 v131, 31, v0
	v_and_b32_e32 v132, 64, v130
	v_and_b32_e32 v130, 0xffffff80, v130
	v_lshrrev_b32_e32 v0, 3, v0
	v_add_u32_e32 v243, s22, v130
	v_and_b32_e32 v244, 4, v0
	v_or3_b32 v130, v131, v132, s20
	v_or_b32_e32 v0, v243, v244
	v_lshlrev_b32_e32 v0, 12, v0
	v_lshl_add_u32 v0, v130, 2, v0
	s_mov_b64 s[20:21], s[8:9]
	s_cmp_lg_u64 s[2:3], 0
	s_cbranch_scc1 .Lr6_src_done
	v_readlane_b32 s20, v252, 58
	v_readlane_b32 s21, v252, 59
	s_cmp_lt_u32 s22, 0x4000
	s_cbranch_scc1 .Lr6_src_done
	v_readlane_b32 s20, v252, 60
	v_readlane_b32 s21, v252, 61
	s_nop 0
	s_sub_u32 s20, s20, 0x4000000
	s_subb_u32 s21, s21, 0

; #define ZERO_ACC(acc, MI_, NI_)                 \
;   _Pragma("unroll") for (int mi = 0; mi < MI_; ++mi) \
;   _Pragma("unroll") for (int ni = 0; ni < NI_; ++ni) \
;   _Pragma("unroll") for (int e = 0; e < 16; ++e) acc[mi][ni][e] = 0.f;
; __device__ __forceinline__ void gemm1_tile(const Params& p, int layer, int mt, int nt, bf16* sA, bf16* sB) {
;   const int m0 = mt * 256;
;   f16v acc[4][2];
;   ZERO_ACC(acc, 4, 2)
;   gemm_kloop<4, 2>(p.h + (size_t)m0 * DM, DM, p.WinT + (size_t)nt * 128 * DM, DM, DM, acc, sA, sB);
.LBB0_1595:
	s_lshr_b32 s0, s28, 4
	s_and_b32 s0, s0, 16
	s_xor_b32 s20, s0, 31
	s_min_u32 s22, s20, 16
	s_lshl_b32 s20, s22, 2
	v_cvt_f32_ubyte0_e32 v0, s20
	v_rcp_iflag_f32_e32 v2, v0
	v_cvt_f32_ubyte0_e32 v3, s28
	s_and_b32 s23, s28, 0xff
	v_readlane_b32 s64, v252, 23
	v_mul_f32_e32 v2, v3, v2
	v_trunc_f32_e32 v2, v2
	v_cvt_u32_f32_e32 v4, v2
	v_fma_f32 v2, -v2, v0, v3
	v_cmp_ge_f32_e64 s[20:21], |v2|, v0
	s_cmp_lg_u64 s[20:21], 0
	v_readfirstlane_b32 s20, v4
	s_addc_u32 s20, s20, 0
	s_and_b32 s20, s20, 0xff
	s_lshl_b32 s20, s20, 2
	s_mul_i32 s22, s22, s20
	s_sub_i32 s21, s23, s22
	s_sext_i32_i16 s22, s21
	s_bfe_u32 s22, s22, 0x2001d
	s_add_i32 s22, s21, s22
	s_sext_i32_i16 s23, s22
	s_and_b32 s22, s22, 0xfffc
	s_sub_i32 s21, s21, s22
	s_add_i32 s20, s20, s88
	s_sext_i32_i16 s21, s21
	s_add_i32 s20, s20, s21
	s_ashr_i32 s21, s23, 2
	s_lshl_b32 s20, s20, 8
	s_add_i32 s22, s0, s21
	s_ashr_i32 s21, s20, 31
	s_lshl_b64 s[24:25], s[20:21], 11
	v_readlane_b32 s66, v252, 25
	v_mov_b32_e32 v18, v195
	v_readlane_b32 s67, v252, 26
	s_add_u32 s26, s66, s24
	s_addc_u32 s27, s67, s25
	v_ashrrev_i32_e32 v2, 3, v18
	v_lshlrev_b32_e32 v0, 4, v18
	v_and_b32_e32 v0, 0x70, v0
	v_ashrrev_i32_e32 v3, 31, v2
	v_lshl_add_u64 v[4:5], s[26:27], 0, v[0:1]
	v_lshlrev_b64 v[6:7], 11, v[2:3]
	s_mov_b64 s[26:27], 0x10000
	v_lshl_add_u64 v[10:11], v[6:7], 0, s[26:27]
	v_lshl_add_u64 v[8:9], v[4:5], 0, v[6:7]
	v_lshl_add_u64 v[12:13], v[4:5], 0, v[10:11]
	s_mov_b64 s[26:27], 0x20000
	global_load_dwordx4 v[130:133], v[8:9], off
	global_load_dwordx4 v[138:141], v[12:13], off
	v_lshl_add_u64 v[12:13], v[6:7], 0, s[26:27]
	s_mov_b64 s[26:27], 0x30000
	v_lshl_add_u64 v[16:17], v[6:7], 0, s[26:27]
	v_lshl_add_u64 v[14:15], v[4:5], 0, v[12:13]
	v_lshl_add_u64 v[4:5], v[4:5], 0, v[16:17]
	global_load_dwordx4 v[142:145], v[14:15], off
	global_load_dwordx4 v[146:149], v[4:5], off
	v_add_co_u32_e32 v4, vcc, s62, v8
	s_mov_b32 s0, 0x50000
	s_nop 0
	v_addc_co_u32_e32 v5, vcc, 0, v9, vcc
	v_add_co_u32_e32 v14, vcc, s0, v8
	s_ashr_i32 s23, s22, 31
	s_nop 0
	v_addc_co_u32_e32 v15, vcc, 0, v9, vcc
	s_lshl_b64 s[30:31], s[22:23], 18
	global_load_dwordx4 v[150:153], v[4:5], off
	global_load_dwordx4 v[154:157], v[14:15], off
	v_add_co_u32_e32 v4, vcc, s92, v8
	s_add_u32 s34, s10, s30
	s_nop 0
	v_addc_co_u32_e32 v5, vcc, 0, v9, vcc
	s_addc_u32 s35, s11, s31
	v_add_co_u32_e32 v8, vcc, s93, v8
	v_and_b32_e32 v3, 0xfffff9f, v18
	s_nop 0
	v_addc_co_u32_e32 v9, vcc, 0, v9, vcc
	global_load_dwordx4 v[158:161], v[4:5], off
	global_load_dwordx4 v[162:165], v[8:9], off
	v_lshl_add_u64 v[4:5], s[34:35], 0, v[0:1]
	v_lshl_add_u64 v[8:9], v[4:5], 0, v[6:7]
	v_lshl_add_u64 v[10:11], v[4:5], 0, v[10:11]
	v_lshl_add_u64 v[8:9], v[4:5], 0, v[12:13]
	v_lshl_add_u64 v[4:5], v[4:5], 0, v[16:17]
	v_mul_lo_u32 v8, v2, s33
	v_or_b32_e32 v2, 0x60, v18
	v_mul_lo_u32 v9, v3, s33
	v_mul_lo_u32 v10, v2, s33
	v_lshl_add_u64 v[2:3], v[6:7], 0, s[24:25]
	v_or_b32_e32 v2, v2, v0
	s_waitcnt vmcnt(31)
	v_lshl_add_u64 v[178:179], s[66:67], 0, v[2:3]
	v_lshl_add_u64 v[2:3], s[30:31], 0, v[6:7]
	v_lshrrev_b32_e32 v4, 1, v18
	v_and_b32_e32 v5, 0x5f, v18
	v_or_b32_e32 v2, v2, v0
	v_and_b32_e32 v4, 16, v4
	v_mul_u32_u24_e32 v5, 0x90, v5
	v_lshl_add_u64 v[180:181], s[10:11], 0, v[2:3]
	v_mov_b32_e32 v2, 0
	s_mov_b64 s[24:25], 0
	s_waitcnt vmcnt(30)
	v_add_u32_e32 v184, v0, v8
	v_add_u32_e32 v182, v4, v9
	v_add_u32_e32 v0, v4, v10
	v_add_u32_e32 v183, v4, v5
	v_mov_b32_e32 v3, v2
	v_mov_b32_e32 v4, v2
	v_mov_b32_e32 v5, v2
	v_mov_b32_e32 v6, v2
	v_mov_b32_e32 v7, v2
	v_mov_b32_e32 v8, v2
	v_mov_b32_e32 v9, v2
	v_mov_b32_e32 v10, v2
	v_mov_b32_e32 v11, v2
	v_mov_b32_e32 v12, v2
	v_mov_b32_e32 v13, v2
	v_mov_b32_e32 v14, v2
	v_mov_b32_e32 v15, v2
	v_mov_b32_e32 v16, v2
	v_mov_b32_e32 v17, v2
	v_mov_b32_e32 v18, v2
	v_mov_b32_e32 v19, v2
	v_mov_b32_e32 v20, v2
	v_mov_b32_e32 v21, v2
	v_mov_b32_e32 v22, v2
	v_mov_b32_e32 v23, v2
	v_mov_b32_e32 v24, v2
	v_mov_b32_e32 v25, v2
	v_mov_b32_e32 v26, v2
	v_mov_b32_e32 v27, v2
	v_mov_b32_e32 v28, v2
	v_mov_b32_e32 v29, v2
	v_mov_b32_e32 v30, v2
	v_mov_b32_e32 v31, v2
	v_mov_b32_e32 v32, v2
	v_mov_b32_e32 v33, v2
	v_mov_b32_e32 v34, v2
	v_mov_b32_e32 v35, v2
	v_mov_b32_e32 v36, v2
	v_mov_b32_e32 v37, v2
	v_mov_b32_e32 v38, v2
	v_mov_b32_e32 v39, v2
	v_mov_b32_e32 v40, v2
	v_mov_b32_e32 v41, v2
	v_mov_b32_e32 v42, v2
	v_mov_b32_e32 v43, v2
	v_mov_b32_e32 v44, v2
	v_mov_b32_e32 v45, v2
	v_mov_b32_e32 v46, v2
	v_mov_b32_e32 v47, v2
	v_mov_b32_e32 v48, v2
	v_mov_b32_e32 v49, v2
	v_mov_b32_e32 v50, v2
	v_mov_b32_e32 v51, v2
	v_mov_b32_e32 v52, v2
	v_mov_b32_e32 v53, v2
	v_mov_b32_e32 v54, v2
	v_mov_b32_e32 v55, v2
	v_mov_b32_e32 v56, v2
	v_mov_b32_e32 v57, v2
	v_mov_b32_e32 v58, v2
	v_mov_b32_e32 v59, v2
	v_mov_b32_e32 v60, v2
	v_mov_b32_e32 v61, v2
	v_mov_b32_e32 v62, v2
	v_mov_b32_e32 v63, v2
	v_mov_b32_e32 v64, v2
	v_mov_b32_e32 v65, v2
	v_mov_b32_e32 v66, v2
	v_mov_b32_e32 v67, v2
	v_mov_b32_e32 v68, v2
	v_mov_b32_e32 v69, v2
	v_mov_b32_e32 v70, v2
	v_mov_b32_e32 v71, v2
	v_mov_b32_e32 v72, v2
	v_mov_b32_e32 v73, v2
	v_mov_b32_e32 v74, v2
	v_mov_b32_e32 v75, v2
	v_mov_b32_e32 v76, v2
	v_mov_b32_e32 v77, v2
	v_mov_b32_e32 v78, v2
	v_mov_b32_e32 v79, v2
	v_mov_b32_e32 v80, v2
	v_mov_b32_e32 v81, v2
	v_mov_b32_e32 v82, v2
	v_mov_b32_e32 v83, v2
	v_mov_b32_e32 v84, v2
	v_mov_b32_e32 v85, v2
	v_mov_b32_e32 v86, v2
	v_mov_b32_e32 v87, v2
	v_mov_b32_e32 v88, v2
	v_mov_b32_e32 v89, v2
	v_mov_b32_e32 v90, v2
	v_mov_b32_e32 v91, v2
	v_mov_b32_e32 v92, v2
	v_mov_b32_e32 v93, v2
	v_mov_b32_e32 v94, v2
	v_mov_b32_e32 v95, v2
	v_mov_b32_e32 v96, v2
	v_mov_b32_e32 v97, v2
	v_mov_b32_e32 v98, v2
; template <int MI, int NI>
; __device__ __forceinline__ void gemm_kloop(const bf16* __restrict__ A, size_t lda, const bf16* __restrict__ Bt, size_t ldb, int K,
;                                            f16v (&acc)[MI][NI], bf16* sA, bf16* sB) {
;   const int tid = tid_opaque(), lane = tid & 63, w = tid >> 6;
;   const int r = lane & 31, hh = lane >> 5;
;   const int wm = w >> 1, wn = w & 1;
;   const int lrow = tid >> 3, lseg = tid & 7;
;   u4v ra[2 * MI], rb[2 * NI];
;   const int KT = K >> 6;
; #pragma unroll
;   for (int i = 0; i < 2 * MI; ++i) ra[i] = *(const u4v*)(A + (size_t)(lrow + 32 * i) * lda + lseg * 8);
; #pragma unroll
;   for (int i = 0; i < 2 * NI; ++i) rb[i] = *(const u4v*)(Bt + (size_t)(lrow + 32 * i) * ldb + lseg * 8);
;   unsigned pfs = 0;
;   {
;     if (tid < 64 * MI) pfs ^= *(const unsigned*)(A + (size_t)tid * lda + 64) ^ *(const unsigned*)(A + (size_t)tid * lda + 128);
;     if (tid < 64 * NI) pfs ^= *(const unsigned*)(Bt + (size_t)tid * ldb + 64) ^ *(const unsigned*)(Bt + (size_t)tid * ldb + 128);
;   }
;   for (int kt = 0; kt < KT; ++kt) {
;     __syncthreads();
; #pragma unroll
;     for (int i = 0; i < 2 * MI; ++i) *(u4v*)(sA + (lrow + 32 * i) * 72 + lseg * 8) = ra[i];
; #pragma unroll
;     for (int i = 0; i < 2 * NI; ++i) *(u4v*)(sB + (lrow + 32 * i) * 72 + lseg * 8) = rb[i];
;     __syncthreads();
;     if (kt + 3 < KT) {
;       const int k2 = (kt + 3) << 6;
;       if (tid < 64 * MI) pfs ^= *(const unsigned*)(A + (size_t)tid * lda + k2);
;       if (tid < 64 * NI) pfs ^= *(const unsigned*)(Bt + (size_t)tid * ldb + k2);
;     }
;     if (kt + 1 < KT) {
;       const int k0 = (kt + 1) << 6;
; #pragma unroll
;       for (int i = 0; i < 2 * MI; ++i) ra[i] = *(const u4v*)(A + (size_t)(lrow + 32 * i) * lda + k0 + lseg * 8);
; #pragma unroll
;       for (int i = 0; i < 2 * NI; ++i) rb[i] = *(const u4v*)(Bt + (size_t)(lrow + 32 * i) * ldb + k0 + lseg * 8);
;     }
; #pragma unroll
;     for (int ks = 0; ks < 4; ++ks) {
;       s8v a[MI], b[NI];
; #pragma unroll
;       for (int mi = 0; mi < MI; ++mi) a[mi] = *(const s8v*)(sA + (wm * 32 * MI + mi * 32 + r) * 72 + ks * 16 + hh * 8);
; #pragma unroll
;       for (int ni = 0; ni < NI; ++ni) b[ni] = *(const s8v*)(sB + (wn * 32 * NI + ni * 32 + r) * 72 + ks * 16 + hh * 8);
; #pragma unroll
;       for (int mi = 0; mi < MI; ++mi)
; #pragma unroll
	v_mov_b32_e32 v99, v2
	v_mov_b32_e32 v100, v2
	v_mov_b32_e32 v101, v2
	v_mov_b32_e32 v102, v2
	v_mov_b32_e32 v103, v2
	v_mov_b32_e32 v104, v2
	v_mov_b32_e32 v105, v2
	v_mov_b32_e32 v106, v2
	v_mov_b32_e32 v107, v2
	v_mov_b32_e32 v108, v2
	v_mov_b32_e32 v109, v2
	v_mov_b32_e32 v110, v2
	v_mov_b32_e32 v111, v2
	v_mov_b32_e32 v112, v2
	v_mov_b32_e32 v113, v2
	v_mov_b32_e32 v114, v2
	v_mov_b32_e32 v115, v2
	v_mov_b32_e32 v116, v2
	v_mov_b32_e32 v117, v2
	v_mov_b32_e32 v118, v2
	v_mov_b32_e32 v119, v2
	v_mov_b32_e32 v120, v2
	v_mov_b32_e32 v121, v2
	v_mov_b32_e32 v122, v2
	v_mov_b32_e32 v123, v2
	v_mov_b32_e32 v124, v2
	v_mov_b32_e32 v125, v2
	v_mov_b32_e32 v126, v2
	v_mov_b32_e32 v127, v2
	v_mov_b32_e32 v128, v2
	v_mov_b32_e32 v129, v2
	v_readlane_b32 s65, v252, 24
	v_readlane_b32 s68, v252, 27
	v_readlane_b32 s69, v252, 28
	v_readlane_b32 s70, v252, 29
	v_readlane_b32 s71, v252, 30
	v_readlane_b32 s72, v252, 31
	v_readlane_b32 s73, v252, 32
	v_readlane_b32 s74, v252, 33
	v_readlane_b32 s75, v252, 34
	v_readlane_b32 s76, v252, 35
	v_readlane_b32 s77, v252, 36
	v_readlane_b32 s78, v252, 37
	v_readlane_b32 s79, v252, 38
	v_readfirstlane_b32 s56, v178
	v_readfirstlane_b32 s57, v179
	v_readfirstlane_b32 s58, v180
	v_readfirstlane_b32 s59, v181
	v_readfirstlane_b32 s94, v195
	v_subrev_u32_e32 v178, s56, v178
	v_add_u32_e32 v179, 0x10000, v178
	v_add_u32_e32 v180, 0x20000, v178
	v_add_u32_e32 v181, 0x30000, v178
	v_add_u32_e32 v185, 0x40000, v178
	v_add_u32_e32 v222, 0x50000, v178
	v_add_u32_e32 v223, 0x60000, v178
	v_add_u32_e32 v227, 0x70000, v178
	s_lshr_b32 s94, s94, 6
	s_mul_i32 s95, s94, 0x4000
	s_sub_u32 s58, s58, s95
	s_subb_u32 s59, s59, 0
	s_lshl_b32 s96, s94, 12
	s_add_u32 s96, s96, 36864
	v_and_b32_e32 v170, 63, v195
	v_lshrrev_b32_e32 v171, 3, v170
	v_lshrrev_b32_e32 v172, 4, v170
	v_and_b32_e32 v173, 7, v170
	v_xor_b32_e32 v172, v172, v173
	v_lshlrev_b32_e32 v172, 4, v172
	v_lshrrev_b32_e32 v173, 6, v195
	v_lshl_add_u32 v170, v173, 5, v171
	v_mul_u32_u24_e32 v170, 0x800, v170
	v_add_u32_e32 v134, v170, v172
	v_xor_b32_e32 v172, 64, v172
	v_add_u32_e32 v170, v170, v172
	v_add_u32_e32 v135, 0x3c00, v170
	v_add_u32_e32 v136, 0x7800, v134
	v_add_u32_e32 v137, 0xb400, v170
	v_and_b32_e32 v170, 31, v195
	v_bfe_u32 v171, v195, 5, 1
	v_bfe_u32 v172, v170, 1, 3
	v_xor_b32_e32 v171, v171, v172
	v_lshlrev_b32_e32 v171, 4, v171
	v_bfe_u32 v172, v195, 6, 1
	v_lshl_add_u32 v172, v172, 6, v170
	v_lshl_add_u32 v166, v172, 7, v171
	v_xor_b32_e32 v167, 32, v166
	v_xor_b32_e32 v168, 64, v166
	v_xor_b32_e32 v169, 96, v166
	s_barrier
	s_add_u32 m0, s96, 0
	s_nop 0
	global_load_lds_dwordx4 v134, s[58:59] offset:0
	global_load_lds_dwordx4 v135, s[58:59] offset:1024
	global_load_lds_dwordx4 v136, s[58:59] offset:2048
	global_load_lds_dwordx4 v137, s[58:59] offset:3072
	s_barrier
	s_waitcnt vmcnt(11)
	ds_write_b128 v184, v[130:133]
	s_waitcnt vmcnt(10)
	ds_write_b128 v184, v[138:141] offset:4608
	s_waitcnt vmcnt(9)
	ds_write_b128 v184, v[142:145] offset:9216
	s_waitcnt vmcnt(8)
	ds_write_b128 v184, v[146:149] offset:13824
	s_waitcnt vmcnt(7)
	ds_write_b128 v184, v[150:153] offset:18432
	s_waitcnt vmcnt(6)
	ds_write_b128 v184, v[154:157] offset:23040
	s_waitcnt vmcnt(5)
	ds_write_b128 v184, v[158:161] offset:27648
	s_waitcnt vmcnt(4)
	ds_write_b128 v184, v[162:165] offset:32256
	s_waitcnt vmcnt(0) lgkmcnt(0)
	s_barrier
	ds_read_b128 v[186:189], v182
	ds_read_b128 v[204:207], v166 offset:36864
	ds_read_b128 v[208:211], v166 offset:40960
	ds_read_b128 v[190:193], v182 offset:4608
	ds_read_b128 v[196:199], v182 offset:9216
	ds_read_b128 v[200:203], v0
	ds_read_b128 v[212:215], v182 offset:32
	ds_read_b128 v[244:247], v167 offset:36864
	ds_read_b128 v[248:251], v167 offset:40960
	ds_read_b128 v[216:219], v182 offset:4640
	ds_read_b128 v[232:235], v182 offset:9248
	ds_read_b128 v[236:239], v0 offset:32
	s_waitcnt lgkmcnt(10)
	v_mfma_f32_32x32x16_bf16 v[114:129], v[186:189], v[204:207], v[114:129]
	s_add_u32 m0, s96, 16256
	s_nop 0
	s_waitcnt lgkmcnt(9)
	v_mfma_f32_32x32x16_bf16 v[98:113], v[186:189], v[208:211], v[98:113]
	global_load_lds_dwordx4 v134, s[58:59] offset:128
	ds_read_b128 v[186:189], v182 offset:64
	s_waitcnt lgkmcnt(9)
	v_mfma_f32_32x32x16_bf16 v[82:97], v[190:193], v[204:207], v[82:97]
	global_load_lds_dwordx4 v135, s[58:59] offset:1152
	v_mfma_f32_32x32x16_bf16 v[66:81], v[190:193], v[208:211], v[66:81]
	global_load_lds_dwordx4 v136, s[58:59] offset:2176
	ds_read_b128 v[190:193], v182 offset:4672
	s_waitcnt lgkmcnt(9)
	v_mfma_f32_32x32x16_bf16 v[50:65], v[196:199], v[204:207], v[50:65]
	global_load_lds_dwordx4 v137, s[58:59] offset:3200
	v_mfma_f32_32x32x16_bf16 v[34:49], v[196:199], v[208:211], v[34:49]
	global_load_dwordx4 v[130:133], v178, s[56:57] offset:128
	ds_read_b128 v[196:199], v182 offset:9280
	s_waitcnt lgkmcnt(9)
	v_mfma_f32_32x32x16_bf16 v[18:33], v[200:203], v[204:207], v[18:33]
	global_load_dwordx4 v[138:141], v179, s[56:57] offset:128
	v_mfma_f32_32x32x16_bf16 v[2:17], v[200:203], v[208:211], v[2:17]
	global_load_dwordx4 v[142:145], v180, s[56:57] offset:128
	ds_read_b128 v[200:203], v0 offset:64
	ds_read_b128 v[204:207], v168 offset:36864
	ds_read_b128 v[208:211], v168 offset:40960
	s_waitcnt lgkmcnt(10)
	v_mfma_f32_32x32x16_bf16 v[114:129], v[212:215], v[244:247], v[114:129]
	global_load_dwordx4 v[146:149], v181, s[56:57] offset:128
	s_waitcnt lgkmcnt(9)
	v_mfma_f32_32x32x16_bf16 v[98:113], v[212:215], v[248:251], v[98:113]
	global_load_dwordx4 v[150:153], v185, s[56:57] offset:128
	ds_read_b128 v[212:215], v182 offset:96
	s_waitcnt lgkmcnt(9)
; #define MFMA(a, b, c) __builtin_amdgcn_mfma_f32_32x32x16_bf16((a), (b), (c), 0, 0, 0)
; template <int MI, int NI>
; __device__ __forceinline__ void gemm_kloop(const bf16* __restrict__ A, size_t lda, const bf16* __restrict__ Bt, size_t ldb, int K,
;                                            f16v (&acc)[MI][NI], bf16* sA, bf16* sB) {
;     ...
;   for (int kt = 0; kt < KT; ++kt) {
;     __syncthreads();
; #pragma unroll
;     for (int i = 0; i < 2 * MI; ++i) *(u4v*)(sA + (lrow + 32 * i) * 72 + lseg * 8) = ra[i];
; #pragma unroll
;     for (int i = 0; i < 2 * NI; ++i) *(u4v*)(sB + (lrow + 32 * i) * 72 + lseg * 8) = rb[i];
;     __syncthreads();
;     if (kt + 3 < KT) {
;       const int k2 = (kt + 3) << 6;
;       if (tid < 64 * MI) pfs ^= *(const unsigned*)(A + (size_t)tid * lda + k2);
;       if (tid < 64 * NI) pfs ^= *(const unsigned*)(Bt + (size_t)tid * ldb + k2);
;     }
;     if (kt + 1 < KT) {
;       const int k0 = (kt + 1) << 6;
; #pragma unroll
;       for (int i = 0; i < 2 * MI; ++i) ra[i] = *(const u4v*)(A + (size_t)(lrow + 32 * i) * lda + k0 + lseg * 8);
; #pragma unroll
;       for (int i = 0; i < 2 * NI; ++i) rb[i] = *(const u4v*)(Bt + (size_t)(lrow + 32 * i) * ldb + k0 + lseg * 8);
;     }
; #pragma unroll
;     for (int ks = 0; ks < 4; ++ks) {
;       s8v a[MI], b[NI];
; #pragma unroll
;       for (int mi = 0; mi < MI; ++mi) a[mi] = *(const s8v*)(sA + (wm * 32 * MI + mi * 32 + r) * 72 + ks * 16 + hh * 8);
; #pragma unroll
;       for (int ni = 0; ni < NI; ++ni) b[ni] = *(const s8v*)(sB + (wn * 32 * NI + ni * 32 + r) * 72 + ks * 16 + hh * 8);
; #pragma unroll
;       for (int mi = 0; mi < MI; ++mi)
; #pragma unroll
;         for (int ni = 0; ni < NI; ++ni) acc[mi][ni] = MFMA(a[mi], b[ni], acc[mi][ni]);
	v_mfma_f32_32x32x16_bf16 v[82:97], v[216:219], v[244:247], v[82:97]
	global_load_dwordx4 v[154:157], v222, s[56:57] offset:128
	v_mfma_f32_32x32x16_bf16 v[66:81], v[216:219], v[248:251], v[66:81]
	global_load_dwordx4 v[158:161], v223, s[56:57] offset:128
	ds_read_b128 v[216:219], v182 offset:4704
	s_waitcnt lgkmcnt(9)
	v_mfma_f32_32x32x16_bf16 v[50:65], v[232:235], v[244:247], v[50:65]
	global_load_dwordx4 v[162:165], v227, s[56:57] offset:128
	v_mfma_f32_32x32x16_bf16 v[34:49], v[232:235], v[248:251], v[34:49]
	ds_read_b128 v[232:235], v182 offset:9312
	s_waitcnt lgkmcnt(9)
	v_mfma_f32_32x32x16_bf16 v[18:33], v[236:239], v[244:247], v[18:33]
	v_mfma_f32_32x32x16_bf16 v[2:17], v[236:239], v[248:251], v[2:17]
	ds_read_b128 v[236:239], v0 offset:96
	ds_read_b128 v[244:247], v169 offset:36864
	ds_read_b128 v[248:251], v169 offset:40960
	s_waitcnt lgkmcnt(7)
	v_mfma_f32_32x32x16_bf16 v[114:129], v[186:189], v[204:207], v[114:129]
	s_waitcnt lgkmcnt(6)
	v_mfma_f32_32x32x16_bf16 v[98:113], v[186:189], v[208:211], v[98:113]
	v_mfma_f32_32x32x16_bf16 v[82:97], v[190:193], v[204:207], v[82:97]
	v_mfma_f32_32x32x16_bf16 v[66:81], v[190:193], v[208:211], v[66:81]
	v_mfma_f32_32x32x16_bf16 v[50:65], v[196:199], v[204:207], v[50:65]
	v_mfma_f32_32x32x16_bf16 v[34:49], v[196:199], v[208:211], v[34:49]
	v_mfma_f32_32x32x16_bf16 v[2:17], v[200:203], v[208:211], v[2:17]
	v_mfma_f32_32x32x16_bf16 v[18:33], v[200:203], v[204:207], v[18:33]
	s_waitcnt lgkmcnt(1)
	v_mfma_f32_32x32x16_bf16 v[114:129], v[212:215], v[244:247], v[114:129]
	s_waitcnt lgkmcnt(0)
	v_mfma_f32_32x32x16_bf16 v[98:113], v[212:215], v[248:251], v[98:113]
	v_mfma_f32_32x32x16_bf16 v[82:97], v[216:219], v[244:247], v[82:97]
	v_mfma_f32_32x32x16_bf16 v[66:81], v[216:219], v[248:251], v[66:81]
	v_mfma_f32_32x32x16_bf16 v[50:65], v[232:235], v[244:247], v[50:65]
	v_mfma_f32_32x32x16_bf16 v[34:49], v[232:235], v[248:251], v[34:49]
	v_mfma_f32_32x32x16_bf16 v[18:33], v[236:239], v[244:247], v[18:33]
	v_mfma_f32_32x32x16_bf16 v[2:17], v[236:239], v[248:251], v[2:17]
	s_add_u32 s56, s56, 0x80
	s_addc_u32 s57, s57, 0
	s_add_u32 s58, s58, 0x80
	s_addc_u32 s59, s59, 0
	s_barrier
	s_waitcnt vmcnt(7)
	ds_write_b128 v184, v[130:133]
	s_waitcnt vmcnt(6)
	ds_write_b128 v184, v[138:141] offset:4608
	s_waitcnt vmcnt(5)
	ds_write_b128 v184, v[142:145] offset:9216
	s_waitcnt vmcnt(4)
	ds_write_b128 v184, v[146:149] offset:13824
	s_waitcnt vmcnt(3)
	ds_write_b128 v184, v[150:153] offset:18432
	s_waitcnt vmcnt(2)
	ds_write_b128 v184, v[154:157] offset:23040
	s_waitcnt vmcnt(1)
	ds_write_b128 v184, v[158:161] offset:27648
	s_waitcnt vmcnt(0)
	ds_write_b128 v184, v[162:165] offset:32256
	s_waitcnt lgkmcnt(0)
	s_barrier
	ds_read_b128 v[186:189], v182
	ds_read_b128 v[204:207], v166 offset:53248
	ds_read_b128 v[208:211], v166 offset:57344
	ds_read_b128 v[190:193], v182 offset:4608
	ds_read_b128 v[196:199], v182 offset:9216
	ds_read_b128 v[200:203], v0
	ds_read_b128 v[212:215], v182 offset:32
	ds_read_b128 v[244:247], v167 offset:53248
	ds_read_b128 v[248:251], v167 offset:57344
	ds_read_b128 v[216:219], v182 offset:4640
	ds_read_b128 v[232:235], v182 offset:9248
	ds_read_b128 v[236:239], v0 offset:32
	s_waitcnt lgkmcnt(10)
	v_mfma_f32_32x32x16_bf16 v[114:129], v[186:189], v[204:207], v[114:129]
	s_add_u32 m0, s96, -128
	s_nop 0
	s_waitcnt lgkmcnt(9)
	v_mfma_f32_32x32x16_bf16 v[98:113], v[186:189], v[208:211], v[98:113]
	global_load_lds_dwordx4 v134, s[58:59] offset:128
	ds_read_b128 v[186:189], v182 offset:64
	s_waitcnt lgkmcnt(9)
	v_mfma_f32_32x32x16_bf16 v[82:97], v[190:193], v[204:207], v[82:97]
	global_load_lds_dwordx4 v135, s[58:59] offset:1152
	v_mfma_f32_32x32x16_bf16 v[66:81], v[190:193], v[208:211], v[66:81]
	global_load_lds_dwordx4 v136, s[58:59] offset:2176
	ds_read_b128 v[190:193], v182 offset:4672
	s_waitcnt lgkmcnt(9)
	v_mfma_f32_32x32x16_bf16 v[50:65], v[196:199], v[204:207], v[50:65]
	global_load_lds_dwordx4 v137, s[58:59] offset:3200
	v_mfma_f32_32x32x16_bf16 v[34:49], v[196:199], v[208:211], v[34:49]
	global_load_dwordx4 v[130:133], v178, s[56:57] offset:128
	ds_read_b128 v[196:199], v182 offset:9280
	s_waitcnt lgkmcnt(9)
	v_mfma_f32_32x32x16_bf16 v[18:33], v[200:203], v[204:207], v[18:33]
	global_load_dwordx4 v[138:141], v179, s[56:57] offset:128
	v_mfma_f32_32x32x16_bf16 v[2:17], v[200:203], v[208:211], v[2:17]
	global_load_dwordx4 v[142:145], v180, s[56:57] offset:128
	ds_read_b128 v[200:203], v0 offset:64
	ds_read_b128 v[204:207], v168 offset:53248
	ds_read_b128 v[208:211], v168 offset:57344
	s_waitcnt lgkmcnt(10)
	v_mfma_f32_32x32x16_bf16 v[114:129], v[212:215], v[244:247], v[114:129]
	global_load_dwordx4 v[146:149], v181, s[56:57] offset:128
	s_waitcnt lgkmcnt(9)
	v_mfma_f32_32x32x16_bf16 v[98:113], v[212:215], v[248:251], v[98:113]
	global_load_dwordx4 v[150:153], v185, s[56:57] offset:128
	ds_read_b128 v[212:215], v182 offset:96
	s_waitcnt lgkmcnt(9)
	v_mfma_f32_32x32x16_bf16 v[82:97], v[216:219], v[244:247], v[82:97]
	global_load_dwordx4 v[154:157], v222, s[56:57] offset:128
	v_mfma_f32_32x32x16_bf16 v[66:81], v[216:219], v[248:251], v[66:81]
	global_load_dwordx4 v[158:161], v223, s[56:57] offset:128
	ds_read_b128 v[216:219], v182 offset:4704
	s_waitcnt lgkmcnt(9)
	v_mfma_f32_32x32x16_bf16 v[50:65], v[232:235], v[244:247], v[50:65]
	global_load_dwordx4 v[162:165], v227, s[56:57] offset:128
	v_mfma_f32_32x32x16_bf16 v[34:49], v[232:235], v[248:251], v[34:49]
	ds_read_b128 v[232:235], v182 offset:9312
	s_waitcnt lgkmcnt(9)
	v_mfma_f32_32x32x16_bf16 v[18:33], v[236:239], v[244:247], v[18:33]
	v_mfma_f32_32x32x16_bf16 v[2:17], v[236:239], v[248:251], v[2:17]
	ds_read_b128 v[236:239], v0 offset:96
	ds_read_b128 v[244:247], v169 offset:53248
	ds_read_b128 v[248:251], v169 offset:57344
	s_waitcnt lgkmcnt(7)
; #define MFMA(a, b, c) __builtin_amdgcn_mfma_f32_32x32x16_bf16((a), (b), (c), 0, 0, 0)
; template <int MI, int NI>
; __device__ __forceinline__ void gemm_kloop(const bf16* __restrict__ A, size_t lda, const bf16* __restrict__ Bt, size_t ldb, int K,
;                                            f16v (&acc)[MI][NI], bf16* sA, bf16* sB) {
;     ...
;   for (int kt = 0; kt < KT; ++kt) {
;     __syncthreads();
; #pragma unroll
;     for (int i = 0; i < 2 * MI; ++i) *(u4v*)(sA + (lrow + 32 * i) * 72 + lseg * 8) = ra[i];
; #pragma unroll
;     for (int i = 0; i < 2 * NI; ++i) *(u4v*)(sB + (lrow + 32 * i) * 72 + lseg * 8) = rb[i];
;     __syncthreads();
;     if (kt + 3 < KT) {
;       const int k2 = (kt + 3) << 6;
;       if (tid < 64 * MI) pfs ^= *(const unsigned*)(A + (size_t)tid * lda + k2);
;       if (tid < 64 * NI) pfs ^= *(const unsigned*)(Bt + (size_t)tid * ldb + k2);
;     }
;     if (kt + 1 < KT) {
;       const int k0 = (kt + 1) << 6;
; #pragma unroll
;       for (int i = 0; i < 2 * MI; ++i) ra[i] = *(const u4v*)(A + (size_t)(lrow + 32 * i) * lda + k0 + lseg * 8);
; #pragma unroll
;       for (int i = 0; i < 2 * NI; ++i) rb[i] = *(const u4v*)(Bt + (size_t)(lrow + 32 * i) * ldb + k0 + lseg * 8);
;     }
; #pragma unroll
;     for (int ks = 0; ks < 4; ++ks) {
;       s8v a[MI], b[NI];
; #pragma unroll
;       for (int mi = 0; mi < MI; ++mi) a[mi] = *(const s8v*)(sA + (wm * 32 * MI + mi * 32 + r) * 72 + ks * 16 + hh * 8);
; #pragma unroll
;       for (int ni = 0; ni < NI; ++ni) b[ni] = *(const s8v*)(sB + (wn * 32 * NI + ni * 32 + r) * 72 + ks * 16 + hh * 8);
; #pragma unroll
;       for (int mi = 0; mi < MI; ++mi)
; #pragma unroll
;         for (int ni = 0; ni < NI; ++ni) acc[mi][ni] = MFMA(a[mi], b[ni], acc[mi][ni]);
	v_mfma_f32_32x32x16_bf16 v[114:129], v[186:189], v[204:207], v[114:129]
	s_waitcnt lgkmcnt(6)
	v_mfma_f32_32x32x16_bf16 v[98:113], v[186:189], v[208:211], v[98:113]
	v_mfma_f32_32x32x16_bf16 v[82:97], v[190:193], v[204:207], v[82:97]
	v_mfma_f32_32x32x16_bf16 v[66:81], v[190:193], v[208:211], v[66:81]
	v_mfma_f32_32x32x16_bf16 v[50:65], v[196:199], v[204:207], v[50:65]
	v_mfma_f32_32x32x16_bf16 v[34:49], v[196:199], v[208:211], v[34:49]
	v_mfma_f32_32x32x16_bf16 v[2:17], v[200:203], v[208:211], v[2:17]
	v_mfma_f32_32x32x16_bf16 v[18:33], v[200:203], v[204:207], v[18:33]
	s_waitcnt lgkmcnt(1)
	v_mfma_f32_32x32x16_bf16 v[114:129], v[212:215], v[244:247], v[114:129]
	s_waitcnt lgkmcnt(0)
	v_mfma_f32_32x32x16_bf16 v[98:113], v[212:215], v[248:251], v[98:113]
	v_mfma_f32_32x32x16_bf16 v[82:97], v[216:219], v[244:247], v[82:97]
	v_mfma_f32_32x32x16_bf16 v[66:81], v[216:219], v[248:251], v[66:81]
	v_mfma_f32_32x32x16_bf16 v[50:65], v[232:235], v[244:247], v[50:65]
	v_mfma_f32_32x32x16_bf16 v[34:49], v[232:235], v[248:251], v[34:49]
	v_mfma_f32_32x32x16_bf16 v[18:33], v[236:239], v[244:247], v[18:33]
	v_mfma_f32_32x32x16_bf16 v[2:17], v[236:239], v[248:251], v[2:17]
	s_add_u32 s56, s56, 0x80
	s_addc_u32 s57, s57, 0
	s_add_u32 s58, s58, 0x80
	s_addc_u32 s59, s59, 0
	s_movk_i32 s94, 6
.Lhyb_p1_loop:
	s_barrier
	s_waitcnt vmcnt(7)
	ds_write_b128 v184, v[130:133]
	s_waitcnt vmcnt(6)
	ds_write_b128 v184, v[138:141] offset:4608
	s_waitcnt vmcnt(5)
	ds_write_b128 v184, v[142:145] offset:9216
	s_waitcnt vmcnt(4)
	ds_write_b128 v184, v[146:149] offset:13824
	s_waitcnt vmcnt(3)
	ds_write_b128 v184, v[150:153] offset:18432
	s_waitcnt vmcnt(2)
	ds_write_b128 v184, v[154:157] offset:23040
	s_waitcnt vmcnt(1)
	ds_write_b128 v184, v[158:161] offset:27648
	s_waitcnt vmcnt(0)
	ds_write_b128 v184, v[162:165] offset:32256
	s_waitcnt lgkmcnt(0)
	s_barrier
	ds_read_b128 v[186:189], v182
	ds_read_b128 v[204:207], v166 offset:36864
	ds_read_b128 v[208:211], v166 offset:40960
	ds_read_b128 v[190:193], v182 offset:4608
	ds_read_b128 v[196:199], v182 offset:9216
	ds_read_b128 v[200:203], v0
	ds_read_b128 v[212:215], v182 offset:32
	ds_read_b128 v[244:247], v167 offset:36864
	ds_read_b128 v[248:251], v167 offset:40960
	ds_read_b128 v[216:219], v182 offset:4640
	ds_read_b128 v[232:235], v182 offset:9248
	ds_read_b128 v[236:239], v0 offset:32
	s_waitcnt lgkmcnt(10)
	v_mfma_f32_32x32x16_bf16 v[114:129], v[186:189], v[204:207], v[114:129]
	s_add_u32 m0, s96, 16256
	s_nop 0
	s_waitcnt lgkmcnt(9)
	v_mfma_f32_32x32x16_bf16 v[98:113], v[186:189], v[208:211], v[98:113]
	global_load_lds_dwordx4 v134, s[58:59] offset:128
	ds_read_b128 v[186:189], v182 offset:64
	s_waitcnt lgkmcnt(9)
	v_mfma_f32_32x32x16_bf16 v[82:97], v[190:193], v[204:207], v[82:97]
	global_load_lds_dwordx4 v135, s[58:59] offset:1152
	v_mfma_f32_32x32x16_bf16 v[66:81], v[190:193], v[208:211], v[66:81]
	global_load_lds_dwordx4 v136, s[58:59] offset:2176
	ds_read_b128 v[190:193], v182 offset:4672
	s_waitcnt lgkmcnt(9)
	v_mfma_f32_32x32x16_bf16 v[50:65], v[196:199], v[204:207], v[50:65]
	global_load_lds_dwordx4 v137, s[58:59] offset:3200
	v_mfma_f32_32x32x16_bf16 v[34:49], v[196:199], v[208:211], v[34:49]
	global_load_dwordx4 v[130:133], v178, s[56:57] offset:128
	ds_read_b128 v[196:199], v182 offset:9280
	s_waitcnt lgkmcnt(9)
	v_mfma_f32_32x32x16_bf16 v[18:33], v[200:203], v[204:207], v[18:33]
	global_load_dwordx4 v[138:141], v179, s[56:57] offset:128
	v_mfma_f32_32x32x16_bf16 v[2:17], v[200:203], v[208:211], v[2:17]
	global_load_dwordx4 v[142:145], v180, s[56:57] offset:128
	ds_read_b128 v[200:203], v0 offset:64
	ds_read_b128 v[204:207], v168 offset:36864
	ds_read_b128 v[208:211], v168 offset:40960
	s_waitcnt lgkmcnt(10)
	v_mfma_f32_32x32x16_bf16 v[114:129], v[212:215], v[244:247], v[114:129]
	global_load_dwordx4 v[146:149], v181, s[56:57] offset:128
	s_waitcnt lgkmcnt(9)
	v_mfma_f32_32x32x16_bf16 v[98:113], v[212:215], v[248:251], v[98:113]
	global_load_dwordx4 v[150:153], v185, s[56:57] offset:128
	ds_read_b128 v[212:215], v182 offset:96
	s_waitcnt lgkmcnt(9)
	v_mfma_f32_32x32x16_bf16 v[82:97], v[216:219], v[244:247], v[82:97]
	global_load_dwordx4 v[154:157], v222, s[56:57] offset:128
	v_mfma_f32_32x32x16_bf16 v[66:81], v[216:219], v[248:251], v[66:81]
	global_load_dwordx4 v[158:161], v223, s[56:57] offset:128
	ds_read_b128 v[216:219], v182 offset:4704
	s_waitcnt lgkmcnt(9)
	v_mfma_f32_32x32x16_bf16 v[50:65], v[232:235], v[244:247], v[50:65]
	global_load_dwordx4 v[162:165], v227, s[56:57] offset:128
	v_mfma_f32_32x32x16_bf16 v[34:49], v[232:235], v[248:251], v[34:49]
	ds_read_b128 v[232:235], v182 offset:9312
	s_waitcnt lgkmcnt(9)
	v_mfma_f32_32x32x16_bf16 v[18:33], v[236:239], v[244:247], v[18:33]
	v_mfma_f32_32x32x16_bf16 v[2:17], v[236:239], v[248:251], v[2:17]
	ds_read_b128 v[236:239], v0 offset:96
	ds_read_b128 v[244:247], v169 offset:36864
	ds_read_b128 v[248:251], v169 offset:40960
	s_waitcnt lgkmcnt(7)
	v_mfma_f32_32x32x16_bf16 v[114:129], v[186:189], v[204:207], v[114:129]
	s_waitcnt lgkmcnt(6)
	v_mfma_f32_32x32x16_bf16 v[98:113], v[186:189], v[208:211], v[98:113]
	v_mfma_f32_32x32x16_bf16 v[82:97], v[190:193], v[204:207], v[82:97]
	v_mfma_f32_32x32x16_bf16 v[66:81], v[190:193], v[208:211], v[66:81]
	v_mfma_f32_32x32x16_bf16 v[50:65], v[196:199], v[204:207], v[50:65]
	v_mfma_f32_32x32x16_bf16 v[34:49], v[196:199], v[208:211], v[34:49]
	v_mfma_f32_32x32x16_bf16 v[2:17], v[200:203], v[208:211], v[2:17]
	v_mfma_f32_32x32x16_bf16 v[18:33], v[200:203], v[204:207], v[18:33]
	s_waitcnt lgkmcnt(1)
	v_mfma_f32_32x32x16_bf16 v[114:129], v[212:215], v[244:247], v[114:129]
	s_waitcnt lgkmcnt(0)
	v_mfma_f32_32x32x16_bf16 v[98:113], v[212:215], v[248:251], v[98:113]
	v_mfma_f32_32x32x16_bf16 v[82:97], v[216:219], v[244:247], v[82:97]
	v_mfma_f32_32x32x16_bf16 v[66:81], v[216:219], v[248:251], v[66:81]
	v_mfma_f32_32x32x16_bf16 v[50:65], v[232:235], v[244:247], v[50:65]
	v_mfma_f32_32x32x16_bf16 v[34:49], v[232:235], v[248:251], v[34:49]
	v_mfma_f32_32x32x16_bf16 v[18:33], v[236:239], v[244:247], v[18:33]
	v_mfma_f32_32x32x16_bf16 v[2:17], v[236:239], v[248:251], v[2:17]
	s_add_u32 s56, s56, 0x80
	s_addc_u32 s57, s57, 0
	s_add_u32 s58, s58, 0x80
	s_addc_u32 s59, s59, 0
	s_barrier
; #define MFMA(a, b, c) __builtin_amdgcn_mfma_f32_32x32x16_bf16((a), (b), (c), 0, 0, 0)
; template <int MI, int NI>
; __device__ __forceinline__ void gemm_kloop(const bf16* __restrict__ A, size_t lda, const bf16* __restrict__ Bt, size_t ldb, int K,
;                                            f16v (&acc)[MI][NI], bf16* sA, bf16* sB) {
;     ...
;   for (int kt = 0; kt < KT; ++kt) {
;     __syncthreads();
; #pragma unroll
;     for (int i = 0; i < 2 * MI; ++i) *(u4v*)(sA + (lrow + 32 * i) * 72 + lseg * 8) = ra[i];
; #pragma unroll
;     for (int i = 0; i < 2 * NI; ++i) *(u4v*)(sB + (lrow + 32 * i) * 72 + lseg * 8) = rb[i];
;     __syncthreads();
;     if (kt + 3 < KT) {
;       const int k2 = (kt + 3) << 6;
;       if (tid < 64 * MI) pfs ^= *(const unsigned*)(A + (size_t)tid * lda + k2);
;       if (tid < 64 * NI) pfs ^= *(const unsigned*)(Bt + (size_t)tid * ldb + k2);
;     }
;     if (kt + 1 < KT) {
;       const int k0 = (kt + 1) << 6;
; #pragma unroll
;       for (int i = 0; i < 2 * MI; ++i) ra[i] = *(const u4v*)(A + (size_t)(lrow + 32 * i) * lda + k0 + lseg * 8);
; #pragma unroll
;       for (int i = 0; i < 2 * NI; ++i) rb[i] = *(const u4v*)(Bt + (size_t)(lrow + 32 * i) * ldb + k0 + lseg * 8);
;     }
; #pragma unroll
;     for (int ks = 0; ks < 4; ++ks) {
;       s8v a[MI], b[NI];
; #pragma unroll
;       for (int mi = 0; mi < MI; ++mi) a[mi] = *(const s8v*)(sA + (wm * 32 * MI + mi * 32 + r) * 72 + ks * 16 + hh * 8);
; #pragma unroll
;       for (int ni = 0; ni < NI; ++ni) b[ni] = *(const s8v*)(sB + (wn * 32 * NI + ni * 32 + r) * 72 + ks * 16 + hh * 8);
; #pragma unroll
;       for (int mi = 0; mi < MI; ++mi)
; #pragma unroll
;         for (int ni = 0; ni < NI; ++ni) acc[mi][ni] = MFMA(a[mi], b[ni], acc[mi][ni]);
	s_waitcnt vmcnt(7)
	ds_write_b128 v184, v[130:133]
	s_waitcnt vmcnt(6)
	ds_write_b128 v184, v[138:141] offset:4608
	s_waitcnt vmcnt(5)
	ds_write_b128 v184, v[142:145] offset:9216
	s_waitcnt vmcnt(4)
	ds_write_b128 v184, v[146:149] offset:13824
	s_waitcnt vmcnt(3)
	ds_write_b128 v184, v[150:153] offset:18432
	s_waitcnt vmcnt(2)
	ds_write_b128 v184, v[154:157] offset:23040
	s_waitcnt vmcnt(1)
	ds_write_b128 v184, v[158:161] offset:27648
	s_waitcnt vmcnt(0)
	ds_write_b128 v184, v[162:165] offset:32256
	s_waitcnt lgkmcnt(0)
	s_barrier
	ds_read_b128 v[186:189], v182
	ds_read_b128 v[204:207], v166 offset:53248
	ds_read_b128 v[208:211], v166 offset:57344
	ds_read_b128 v[190:193], v182 offset:4608
	ds_read_b128 v[196:199], v182 offset:9216
	ds_read_b128 v[200:203], v0
	ds_read_b128 v[212:215], v182 offset:32
	ds_read_b128 v[244:247], v167 offset:53248
	ds_read_b128 v[248:251], v167 offset:57344
	ds_read_b128 v[216:219], v182 offset:4640
	ds_read_b128 v[232:235], v182 offset:9248
	ds_read_b128 v[236:239], v0 offset:32
	s_waitcnt lgkmcnt(10)
	v_mfma_f32_32x32x16_bf16 v[114:129], v[186:189], v[204:207], v[114:129]
	s_add_u32 m0, s96, -128
	s_nop 0
	s_waitcnt lgkmcnt(9)
	v_mfma_f32_32x32x16_bf16 v[98:113], v[186:189], v[208:211], v[98:113]
	global_load_lds_dwordx4 v134, s[58:59] offset:128
	ds_read_b128 v[186:189], v182 offset:64
	s_waitcnt lgkmcnt(9)
	v_mfma_f32_32x32x16_bf16 v[82:97], v[190:193], v[204:207], v[82:97]
	global_load_lds_dwordx4 v135, s[58:59] offset:1152
	v_mfma_f32_32x32x16_bf16 v[66:81], v[190:193], v[208:211], v[66:81]
	global_load_lds_dwordx4 v136, s[58:59] offset:2176
	ds_read_b128 v[190:193], v182 offset:4672
	s_waitcnt lgkmcnt(9)
	v_mfma_f32_32x32x16_bf16 v[50:65], v[196:199], v[204:207], v[50:65]
	global_load_lds_dwordx4 v137, s[58:59] offset:3200
	v_mfma_f32_32x32x16_bf16 v[34:49], v[196:199], v[208:211], v[34:49]
	global_load_dwordx4 v[130:133], v178, s[56:57] offset:128
	ds_read_b128 v[196:199], v182 offset:9280
	s_waitcnt lgkmcnt(9)
	v_mfma_f32_32x32x16_bf16 v[18:33], v[200:203], v[204:207], v[18:33]
	global_load_dwordx4 v[138:141], v179, s[56:57] offset:128
	v_mfma_f32_32x32x16_bf16 v[2:17], v[200:203], v[208:211], v[2:17]
	global_load_dwordx4 v[142:145], v180, s[56:57] offset:128
	ds_read_b128 v[200:203], v0 offset:64
	ds_read_b128 v[204:207], v168 offset:53248
	ds_read_b128 v[208:211], v168 offset:57344
	s_waitcnt lgkmcnt(10)
	v_mfma_f32_32x32x16_bf16 v[114:129], v[212:215], v[244:247], v[114:129]
	global_load_dwordx4 v[146:149], v181, s[56:57] offset:128
	s_waitcnt lgkmcnt(9)
	v_mfma_f32_32x32x16_bf16 v[98:113], v[212:215], v[248:251], v[98:113]
	global_load_dwordx4 v[150:153], v185, s[56:57] offset:128
	ds_read_b128 v[212:215], v182 offset:96
	s_waitcnt lgkmcnt(9)
	v_mfma_f32_32x32x16_bf16 v[82:97], v[216:219], v[244:247], v[82:97]
	global_load_dwordx4 v[154:157], v222, s[56:57] offset:128
	v_mfma_f32_32x32x16_bf16 v[66:81], v[216:219], v[248:251], v[66:81]
	global_load_dwordx4 v[158:161], v223, s[56:57] offset:128
	ds_read_b128 v[216:219], v182 offset:4704
	s_waitcnt lgkmcnt(9)
	v_mfma_f32_32x32x16_bf16 v[50:65], v[232:235], v[244:247], v[50:65]
	global_load_dwordx4 v[162:165], v227, s[56:57] offset:128
	v_mfma_f32_32x32x16_bf16 v[34:49], v[232:235], v[248:251], v[34:49]
	ds_read_b128 v[232:235], v182 offset:9312
	s_waitcnt lgkmcnt(9)
	v_mfma_f32_32x32x16_bf16 v[18:33], v[236:239], v[244:247], v[18:33]
	v_mfma_f32_32x32x16_bf16 v[2:17], v[236:239], v[248:251], v[2:17]
	ds_read_b128 v[236:239], v0 offset:96
	ds_read_b128 v[244:247], v169 offset:53248
	ds_read_b128 v[248:251], v169 offset:57344
	s_waitcnt lgkmcnt(7)
	v_mfma_f32_32x32x16_bf16 v[114:129], v[186:189], v[204:207], v[114:129]
	s_waitcnt lgkmcnt(6)
	v_mfma_f32_32x32x16_bf16 v[98:113], v[186:189], v[208:211], v[98:113]
	v_mfma_f32_32x32x16_bf16 v[82:97], v[190:193], v[204:207], v[82:97]
	v_mfma_f32_32x32x16_bf16 v[66:81], v[190:193], v[208:211], v[66:81]
	v_mfma_f32_32x32x16_bf16 v[50:65], v[196:199], v[204:207], v[50:65]
	v_mfma_f32_32x32x16_bf16 v[34:49], v[196:199], v[208:211], v[34:49]
	v_mfma_f32_32x32x16_bf16 v[2:17], v[200:203], v[208:211], v[2:17]
	v_mfma_f32_32x32x16_bf16 v[18:33], v[200:203], v[204:207], v[18:33]
	s_waitcnt lgkmcnt(1)
	v_mfma_f32_32x32x16_bf16 v[114:129], v[212:215], v[244:247], v[114:129]
	s_waitcnt lgkmcnt(0)
	v_mfma_f32_32x32x16_bf16 v[98:113], v[212:215], v[248:251], v[98:113]
	v_mfma_f32_32x32x16_bf16 v[82:97], v[216:219], v[244:247], v[82:97]
	v_mfma_f32_32x32x16_bf16 v[66:81], v[216:219], v[248:251], v[66:81]
	v_mfma_f32_32x32x16_bf16 v[50:65], v[232:235], v[244:247], v[50:65]
	v_mfma_f32_32x32x16_bf16 v[34:49], v[232:235], v[248:251], v[34:49]
	v_mfma_f32_32x32x16_bf16 v[18:33], v[236:239], v[244:247], v[18:33]
	v_mfma_f32_32x32x16_bf16 v[2:17], v[236:239], v[248:251], v[2:17]
	s_add_u32 s56, s56, 0x80
	s_addc_u32 s57, s57, 0
	s_add_u32 s58, s58, 0x80
	s_addc_u32 s59, s59, 0
	s_sub_u32 s94, s94, 1
	s_cmp_lg_u32 s94, 0
	s_cbranch_scc1 .Lhyb_p1_loop
	s_barrier
	s_waitcnt vmcnt(7)
	ds_write_b128 v184, v[130:133]
	s_waitcnt vmcnt(6)
	ds_write_b128 v184, v[138:141] offset:4608
	s_waitcnt vmcnt(5)
	ds_write_b128 v184, v[142:145] offset:9216
	s_waitcnt vmcnt(4)
	ds_write_b128 v184, v[146:149] offset:13824
	s_waitcnt vmcnt(3)
	ds_write_b128 v184, v[150:153] offset:18432
	s_waitcnt vmcnt(2)
	ds_write_b128 v184, v[154:157] offset:23040
	s_waitcnt vmcnt(1)
	ds_write_b128 v184, v[158:161] offset:27648
	s_waitcnt vmcnt(0)
	ds_write_b128 v184, v[162:165] offset:32256
	s_waitcnt lgkmcnt(0)
	s_barrier
; #define MFMA(a, b, c) __builtin_amdgcn_mfma_f32_32x32x16_bf16((a), (b), (c), 0, 0, 0)
; template <int MI, int NI>
; __device__ __forceinline__ void gemm_kloop(const bf16* __restrict__ A, size_t lda, const bf16* __restrict__ Bt, size_t ldb, int K,
;                                            f16v (&acc)[MI][NI], bf16* sA, bf16* sB) {
;     ...
;   for (int kt = 0; kt < KT; ++kt) {
;     __syncthreads();
; #pragma unroll
;     for (int i = 0; i < 2 * MI; ++i) *(u4v*)(sA + (lrow + 32 * i) * 72 + lseg * 8) = ra[i];
; #pragma unroll
;     for (int i = 0; i < 2 * NI; ++i) *(u4v*)(sB + (lrow + 32 * i) * 72 + lseg * 8) = rb[i];
;     __syncthreads();
;     if (kt + 3 < KT) {
;       const int k2 = (kt + 3) << 6;
;       if (tid < 64 * MI) pfs ^= *(const unsigned*)(A + (size_t)tid * lda + k2);
;       if (tid < 64 * NI) pfs ^= *(const unsigned*)(Bt + (size_t)tid * ldb + k2);
;     }
;     if (kt + 1 < KT) {
;       const int k0 = (kt + 1) << 6;
; #pragma unroll
;       for (int i = 0; i < 2 * MI; ++i) ra[i] = *(const u4v*)(A + (size_t)(lrow + 32 * i) * lda + k0 + lseg * 8);
; #pragma unroll
;       for (int i = 0; i < 2 * NI; ++i) rb[i] = *(const u4v*)(Bt + (size_t)(lrow + 32 * i) * ldb + k0 + lseg * 8);
;     }
; #pragma unroll
;     for (int ks = 0; ks < 4; ++ks) {
;       s8v a[MI], b[NI];
; #pragma unroll
;       for (int mi = 0; mi < MI; ++mi) a[mi] = *(const s8v*)(sA + (wm * 32 * MI + mi * 32 + r) * 72 + ks * 16 + hh * 8);
; #pragma unroll
;       for (int ni = 0; ni < NI; ++ni) b[ni] = *(const s8v*)(sB + (wn * 32 * NI + ni * 32 + r) * 72 + ks * 16 + hh * 8);
; #pragma unroll
;       for (int mi = 0; mi < MI; ++mi)
; #pragma unroll
;         for (int ni = 0; ni < NI; ++ni) acc[mi][ni] = MFMA(a[mi], b[ni], acc[mi][ni]);
	ds_read_b128 v[186:189], v182
	ds_read_b128 v[204:207], v166 offset:36864
	ds_read_b128 v[208:211], v166 offset:40960
	ds_read_b128 v[190:193], v182 offset:4608
	ds_read_b128 v[196:199], v182 offset:9216
	ds_read_b128 v[200:203], v0
	ds_read_b128 v[212:215], v182 offset:32
	ds_read_b128 v[244:247], v167 offset:36864
	ds_read_b128 v[248:251], v167 offset:40960
	ds_read_b128 v[216:219], v182 offset:4640
	ds_read_b128 v[232:235], v182 offset:9248
	ds_read_b128 v[236:239], v0 offset:32
	s_waitcnt lgkmcnt(10)
	v_mfma_f32_32x32x16_bf16 v[114:129], v[186:189], v[204:207], v[114:129]
	s_add_u32 m0, s96, 16256
	s_nop 0
	s_waitcnt lgkmcnt(9)
	v_mfma_f32_32x32x16_bf16 v[98:113], v[186:189], v[208:211], v[98:113]
	global_load_lds_dwordx4 v134, s[58:59] offset:128
	ds_read_b128 v[186:189], v182 offset:64
	s_waitcnt lgkmcnt(9)
	v_mfma_f32_32x32x16_bf16 v[82:97], v[190:193], v[204:207], v[82:97]
	global_load_lds_dwordx4 v135, s[58:59] offset:1152
	v_mfma_f32_32x32x16_bf16 v[66:81], v[190:193], v[208:211], v[66:81]
	global_load_lds_dwordx4 v136, s[58:59] offset:2176
	ds_read_b128 v[190:193], v182 offset:4672
	s_waitcnt lgkmcnt(9)
	v_mfma_f32_32x32x16_bf16 v[50:65], v[196:199], v[204:207], v[50:65]
	global_load_lds_dwordx4 v137, s[58:59] offset:3200
	v_mfma_f32_32x32x16_bf16 v[34:49], v[196:199], v[208:211], v[34:49]
	global_load_dwordx4 v[130:133], v178, s[56:57] offset:128
	ds_read_b128 v[196:199], v182 offset:9280
	s_waitcnt lgkmcnt(9)
	v_mfma_f32_32x32x16_bf16 v[18:33], v[200:203], v[204:207], v[18:33]
	global_load_dwordx4 v[138:141], v179, s[56:57] offset:128
	v_mfma_f32_32x32x16_bf16 v[2:17], v[200:203], v[208:211], v[2:17]
	global_load_dwordx4 v[142:145], v180, s[56:57] offset:128
	ds_read_b128 v[200:203], v0 offset:64
	ds_read_b128 v[204:207], v168 offset:36864
	ds_read_b128 v[208:211], v168 offset:40960
	s_waitcnt lgkmcnt(10)
	v_mfma_f32_32x32x16_bf16 v[114:129], v[212:215], v[244:247], v[114:129]
	global_load_dwordx4 v[146:149], v181, s[56:57] offset:128
	s_waitcnt lgkmcnt(9)
	v_mfma_f32_32x32x16_bf16 v[98:113], v[212:215], v[248:251], v[98:113]
	global_load_dwordx4 v[150:153], v185, s[56:57] offset:128
	ds_read_b128 v[212:215], v182 offset:96
	s_waitcnt lgkmcnt(9)
	v_mfma_f32_32x32x16_bf16 v[82:97], v[216:219], v[244:247], v[82:97]
	global_load_dwordx4 v[154:157], v222, s[56:57] offset:128
	v_mfma_f32_32x32x16_bf16 v[66:81], v[216:219], v[248:251], v[66:81]
	global_load_dwordx4 v[158:161], v223, s[56:57] offset:128
	ds_read_b128 v[216:219], v182 offset:4704
	s_waitcnt lgkmcnt(9)
	v_mfma_f32_32x32x16_bf16 v[50:65], v[232:235], v[244:247], v[50:65]
	global_load_dwordx4 v[162:165], v227, s[56:57] offset:128
	v_mfma_f32_32x32x16_bf16 v[34:49], v[232:235], v[248:251], v[34:49]
	ds_read_b128 v[232:235], v182 offset:9312
	s_waitcnt lgkmcnt(9)
	v_mfma_f32_32x32x16_bf16 v[18:33], v[236:239], v[244:247], v[18:33]
	v_mfma_f32_32x32x16_bf16 v[2:17], v[236:239], v[248:251], v[2:17]
	ds_read_b128 v[236:239], v0 offset:96
	ds_read_b128 v[244:247], v169 offset:36864
	ds_read_b128 v[248:251], v169 offset:40960
	s_waitcnt lgkmcnt(7)
	v_mfma_f32_32x32x16_bf16 v[114:129], v[186:189], v[204:207], v[114:129]
	s_waitcnt lgkmcnt(6)
	v_mfma_f32_32x32x16_bf16 v[98:113], v[186:189], v[208:211], v[98:113]
	v_mfma_f32_32x32x16_bf16 v[82:97], v[190:193], v[204:207], v[82:97]
	v_mfma_f32_32x32x16_bf16 v[66:81], v[190:193], v[208:211], v[66:81]
	v_mfma_f32_32x32x16_bf16 v[50:65], v[196:199], v[204:207], v[50:65]
	v_mfma_f32_32x32x16_bf16 v[34:49], v[196:199], v[208:211], v[34:49]
	v_mfma_f32_32x32x16_bf16 v[2:17], v[200:203], v[208:211], v[2:17]
	v_mfma_f32_32x32x16_bf16 v[18:33], v[200:203], v[204:207], v[18:33]
	s_waitcnt lgkmcnt(1)
	v_mfma_f32_32x32x16_bf16 v[114:129], v[212:215], v[244:247], v[114:129]
	s_waitcnt lgkmcnt(0)
	v_mfma_f32_32x32x16_bf16 v[98:113], v[212:215], v[248:251], v[98:113]
	v_mfma_f32_32x32x16_bf16 v[82:97], v[216:219], v[244:247], v[82:97]
	v_mfma_f32_32x32x16_bf16 v[66:81], v[216:219], v[248:251], v[66:81]
	v_mfma_f32_32x32x16_bf16 v[50:65], v[232:235], v[244:247], v[50:65]
	v_mfma_f32_32x32x16_bf16 v[34:49], v[232:235], v[248:251], v[34:49]
	v_mfma_f32_32x32x16_bf16 v[18:33], v[236:239], v[244:247], v[18:33]
	v_mfma_f32_32x32x16_bf16 v[2:17], v[236:239], v[248:251], v[2:17]
	s_add_u32 s56, s56, 0x80
	s_addc_u32 s57, s57, 0
	s_add_u32 s58, s58, 0x80
	s_addc_u32 s59, s59, 0
	s_barrier
	s_waitcnt vmcnt(7)
	ds_write_b128 v184, v[130:133]
	s_waitcnt vmcnt(6)
	ds_write_b128 v184, v[138:141] offset:4608
	s_waitcnt vmcnt(5)
	ds_write_b128 v184, v[142:145] offset:9216
	s_waitcnt vmcnt(4)
	ds_write_b128 v184, v[146:149] offset:13824
	s_waitcnt vmcnt(3)
	ds_write_b128 v184, v[150:153] offset:18432
	s_waitcnt vmcnt(2)
	ds_write_b128 v184, v[154:157] offset:23040
	s_waitcnt vmcnt(1)
	ds_write_b128 v184, v[158:161] offset:27648
	s_waitcnt vmcnt(0)
	ds_write_b128 v184, v[162:165] offset:32256
	s_waitcnt lgkmcnt(0)
	s_barrier
; #define MFMA(a, b, c) __builtin_amdgcn_mfma_f32_32x32x16_bf16((a), (b), (c), 0, 0, 0)
; template <int MI, int NI>
; __device__ __forceinline__ void gemm_kloop(const bf16* __restrict__ A, size_t lda, const bf16* __restrict__ Bt, size_t ldb, int K,
;                                            f16v (&acc)[MI][NI], bf16* sA, bf16* sB) {
;     ...
;     for (int ks = 0; ks < 4; ++ks) {
;       s8v a[MI], b[NI];
; #pragma unroll
;       for (int mi = 0; mi < MI; ++mi) a[mi] = *(const s8v*)(sA + (wm * 32 * MI + mi * 32 + r) * 72 + ks * 16 + hh * 8);
; #pragma unroll
;       for (int ni = 0; ni < NI; ++ni) b[ni] = *(const s8v*)(sB + (wn * 32 * NI + ni * 32 + r) * 72 + ks * 16 + hh * 8);
; #pragma unroll
;       for (int mi = 0; mi < MI; ++mi)
; #pragma unroll
;         for (int ni = 0; ni < NI; ++ni) acc[mi][ni] = MFMA(a[mi], b[ni], acc[mi][ni]);
; __device__ __forceinline__ void gemm1_tile(const Params& p, int layer, int mt, int nt, bf16* sA, bf16* sB) {
;     ...
;   } else {
;     if (wn == 0) {
; #pragma unroll
;       for (int mi = 0; mi < 4; ++mi)
; #pragma unroll
;         for (int e = 0; e < 16; ++e) {
;           const int t = m0 + wm * 128 + mi * 32 + ROW_OF(e, hh);
;           p.glow[(size_t)t * 32 + r] = acc[mi][0][e];
;         }
;     }
	ds_read_b128 v[186:189], v182
	ds_read_b128 v[204:207], v166 offset:53248
	ds_read_b128 v[208:211], v166 offset:57344
	ds_read_b128 v[190:193], v182 offset:4608
	ds_read_b128 v[196:199], v182 offset:9216
	ds_read_b128 v[200:203], v0
	ds_read_b128 v[212:215], v182 offset:32
	ds_read_b128 v[244:247], v167 offset:53248
	ds_read_b128 v[248:251], v167 offset:57344
	ds_read_b128 v[216:219], v182 offset:4640
	ds_read_b128 v[232:235], v182 offset:9248
	ds_read_b128 v[236:239], v0 offset:32
	s_waitcnt lgkmcnt(10)
	v_mfma_f32_32x32x16_bf16 v[114:129], v[186:189], v[204:207], v[114:129]
	s_waitcnt lgkmcnt(9)
	v_mfma_f32_32x32x16_bf16 v[98:113], v[186:189], v[208:211], v[98:113]
	ds_read_b128 v[186:189], v182 offset:64
	s_waitcnt lgkmcnt(9)
	v_mfma_f32_32x32x16_bf16 v[82:97], v[190:193], v[204:207], v[82:97]
	v_mfma_f32_32x32x16_bf16 v[66:81], v[190:193], v[208:211], v[66:81]
	ds_read_b128 v[190:193], v182 offset:4672
	s_waitcnt lgkmcnt(9)
	v_mfma_f32_32x32x16_bf16 v[50:65], v[196:199], v[204:207], v[50:65]
	v_mfma_f32_32x32x16_bf16 v[34:49], v[196:199], v[208:211], v[34:49]
	ds_read_b128 v[196:199], v182 offset:9280
	s_waitcnt lgkmcnt(9)
	v_mfma_f32_32x32x16_bf16 v[18:33], v[200:203], v[204:207], v[18:33]
	v_mfma_f32_32x32x16_bf16 v[2:17], v[200:203], v[208:211], v[2:17]
	ds_read_b128 v[200:203], v0 offset:64
	ds_read_b128 v[204:207], v168 offset:53248
	ds_read_b128 v[208:211], v168 offset:57344
	s_waitcnt lgkmcnt(10)
	v_mfma_f32_32x32x16_bf16 v[114:129], v[212:215], v[244:247], v[114:129]
	s_waitcnt lgkmcnt(9)
	v_mfma_f32_32x32x16_bf16 v[98:113], v[212:215], v[248:251], v[98:113]
	ds_read_b128 v[212:215], v182 offset:96
	s_waitcnt lgkmcnt(9)
	v_mfma_f32_32x32x16_bf16 v[82:97], v[216:219], v[244:247], v[82:97]
	v_mfma_f32_32x32x16_bf16 v[66:81], v[216:219], v[248:251], v[66:81]
	ds_read_b128 v[216:219], v182 offset:4704
	s_waitcnt lgkmcnt(9)
	v_mfma_f32_32x32x16_bf16 v[50:65], v[232:235], v[244:247], v[50:65]
	v_mfma_f32_32x32x16_bf16 v[34:49], v[232:235], v[248:251], v[34:49]
	ds_read_b128 v[232:235], v182 offset:9312
	s_waitcnt lgkmcnt(9)
	v_mfma_f32_32x32x16_bf16 v[18:33], v[236:239], v[244:247], v[18:33]
	v_mfma_f32_32x32x16_bf16 v[2:17], v[236:239], v[248:251], v[2:17]
	ds_read_b128 v[236:239], v0 offset:96
	ds_read_b128 v[244:247], v169 offset:53248
	ds_read_b128 v[248:251], v169 offset:57344
	s_waitcnt lgkmcnt(7)
	v_mfma_f32_32x32x16_bf16 v[114:129], v[186:189], v[204:207], v[114:129]
	s_waitcnt lgkmcnt(6)
	v_mfma_f32_32x32x16_bf16 v[98:113], v[186:189], v[208:211], v[98:113]
	v_mfma_f32_32x32x16_bf16 v[82:97], v[190:193], v[204:207], v[82:97]
	v_mfma_f32_32x32x16_bf16 v[66:81], v[190:193], v[208:211], v[66:81]
	v_mfma_f32_32x32x16_bf16 v[50:65], v[196:199], v[204:207], v[50:65]
	v_mfma_f32_32x32x16_bf16 v[34:49], v[196:199], v[208:211], v[34:49]
	v_mfma_f32_32x32x16_bf16 v[2:17], v[200:203], v[208:211], v[2:17]
	v_mfma_f32_32x32x16_bf16 v[18:33], v[200:203], v[204:207], v[18:33]
	s_waitcnt lgkmcnt(1)
	v_mfma_f32_32x32x16_bf16 v[114:129], v[212:215], v[244:247], v[114:129]
	s_waitcnt lgkmcnt(0)
	v_mfma_f32_32x32x16_bf16 v[98:113], v[212:215], v[248:251], v[98:113]
	v_mfma_f32_32x32x16_bf16 v[82:97], v[216:219], v[244:247], v[82:97]
	v_mfma_f32_32x32x16_bf16 v[66:81], v[216:219], v[248:251], v[66:81]
	v_mfma_f32_32x32x16_bf16 v[50:65], v[232:235], v[244:247], v[50:65]
	v_mfma_f32_32x32x16_bf16 v[34:49], v[232:235], v[248:251], v[34:49]
	v_mfma_f32_32x32x16_bf16 v[18:33], v[236:239], v[244:247], v[18:33]
	v_mfma_f32_32x32x16_bf16 v[2:17], v[236:239], v[248:251], v[2:17]
	s_nop 15
	s_mov_b64 s[24:25], -1
	s_cmp_gt_i32 s22, 4
	v_mov_b32_e32 v137, v195
	v_mov_b32_e32 v135, v195
	s_nop 0
	v_and_b32_e32 v134, 31, v137
	v_bfe_u32 v140, v135, 6, 1
	v_bfe_u32 v145, v137, 5, 1
	s_cbranch_scc0 .LBB0_1621
	s_cmp_lg_u32 s22, 5
	s_cbranch_scc0 .LBB0_1618
	s_cmp_gt_u32 s22, 29
	s_cbranch_scc0 .LBB0_1603
	v_cmp_eq_u32_e32 vcc, 0, v140
	s_and_saveexec_b64 s[24:25], vcc
	s_cbranch_execz .LBB0_1602
	v_and_b32_e32 v0, 0xffffff80, v135
	v_add_u32_e32 v0, s20, v0
	v_lshl_or_b32 v130, v145, 2, v0
	v_readlane_b32 s64, v254, 18
	v_lshlrev_b32_e32 v0, 2, v134
	v_readlane_b32 s72, v254, 26
	v_readlane_b32 s73, v254, 27
	v_ashrrev_i32_e32 v131, 31, v130
	v_lshlrev_b64 v[138:139], 7, v[130:131]
	v_lshl_add_u64 v[132:133], s[72:73], 0, v[0:1]
	v_lshl_add_u64 v[138:139], v[132:133], 0, v[138:139]
	global_store_dword v[138:139], v114, off
	v_or_b32_e32 v138, 1, v130
	v_ashrrev_i32_e32 v139, 31, v138
	v_lshlrev_b64 v[138:139], 7, v[138:139]
	v_lshl_add_u64 v[138:139], v[132:133], 0, v[138:139]
	global_store_dword v[138:139], v115, off
	v_or_b32_e32 v138, 2, v130
	v_ashrrev_i32_e32 v139, 31, v138
	v_lshlrev_b64 v[138:139], 7, v[138:139]
	v_lshl_add_u64 v[138:139], v[132:133], 0, v[138:139]
	global_store_dword v[138:139], v116, off
	v_or_b32_e32 v138, 3, v130
	v_ashrrev_i32_e32 v139, 31, v138
	v_lshlrev_b64 v[138:139], 7, v[138:139]
	v_lshl_add_u64 v[138:139], v[132:133], 0, v[138:139]
	global_store_dword v[138:139], v117, off
	v_or_b32_e32 v138, 8, v130
	v_ashrrev_i32_e32 v139, 31, v138
	v_lshlrev_b64 v[138:139], 7, v[138:139]
	v_lshl_add_u64 v[138:139], v[132:133], 0, v[138:139]
	global_store_dword v[138:139], v118, off
	v_or_b32_e32 v138, 9, v130
	v_ashrrev_i32_e32 v139, 31, v138
	v_lshlrev_b64 v[138:139], 7, v[138:139]
	v_lshl_add_u64 v[138:139], v[132:133], 0, v[138:139]
	global_store_dword v[138:139], v119, off
	v_or_b32_e32 v138, 10, v130
	v_ashrrev_i32_e32 v139, 31, v138
	v_lshlrev_b64 v[138:139], 7, v[138:139]
	v_lshl_add_u64 v[138:139], v[132:133], 0, v[138:139]
	global_store_dword v[138:139], v120, off
	v_or_b32_e32 v138, 11, v130
	v_ashrrev_i32_e32 v139, 31, v138
; __device__ __forceinline__ void gemm1_tile(const Params& p, int layer, int mt, int nt, bf16* sA, bf16* sB) {
;     ...
;   } else {
;     if (wn == 0) {
; #pragma unroll
;       for (int mi = 0; mi < 4; ++mi)
; #pragma unroll
;         for (int e = 0; e < 16; ++e) {
;           const int t = m0 + wm * 128 + mi * 32 + ROW_OF(e, hh);
;           p.glow[(size_t)t * 32 + r] = acc[mi][0][e];
;         }
;     }
	v_lshlrev_b64 v[138:139], 7, v[138:139]
	v_lshl_add_u64 v[138:139], v[132:133], 0, v[138:139]
	global_store_dword v[138:139], v121, off
	v_or_b32_e32 v138, 16, v130
	v_ashrrev_i32_e32 v139, 31, v138
	v_lshlrev_b64 v[138:139], 7, v[138:139]
	v_lshl_add_u64 v[138:139], v[132:133], 0, v[138:139]
	global_store_dword v[138:139], v122, off
	v_or_b32_e32 v138, 17, v130
	v_ashrrev_i32_e32 v139, 31, v138
	v_lshlrev_b64 v[138:139], 7, v[138:139]
	v_lshl_add_u64 v[138:139], v[132:133], 0, v[138:139]
	global_store_dword v[138:139], v123, off
	v_or_b32_e32 v138, 18, v130
	v_ashrrev_i32_e32 v139, 31, v138
	v_lshlrev_b64 v[138:139], 7, v[138:139]
	v_lshl_add_u64 v[138:139], v[132:133], 0, v[138:139]
	global_store_dword v[138:139], v124, off
	v_or_b32_e32 v138, 19, v130
	v_ashrrev_i32_e32 v139, 31, v138
	v_lshlrev_b64 v[138:139], 7, v[138:139]
	v_lshl_add_u64 v[138:139], v[132:133], 0, v[138:139]
	global_store_dword v[138:139], v125, off
	v_or_b32_e32 v138, 24, v130
	v_ashrrev_i32_e32 v139, 31, v138
	v_lshlrev_b64 v[138:139], 7, v[138:139]
	v_lshl_add_u64 v[138:139], v[132:133], 0, v[138:139]
	global_store_dword v[138:139], v126, off
	v_or_b32_e32 v138, 25, v130
	v_ashrrev_i32_e32 v139, 31, v138
	v_lshlrev_b64 v[138:139], 7, v[138:139]
	v_lshl_add_u64 v[138:139], v[132:133], 0, v[138:139]
	global_store_dword v[138:139], v127, off
	v_or_b32_e32 v138, 26, v130
	v_ashrrev_i32_e32 v139, 31, v138
	v_lshlrev_b64 v[138:139], 7, v[138:139]
	v_lshl_add_u64 v[138:139], v[132:133], 0, v[138:139]
	global_store_dword v[138:139], v128, off
	v_or_b32_e32 v138, 27, v130
	v_ashrrev_i32_e32 v139, 31, v138
	v_lshlrev_b64 v[138:139], 7, v[138:139]
	v_lshl_add_u64 v[138:139], v[132:133], 0, v[138:139]
	global_store_dword v[138:139], v129, off
	v_or_b32_e32 v138, 32, v130
	v_ashrrev_i32_e32 v139, 31, v138
	v_lshlrev_b64 v[138:139], 7, v[138:139]
	v_lshl_add_u64 v[138:139], v[132:133], 0, v[138:139]
	global_store_dword v[138:139], v82, off
	v_or_b32_e32 v138, 33, v130
	v_ashrrev_i32_e32 v139, 31, v138
	v_lshlrev_b64 v[138:139], 7, v[138:139]
	v_lshl_add_u64 v[138:139], v[132:133], 0, v[138:139]
	global_store_dword v[138:139], v83, off
	v_or_b32_e32 v138, 34, v130
	v_ashrrev_i32_e32 v139, 31, v138
	v_lshlrev_b64 v[138:139], 7, v[138:139]
	v_lshl_add_u64 v[138:139], v[132:133], 0, v[138:139]
	global_store_dword v[138:139], v84, off
	v_or_b32_e32 v138, 35, v130
	v_ashrrev_i32_e32 v139, 31, v138
	v_lshlrev_b64 v[138:139], 7, v[138:139]
	v_lshl_add_u64 v[138:139], v[132:133], 0, v[138:139]
	global_store_dword v[138:139], v85, off
	v_or_b32_e32 v138, 40, v130
	v_ashrrev_i32_e32 v139, 31, v138
	v_lshlrev_b64 v[138:139], 7, v[138:139]
	v_lshl_add_u64 v[138:139], v[132:133], 0, v[138:139]
	global_store_dword v[138:139], v86, off
	v_or_b32_e32 v138, 41, v130
	v_ashrrev_i32_e32 v139, 31, v138
	v_lshlrev_b64 v[138:139], 7, v[138:139]
	v_lshl_add_u64 v[138:139], v[132:133], 0, v[138:139]
	global_store_dword v[138:139], v87, off
	v_or_b32_e32 v138, 42, v130
	v_ashrrev_i32_e32 v139, 31, v138
	v_lshlrev_b64 v[138:139], 7, v[138:139]
	v_lshl_add_u64 v[138:139], v[132:133], 0, v[138:139]
	global_store_dword v[138:139], v88, off
	v_or_b32_e32 v138, 43, v130
	v_ashrrev_i32_e32 v139, 31, v138
	v_lshlrev_b64 v[138:139], 7, v[138:139]
	v_lshl_add_u64 v[138:139], v[132:133], 0, v[138:139]
	global_store_dword v[138:139], v89, off
	v_or_b32_e32 v138, 48, v130
	v_ashrrev_i32_e32 v139, 31, v138
	v_lshlrev_b64 v[138:139], 7, v[138:139]
	v_lshl_add_u64 v[138:139], v[132:133], 0, v[138:139]
	global_store_dword v[138:139], v90, off
	v_or_b32_e32 v138, 49, v130
	v_ashrrev_i32_e32 v139, 31, v138
	v_lshlrev_b64 v[138:139], 7, v[138:139]
	v_lshl_add_u64 v[138:139], v[132:133], 0, v[138:139]
	global_store_dword v[138:139], v91, off
	v_or_b32_e32 v138, 50, v130
	v_ashrrev_i32_e32 v139, 31, v138
	v_lshlrev_b64 v[138:139], 7, v[138:139]
	v_lshl_add_u64 v[138:139], v[132:133], 0, v[138:139]
	global_store_dword v[138:139], v92, off
	v_or_b32_e32 v138, 51, v130
	v_ashrrev_i32_e32 v139, 31, v138
	v_lshlrev_b64 v[138:139], 7, v[138:139]
	v_lshl_add_u64 v[138:139], v[132:133], 0, v[138:139]
	global_store_dword v[138:139], v93, off
	v_or_b32_e32 v138, 56, v130
	v_ashrrev_i32_e32 v139, 31, v138
	v_lshlrev_b64 v[138:139], 7, v[138:139]
	v_lshl_add_u64 v[138:139], v[132:133], 0, v[138:139]
	global_store_dword v[138:139], v94, off
	v_or_b32_e32 v138, 57, v130
	v_ashrrev_i32_e32 v139, 31, v138
	v_lshlrev_b64 v[138:139], 7, v[138:139]
	v_lshl_add_u64 v[138:139], v[132:133], 0, v[138:139]
	global_store_dword v[138:139], v95, off
	v_or_b32_e32 v138, 58, v130
	v_ashrrev_i32_e32 v139, 31, v138
	v_lshlrev_b64 v[138:139], 7, v[138:139]
	v_lshl_add_u64 v[138:139], v[132:133], 0, v[138:139]
	global_store_dword v[138:139], v96, off
	v_or_b32_e32 v138, 59, v130
	v_ashrrev_i32_e32 v139, 31, v138
	v_lshlrev_b64 v[138:139], 7, v[138:139]
	v_lshl_add_u64 v[138:139], v[132:133], 0, v[138:139]
	global_store_dword v[138:139], v97, off
	v_or_b32_e32 v138, 64, v130
	v_ashrrev_i32_e32 v139, 31, v138
	v_lshlrev_b64 v[138:139], 7, v[138:139]
	v_lshl_add_u64 v[138:139], v[132:133], 0, v[138:139]
	global_store_dword v[138:139], v50, off
	v_or_b32_e32 v138, 0x41, v130
	v_ashrrev_i32_e32 v139, 31, v138
	v_lshlrev_b64 v[138:139], 7, v[138:139]
	v_lshl_add_u64 v[138:139], v[132:133], 0, v[138:139]
	global_store_dword v[138:139], v51, off
	v_or_b32_e32 v138, 0x42, v130
	v_ashrrev_i32_e32 v139, 31, v138
	v_lshlrev_b64 v[138:139], 7, v[138:139]
	v_lshl_add_u64 v[138:139], v[132:133], 0, v[138:139]
	global_store_dword v[138:139], v52, off
	v_or_b32_e32 v138, 0x43, v130
	v_ashrrev_i32_e32 v139, 31, v138
	v_lshlrev_b64 v[138:139], 7, v[138:139]
; __device__ __forceinline__ void gemm1_tile(const Params& p, int layer, int mt, int nt, bf16* sA, bf16* sB) {
;     ...
;     if (wn == 0) {
; #pragma unroll
;       for (int mi = 0; mi < 4; ++mi)
; #pragma unroll
;         for (int e = 0; e < 16; ++e) {
;           const int t = m0 + wm * 128 + mi * 32 + ROW_OF(e, hh);
;           p.glow[(size_t)t * 32 + r] = acc[mi][0][e];
;         }
;     }
	v_lshl_add_u64 v[138:139], v[132:133], 0, v[138:139]
	global_store_dword v[138:139], v53, off
	v_or_b32_e32 v138, 0x48, v130
	v_ashrrev_i32_e32 v139, 31, v138
	v_lshlrev_b64 v[138:139], 7, v[138:139]
	v_lshl_add_u64 v[138:139], v[132:133], 0, v[138:139]
	global_store_dword v[138:139], v54, off
	v_or_b32_e32 v138, 0x49, v130
	v_ashrrev_i32_e32 v139, 31, v138
	v_lshlrev_b64 v[138:139], 7, v[138:139]
	v_lshl_add_u64 v[138:139], v[132:133], 0, v[138:139]
	global_store_dword v[138:139], v55, off
	v_or_b32_e32 v138, 0x4a, v130
	v_ashrrev_i32_e32 v139, 31, v138
	v_lshlrev_b64 v[138:139], 7, v[138:139]
	v_lshl_add_u64 v[138:139], v[132:133], 0, v[138:139]
	global_store_dword v[138:139], v56, off
	v_or_b32_e32 v138, 0x4b, v130
	v_ashrrev_i32_e32 v139, 31, v138
	v_lshlrev_b64 v[138:139], 7, v[138:139]
	v_lshl_add_u64 v[138:139], v[132:133], 0, v[138:139]
	global_store_dword v[138:139], v57, off
	v_or_b32_e32 v138, 0x50, v130
	v_ashrrev_i32_e32 v139, 31, v138
	v_lshlrev_b64 v[138:139], 7, v[138:139]
	v_lshl_add_u64 v[138:139], v[132:133], 0, v[138:139]
	global_store_dword v[138:139], v58, off
	v_or_b32_e32 v138, 0x51, v130
	v_ashrrev_i32_e32 v139, 31, v138
	v_lshlrev_b64 v[138:139], 7, v[138:139]
	v_lshl_add_u64 v[138:139], v[132:133], 0, v[138:139]
	global_store_dword v[138:139], v59, off
	v_or_b32_e32 v138, 0x52, v130
	v_ashrrev_i32_e32 v139, 31, v138
	v_lshlrev_b64 v[138:139], 7, v[138:139]
	v_lshl_add_u64 v[138:139], v[132:133], 0, v[138:139]
	global_store_dword v[138:139], v60, off
	v_or_b32_e32 v138, 0x53, v130
	v_ashrrev_i32_e32 v139, 31, v138
	v_lshlrev_b64 v[138:139], 7, v[138:139]
	v_lshl_add_u64 v[138:139], v[132:133], 0, v[138:139]
	global_store_dword v[138:139], v61, off
	v_or_b32_e32 v138, 0x58, v130
	v_ashrrev_i32_e32 v139, 31, v138
	v_lshlrev_b64 v[138:139], 7, v[138:139]
	v_lshl_add_u64 v[138:139], v[132:133], 0, v[138:139]
	global_store_dword v[138:139], v62, off
	v_or_b32_e32 v138, 0x59, v130
	v_ashrrev_i32_e32 v139, 31, v138
	v_lshlrev_b64 v[138:139], 7, v[138:139]
	v_lshl_add_u64 v[138:139], v[132:133], 0, v[138:139]
	global_store_dword v[138:139], v63, off
	v_or_b32_e32 v138, 0x5a, v130
	v_ashrrev_i32_e32 v139, 31, v138
	v_lshlrev_b64 v[138:139], 7, v[138:139]
	v_lshl_add_u64 v[138:139], v[132:133], 0, v[138:139]
	global_store_dword v[138:139], v64, off
	v_or_b32_e32 v138, 0x5b, v130
	v_ashrrev_i32_e32 v139, 31, v138
	v_lshlrev_b64 v[138:139], 7, v[138:139]
	v_lshl_add_u64 v[138:139], v[132:133], 0, v[138:139]
	global_store_dword v[138:139], v65, off
	v_or_b32_e32 v138, 0x60, v130
	v_ashrrev_i32_e32 v139, 31, v138
	v_lshlrev_b64 v[138:139], 7, v[138:139]
	v_lshl_add_u64 v[138:139], v[132:133], 0, v[138:139]
	global_store_dword v[138:139], v18, off
	v_or_b32_e32 v138, 0x61, v130
	v_ashrrev_i32_e32 v139, 31, v138
	v_lshlrev_b64 v[138:139], 7, v[138:139]
	v_lshl_add_u64 v[138:139], v[132:133], 0, v[138:139]
	global_store_dword v[138:139], v19, off
	v_or_b32_e32 v138, 0x62, v130
	v_ashrrev_i32_e32 v139, 31, v138
	v_lshlrev_b64 v[138:139], 7, v[138:139]
	v_lshl_add_u64 v[138:139], v[132:133], 0, v[138:139]
	global_store_dword v[138:139], v20, off
	v_or_b32_e32 v138, 0x63, v130
	v_ashrrev_i32_e32 v139, 31, v138
	v_lshlrev_b64 v[138:139], 7, v[138:139]
	v_lshl_add_u64 v[138:139], v[132:133], 0, v[138:139]
	global_store_dword v[138:139], v21, off
	v_or_b32_e32 v138, 0x68, v130
	v_ashrrev_i32_e32 v139, 31, v138
	v_lshlrev_b64 v[138:139], 7, v[138:139]
	v_lshl_add_u64 v[138:139], v[132:133], 0, v[138:139]
	global_store_dword v[138:139], v22, off
	v_or_b32_e32 v138, 0x69, v130
	v_ashrrev_i32_e32 v139, 31, v138
	v_lshlrev_b64 v[138:139], 7, v[138:139]
	v_lshl_add_u64 v[138:139], v[132:133], 0, v[138:139]
	global_store_dword v[138:139], v23, off
	v_or_b32_e32 v138, 0x6a, v130
	v_ashrrev_i32_e32 v139, 31, v138
	v_lshlrev_b64 v[138:139], 7, v[138:139]
	v_lshl_add_u64 v[138:139], v[132:133], 0, v[138:139]
	global_store_dword v[138:139], v24, off
	v_or_b32_e32 v138, 0x6b, v130
	v_ashrrev_i32_e32 v139, 31, v138
	v_lshlrev_b64 v[138:139], 7, v[138:139]
	v_lshl_add_u64 v[138:139], v[132:133], 0, v[138:139]
	global_store_dword v[138:139], v25, off
	v_or_b32_e32 v138, 0x70, v130
	v_ashrrev_i32_e32 v139, 31, v138
	v_lshlrev_b64 v[138:139], 7, v[138:139]
	v_lshl_add_u64 v[138:139], v[132:133], 0, v[138:139]
	global_store_dword v[138:139], v26, off
	v_or_b32_e32 v138, 0x71, v130
	v_ashrrev_i32_e32 v139, 31, v138
	v_lshlrev_b64 v[138:139], 7, v[138:139]
	v_lshl_add_u64 v[138:139], v[132:133], 0, v[138:139]
	global_store_dword v[138:139], v27, off
	v_or_b32_e32 v138, 0x72, v130
	v_ashrrev_i32_e32 v139, 31, v138
	v_lshlrev_b64 v[138:139], 7, v[138:139]
	v_lshl_add_u64 v[138:139], v[132:133], 0, v[138:139]
	global_store_dword v[138:139], v28, off
	v_or_b32_e32 v138, 0x73, v130
	v_ashrrev_i32_e32 v139, 31, v138
	v_lshlrev_b64 v[138:139], 7, v[138:139]
	v_lshl_add_u64 v[138:139], v[132:133], 0, v[138:139]
	global_store_dword v[138:139], v29, off
	v_or_b32_e32 v138, 0x78, v130
	v_ashrrev_i32_e32 v139, 31, v138
	v_lshlrev_b64 v[138:139], 7, v[138:139]
	v_lshl_add_u64 v[138:139], v[132:133], 0, v[138:139]
	global_store_dword v[138:139], v30, off
	v_or_b32_e32 v138, 0x79, v130
	v_ashrrev_i32_e32 v139, 31, v138
	v_lshlrev_b64 v[138:139], 7, v[138:139]
	v_lshl_add_u64 v[138:139], v[132:133], 0, v[138:139]
	global_store_dword v[138:139], v31, off
	v_or_b32_e32 v138, 0x7a, v130
	v_or_b32_e32 v130, 0x7b, v130
	v_ashrrev_i32_e32 v139, 31, v138
	v_ashrrev_i32_e32 v131, 31, v130
	v_lshlrev_b64 v[138:139], 7, v[138:139]
	v_lshlrev_b64 v[130:131], 7, v[130:131]
	v_lshl_add_u64 v[138:139], v[132:133], 0, v[138:139]
	v_lshl_add_u64 v[130:131], v[132:133], 0, v[130:131]
	v_readlane_b32 s65, v254, 19
	v_readlane_b32 s66, v254, 20
	v_readlane_b32 s67, v254, 21
	v_readlane_b32 s68, v254, 22
	v_readlane_b32 s69, v254, 23
	v_readlane_b32 s70, v254, 24
	v_readlane_b32 s71, v254, 25
	v_readlane_b32 s74, v254, 28
	v_readlane_b32 s75, v254, 29
	v_readlane_b32 s76, v254, 30
	v_readlane_b32 s77, v254, 31
	v_readlane_b32 s78, v254, 32
	v_readlane_b32 s79, v254, 33
	global_store_dword v[138:139], v32, off
	global_store_dword v[130:131], v33, off

; __device__ __forceinline__ int tid_opaque() { int t = threadIdx.x; asm volatile("" : "+v"(t)); return t; }
; __device__ __forceinline__ unsigned pack2(float a, float b) { f2_t f = {a, b}; return __builtin_bit_cast(unsigned, __builtin_convertvector(f, bf2_t)); }
; __device__ __forceinline__ void conv_tile(const Params& p, int layer, int item, float* sT) {
;     ...
;   const int tid = tid_opaque();
;   {
;     const int n = tid & 63, kq = tid >> 6;
;     const int j = nt * 64 + n;
;     const float* sp = src;
;     int col = col0 + j;
;     bool valid = j < nvalid;
;     if (mode == 1) {
;       int blk = j >> 7, wn = (j >> 6) & 1, ni = (j >> 5) & 1, c = j & 31;
;       col = blk * 64 + wn * 32 + c;
;       sp = ni ? src2 : src;
;     }
; #pragma unroll
;     for (int kk = 0; kk < 16; ++kk) {
;       int kr = kt * 64 + kq * 16 + kk;
;       float v = valid ? sp[(size_t)kr * ld + col] : 0.f;
;       sT[(kq * 16 + kk) * 65 + n] = v;
;     }
;   }
;   __syncthreads();
;   {
;     const int n = tid >> 2, ks = tid & 3;
;     unsigned u[8];
; #pragma unroll
;     for (int e = 0; e < 8; ++e) u[e] = pack2(sT[(ks * 16 + 2 * e) * 65 + n], sT[(ks * 16 + 2 * e + 1) * 65 + n]);
;     u4v* d4 = (u4v*)(dst + (size_t)(nt * 64 + n) * K + kt * 64 + ks * 16);
;     d4[0] = (u4v){u[0], u[1], u[2], u[3]};
;     d4[1] = (u4v){u[4], u[5], u[6], u[7]};
;   }
.LBB0_1654:
	v_mov_b32_e32 v6, v195
	s_lshl_b32 s0, s45, 6
	v_and_b32_e32 v2, 63, v6
	v_or_b32_e32 v0, s0, v2
	v_and_b32_e32 v3, 32, v6
	v_cmp_gt_u32_e32 vcc, s43, v0
	v_cmp_le_u32_e64 s[40:41], s43, v0
	v_cmp_eq_u32_e64 s[42:43], 0, v3
	v_ashrrev_i32_e32 v3, 2, v6
	v_and_b32_e32 v4, -16, v3
	s_movk_i32 s64, 0x104
	v_lshlrev_b32_e32 v2, 2, v2
	v_mul_lo_u32 v8, v4, s64
	s_lshl_b32 s45, s45, 5
	v_mov_b32_e32 v7, s88
	v_mov_b32_e32 v9, s84
	v_mov_b32_e32 v10, s89
	v_mov_b32_e32 v11, s85
	v_add_u32_e32 v0, s68, v0
	v_and_or_b32 v5, v6, 31, s45
	v_cndmask_b32_e64 v7, v7, v9, s[42:43]
	v_cndmask_b32_e64 v10, v10, v11, s[42:43]
	s_lshl_b32 s45, s67, 6
	v_cndmask_b32_e64 v0, v0, v5, s[86:87]
	v_cndmask_b32_e64 v11, v11, v10, s[86:87]
	v_cndmask_b32_e64 v10, v9, v7, s[86:87]
	v_add_u32_e32 v7, s45, v4
	v_lshl_add_u64 v[4:5], v[0:1], 2, v[10:11]
	v_ashrrev_i32_e32 v0, 31, v7
	v_mul_lo_u32 v0, s82, v0
	v_add_u32_e32 v8, v2, v8
	v_mov_b32_e32 v16, 0
	v_mov_b32_e32 v17, 0
	v_mov_b32_e32 v18, 0
	v_mov_b32_e32 v19, 0
	v_mov_b32_e32 v20, 0
	v_mov_b32_e32 v21, 0
	v_mov_b32_e32 v22, 0
	v_mov_b32_e32 v23, 0
	v_mov_b32_e32 v24, 0
	v_mov_b32_e32 v25, 0
	v_mov_b32_e32 v26, 0
	v_mov_b32_e32 v27, 0
	v_mov_b32_e32 v28, 0
	v_mov_b32_e32 v29, 0
	v_mov_b32_e32 v30, 0
	v_mov_b32_e32 v31, 0
	s_and_saveexec_b64 s[90:91], vcc
	v_mul_lo_u32 v12, s83, v7
	v_mad_u64_u32 v[10:11], s[70:71], s82, v7, 0
	v_add3_u32 v11, v11, v0, v12
	v_lshl_add_u64 v[10:11], v[10:11], 2, v[4:5]
	global_load_dword v16, v[10:11], off
	v_or_b32_e32 v9, 1, v7
	v_mul_lo_u32 v12, s83, v9
	v_mad_u64_u32 v[10:11], s[70:71], s82, v9, 0
	v_add3_u32 v11, v11, v0, v12
	v_lshl_add_u64 v[10:11], v[10:11], 2, v[4:5]
	global_load_dword v17, v[10:11], off
	v_or_b32_e32 v9, 2, v7
	v_mul_lo_u32 v12, s83, v9
	v_mad_u64_u32 v[10:11], s[70:71], s82, v9, 0
	v_add3_u32 v11, v11, v0, v12
	v_lshl_add_u64 v[10:11], v[10:11], 2, v[4:5]
	global_load_dword v18, v[10:11], off
	v_or_b32_e32 v9, 3, v7
	v_mul_lo_u32 v12, s83, v9
	v_mad_u64_u32 v[10:11], s[70:71], s82, v9, 0
	v_add3_u32 v11, v11, v0, v12
	v_lshl_add_u64 v[10:11], v[10:11], 2, v[4:5]
	global_load_dword v19, v[10:11], off
	v_or_b32_e32 v9, 4, v7
	v_mul_lo_u32 v12, s83, v9
	v_mad_u64_u32 v[10:11], s[70:71], s82, v9, 0
	v_add3_u32 v11, v11, v0, v12
	v_lshl_add_u64 v[10:11], v[10:11], 2, v[4:5]
	global_load_dword v20, v[10:11], off
	v_or_b32_e32 v9, 5, v7
	v_mul_lo_u32 v12, s83, v9
	v_mad_u64_u32 v[10:11], s[70:71], s82, v9, 0
	v_add3_u32 v11, v11, v0, v12
	v_lshl_add_u64 v[10:11], v[10:11], 2, v[4:5]
	global_load_dword v21, v[10:11], off
	v_or_b32_e32 v9, 6, v7
	v_mul_lo_u32 v12, s83, v9
	v_mad_u64_u32 v[10:11], s[70:71], s82, v9, 0
	v_add3_u32 v11, v11, v0, v12
	v_lshl_add_u64 v[10:11], v[10:11], 2, v[4:5]
	global_load_dword v22, v[10:11], off
	v_or_b32_e32 v9, 7, v7
	v_mul_lo_u32 v12, s83, v9
	v_mad_u64_u32 v[10:11], s[70:71], s82, v9, 0
	v_add3_u32 v11, v11, v0, v12
	v_lshl_add_u64 v[10:11], v[10:11], 2, v[4:5]
	global_load_dword v23, v[10:11], off
	v_or_b32_e32 v9, 8, v7
	v_mul_lo_u32 v12, s83, v9
	v_mad_u64_u32 v[10:11], s[70:71], s82, v9, 0
	v_add3_u32 v11, v11, v0, v12
	v_lshl_add_u64 v[10:11], v[10:11], 2, v[4:5]
	global_load_dword v24, v[10:11], off
	v_or_b32_e32 v9, 9, v7
	v_mul_lo_u32 v12, s83, v9
	v_mad_u64_u32 v[10:11], s[70:71], s82, v9, 0
	v_add3_u32 v11, v11, v0, v12
	v_lshl_add_u64 v[10:11], v[10:11], 2, v[4:5]
	global_load_dword v25, v[10:11], off
	v_or_b32_e32 v9, 10, v7
	v_mul_lo_u32 v12, s83, v9
	v_mad_u64_u32 v[10:11], s[70:71], s82, v9, 0
	v_add3_u32 v11, v11, v0, v12
	v_lshl_add_u64 v[10:11], v[10:11], 2, v[4:5]
	global_load_dword v26, v[10:11], off
	v_or_b32_e32 v9, 11, v7
	v_mul_lo_u32 v12, s83, v9
	v_mad_u64_u32 v[10:11], s[70:71], s82, v9, 0
	v_add3_u32 v11, v11, v0, v12
	v_lshl_add_u64 v[10:11], v[10:11], 2, v[4:5]
	global_load_dword v27, v[10:11], off
	v_or_b32_e32 v9, 12, v7
	v_mul_lo_u32 v12, s83, v9
	v_mad_u64_u32 v[10:11], s[70:71], s82, v9, 0
	v_add3_u32 v11, v11, v0, v12
	v_lshl_add_u64 v[10:11], v[10:11], 2, v[4:5]
	global_load_dword v28, v[10:11], off
	v_or_b32_e32 v9, 13, v7
	v_mul_lo_u32 v12, s83, v9
	v_mad_u64_u32 v[10:11], s[70:71], s82, v9, 0
	v_add3_u32 v11, v11, v0, v12
	v_lshl_add_u64 v[10:11], v[10:11], 2, v[4:5]
	global_load_dword v29, v[10:11], off
	v_or_b32_e32 v9, 14, v7
	v_mul_lo_u32 v12, s83, v9
	v_mad_u64_u32 v[10:11], s[70:71], s82, v9, 0
	v_add3_u32 v11, v11, v0, v12
	v_lshl_add_u64 v[10:11], v[10:11], 2, v[4:5]
	global_load_dword v30, v[10:11], off
	v_or_b32_e32 v9, 15, v7
	v_mul_lo_u32 v12, s83, v9
	v_mad_u64_u32 v[10:11], s[70:71], s82, v9, 0
	v_add3_u32 v11, v11, v0, v12
	v_lshl_add_u64 v[10:11], v[10:11], 2, v[4:5]
	global_load_dword v31, v[10:11], off
	s_or_b64 exec, exec, s[90:91]
	v_readlane_b32 s88, v254, 53
	s_waitcnt vmcnt(0)
	ds_write_b32 v8, v16
	ds_write_b32 v8, v17 offset:260
	ds_write_b32 v8, v18 offset:520
	ds_write_b32 v8, v19 offset:780
	ds_write_b32 v8, v20 offset:1040
	ds_write_b32 v8, v21 offset:1300
	ds_write_b32 v8, v22 offset:1560
	ds_write_b32 v8, v23 offset:1820
	ds_write_b32 v8, v24 offset:2080
	ds_write_b32 v8, v25 offset:2340
	ds_write_b32 v8, v26 offset:2600
	ds_write_b32 v8, v27 offset:2860
	ds_write_b32 v8, v28 offset:3120
	ds_write_b32 v8, v29 offset:3380
	ds_write_b32 v8, v30 offset:3640
	ds_write_b32 v8, v31 offset:3900
	v_lshlrev_b32_e32 v0, 4, v6
	v_and_b32_e32 v0, 48, v0
	v_mul_u32_u24_e32 v2, 0x41, v0
	v_lshlrev_b32_e32 v2, 2, v2
	v_lshl_add_u32 v2, v3, 2, v2
	s_waitcnt lgkmcnt(0)
	s_barrier
	ds_read2_b32 v[4:5], v2 offset1:65
	ds_read2_b32 v[6:7], v2 offset0:130 offset1:195
	v_add_u32_e32 v8, 0x400, v2
	v_add_u32_e32 v10, 0x800, v2
	v_add_u32_e32 v2, 0xc00, v2
	s_waitcnt lgkmcnt(1)
	v_cvt_pk_bf16_f32 v4, v4, v5
	s_waitcnt lgkmcnt(0)
	v_cvt_pk_bf16_f32 v5, v6, v7
	ds_read2_b32 v[6:7], v8 offset0:4 offset1:69
	ds_read2_b32 v[8:9], v8 offset0:134 offset1:199
	ds_read2_b32 v[12:13], v2 offset0:142 offset1:207
	v_lshlrev_b32_e32 v0, 1, v0
	s_waitcnt lgkmcnt(2)
	v_cvt_pk_bf16_f32 v6, v6, v7
	s_waitcnt lgkmcnt(1)
	v_cvt_pk_bf16_f32 v7, v8, v9
	ds_read2_b32 v[8:9], v10 offset0:8 offset1:73
	ds_read2_b32 v[10:11], v10 offset0:138 offset1:203
	s_waitcnt lgkmcnt(1)
	v_cvt_pk_bf16_f32 v8, v8, v9
	s_waitcnt lgkmcnt(0)
	v_cvt_pk_bf16_f32 v9, v10, v11
	ds_read2_b32 v[10:11], v2 offset0:12 offset1:77
	v_add_u32_e32 v2, s0, v3
	v_ashrrev_i32_e32 v3, 31, v2
	s_lshl_b32 s0, s45, 1
	s_waitcnt lgkmcnt(0)
	v_cvt_pk_bf16_f32 v10, v10, v11
	v_cvt_pk_bf16_f32 v11, v12, v13
	v_mul_lo_u32 v12, s80, v3
	v_mul_lo_u32 v13, s81, v2
	v_mad_u64_u32 v[2:3], s[40:41], s80, v2, 0
	v_add3_u32 v3, v3, v12, v13
	v_lshl_add_u64 v[2:3], v[2:3], 1, s[78:79]
	v_lshl_add_u64 v[2:3], v[2:3], 0, s[0:1]
	v_lshl_add_u64 v[2:3], v[2:3], 0, v[0:1]
	s_mov_b64 s[40:41], 0
	global_store_dwordx4 v[2:3], v[4:7], off
	global_store_dwordx4 v[2:3], v[8:11], off offset:16
	s_barrier
